# younger wave group's deferred barrier moved to the next K-loop entry / phase end (its unit scheduling and accumulator clearing also overlap the older group's)
# baseline (speedup 1.0000x reference)
; #define LAS __attribute__((address_space(3)))
; #define LOADP(Pl) Params Pl; { CParams q_ = pk; asm volatile("" : "+s"(q_)); Pl = *q_; }
; __global__ void __launch_bounds__(512) fwd_megakernel(Params Parg) {
;     ...
;     cg::grid_group grid = cg::this_grid();
;     extern __shared__ __attribute__((aligned(16))) unsigned char smem[];
;     LAS unsigned char* lds = (LAS unsigned char*)smem;
;     CParams pk = (CParams)__builtin_amdgcn_kernarg_segment_ptr();
;     volatile LAS unsigned* xst = (volatile LAS unsigned*)(lds + STAGE_BYTES);
;     if (threadIdx.x == 0) { xst[0] = 0u; xst[1] = 0u; }
;     __syncthreads();
;     XcdBarrier xb; { LOADP(P) xb = xcd_barrier_post((unsigned*)(P.ws + OFF_BAR), xst); }
_Z14fwd_megakernel6Params:
	s_mov_b32 s101, 0
	s_load_dwordx2 s[56:57], s[0:1], 0xd8
	s_load_dword s33, s[0:1], 0xe0
	s_add_u32 s4, s0, 0xd8
	v_and_b32_e32 v186, 0x3ff, v0
	s_mov_b32 s72, s2
	s_addc_u32 s5, s1, 0
	v_cmp_ne_u32_e64 s[6:7], 0, v186
	v_cmp_eq_u32_e64 s[2:3], 0, v186
	s_mov_b64 s[8:9], exec
	s_nop 0
	v_writelane_b32 v233, s2, 0
	s_nop 1
	v_writelane_b32 v233, s3, 1
	s_and_b64 s[2:3], s[8:9], s[2:3]
	s_mov_b64 exec, s[2:3]
	s_cbranch_execz .LBB0_2
	s_add_i32 s2, 0, 0x20000
	v_mov_b32_e32 v1, 0
	v_mov_b32_e32 v2, s2
	s_add_i32 s2, 0, 0x20004
	ds_write_b32 v2, v1
	v_mov_b32_e32 v2, s2
	ds_write_b32 v2, v1

; #define G_STAGE(bufoff, gbase, o0, h64) do { \
;         __builtin_amdgcn_global_load_lds((const unsigned*)((const char*)(gbase) + (o0)), (LAS unsigned*)(lds + (bufoff) + ldsw), 16, 0, 0); \
;         __builtin_amdgcn_global_load_lds((const unsigned*)((const char*)(gbase) + (h64) + (o0)), (LAS unsigned*)(lds + (bufoff) + ldsw + 8192), 16, 0, 0); } while (0)
; #define G_LDA(dst, b, h) do { _Pragma("unroll") for (int m = 0; m < 4; ++m) _Pragma("unroll") for (int k = 0; k < 2; ++k) dst[m][k] = *(const LAS bf16x8*)(lds + G_SA(b, h) + aoff + m * 2048 + k * 1024); } while (0)
; #define G_LDB(dst, b, h) do { _Pragma("unroll") for (int n = 0; n < 2; ++n) _Pragma("unroll") for (int k = 0; k < 2; ++k) dst[n][k] = *(const LAS bf16x8*)(lds + G_SB(b, h) + boff + n * 2048 + k * 1024); } while (0)
; #define G_WAIT_L(n) asm volatile("s_waitcnt lgkmcnt(" #n ")" ::: "memory")
; #define G_BAR __builtin_amdgcn_s_barrier()
; #define G_SCHED __builtin_amdgcn_sched_barrier(0)
;     ...
;         const bool has_next = sched_next<PH, SUB>(E.ws, E.layer, ui + 1, nxt, E.x);
;         if (!has_next) nxt = cur;
;         const char* nA = nxt.A; const char* nB = nxt.B;
; #pragma unroll 1
;         for (int t = 0; t < nt; t += 2) {
;             const bool last = (t == nt - 2);
;             const char* a1 = cA + (size_t)(t + 1) * ckA;
;             const char* a2 = last ? nA : cA + (size_t)(t + 2) * ckA; const char* b2 = last ? nB : cB + (size_t)(t + 2) * kB;
;             const char* a3 = a2 + ckA; const char* b3 = b2 + kB;
;             G_LDB(B0, 0, 0); G_SCHED; G_LDA(At, 0, 0); G_STAGE(G_SA(1, 1), a1 + chA, cA0, qA);
;             G_WAIT_L(8); G_BAR; G_WAIT_L(0); G_MMA(0, 0, At, B0); G_BAR; G_SCHED;
;             G_LDB(B1, 0, 1); G_STAGE(G_SB(0, 0), b2, cB0, qB);
;             G_BAR; G_WAIT_L(0); G_MMA(0, 1, At, B1); G_BAR;
;             G_LDA(At, 0, 1); G_STAGE(G_SA(0, 0), a2, cA0, qA);
;     ...
;         if (!(cs.kind == K_MG_B && cur.aux < 2))
; #pragma unroll
;         for (int a = 0; a < 2; ++a)
; #pragma unroll
;             for (int b = 0; b < 2; ++b)
; #pragma unroll
;                 for (int m = 0; m < 4; ++m)
; #pragma unroll
;                     for (int n = 0; n < 2; ++n) acc[a][b][m][n] = (f32x4){0.f, 0.f, 0.f, 0.f};
;         cur = nxt; cA = nA; cB = nB; ++ui;
.LBB0_211:
	s_add_u32 s2, s2, 0x40080
	s_addc_u32 s3, s3, 0
	s_add_u32 s7, s22, 0x100
	v_mov_b64_e32 v[8:9], 0
	s_addc_u32 s22, s23, 0
	s_mov_b32 s23, -2
	v_mov_b64_e32 v[10:11], 0
	v_mov_b64_e32 v[12:13], 0
	v_mov_b64_e32 v[14:15], 0
	v_mov_b64_e32 v[24:25], 0
	v_mov_b64_e32 v[26:27], 0
	v_mov_b64_e32 v[28:29], 0
	v_mov_b64_e32 v[30:31], 0
	v_mov_b64_e32 v[40:41], 0
	v_mov_b64_e32 v[42:43], 0
	v_mov_b64_e32 v[44:45], 0
	v_mov_b64_e32 v[46:47], 0
	v_mov_b64_e32 v[56:57], 0
	v_mov_b64_e32 v[58:59], 0
	v_mov_b64_e32 v[60:61], 0
	v_mov_b64_e32 v[62:63], 0
	v_mov_b64_e32 v[16:17], 0
	v_mov_b64_e32 v[18:19], 0
	v_mov_b64_e32 v[20:21], 0
	v_mov_b64_e32 v[22:23], 0
	v_mov_b64_e32 v[32:33], 0
	v_mov_b64_e32 v[34:35], 0
	v_mov_b64_e32 v[36:37], 0
	v_mov_b64_e32 v[38:39], 0
	v_mov_b64_e32 v[48:49], 0
	v_mov_b64_e32 v[50:51], 0
	v_mov_b64_e32 v[52:53], 0
	v_mov_b64_e32 v[54:55], 0
	v_mov_b64_e32 v[64:65], 0
	v_mov_b64_e32 v[66:67], 0
	v_mov_b64_e32 v[68:69], 0
	v_mov_b64_e32 v[70:71], 0
	v_mov_b64_e32 v[72:73], 0
	v_mov_b64_e32 v[74:75], 0
	v_mov_b64_e32 v[76:77], 0
	v_mov_b64_e32 v[78:79], 0
	v_mov_b64_e32 v[88:89], 0
	v_mov_b64_e32 v[90:91], 0
	v_mov_b64_e32 v[92:93], 0
	v_mov_b64_e32 v[94:95], 0
	v_mov_b64_e32 v[104:105], 0
	v_mov_b64_e32 v[106:107], 0
	v_mov_b64_e32 v[108:109], 0
	v_mov_b64_e32 v[110:111], 0
	v_mov_b64_e32 v[120:121], 0
	v_mov_b64_e32 v[122:123], 0
	v_mov_b64_e32 v[124:125], 0
	v_mov_b64_e32 v[126:127], 0
	v_mov_b64_e32 v[80:81], 0
	v_mov_b64_e32 v[82:83], 0
	v_mov_b64_e32 v[84:85], 0
	v_mov_b64_e32 v[86:87], 0
	v_mov_b64_e32 v[96:97], 0
	v_mov_b64_e32 v[98:99], 0
	v_mov_b64_e32 v[100:101], 0
	v_mov_b64_e32 v[102:103], 0
	v_mov_b64_e32 v[112:113], 0
	v_mov_b64_e32 v[114:115], 0
	v_mov_b64_e32 v[116:117], 0
	v_mov_b64_e32 v[118:119], 0
	v_mov_b64_e32 v[128:129], 0
	v_mov_b64_e32 v[130:131], 0
	v_mov_b64_e32 v[132:133], 0
	v_mov_b64_e32 v[134:135], 0
	s_mov_b64 s[52:53], 0x40000
	s_mov_b64 s[54:55], 0x60000
	s_mov_b64 s[58:59], 0x20080
	s_mov_b64 s[62:63], 0x40080
	s_mov_b64 s[64:65], 0x60080
	s_cmpk_gt_u32 s101, 0xff
	s_cbranch_scc0 .Ldbj_WIN_in
	s_barrier
	s_mov_b32 s101, 0
.Ldbj_WIN_in:
.LBB0_212:
	s_add_u32 s4, s2, 0xfffc0080
	s_addc_u32 s5, s3, -1
	s_add_i32 s41, 0, 0x10000
	v_add_u32_e32 v0, s41, v167
	ds_read_b128 v[136:139], v0
	ds_read_b128 v[144:147], v0 offset:1024
	ds_read_b128 v[148:151], v0 offset:2048
	ds_read_b128 v[152:155], v0 offset:3072
	s_cmp_eq_u32 s23, 12
	s_cselect_b32 s43, s19, s5
	s_cselect_b32 s42, s18, s4
	s_cselect_b32 s51, s21, s22
	s_cselect_b32 s50, s20, s7
	v_lshl_add_u64 v[164:165], s[2:3], 0, v[142:143]
	s_add_i32 m0, s27, 0xc000
	ds_read_b128 v[156:159], v172
	ds_read_b128 v[160:163], v172 offset:1024
	ds_read_b128 v[174:177], v172 offset:2048
	ds_read_b128 v[178:181], v172 offset:3072
	ds_read_b128 v[182:185], v172 offset:4096
	ds_read_b128 v[196:199], v172 offset:5120
	ds_read_b128 v[200:203], v172 offset:6144
	ds_read_b128 v[204:207], v172 offset:7168
	global_load_lds_dwordx4 v[164:165], off
	v_lshl_add_u64 v[164:165], v[164:165], 0, s[0:1]
	s_add_i32 m0, s27, 0xe000
	s_nop 0
	global_load_lds_dwordx4 v[164:165], off
	s_waitcnt lgkmcnt(8)
	s_barrier
	s_waitcnt lgkmcnt(0)
	s_setprio 3
	s_waitcnt lgkmcnt(0)
	v_mfma_f32_16x16x32_bf16 v[132:135], v[136:139], v[156:159], v[132:135]
	v_mfma_f32_16x16x32_bf16 v[128:131], v[148:151], v[156:159], v[128:131]
	v_mfma_f32_16x16x32_bf16 v[116:119], v[136:139], v[174:177], v[116:119]
	v_mfma_f32_16x16x32_bf16 v[112:115], v[148:151], v[174:177], v[112:115]
	v_mfma_f32_16x16x32_bf16 v[100:103], v[136:139], v[182:185], v[100:103]
	v_mfma_f32_16x16x32_bf16 v[96:99], v[148:151], v[182:185], v[96:99]
	v_mfma_f32_16x16x32_bf16 v[84:87], v[136:139], v[200:203], v[84:87]
	v_mfma_f32_16x16x32_bf16 v[80:83], v[148:151], v[200:203], v[80:83]
	v_mfma_f32_16x16x32_bf16 v[132:135], v[144:147], v[160:163], v[132:135]
	v_mfma_f32_16x16x32_bf16 v[128:131], v[152:155], v[160:163], v[128:131]
	v_mfma_f32_16x16x32_bf16 v[116:119], v[144:147], v[178:181], v[116:119]
	v_mfma_f32_16x16x32_bf16 v[112:115], v[152:155], v[178:181], v[112:115]
	v_mfma_f32_16x16x32_bf16 v[100:103], v[144:147], v[196:199], v[100:103]
	v_mfma_f32_16x16x32_bf16 v[96:99], v[152:155], v[196:199], v[96:99]
	v_mfma_f32_16x16x32_bf16 v[84:87], v[144:147], v[204:207], v[84:87]
	v_mfma_f32_16x16x32_bf16 v[80:83], v[152:155], v[204:207], v[80:83]
	s_setprio 0
	s_barrier
	s_add_i32 s4, 0, 0x14000
	s_add_i32 s5, s41, s26
	v_add_u32_e32 v0, s4, v167
	v_lshl_add_u64 v[164:165], s[50:51], 0, v[140:141]
	s_mov_b32 m0, s5
	ds_read_b128 v[208:211], v0
	ds_read_b128 v[212:215], v0 offset:1024
	ds_read_b128 v[216:219], v0 offset:2048
	ds_read_b128 v[220:223], v0 offset:3072
	global_load_lds_dwordx4 v[164:165], off
	v_lshl_add_u64 v[224:225], v[164:165], 0, s[0:1]
	s_add_i32 m0, s5, 0x2000
	s_nop 0
	global_load_lds_dwordx4 v[224:225], off
	s_barrier
	s_waitcnt lgkmcnt(0)
	s_setprio 3
	s_waitcnt lgkmcnt(0)
	v_mfma_f32_16x16x32_bf16 v[124:127], v[208:211], v[156:159], v[124:127]
	v_mfma_f32_16x16x32_bf16 v[120:123], v[216:219], v[156:159], v[120:123]
	v_mfma_f32_16x16x32_bf16 v[108:111], v[208:211], v[174:177], v[108:111]
	v_mfma_f32_16x16x32_bf16 v[104:107], v[216:219], v[174:177], v[104:107]
	v_mfma_f32_16x16x32_bf16 v[92:95], v[208:211], v[182:185], v[92:95]
	v_mfma_f32_16x16x32_bf16 v[88:91], v[216:219], v[182:185], v[88:91]
	v_mfma_f32_16x16x32_bf16 v[76:79], v[208:211], v[200:203], v[76:79]
	v_mfma_f32_16x16x32_bf16 v[72:75], v[216:219], v[200:203], v[72:75]
	v_mfma_f32_16x16x32_bf16 v[124:127], v[212:215], v[160:163], v[124:127]
	v_mfma_f32_16x16x32_bf16 v[120:123], v[220:223], v[160:163], v[120:123]
	v_mfma_f32_16x16x32_bf16 v[108:111], v[212:215], v[178:181], v[108:111]
	v_mfma_f32_16x16x32_bf16 v[104:107], v[220:223], v[178:181], v[104:107]
	v_mfma_f32_16x16x32_bf16 v[92:95], v[212:215], v[196:199], v[92:95]
	v_mfma_f32_16x16x32_bf16 v[88:91], v[220:223], v[196:199], v[88:91]
	v_mfma_f32_16x16x32_bf16 v[76:79], v[212:215], v[204:207], v[76:79]
	v_mfma_f32_16x16x32_bf16 v[72:75], v[220:223], v[204:207], v[72:75]
	s_setprio 0
	s_mov_b32 m0, s27
	v_lshl_add_u64 v[224:225], s[42:43], 0, v[2:3]
	s_barrier
; #define G_STAGE(bufoff, gbase, o0, h64) do { \
;         __builtin_amdgcn_global_load_lds((const unsigned*)((const char*)(gbase) + (o0)), (LAS unsigned*)(lds + (bufoff) + ldsw), 16, 0, 0); \
;         __builtin_amdgcn_global_load_lds((const unsigned*)((const char*)(gbase) + (h64) + (o0)), (LAS unsigned*)(lds + (bufoff) + ldsw + 8192), 16, 0, 0); } while (0)
; #define G_LDA(dst, b, h) do { _Pragma("unroll") for (int m = 0; m < 4; ++m) _Pragma("unroll") for (int k = 0; k < 2; ++k) dst[m][k] = *(const LAS bf16x8*)(lds + G_SA(b, h) + aoff + m * 2048 + k * 1024); } while (0)
; #define G_LDB(dst, b, h) do { _Pragma("unroll") for (int n = 0; n < 2; ++n) _Pragma("unroll") for (int k = 0; k < 2; ++k) dst[n][k] = *(const LAS bf16x8*)(lds + G_SB(b, h) + boff + n * 2048 + k * 1024); } while (0)
; #define G_WAIT_V(n) asm volatile("s_waitcnt vmcnt(" #n ")" ::: "memory")
; #define G_WAIT_L(n) asm volatile("s_waitcnt lgkmcnt(" #n ")" ::: "memory")
; #define G_BAR __builtin_amdgcn_s_barrier()
; #define G_SCHED __builtin_amdgcn_sched_barrier(0)
;     ...
;             G_LDA(At, 0, 1); G_STAGE(G_SA(0, 0), a2, cA0, qA);
;             G_BAR; G_WAIT_L(0); G_MMA(1, 0, At, B0); G_BAR; G_SCHED;
;             G_STAGE(G_SB(0, 1), b2 + chB, cB0, qB);
;             G_WAIT_V(6); G_BAR; G_MMA(1, 1, At, B1); G_BAR;
;             G_LDB(B0, 1, 0); G_SCHED; G_LDA(At, 1, 0); G_STAGE(G_SA(0, 1), a2 + chA, cA0, qA);
;             G_WAIT_L(8); G_BAR; G_WAIT_L(0); G_MMA(0, 0, At, B0); G_BAR; G_SCHED;
	ds_read_b128 v[156:159], v172 offset:16384
	ds_read_b128 v[160:163], v172 offset:17408
	ds_read_b128 v[174:177], v172 offset:18432
	ds_read_b128 v[178:181], v172 offset:19456
	ds_read_b128 v[182:185], v172 offset:20480
	ds_read_b128 v[196:199], v172 offset:21504
	ds_read_b128 v[200:203], v172 offset:22528
	ds_read_b128 v[204:207], v172 offset:23552
	global_load_lds_dwordx4 v[224:225], off
	v_lshl_add_u64 v[226:227], v[224:225], 0, s[0:1]
	s_mov_b32 m0, s28
	s_nop 0
	global_load_lds_dwordx4 v[226:227], off
	s_barrier
	s_waitcnt lgkmcnt(0)
	s_setprio 3
	s_waitcnt lgkmcnt(0)
	v_mfma_f32_16x16x32_bf16 v[68:71], v[136:139], v[156:159], v[68:71]
	v_mfma_f32_16x16x32_bf16 v[64:67], v[148:151], v[156:159], v[64:67]
	v_mfma_f32_16x16x32_bf16 v[52:55], v[136:139], v[174:177], v[52:55]
	v_mfma_f32_16x16x32_bf16 v[48:51], v[148:151], v[174:177], v[48:51]
	v_mfma_f32_16x16x32_bf16 v[36:39], v[136:139], v[182:185], v[36:39]
	v_mfma_f32_16x16x32_bf16 v[32:35], v[148:151], v[182:185], v[32:35]
	v_mfma_f32_16x16x32_bf16 v[20:23], v[136:139], v[200:203], v[20:23]
	v_mfma_f32_16x16x32_bf16 v[16:19], v[148:151], v[200:203], v[16:19]
	v_mfma_f32_16x16x32_bf16 v[68:71], v[144:147], v[160:163], v[68:71]
	v_mfma_f32_16x16x32_bf16 v[64:67], v[152:155], v[160:163], v[64:67]
	v_mfma_f32_16x16x32_bf16 v[52:55], v[144:147], v[178:181], v[52:55]
	v_mfma_f32_16x16x32_bf16 v[48:51], v[152:155], v[178:181], v[48:51]
	v_mfma_f32_16x16x32_bf16 v[36:39], v[144:147], v[196:199], v[36:39]
	v_mfma_f32_16x16x32_bf16 v[32:35], v[152:155], v[196:199], v[32:35]
	v_mfma_f32_16x16x32_bf16 v[20:23], v[144:147], v[204:207], v[20:23]
	v_mfma_f32_16x16x32_bf16 v[16:19], v[152:155], v[204:207], v[16:19]
	s_setprio 0
	s_barrier
	s_add_i32 s4, s4, s26
	v_lshl_add_u64 v[136:137], v[164:165], 0, s[52:53]
	s_mov_b32 m0, s4
	s_nop 0
	global_load_lds_dwordx4 v[136:137], off
	v_lshl_add_u64 v[136:137], v[164:165], 0, s[54:55]
	s_add_i32 m0, s4, 0x2000
	s_nop 0
	global_load_lds_dwordx4 v[136:137], off
	s_waitcnt vmcnt(6)
	s_barrier
	s_setprio 3
	v_mfma_f32_16x16x32_bf16 v[60:63], v[208:211], v[156:159], v[60:63]
	v_mfma_f32_16x16x32_bf16 v[56:59], v[216:219], v[156:159], v[56:59]
	v_mfma_f32_16x16x32_bf16 v[44:47], v[208:211], v[174:177], v[44:47]
	v_mfma_f32_16x16x32_bf16 v[40:43], v[216:219], v[174:177], v[40:43]
	v_mfma_f32_16x16x32_bf16 v[28:31], v[208:211], v[182:185], v[28:31]
	v_mfma_f32_16x16x32_bf16 v[24:27], v[216:219], v[182:185], v[24:27]
	v_mfma_f32_16x16x32_bf16 v[12:15], v[208:211], v[200:203], v[12:15]
	v_mfma_f32_16x16x32_bf16 v[8:11], v[216:219], v[200:203], v[8:11]
	v_mfma_f32_16x16x32_bf16 v[60:63], v[212:215], v[160:163], v[60:63]
	v_mfma_f32_16x16x32_bf16 v[56:59], v[220:223], v[160:163], v[56:59]
	v_mfma_f32_16x16x32_bf16 v[44:47], v[212:215], v[178:181], v[44:47]
	v_mfma_f32_16x16x32_bf16 v[40:43], v[220:223], v[178:181], v[40:43]
	v_mfma_f32_16x16x32_bf16 v[28:31], v[212:215], v[196:199], v[28:31]
	v_mfma_f32_16x16x32_bf16 v[24:27], v[220:223], v[196:199], v[24:27]
	v_mfma_f32_16x16x32_bf16 v[12:15], v[212:215], v[204:207], v[12:15]
	v_mfma_f32_16x16x32_bf16 v[8:11], v[220:223], v[204:207], v[8:11]
	s_setprio 0
	s_add_i32 s4, 0, 0x18000
	v_add_u32_e32 v0, s4, v167
	s_barrier
	ds_read_b128 v[136:139], v0
	ds_read_b128 v[144:147], v0 offset:1024
	ds_read_b128 v[148:151], v0 offset:2048
	ds_read_b128 v[152:155], v0 offset:3072
	s_mov_b32 m0, s29
	v_lshl_add_u64 v[208:209], v[224:225], 0, s[52:53]
	ds_read_b128 v[156:159], v172 offset:32768
	ds_read_b128 v[160:163], v172 offset:33792
	ds_read_b128 v[174:177], v172 offset:34816
	ds_read_b128 v[178:181], v172 offset:35840
	ds_read_b128 v[182:185], v172 offset:36864
	ds_read_b128 v[196:199], v172 offset:37888
	ds_read_b128 v[200:203], v172 offset:38912
	ds_read_b128 v[204:207], v172 offset:39936
	global_load_lds_dwordx4 v[208:209], off
	v_lshl_add_u64 v[208:209], v[224:225], 0, s[54:55]
	s_mov_b32 m0, s30
	s_nop 0
	global_load_lds_dwordx4 v[208:209], off
	s_waitcnt lgkmcnt(8)
	s_barrier
	s_waitcnt lgkmcnt(0)
	s_setprio 3
	s_waitcnt lgkmcnt(0)
	v_mfma_f32_16x16x32_bf16 v[132:135], v[136:139], v[156:159], v[132:135]
	v_mfma_f32_16x16x32_bf16 v[128:131], v[148:151], v[156:159], v[128:131]
	v_mfma_f32_16x16x32_bf16 v[116:119], v[136:139], v[174:177], v[116:119]
	v_mfma_f32_16x16x32_bf16 v[112:115], v[148:151], v[174:177], v[112:115]
	v_mfma_f32_16x16x32_bf16 v[100:103], v[136:139], v[182:185], v[100:103]
	v_mfma_f32_16x16x32_bf16 v[96:99], v[148:151], v[182:185], v[96:99]
	v_mfma_f32_16x16x32_bf16 v[84:87], v[136:139], v[200:203], v[84:87]
	v_mfma_f32_16x16x32_bf16 v[80:83], v[148:151], v[200:203], v[80:83]
	v_mfma_f32_16x16x32_bf16 v[132:135], v[144:147], v[160:163], v[132:135]
	v_mfma_f32_16x16x32_bf16 v[128:131], v[152:155], v[160:163], v[128:131]
	v_mfma_f32_16x16x32_bf16 v[116:119], v[144:147], v[178:181], v[116:119]
	v_mfma_f32_16x16x32_bf16 v[112:115], v[152:155], v[178:181], v[112:115]
	v_mfma_f32_16x16x32_bf16 v[100:103], v[144:147], v[196:199], v[100:103]
	v_mfma_f32_16x16x32_bf16 v[96:99], v[152:155], v[196:199], v[96:99]
	v_mfma_f32_16x16x32_bf16 v[84:87], v[144:147], v[204:207], v[84:87]
	v_mfma_f32_16x16x32_bf16 v[80:83], v[152:155], v[204:207], v[80:83]
	s_setprio 0
	s_barrier
; #define G_STAGE(bufoff, gbase, o0, h64) do { \
;         __builtin_amdgcn_global_load_lds((const unsigned*)((const char*)(gbase) + (o0)), (LAS unsigned*)(lds + (bufoff) + ldsw), 16, 0, 0); \
;         __builtin_amdgcn_global_load_lds((const unsigned*)((const char*)(gbase) + (h64) + (o0)), (LAS unsigned*)(lds + (bufoff) + ldsw + 8192), 16, 0, 0); } while (0)
; #define G_LDA(dst, b, h) do { _Pragma("unroll") for (int m = 0; m < 4; ++m) _Pragma("unroll") for (int k = 0; k < 2; ++k) dst[m][k] = *(const LAS bf16x8*)(lds + G_SA(b, h) + aoff + m * 2048 + k * 1024); } while (0)
; #define G_LDB(dst, b, h) do { _Pragma("unroll") for (int n = 0; n < 2; ++n) _Pragma("unroll") for (int k = 0; k < 2; ++k) dst[n][k] = *(const LAS bf16x8*)(lds + G_SB(b, h) + boff + n * 2048 + k * 1024); } while (0)
; #define G_WAIT_V(n) asm volatile("s_waitcnt vmcnt(" #n ")" ::: "memory")
; #define G_WAIT_L(n) asm volatile("s_waitcnt lgkmcnt(" #n ")" ::: "memory")
; #define G_BAR __builtin_amdgcn_s_barrier()
; #define G_SCHED __builtin_amdgcn_sched_barrier(0)
;     ...
;             G_LDB(B1, 1, 1); G_STAGE(G_SB(1, 0), b3, cB0, qB);
;             G_BAR; G_WAIT_L(0); G_MMA(0, 1, At, B1); G_BAR;
;             G_LDA(At, 1, 1); G_STAGE(G_SA(1, 0), a3, cA0, qA);
;             G_BAR; G_WAIT_L(0); G_MMA(1, 0, At, B0); G_BAR; G_SCHED;
;             G_STAGE(G_SB(1, 1), b3 + chB, cB0, qB);
;             G_WAIT_V(6); G_BAR; G_MMA(1, 1, At, B1); G_BAR;
;         }
;         E.template run<cs.kind>(acc, cur, tid);
;         if (!has_next) break;
	s_add_i32 s5, 0, 0x1c000
	s_add_i32 s4, s4, s26
	v_add_u32_e32 v0, s5, v167
	v_lshl_add_u64 v[226:227], v[164:165], 0, s[46:47]
	s_mov_b32 m0, s4
	ds_read_b128 v[208:211], v0
	ds_read_b128 v[212:215], v0 offset:1024
	ds_read_b128 v[216:219], v0 offset:2048
	ds_read_b128 v[220:223], v0 offset:3072
	global_load_lds_dwordx4 v[226:227], off
	v_lshl_add_u64 v[226:227], v[164:165], 0, s[58:59]
	s_add_i32 m0, s4, 0x2000
	s_nop 0
	global_load_lds_dwordx4 v[226:227], off
	s_barrier
	s_waitcnt lgkmcnt(0)
	s_setprio 3
	s_waitcnt lgkmcnt(0)
	v_mfma_f32_16x16x32_bf16 v[124:127], v[208:211], v[156:159], v[124:127]
	v_mfma_f32_16x16x32_bf16 v[120:123], v[216:219], v[156:159], v[120:123]
	v_mfma_f32_16x16x32_bf16 v[108:111], v[208:211], v[174:177], v[108:111]
	v_mfma_f32_16x16x32_bf16 v[104:107], v[216:219], v[174:177], v[104:107]
	v_mfma_f32_16x16x32_bf16 v[92:95], v[208:211], v[182:185], v[92:95]
	v_mfma_f32_16x16x32_bf16 v[88:91], v[216:219], v[182:185], v[88:91]
	v_mfma_f32_16x16x32_bf16 v[76:79], v[208:211], v[200:203], v[76:79]
	v_mfma_f32_16x16x32_bf16 v[72:75], v[216:219], v[200:203], v[72:75]
	v_mfma_f32_16x16x32_bf16 v[124:127], v[212:215], v[160:163], v[124:127]
	v_mfma_f32_16x16x32_bf16 v[120:123], v[220:223], v[160:163], v[120:123]
	v_mfma_f32_16x16x32_bf16 v[108:111], v[212:215], v[178:181], v[108:111]
	v_mfma_f32_16x16x32_bf16 v[104:107], v[220:223], v[178:181], v[104:107]
	v_mfma_f32_16x16x32_bf16 v[92:95], v[212:215], v[196:199], v[92:95]
	v_mfma_f32_16x16x32_bf16 v[88:91], v[220:223], v[196:199], v[88:91]
	v_mfma_f32_16x16x32_bf16 v[76:79], v[212:215], v[204:207], v[76:79]
	v_mfma_f32_16x16x32_bf16 v[72:75], v[220:223], v[204:207], v[72:75]
	s_setprio 0
	s_mov_b32 m0, s31
	v_lshl_add_u64 v[226:227], v[224:225], 0, s[46:47]
	s_barrier
	ds_read_b128 v[156:159], v172 offset:49152
	ds_read_b128 v[160:163], v172 offset:50176
	ds_read_b128 v[174:177], v172 offset:51200
	ds_read_b128 v[178:181], v172 offset:52224
	ds_read_b128 v[182:185], v172 offset:53248
	ds_read_b128 v[196:199], v172 offset:54272
	ds_read_b128 v[200:203], v172 offset:55296
	ds_read_b128 v[204:207], v172 offset:56320
	global_load_lds_dwordx4 v[226:227], off
	v_lshl_add_u64 v[224:225], v[224:225], 0, s[58:59]
	s_mov_b32 m0, s34
	s_nop 0
	global_load_lds_dwordx4 v[224:225], off
	s_barrier
	s_waitcnt lgkmcnt(0)
	s_setprio 3
	s_waitcnt lgkmcnt(0)
	v_mfma_f32_16x16x32_bf16 v[68:71], v[136:139], v[156:159], v[68:71]
	v_mfma_f32_16x16x32_bf16 v[64:67], v[148:151], v[156:159], v[64:67]
	v_mfma_f32_16x16x32_bf16 v[52:55], v[136:139], v[174:177], v[52:55]
	v_mfma_f32_16x16x32_bf16 v[48:51], v[148:151], v[174:177], v[48:51]
	v_mfma_f32_16x16x32_bf16 v[36:39], v[136:139], v[182:185], v[36:39]
	v_mfma_f32_16x16x32_bf16 v[32:35], v[148:151], v[182:185], v[32:35]
	v_mfma_f32_16x16x32_bf16 v[20:23], v[136:139], v[200:203], v[20:23]
	v_mfma_f32_16x16x32_bf16 v[16:19], v[148:151], v[200:203], v[16:19]
	v_mfma_f32_16x16x32_bf16 v[68:71], v[144:147], v[160:163], v[68:71]
	v_mfma_f32_16x16x32_bf16 v[64:67], v[152:155], v[160:163], v[64:67]
	v_mfma_f32_16x16x32_bf16 v[52:55], v[144:147], v[178:181], v[52:55]
	v_mfma_f32_16x16x32_bf16 v[48:51], v[152:155], v[178:181], v[48:51]
	v_mfma_f32_16x16x32_bf16 v[36:39], v[144:147], v[196:199], v[36:39]
	v_mfma_f32_16x16x32_bf16 v[32:35], v[152:155], v[196:199], v[32:35]
	v_mfma_f32_16x16x32_bf16 v[20:23], v[144:147], v[204:207], v[20:23]
	v_mfma_f32_16x16x32_bf16 v[16:19], v[152:155], v[204:207], v[16:19]
	s_setprio 0
	s_barrier
	s_add_i32 s4, s5, s26
	v_lshl_add_u64 v[136:137], v[164:165], 0, s[62:63]
	s_mov_b32 m0, s4
	s_nop 0
	global_load_lds_dwordx4 v[136:137], off
	v_lshl_add_u64 v[136:137], v[164:165], 0, s[64:65]
	s_add_i32 m0, s4, 0x2000
	s_nop 0
	global_load_lds_dwordx4 v[136:137], off
	s_waitcnt vmcnt(6)
	s_barrier
	s_setprio 3
	v_mfma_f32_16x16x32_bf16 v[60:63], v[208:211], v[156:159], v[60:63]
	v_mfma_f32_16x16x32_bf16 v[56:59], v[216:219], v[156:159], v[56:59]
	v_mfma_f32_16x16x32_bf16 v[44:47], v[208:211], v[174:177], v[44:47]
	v_mfma_f32_16x16x32_bf16 v[40:43], v[216:219], v[174:177], v[40:43]
	v_mfma_f32_16x16x32_bf16 v[28:31], v[208:211], v[182:185], v[28:31]
	v_mfma_f32_16x16x32_bf16 v[24:27], v[216:219], v[182:185], v[24:27]
	v_mfma_f32_16x16x32_bf16 v[12:15], v[208:211], v[200:203], v[12:15]
	v_mfma_f32_16x16x32_bf16 v[8:11], v[216:219], v[200:203], v[8:11]
	v_mfma_f32_16x16x32_bf16 v[60:63], v[212:215], v[160:163], v[60:63]
	v_mfma_f32_16x16x32_bf16 v[56:59], v[220:223], v[160:163], v[56:59]
	v_mfma_f32_16x16x32_bf16 v[44:47], v[212:215], v[178:181], v[44:47]
	v_mfma_f32_16x16x32_bf16 v[40:43], v[220:223], v[178:181], v[40:43]
	v_mfma_f32_16x16x32_bf16 v[28:31], v[212:215], v[196:199], v[28:31]
	v_mfma_f32_16x16x32_bf16 v[24:27], v[220:223], v[196:199], v[24:27]
	v_mfma_f32_16x16x32_bf16 v[12:15], v[212:215], v[204:207], v[12:15]
	v_mfma_f32_16x16x32_bf16 v[8:11], v[220:223], v[204:207], v[8:11]
	s_setprio 0
	s_add_i32 s23, s23, 2
	s_add_u32 s2, s2, 0x100
	s_addc_u32 s3, s3, 0
	s_add_u32 s7, s7, 0x100
	s_addc_u32 s22, s22, 0
	s_cmp_gt_u32 s23, 13
	s_cbranch_scc0 .Ldb_WIN_cont
	v_readfirstlane_b32 s101, v186
	s_cmpk_gt_u32 s101, 0xff
	s_cbranch_scc1 .Ldb_WIN_exit
	s_barrier
	s_branch .Ldb_WIN_exit

; #define G_WAIT_V(n) asm volatile("s_waitcnt vmcnt(" #n ")" ::: "memory")
; #define G_BAR __builtin_amdgcn_s_barrier()
;     ...
;     G_WAIT_V(0);
;     if (wr == 0) G_BAR;
;     G_BAR;
.LBB0_341:
	s_cmpk_gt_u32 s101, 0xff
	s_cbranch_scc0 .Ldbj_WIN_pe
	s_barrier
	s_mov_b32 s101, 0

; #define G_STAGE(bufoff, gbase, o0, h64) do { \
;         __builtin_amdgcn_global_load_lds((const unsigned*)((const char*)(gbase) + (o0)), (LAS unsigned*)(lds + (bufoff) + ldsw), 16, 0, 0); \
;         __builtin_amdgcn_global_load_lds((const unsigned*)((const char*)(gbase) + (h64) + (o0)), (LAS unsigned*)(lds + (bufoff) + ldsw + 8192), 16, 0, 0); } while (0)
; #define G_LDA(dst, b, h) do { _Pragma("unroll") for (int m = 0; m < 4; ++m) _Pragma("unroll") for (int k = 0; k < 2; ++k) dst[m][k] = *(const LAS bf16x8*)(lds + G_SA(b, h) + aoff + m * 2048 + k * 1024); } while (0)
; #define G_LDB(dst, b, h) do { _Pragma("unroll") for (int n = 0; n < 2; ++n) _Pragma("unroll") for (int k = 0; k < 2; ++k) dst[n][k] = *(const LAS bf16x8*)(lds + G_SB(b, h) + boff + n * 2048 + k * 1024); } while (0)
; #define G_WAIT_L(n) asm volatile("s_waitcnt lgkmcnt(" #n ")" ::: "memory")
; #define G_BAR __builtin_amdgcn_s_barrier()
; #define G_SCHED __builtin_amdgcn_sched_barrier(0)
;     ...
;         const bool has_next = sched_next<PH, SUB>(E.ws, E.layer, ui + 1, nxt, E.x);
;         if (!has_next) nxt = cur;
;         const char* nA = nxt.A; const char* nB = nxt.B;
; #pragma unroll 1
;         for (int t = 0; t < nt; t += 2) {
;             const bool last = (t == nt - 2);
;             const char* a1 = cA + (size_t)(t + 1) * ckA;
;             const char* a2 = last ? nA : cA + (size_t)(t + 2) * ckA; const char* b2 = last ? nB : cB + (size_t)(t + 2) * kB;
;             const char* a3 = a2 + ckA; const char* b3 = b2 + kB;
;             G_LDB(B0, 0, 0); G_SCHED; G_LDA(At, 0, 0); G_STAGE(G_SA(1, 1), a1 + chA, cA0, qA);
;             G_WAIT_L(8); G_BAR; G_WAIT_L(0); G_MMA(0, 0, At, B0); G_BAR; G_SCHED;
;             G_LDB(B1, 0, 1); G_STAGE(G_SB(0, 0), b2, cB0, qB);
;             G_BAR; G_WAIT_L(0); G_MMA(0, 1, At, B1); G_BAR;
;             G_LDA(At, 0, 1); G_STAGE(G_SA(0, 0), a2, cA0, qA);
;     ...
;         if (!(cs.kind == K_MG_B && cur.aux < 2))
; #pragma unroll
;         for (int a = 0; a < 2; ++a)
; #pragma unroll
;             for (int b = 0; b < 2; ++b)
; #pragma unroll
;                 for (int m = 0; m < 4; ++m)
; #pragma unroll
;                     for (int n = 0; n < 2; ++n) acc[a][b][m][n] = (f32x4){0.f, 0.f, 0.f, 0.f};
;         cur = nxt; cA = nA; cB = nB; ++ui;
.LBB0_449:
	s_add_u32 s6, s22, 0x20080
	s_addc_u32 s7, s23, 0
	s_add_u32 s19, s20, 0x100
	v_mov_b64_e32 v[8:9], 0
	s_addc_u32 s20, s21, 0
	s_mov_b32 s21, -2
	v_mov_b64_e32 v[10:11], 0
	v_mov_b64_e32 v[12:13], 0
	v_mov_b64_e32 v[14:15], 0
	v_mov_b64_e32 v[24:25], 0
	v_mov_b64_e32 v[26:27], 0
	v_mov_b64_e32 v[28:29], 0
	v_mov_b64_e32 v[30:31], 0
	v_mov_b64_e32 v[40:41], 0
	v_mov_b64_e32 v[42:43], 0
	v_mov_b64_e32 v[44:45], 0
	v_mov_b64_e32 v[46:47], 0
	v_mov_b64_e32 v[56:57], 0
	v_mov_b64_e32 v[58:59], 0
	v_mov_b64_e32 v[60:61], 0
	v_mov_b64_e32 v[62:63], 0
	v_mov_b64_e32 v[16:17], 0
	v_mov_b64_e32 v[18:19], 0
	v_mov_b64_e32 v[20:21], 0
	v_mov_b64_e32 v[22:23], 0
	v_mov_b64_e32 v[32:33], 0
	v_mov_b64_e32 v[34:35], 0
	v_mov_b64_e32 v[36:37], 0
	v_mov_b64_e32 v[38:39], 0
	v_mov_b64_e32 v[48:49], 0
	v_mov_b64_e32 v[50:51], 0
	v_mov_b64_e32 v[52:53], 0
	v_mov_b64_e32 v[54:55], 0
	v_mov_b64_e32 v[64:65], 0
	v_mov_b64_e32 v[66:67], 0
	v_mov_b64_e32 v[68:69], 0
	v_mov_b64_e32 v[70:71], 0
	v_mov_b64_e32 v[72:73], 0
	v_mov_b64_e32 v[74:75], 0
	v_mov_b64_e32 v[76:77], 0
	v_mov_b64_e32 v[78:79], 0
	v_mov_b64_e32 v[88:89], 0
	v_mov_b64_e32 v[90:91], 0
	v_mov_b64_e32 v[92:93], 0
	v_mov_b64_e32 v[94:95], 0
	v_mov_b64_e32 v[104:105], 0
	v_mov_b64_e32 v[106:107], 0
	v_mov_b64_e32 v[108:109], 0
	v_mov_b64_e32 v[110:111], 0
	v_mov_b64_e32 v[120:121], 0
	v_mov_b64_e32 v[122:123], 0
	v_mov_b64_e32 v[124:125], 0
	v_mov_b64_e32 v[126:127], 0
	v_mov_b64_e32 v[80:81], 0
	v_mov_b64_e32 v[82:83], 0
	v_mov_b64_e32 v[84:85], 0
	v_mov_b64_e32 v[86:87], 0
	v_mov_b64_e32 v[96:97], 0
	v_mov_b64_e32 v[98:99], 0
	v_mov_b64_e32 v[100:101], 0
	v_mov_b64_e32 v[102:103], 0
	v_mov_b64_e32 v[112:113], 0
	v_mov_b64_e32 v[114:115], 0
	v_mov_b64_e32 v[116:117], 0
	v_mov_b64_e32 v[118:119], 0
	v_mov_b64_e32 v[128:129], 0
	v_mov_b64_e32 v[130:131], 0
	v_mov_b64_e32 v[132:133], 0
	v_mov_b64_e32 v[134:135], 0
	s_mov_b64 s[50:51], 0x20080
	s_mov_b64 s[52:53], 0x10000
	s_mov_b64 s[54:55], 0x30000
	s_mov_b64 s[58:59], 0x10080
	s_mov_b64 s[62:63], 0x30080
	s_cmpk_gt_u32 s101, 0xff
	s_cbranch_scc0 .Ldbj_SSM1_in
	s_barrier
	s_mov_b32 s101, 0
.Ldbj_SSM1_in:
.LBB0_450:
	s_add_u32 s4, s6, 0xfffe0080
	s_addc_u32 s5, s7, -1
	s_add_i32 s41, 0, 0x10000
	v_add_u32_e32 v0, s41, v145
	ds_read_b128 v[140:143], v0
	ds_read_b128 v[148:151], v0 offset:1024
	ds_read_b128 v[152:155], v0 offset:2048
	ds_read_b128 v[156:159], v0 offset:3072
	s_cmp_eq_u32 s21, 4
	s_cselect_b32 s23, s11, s5
	s_cselect_b32 s22, s10, s4
	s_cselect_b32 s43, s17, s20
	s_cselect_b32 s42, s16, s19
	v_lshl_add_u64 v[184:185], s[6:7], 0, v[138:139]
	s_add_i32 m0, s27, 0xc000
	ds_read_b128 v[160:163], v146
	ds_read_b128 v[164:167], v146 offset:1024
	ds_read_b128 v[172:175], v146 offset:2048
	ds_read_b128 v[176:179], v146 offset:3072
	ds_read_b128 v[180:183], v146 offset:4096
	ds_read_b128 v[196:199], v146 offset:5120
	ds_read_b128 v[200:203], v146 offset:6144
	ds_read_b128 v[204:207], v146 offset:7168
	global_load_lds_dwordx4 v[184:185], off
	v_lshl_add_u64 v[184:185], v[184:185], 0, s[52:53]
	s_add_i32 m0, s27, 0xe000
	s_nop 0
	global_load_lds_dwordx4 v[184:185], off
	s_waitcnt lgkmcnt(8)
	s_barrier
	s_waitcnt lgkmcnt(0)
	s_setprio 3
	s_waitcnt lgkmcnt(0)
	v_mfma_f32_16x16x32_bf16 v[132:135], v[140:143], v[160:163], v[132:135]
	v_mfma_f32_16x16x32_bf16 v[128:131], v[152:155], v[160:163], v[128:131]
	v_mfma_f32_16x16x32_bf16 v[116:119], v[140:143], v[172:175], v[116:119]
	v_mfma_f32_16x16x32_bf16 v[112:115], v[152:155], v[172:175], v[112:115]
	v_mfma_f32_16x16x32_bf16 v[100:103], v[140:143], v[180:183], v[100:103]
	v_mfma_f32_16x16x32_bf16 v[96:99], v[152:155], v[180:183], v[96:99]
	v_mfma_f32_16x16x32_bf16 v[84:87], v[140:143], v[200:203], v[84:87]
	v_mfma_f32_16x16x32_bf16 v[80:83], v[152:155], v[200:203], v[80:83]
	v_mfma_f32_16x16x32_bf16 v[132:135], v[148:151], v[164:167], v[132:135]
	v_mfma_f32_16x16x32_bf16 v[128:131], v[156:159], v[164:167], v[128:131]
	v_mfma_f32_16x16x32_bf16 v[116:119], v[148:151], v[176:179], v[116:119]
	v_mfma_f32_16x16x32_bf16 v[112:115], v[156:159], v[176:179], v[112:115]
	v_mfma_f32_16x16x32_bf16 v[100:103], v[148:151], v[196:199], v[100:103]
	v_mfma_f32_16x16x32_bf16 v[96:99], v[156:159], v[196:199], v[96:99]
	v_mfma_f32_16x16x32_bf16 v[84:87], v[148:151], v[204:207], v[84:87]
	v_mfma_f32_16x16x32_bf16 v[80:83], v[156:159], v[204:207], v[80:83]
	s_setprio 0
	s_barrier
	s_add_i32 s4, 0, 0x14000
	s_add_i32 s5, s41, s26
	v_add_u32_e32 v0, s4, v145
	v_lshl_add_u64 v[184:185], s[42:43], 0, v[136:137]
	s_mov_b32 m0, s5
	ds_read_b128 v[208:211], v0
	ds_read_b128 v[212:215], v0 offset:1024
	ds_read_b128 v[216:219], v0 offset:2048
	ds_read_b128 v[220:223], v0 offset:3072
	global_load_lds_dwordx4 v[184:185], off
	v_lshl_add_u64 v[224:225], v[184:185], 0, s[52:53]
	s_add_i32 m0, s5, 0x2000
	s_nop 0
	global_load_lds_dwordx4 v[224:225], off
	s_barrier
	s_waitcnt lgkmcnt(0)
	s_setprio 3
	s_waitcnt lgkmcnt(0)
	v_mfma_f32_16x16x32_bf16 v[124:127], v[208:211], v[160:163], v[124:127]
	v_mfma_f32_16x16x32_bf16 v[120:123], v[216:219], v[160:163], v[120:123]
	v_mfma_f32_16x16x32_bf16 v[108:111], v[208:211], v[172:175], v[108:111]
	v_mfma_f32_16x16x32_bf16 v[104:107], v[216:219], v[172:175], v[104:107]
	v_mfma_f32_16x16x32_bf16 v[92:95], v[208:211], v[180:183], v[92:95]
	v_mfma_f32_16x16x32_bf16 v[88:91], v[216:219], v[180:183], v[88:91]
	v_mfma_f32_16x16x32_bf16 v[76:79], v[208:211], v[200:203], v[76:79]
	v_mfma_f32_16x16x32_bf16 v[72:75], v[216:219], v[200:203], v[72:75]
	v_mfma_f32_16x16x32_bf16 v[124:127], v[212:215], v[164:167], v[124:127]
	v_mfma_f32_16x16x32_bf16 v[120:123], v[220:223], v[164:167], v[120:123]
	v_mfma_f32_16x16x32_bf16 v[108:111], v[212:215], v[176:179], v[108:111]
	v_mfma_f32_16x16x32_bf16 v[104:107], v[220:223], v[176:179], v[104:107]
	v_mfma_f32_16x16x32_bf16 v[92:95], v[212:215], v[196:199], v[92:95]
	v_mfma_f32_16x16x32_bf16 v[88:91], v[220:223], v[196:199], v[88:91]
	v_mfma_f32_16x16x32_bf16 v[76:79], v[212:215], v[204:207], v[76:79]
	v_mfma_f32_16x16x32_bf16 v[72:75], v[220:223], v[204:207], v[72:75]
	s_setprio 0
	s_mov_b32 m0, s27
	v_lshl_add_u64 v[224:225], s[22:23], 0, v[2:3]
	s_barrier
; #define G_STAGE(bufoff, gbase, o0, h64) do { \
;         __builtin_amdgcn_global_load_lds((const unsigned*)((const char*)(gbase) + (o0)), (LAS unsigned*)(lds + (bufoff) + ldsw), 16, 0, 0); \
;         __builtin_amdgcn_global_load_lds((const unsigned*)((const char*)(gbase) + (h64) + (o0)), (LAS unsigned*)(lds + (bufoff) + ldsw + 8192), 16, 0, 0); } while (0)
; #define G_LDA(dst, b, h) do { _Pragma("unroll") for (int m = 0; m < 4; ++m) _Pragma("unroll") for (int k = 0; k < 2; ++k) dst[m][k] = *(const LAS bf16x8*)(lds + G_SA(b, h) + aoff + m * 2048 + k * 1024); } while (0)
; #define G_LDB(dst, b, h) do { _Pragma("unroll") for (int n = 0; n < 2; ++n) _Pragma("unroll") for (int k = 0; k < 2; ++k) dst[n][k] = *(const LAS bf16x8*)(lds + G_SB(b, h) + boff + n * 2048 + k * 1024); } while (0)
; #define G_WAIT_V(n) asm volatile("s_waitcnt vmcnt(" #n ")" ::: "memory")
; #define G_WAIT_L(n) asm volatile("s_waitcnt lgkmcnt(" #n ")" ::: "memory")
; #define G_BAR __builtin_amdgcn_s_barrier()
; #define G_SCHED __builtin_amdgcn_sched_barrier(0)
;     ...
;             G_LDA(At, 0, 1); G_STAGE(G_SA(0, 0), a2, cA0, qA);
;             G_BAR; G_WAIT_L(0); G_MMA(1, 0, At, B0); G_BAR; G_SCHED;
;             G_STAGE(G_SB(0, 1), b2 + chB, cB0, qB);
;             G_WAIT_V(6); G_BAR; G_MMA(1, 1, At, B1); G_BAR;
;             G_LDB(B0, 1, 0); G_SCHED; G_LDA(At, 1, 0); G_STAGE(G_SA(0, 1), a2 + chA, cA0, qA);
;             G_WAIT_L(8); G_BAR; G_WAIT_L(0); G_MMA(0, 0, At, B0); G_BAR; G_SCHED;
	ds_read_b128 v[160:163], v146 offset:16384
	ds_read_b128 v[164:167], v146 offset:17408
	ds_read_b128 v[172:175], v146 offset:18432
	ds_read_b128 v[176:179], v146 offset:19456
	ds_read_b128 v[180:183], v146 offset:20480
	ds_read_b128 v[196:199], v146 offset:21504
	ds_read_b128 v[200:203], v146 offset:22528
	ds_read_b128 v[204:207], v146 offset:23552
	global_load_lds_dwordx4 v[224:225], off
	v_lshl_add_u64 v[226:227], v[224:225], 0, s[52:53]
	s_mov_b32 m0, s28
	s_nop 0
	global_load_lds_dwordx4 v[226:227], off
	s_barrier
	s_waitcnt lgkmcnt(0)
	s_setprio 3
	s_waitcnt lgkmcnt(0)
	v_mfma_f32_16x16x32_bf16 v[68:71], v[140:143], v[160:163], v[68:71]
	v_mfma_f32_16x16x32_bf16 v[64:67], v[152:155], v[160:163], v[64:67]
	v_mfma_f32_16x16x32_bf16 v[52:55], v[140:143], v[172:175], v[52:55]
	v_mfma_f32_16x16x32_bf16 v[48:51], v[152:155], v[172:175], v[48:51]
	v_mfma_f32_16x16x32_bf16 v[36:39], v[140:143], v[180:183], v[36:39]
	v_mfma_f32_16x16x32_bf16 v[32:35], v[152:155], v[180:183], v[32:35]
	v_mfma_f32_16x16x32_bf16 v[20:23], v[140:143], v[200:203], v[20:23]
	v_mfma_f32_16x16x32_bf16 v[16:19], v[152:155], v[200:203], v[16:19]
	v_mfma_f32_16x16x32_bf16 v[68:71], v[148:151], v[164:167], v[68:71]
	v_mfma_f32_16x16x32_bf16 v[64:67], v[156:159], v[164:167], v[64:67]
	v_mfma_f32_16x16x32_bf16 v[52:55], v[148:151], v[176:179], v[52:55]
	v_mfma_f32_16x16x32_bf16 v[48:51], v[156:159], v[176:179], v[48:51]
	v_mfma_f32_16x16x32_bf16 v[36:39], v[148:151], v[196:199], v[36:39]
	v_mfma_f32_16x16x32_bf16 v[32:35], v[156:159], v[196:199], v[32:35]
	v_mfma_f32_16x16x32_bf16 v[20:23], v[148:151], v[204:207], v[20:23]
	v_mfma_f32_16x16x32_bf16 v[16:19], v[156:159], v[204:207], v[16:19]
	s_setprio 0
	s_barrier
	s_add_i32 s4, s4, s26
	v_lshl_add_u64 v[140:141], v[184:185], 0, s[0:1]
	s_mov_b32 m0, s4
	s_nop 0
	global_load_lds_dwordx4 v[140:141], off
	v_lshl_add_u64 v[140:141], v[184:185], 0, s[54:55]
	s_add_i32 m0, s4, 0x2000
	s_nop 0
	global_load_lds_dwordx4 v[140:141], off
	s_waitcnt vmcnt(6)
	s_barrier
	s_setprio 3
	v_mfma_f32_16x16x32_bf16 v[60:63], v[208:211], v[160:163], v[60:63]
	v_mfma_f32_16x16x32_bf16 v[56:59], v[216:219], v[160:163], v[56:59]
	v_mfma_f32_16x16x32_bf16 v[44:47], v[208:211], v[172:175], v[44:47]
	v_mfma_f32_16x16x32_bf16 v[40:43], v[216:219], v[172:175], v[40:43]
	v_mfma_f32_16x16x32_bf16 v[28:31], v[208:211], v[180:183], v[28:31]
	v_mfma_f32_16x16x32_bf16 v[24:27], v[216:219], v[180:183], v[24:27]
	v_mfma_f32_16x16x32_bf16 v[12:15], v[208:211], v[200:203], v[12:15]
	v_mfma_f32_16x16x32_bf16 v[8:11], v[216:219], v[200:203], v[8:11]
	v_mfma_f32_16x16x32_bf16 v[60:63], v[212:215], v[164:167], v[60:63]
	v_mfma_f32_16x16x32_bf16 v[56:59], v[220:223], v[164:167], v[56:59]
	v_mfma_f32_16x16x32_bf16 v[44:47], v[212:215], v[176:179], v[44:47]
	v_mfma_f32_16x16x32_bf16 v[40:43], v[220:223], v[176:179], v[40:43]
	v_mfma_f32_16x16x32_bf16 v[28:31], v[212:215], v[196:199], v[28:31]
	v_mfma_f32_16x16x32_bf16 v[24:27], v[220:223], v[196:199], v[24:27]
	v_mfma_f32_16x16x32_bf16 v[12:15], v[212:215], v[204:207], v[12:15]
	v_mfma_f32_16x16x32_bf16 v[8:11], v[220:223], v[204:207], v[8:11]
	s_setprio 0
	s_add_i32 s4, 0, 0x18000
	v_add_u32_e32 v0, s4, v145
	s_barrier
	ds_read_b128 v[140:143], v0
	ds_read_b128 v[148:151], v0 offset:1024
	ds_read_b128 v[152:155], v0 offset:2048
	ds_read_b128 v[156:159], v0 offset:3072
	s_mov_b32 m0, s29
	v_lshl_add_u64 v[208:209], v[224:225], 0, s[0:1]
	ds_read_b128 v[160:163], v146 offset:32768
	ds_read_b128 v[164:167], v146 offset:33792
	ds_read_b128 v[172:175], v146 offset:34816
	ds_read_b128 v[176:179], v146 offset:35840
	ds_read_b128 v[180:183], v146 offset:36864
	ds_read_b128 v[196:199], v146 offset:37888
	ds_read_b128 v[200:203], v146 offset:38912
	ds_read_b128 v[204:207], v146 offset:39936
	global_load_lds_dwordx4 v[208:209], off
	v_lshl_add_u64 v[208:209], v[224:225], 0, s[54:55]
	s_mov_b32 m0, s30
	s_nop 0
	global_load_lds_dwordx4 v[208:209], off
	s_waitcnt lgkmcnt(8)
	s_barrier
	s_waitcnt lgkmcnt(0)
	s_setprio 3
	s_waitcnt lgkmcnt(0)
	v_mfma_f32_16x16x32_bf16 v[132:135], v[140:143], v[160:163], v[132:135]
	v_mfma_f32_16x16x32_bf16 v[128:131], v[152:155], v[160:163], v[128:131]
	v_mfma_f32_16x16x32_bf16 v[116:119], v[140:143], v[172:175], v[116:119]
	v_mfma_f32_16x16x32_bf16 v[112:115], v[152:155], v[172:175], v[112:115]
	v_mfma_f32_16x16x32_bf16 v[100:103], v[140:143], v[180:183], v[100:103]
	v_mfma_f32_16x16x32_bf16 v[96:99], v[152:155], v[180:183], v[96:99]
	v_mfma_f32_16x16x32_bf16 v[84:87], v[140:143], v[200:203], v[84:87]
	v_mfma_f32_16x16x32_bf16 v[80:83], v[152:155], v[200:203], v[80:83]
	v_mfma_f32_16x16x32_bf16 v[132:135], v[148:151], v[164:167], v[132:135]
	v_mfma_f32_16x16x32_bf16 v[128:131], v[156:159], v[164:167], v[128:131]
	v_mfma_f32_16x16x32_bf16 v[116:119], v[148:151], v[176:179], v[116:119]
	v_mfma_f32_16x16x32_bf16 v[112:115], v[156:159], v[176:179], v[112:115]
	v_mfma_f32_16x16x32_bf16 v[100:103], v[148:151], v[196:199], v[100:103]
	v_mfma_f32_16x16x32_bf16 v[96:99], v[156:159], v[196:199], v[96:99]
	v_mfma_f32_16x16x32_bf16 v[84:87], v[148:151], v[204:207], v[84:87]
	v_mfma_f32_16x16x32_bf16 v[80:83], v[156:159], v[204:207], v[80:83]
	s_setprio 0
	s_barrier
; #define G_STAGE(bufoff, gbase, o0, h64) do { \
;         __builtin_amdgcn_global_load_lds((const unsigned*)((const char*)(gbase) + (o0)), (LAS unsigned*)(lds + (bufoff) + ldsw), 16, 0, 0); \
;         __builtin_amdgcn_global_load_lds((const unsigned*)((const char*)(gbase) + (h64) + (o0)), (LAS unsigned*)(lds + (bufoff) + ldsw + 8192), 16, 0, 0); } while (0)
; #define G_LDA(dst, b, h) do { _Pragma("unroll") for (int m = 0; m < 4; ++m) _Pragma("unroll") for (int k = 0; k < 2; ++k) dst[m][k] = *(const LAS bf16x8*)(lds + G_SA(b, h) + aoff + m * 2048 + k * 1024); } while (0)
; #define G_LDB(dst, b, h) do { _Pragma("unroll") for (int n = 0; n < 2; ++n) _Pragma("unroll") for (int k = 0; k < 2; ++k) dst[n][k] = *(const LAS bf16x8*)(lds + G_SB(b, h) + boff + n * 2048 + k * 1024); } while (0)
; #define G_WAIT_V(n) asm volatile("s_waitcnt vmcnt(" #n ")" ::: "memory")
; #define G_WAIT_L(n) asm volatile("s_waitcnt lgkmcnt(" #n ")" ::: "memory")
; #define G_BAR __builtin_amdgcn_s_barrier()
; #define G_SCHED __builtin_amdgcn_sched_barrier(0)
;     ...
;             G_LDB(B1, 1, 1); G_STAGE(G_SB(1, 0), b3, cB0, qB);
;             G_BAR; G_WAIT_L(0); G_MMA(0, 1, At, B1); G_BAR;
;             G_LDA(At, 1, 1); G_STAGE(G_SA(1, 0), a3, cA0, qA);
;             G_BAR; G_WAIT_L(0); G_MMA(1, 0, At, B0); G_BAR; G_SCHED;
;             G_STAGE(G_SB(1, 1), b3 + chB, cB0, qB);
;             G_WAIT_V(6); G_BAR; G_MMA(1, 1, At, B1); G_BAR;
;         }
;         E.template run<cs.kind>(acc, cur, tid);
;         if (!has_next) break;
	s_add_i32 s5, 0, 0x1c000
	s_add_i32 s4, s4, s26
	v_add_u32_e32 v0, s5, v145
	v_lshl_add_u64 v[226:227], v[184:185], 0, s[46:47]
	s_mov_b32 m0, s4
	ds_read_b128 v[208:211], v0
	ds_read_b128 v[212:215], v0 offset:1024
	ds_read_b128 v[216:219], v0 offset:2048
	ds_read_b128 v[220:223], v0 offset:3072
	global_load_lds_dwordx4 v[226:227], off
	v_lshl_add_u64 v[226:227], v[184:185], 0, s[58:59]
	s_add_i32 m0, s4, 0x2000
	s_nop 0
	global_load_lds_dwordx4 v[226:227], off
	s_barrier
	s_waitcnt lgkmcnt(0)
	s_setprio 3
	s_waitcnt lgkmcnt(0)
	v_mfma_f32_16x16x32_bf16 v[124:127], v[208:211], v[160:163], v[124:127]
	v_mfma_f32_16x16x32_bf16 v[120:123], v[216:219], v[160:163], v[120:123]
	v_mfma_f32_16x16x32_bf16 v[108:111], v[208:211], v[172:175], v[108:111]
	v_mfma_f32_16x16x32_bf16 v[104:107], v[216:219], v[172:175], v[104:107]
	v_mfma_f32_16x16x32_bf16 v[92:95], v[208:211], v[180:183], v[92:95]
	v_mfma_f32_16x16x32_bf16 v[88:91], v[216:219], v[180:183], v[88:91]
	v_mfma_f32_16x16x32_bf16 v[76:79], v[208:211], v[200:203], v[76:79]
	v_mfma_f32_16x16x32_bf16 v[72:75], v[216:219], v[200:203], v[72:75]
	v_mfma_f32_16x16x32_bf16 v[124:127], v[212:215], v[164:167], v[124:127]
	v_mfma_f32_16x16x32_bf16 v[120:123], v[220:223], v[164:167], v[120:123]
	v_mfma_f32_16x16x32_bf16 v[108:111], v[212:215], v[176:179], v[108:111]
	v_mfma_f32_16x16x32_bf16 v[104:107], v[220:223], v[176:179], v[104:107]
	v_mfma_f32_16x16x32_bf16 v[92:95], v[212:215], v[196:199], v[92:95]
	v_mfma_f32_16x16x32_bf16 v[88:91], v[220:223], v[196:199], v[88:91]
	v_mfma_f32_16x16x32_bf16 v[76:79], v[212:215], v[204:207], v[76:79]
	v_mfma_f32_16x16x32_bf16 v[72:75], v[220:223], v[204:207], v[72:75]
	s_setprio 0
	s_mov_b32 m0, s31
	v_lshl_add_u64 v[226:227], v[224:225], 0, s[46:47]
	s_barrier
	ds_read_b128 v[160:163], v146 offset:49152
	ds_read_b128 v[164:167], v146 offset:50176
	ds_read_b128 v[172:175], v146 offset:51200
	ds_read_b128 v[176:179], v146 offset:52224
	ds_read_b128 v[180:183], v146 offset:53248
	ds_read_b128 v[196:199], v146 offset:54272
	ds_read_b128 v[200:203], v146 offset:55296
	ds_read_b128 v[204:207], v146 offset:56320
	global_load_lds_dwordx4 v[226:227], off
	v_lshl_add_u64 v[224:225], v[224:225], 0, s[58:59]
	s_mov_b32 m0, s33
	s_nop 0
	global_load_lds_dwordx4 v[224:225], off
	s_barrier
	s_waitcnt lgkmcnt(0)
	s_setprio 3
	s_waitcnt lgkmcnt(0)
	v_mfma_f32_16x16x32_bf16 v[68:71], v[140:143], v[160:163], v[68:71]
	v_mfma_f32_16x16x32_bf16 v[64:67], v[152:155], v[160:163], v[64:67]
	v_mfma_f32_16x16x32_bf16 v[52:55], v[140:143], v[172:175], v[52:55]
	v_mfma_f32_16x16x32_bf16 v[48:51], v[152:155], v[172:175], v[48:51]
	v_mfma_f32_16x16x32_bf16 v[36:39], v[140:143], v[180:183], v[36:39]
	v_mfma_f32_16x16x32_bf16 v[32:35], v[152:155], v[180:183], v[32:35]
	v_mfma_f32_16x16x32_bf16 v[20:23], v[140:143], v[200:203], v[20:23]
	v_mfma_f32_16x16x32_bf16 v[16:19], v[152:155], v[200:203], v[16:19]
	v_mfma_f32_16x16x32_bf16 v[68:71], v[148:151], v[164:167], v[68:71]
	v_mfma_f32_16x16x32_bf16 v[64:67], v[156:159], v[164:167], v[64:67]
	v_mfma_f32_16x16x32_bf16 v[52:55], v[148:151], v[176:179], v[52:55]
	v_mfma_f32_16x16x32_bf16 v[48:51], v[156:159], v[176:179], v[48:51]
	v_mfma_f32_16x16x32_bf16 v[36:39], v[148:151], v[196:199], v[36:39]
	v_mfma_f32_16x16x32_bf16 v[32:35], v[156:159], v[196:199], v[32:35]
	v_mfma_f32_16x16x32_bf16 v[20:23], v[148:151], v[204:207], v[20:23]
	v_mfma_f32_16x16x32_bf16 v[16:19], v[156:159], v[204:207], v[16:19]
	s_setprio 0
	s_barrier
	s_add_i32 s4, s5, s26
	v_lshl_add_u64 v[140:141], v[184:185], 0, s[50:51]
	s_mov_b32 m0, s4
	s_nop 0
	global_load_lds_dwordx4 v[140:141], off
	v_lshl_add_u64 v[140:141], v[184:185], 0, s[62:63]
	s_add_i32 m0, s4, 0x2000
	s_nop 0
	global_load_lds_dwordx4 v[140:141], off
	s_waitcnt vmcnt(6)
	s_barrier
	s_setprio 3
	v_mfma_f32_16x16x32_bf16 v[60:63], v[208:211], v[160:163], v[60:63]
	v_mfma_f32_16x16x32_bf16 v[56:59], v[216:219], v[160:163], v[56:59]
	v_mfma_f32_16x16x32_bf16 v[44:47], v[208:211], v[172:175], v[44:47]
	v_mfma_f32_16x16x32_bf16 v[40:43], v[216:219], v[172:175], v[40:43]
	v_mfma_f32_16x16x32_bf16 v[28:31], v[208:211], v[180:183], v[28:31]
	v_mfma_f32_16x16x32_bf16 v[24:27], v[216:219], v[180:183], v[24:27]
	v_mfma_f32_16x16x32_bf16 v[12:15], v[208:211], v[200:203], v[12:15]
	v_mfma_f32_16x16x32_bf16 v[8:11], v[216:219], v[200:203], v[8:11]
	v_mfma_f32_16x16x32_bf16 v[60:63], v[212:215], v[164:167], v[60:63]
	v_mfma_f32_16x16x32_bf16 v[56:59], v[220:223], v[164:167], v[56:59]
	v_mfma_f32_16x16x32_bf16 v[44:47], v[212:215], v[176:179], v[44:47]
	v_mfma_f32_16x16x32_bf16 v[40:43], v[220:223], v[176:179], v[40:43]
	v_mfma_f32_16x16x32_bf16 v[28:31], v[212:215], v[196:199], v[28:31]
	v_mfma_f32_16x16x32_bf16 v[24:27], v[220:223], v[196:199], v[24:27]
	v_mfma_f32_16x16x32_bf16 v[12:15], v[212:215], v[204:207], v[12:15]
	v_mfma_f32_16x16x32_bf16 v[8:11], v[220:223], v[204:207], v[8:11]
	s_setprio 0
	s_add_i32 s21, s21, 2
	s_add_u32 s6, s6, 0x100
	s_addc_u32 s7, s7, 0
	s_add_u32 s19, s19, 0x100
	s_addc_u32 s20, s20, 0
	s_cmp_gt_u32 s21, 5
	s_cbranch_scc0 .Ldb_SSM1_cont
	v_readfirstlane_b32 s101, v186
	s_cmpk_gt_u32 s101, 0xff
	s_cbranch_scc1 .Ldb_SSM1_exit
	s_barrier
	s_branch .Ldb_SSM1_exit

; #define G_STAGE(bufoff, gbase, o0, h64) do { \
;         __builtin_amdgcn_global_load_lds((const unsigned*)((const char*)(gbase) + (o0)), (LAS unsigned*)(lds + (bufoff) + ldsw), 16, 0, 0); \
;         __builtin_amdgcn_global_load_lds((const unsigned*)((const char*)(gbase) + (h64) + (o0)), (LAS unsigned*)(lds + (bufoff) + ldsw + 8192), 16, 0, 0); } while (0)
; #define G_LDA(dst, b, h) do { _Pragma("unroll") for (int m = 0; m < 4; ++m) _Pragma("unroll") for (int k = 0; k < 2; ++k) dst[m][k] = *(const LAS bf16x8*)(lds + G_SA(b, h) + aoff + m * 2048 + k * 1024); } while (0)
; #define G_LDB(dst, b, h) do { _Pragma("unroll") for (int n = 0; n < 2; ++n) _Pragma("unroll") for (int k = 0; k < 2; ++k) dst[n][k] = *(const LAS bf16x8*)(lds + G_SB(b, h) + boff + n * 2048 + k * 1024); } while (0)
; #define G_WAIT_L(n) asm volatile("s_waitcnt lgkmcnt(" #n ")" ::: "memory")
; #define G_BAR __builtin_amdgcn_s_barrier()
; #define G_SCHED __builtin_amdgcn_sched_barrier(0)
;     ...
;         const bool has_next = sched_next<PH, SUB>(E.ws, E.layer, ui + 1, nxt, E.x);
;         if (!has_next) nxt = cur;
;         const char* nA = nxt.A; const char* nB = nxt.B;
; #pragma unroll 1
;         for (int t = 0; t < nt; t += 2) {
;             const bool last = (t == nt - 2);
;             const char* a1 = cA + (size_t)(t + 1) * ckA;
;             const char* a2 = last ? nA : cA + (size_t)(t + 2) * ckA; const char* b2 = last ? nB : cB + (size_t)(t + 2) * kB;
;             const char* a3 = a2 + ckA; const char* b3 = b2 + kB;
;             G_LDB(B0, 0, 0); G_SCHED; G_LDA(At, 0, 0); G_STAGE(G_SA(1, 1), a1 + chA, cA0, qA);
;             G_WAIT_L(8); G_BAR; G_WAIT_L(0); G_MMA(0, 0, At, B0); G_BAR; G_SCHED;
;             G_LDB(B1, 0, 1); G_STAGE(G_SB(0, 0), b2, cB0, qB);
;             G_BAR; G_WAIT_L(0); G_MMA(0, 1, At, B1); G_BAR;
;     ...
;         if (!(cs.kind == K_MG_B && cur.aux < 2))
; #pragma unroll
;         for (int a = 0; a < 2; ++a)
; #pragma unroll
;             for (int b = 0; b < 2; ++b)
; #pragma unroll
;                 for (int m = 0; m < 4; ++m)
; #pragma unroll
;                     for (int n = 0; n < 2; ++n) acc[a][b][m][n] = (f32x4){0.f, 0.f, 0.f, 0.f};
;         cur = nxt; cA = nA; cB = nB; ++ui;
.LBB0_741:
	v_mov_b64_e32 v[8:9], 0
	s_mov_b64 s[30:31], 0
	s_mov_b64 s[24:25], -1
	s_mov_b64 s[26:27], 0
	v_mov_b64_e32 v[10:11], 0
	v_mov_b64_e32 v[12:13], 0
	v_mov_b64_e32 v[14:15], 0
	v_mov_b64_e32 v[24:25], 0
	v_mov_b64_e32 v[26:27], 0
	v_mov_b64_e32 v[28:29], 0
	v_mov_b64_e32 v[30:31], 0
	v_mov_b64_e32 v[40:41], 0
	v_mov_b64_e32 v[42:43], 0
	v_mov_b64_e32 v[44:45], 0
	v_mov_b64_e32 v[46:47], 0
	v_mov_b64_e32 v[64:65], 0
	v_mov_b64_e32 v[66:67], 0
	v_mov_b64_e32 v[68:69], 0
	v_mov_b64_e32 v[70:71], 0
	v_mov_b64_e32 v[16:17], 0
	v_mov_b64_e32 v[18:19], 0
	v_mov_b64_e32 v[20:21], 0
	v_mov_b64_e32 v[22:23], 0
	v_mov_b64_e32 v[32:33], 0
	v_mov_b64_e32 v[34:35], 0
	v_mov_b64_e32 v[36:37], 0
	v_mov_b64_e32 v[38:39], 0
	v_mov_b64_e32 v[48:49], 0
	v_mov_b64_e32 v[50:51], 0
	v_mov_b64_e32 v[52:53], 0
	v_mov_b64_e32 v[54:55], 0
	v_mov_b64_e32 v[72:73], 0
	v_mov_b64_e32 v[74:75], 0
	v_mov_b64_e32 v[76:77], 0
	v_mov_b64_e32 v[78:79], 0
	v_mov_b64_e32 v[80:81], 0
	v_mov_b64_e32 v[82:83], 0
	v_mov_b64_e32 v[84:85], 0
	v_mov_b64_e32 v[86:87], 0
	v_mov_b64_e32 v[96:97], 0
	v_mov_b64_e32 v[98:99], 0
	v_mov_b64_e32 v[100:101], 0
	v_mov_b64_e32 v[102:103], 0
	v_mov_b64_e32 v[112:113], 0
	v_mov_b64_e32 v[114:115], 0
	v_mov_b64_e32 v[116:117], 0
	v_mov_b64_e32 v[118:119], 0
	v_mov_b64_e32 v[128:129], 0
	v_mov_b64_e32 v[130:131], 0
	v_mov_b64_e32 v[132:133], 0
	v_mov_b64_e32 v[134:135], 0
	v_mov_b64_e32 v[88:89], 0
	v_mov_b64_e32 v[90:91], 0
	v_mov_b64_e32 v[92:93], 0
	v_mov_b64_e32 v[94:95], 0
	v_mov_b64_e32 v[104:105], 0
	v_mov_b64_e32 v[106:107], 0
	v_mov_b64_e32 v[108:109], 0
	v_mov_b64_e32 v[110:111], 0
	v_mov_b64_e32 v[120:121], 0
	v_mov_b64_e32 v[122:123], 0
	v_mov_b64_e32 v[124:125], 0
	v_mov_b64_e32 v[126:127], 0
	v_mov_b64_e32 v[136:137], 0
	v_mov_b64_e32 v[138:139], 0
	v_mov_b64_e32 v[140:141], 0
	v_mov_b64_e32 v[142:143], 0
	s_mov_b64 s[82:83], 0x10000
	s_mov_b64 s[84:85], 0x10080
	s_mov_b64 s[86:87], 0x200000
	s_mov_b64 s[88:89], 0x100000
	s_mov_b64 s[92:93], 0x8000
	s_mov_b64 s[94:95], 0x18000
	s_mov_b64 s[96:97], 0x300000
	s_mov_b64 s[70:71], 0x8080
	s_mov_b64 s[68:69], 0x100080
	s_mov_b64 s[28:29], 0x18080
	s_cmpk_gt_u32 s101, 0xff
	s_cbranch_scc0 .Ldbj_SSM2_in
	s_barrier
	s_mov_b32 s101, 0
.Ldbj_SSM2_in:
.LBB0_742:
	s_add_u32 s36, s2, s30
	s_addc_u32 s37, s3, s31
	s_add_u32 s19, s36, 0x100
	s_addc_u32 s35, s37, 0
	s_and_b64 s[4:5], s[26:27], exec
	s_cselect_b32 s34, s12, s19
	s_cselect_b32 s35, s13, s35
	s_add_u32 s4, s20, s30
	s_addc_u32 s5, s21, s31
	s_add_u32 s19, s4, 0x100
	s_addc_u32 s30, s5, 0
	s_add_i32 s44, 0, 0x10000
	v_add_u32_e32 v0, s44, v183
	ds_read_b128 v[56:59], v0
	ds_read_b128 v[60:63], v0 offset:1024
	ds_read_b128 v[144:147], v0 offset:2048
	ds_read_b128 v[148:151], v0 offset:3072
	s_and_b64 s[4:5], s[26:27], exec
	s_cselect_b32 s26, s16, s19
	s_cselect_b32 s27, s17, s30
	s_add_i32 s48, 0, 0x14000
	s_add_i32 s31, 0, 0x18000
	s_add_i32 s19, 0, 0x1c000
	s_add_i32 s49, s44, s38
	s_add_i32 s63, s48, s38
	s_add_i32 s30, s31, s38
	s_add_i32 s65, s19, s38
	s_add_i32 m0, s43, 0xc000
	s_add_i32 s45, s43, 0xe000
	s_add_i32 s66, s49, 0x2000
	s_add_i32 s62, s63, 0x2000
	s_add_i32 s67, s30, 0x2000
	s_add_i32 s64, s65, 0x2000
	v_lshl_add_u64 v[166:167], s[36:37], 0, v[160:161]
	s_mov_b64 s[4:5], 0x200080
	v_lshl_add_u64 v[180:181], v[166:167], 0, s[4:5]
	s_mov_b64 s[4:5], 0x300080
	ds_read_b128 v[152:155], v184
	ds_read_b128 v[156:159], v184 offset:1024
	ds_read_b128 v[162:165], v184 offset:2048
	ds_read_b128 v[172:175], v184 offset:3072
	ds_read_b128 v[176:179], v184 offset:4096
	ds_read_b128 v[196:199], v184 offset:5120
	ds_read_b128 v[200:203], v184 offset:6144
	ds_read_b128 v[204:207], v184 offset:7168
	global_load_lds_dwordx4 v[180:181], off
	v_lshl_add_u64 v[166:167], v[166:167], 0, s[4:5]
	s_mov_b32 m0, s45
	s_nop 0
	global_load_lds_dwordx4 v[166:167], off
	s_waitcnt lgkmcnt(8)
	s_barrier
	s_waitcnt lgkmcnt(0)
	s_setprio 3
	s_waitcnt lgkmcnt(0)
	v_mfma_f32_16x16x32_bf16 v[140:143], v[56:59], v[152:155], v[140:143]
	v_mfma_f32_16x16x32_bf16 v[136:139], v[144:147], v[152:155], v[136:139]
	v_mfma_f32_16x16x32_bf16 v[124:127], v[56:59], v[162:165], v[124:127]
	v_mfma_f32_16x16x32_bf16 v[120:123], v[144:147], v[162:165], v[120:123]
	v_mfma_f32_16x16x32_bf16 v[108:111], v[56:59], v[176:179], v[108:111]
	v_mfma_f32_16x16x32_bf16 v[104:107], v[144:147], v[176:179], v[104:107]
	v_mfma_f32_16x16x32_bf16 v[92:95], v[56:59], v[200:203], v[92:95]
	v_mfma_f32_16x16x32_bf16 v[88:91], v[144:147], v[200:203], v[88:91]
	v_mfma_f32_16x16x32_bf16 v[140:143], v[60:63], v[156:159], v[140:143]
	v_mfma_f32_16x16x32_bf16 v[136:139], v[148:151], v[156:159], v[136:139]
	v_mfma_f32_16x16x32_bf16 v[124:127], v[60:63], v[172:175], v[124:127]
	v_mfma_f32_16x16x32_bf16 v[120:123], v[148:151], v[172:175], v[120:123]
	v_mfma_f32_16x16x32_bf16 v[108:111], v[60:63], v[196:199], v[108:111]
	v_mfma_f32_16x16x32_bf16 v[104:107], v[148:151], v[196:199], v[104:107]
	v_mfma_f32_16x16x32_bf16 v[92:95], v[60:63], v[204:207], v[92:95]
	v_mfma_f32_16x16x32_bf16 v[88:91], v[148:151], v[204:207], v[88:91]
	s_setprio 0
	s_barrier
	s_mov_b32 m0, s49
	v_add_u32_e32 v0, s48, v183
	v_lshl_add_u64 v[166:167], s[26:27], 0, v[2:3]
	ds_read_b128 v[208:211], v0
	ds_read_b128 v[212:215], v0 offset:1024
	ds_read_b128 v[216:219], v0 offset:2048
	ds_read_b128 v[220:223], v0 offset:3072
	global_load_lds_dwordx4 v[166:167], off
	v_lshl_add_u64 v[180:181], v[166:167], 0, s[92:93]
	s_mov_b32 m0, s66
	s_nop 0
	global_load_lds_dwordx4 v[180:181], off
	s_barrier
; #define G_STAGE(bufoff, gbase, o0, h64) do { \
;         __builtin_amdgcn_global_load_lds((const unsigned*)((const char*)(gbase) + (o0)), (LAS unsigned*)(lds + (bufoff) + ldsw), 16, 0, 0); \
;         __builtin_amdgcn_global_load_lds((const unsigned*)((const char*)(gbase) + (h64) + (o0)), (LAS unsigned*)(lds + (bufoff) + ldsw + 8192), 16, 0, 0); } while (0)
; #define G_LDA(dst, b, h) do { _Pragma("unroll") for (int m = 0; m < 4; ++m) _Pragma("unroll") for (int k = 0; k < 2; ++k) dst[m][k] = *(const LAS bf16x8*)(lds + G_SA(b, h) + aoff + m * 2048 + k * 1024); } while (0)
; #define G_LDB(dst, b, h) do { _Pragma("unroll") for (int n = 0; n < 2; ++n) _Pragma("unroll") for (int k = 0; k < 2; ++k) dst[n][k] = *(const LAS bf16x8*)(lds + G_SB(b, h) + boff + n * 2048 + k * 1024); } while (0)
; #define G_WAIT_V(n) asm volatile("s_waitcnt vmcnt(" #n ")" ::: "memory")
; #define G_WAIT_L(n) asm volatile("s_waitcnt lgkmcnt(" #n ")" ::: "memory")
; #define G_BAR __builtin_amdgcn_s_barrier()
; #define G_SCHED __builtin_amdgcn_sched_barrier(0)
;     ...
;             G_BAR; G_WAIT_L(0); G_MMA(0, 1, At, B1); G_BAR;
;             G_LDA(At, 0, 1); G_STAGE(G_SA(0, 0), a2, cA0, qA);
;             G_BAR; G_WAIT_L(0); G_MMA(1, 0, At, B0); G_BAR; G_SCHED;
;             G_STAGE(G_SB(0, 1), b2 + chB, cB0, qB);
;             G_WAIT_V(6); G_BAR; G_MMA(1, 1, At, B1); G_BAR;
;             G_LDB(B0, 1, 0); G_SCHED; G_LDA(At, 1, 0); G_STAGE(G_SA(0, 1), a2 + chA, cA0, qA);
	s_waitcnt lgkmcnt(0)
	s_setprio 3
	s_waitcnt lgkmcnt(0)
	v_mfma_f32_16x16x32_bf16 v[132:135], v[208:211], v[152:155], v[132:135]
	v_mfma_f32_16x16x32_bf16 v[128:131], v[216:219], v[152:155], v[128:131]
	v_mfma_f32_16x16x32_bf16 v[116:119], v[208:211], v[162:165], v[116:119]
	v_mfma_f32_16x16x32_bf16 v[112:115], v[216:219], v[162:165], v[112:115]
	v_mfma_f32_16x16x32_bf16 v[100:103], v[208:211], v[176:179], v[100:103]
	v_mfma_f32_16x16x32_bf16 v[96:99], v[216:219], v[176:179], v[96:99]
	v_mfma_f32_16x16x32_bf16 v[84:87], v[208:211], v[200:203], v[84:87]
	v_mfma_f32_16x16x32_bf16 v[80:83], v[216:219], v[200:203], v[80:83]
	v_mfma_f32_16x16x32_bf16 v[132:135], v[212:215], v[156:159], v[132:135]
	v_mfma_f32_16x16x32_bf16 v[128:131], v[220:223], v[156:159], v[128:131]
	v_mfma_f32_16x16x32_bf16 v[116:119], v[212:215], v[172:175], v[116:119]
	v_mfma_f32_16x16x32_bf16 v[112:115], v[220:223], v[172:175], v[112:115]
	v_mfma_f32_16x16x32_bf16 v[100:103], v[212:215], v[196:199], v[100:103]
	v_mfma_f32_16x16x32_bf16 v[96:99], v[220:223], v[196:199], v[96:99]
	v_mfma_f32_16x16x32_bf16 v[84:87], v[212:215], v[204:207], v[84:87]
	v_mfma_f32_16x16x32_bf16 v[80:83], v[220:223], v[204:207], v[80:83]
	s_setprio 0
	s_mov_b32 m0, s43
	v_lshl_add_u64 v[180:181], s[34:35], 0, v[160:161]
	s_barrier
	ds_read_b128 v[152:155], v184 offset:16384
	ds_read_b128 v[156:159], v184 offset:17408
	ds_read_b128 v[162:165], v184 offset:18432
	ds_read_b128 v[172:175], v184 offset:19456
	ds_read_b128 v[176:179], v184 offset:20480
	ds_read_b128 v[196:199], v184 offset:21504
	ds_read_b128 v[200:203], v184 offset:22528
	ds_read_b128 v[204:207], v184 offset:23552
	global_load_lds_dwordx4 v[180:181], off
	v_lshl_add_u64 v[224:225], v[180:181], 0, s[88:89]
	s_mov_b32 m0, s50
	s_nop 0
	global_load_lds_dwordx4 v[224:225], off
	s_barrier
	s_waitcnt lgkmcnt(0)
	s_setprio 3
	s_waitcnt lgkmcnt(0)
	v_mfma_f32_16x16x32_bf16 v[76:79], v[56:59], v[152:155], v[76:79]
	v_mfma_f32_16x16x32_bf16 v[72:75], v[144:147], v[152:155], v[72:75]
	v_mfma_f32_16x16x32_bf16 v[52:55], v[56:59], v[162:165], v[52:55]
	v_mfma_f32_16x16x32_bf16 v[48:51], v[144:147], v[162:165], v[48:51]
	v_mfma_f32_16x16x32_bf16 v[36:39], v[56:59], v[176:179], v[36:39]
	v_mfma_f32_16x16x32_bf16 v[32:35], v[144:147], v[176:179], v[32:35]
	v_mfma_f32_16x16x32_bf16 v[20:23], v[56:59], v[200:203], v[20:23]
	v_mfma_f32_16x16x32_bf16 v[16:19], v[144:147], v[200:203], v[16:19]
	v_mfma_f32_16x16x32_bf16 v[76:79], v[60:63], v[156:159], v[76:79]
	v_mfma_f32_16x16x32_bf16 v[72:75], v[148:151], v[156:159], v[72:75]
	v_mfma_f32_16x16x32_bf16 v[52:55], v[60:63], v[172:175], v[52:55]
	v_mfma_f32_16x16x32_bf16 v[48:51], v[148:151], v[172:175], v[48:51]
	v_mfma_f32_16x16x32_bf16 v[36:39], v[60:63], v[196:199], v[36:39]
	v_mfma_f32_16x16x32_bf16 v[32:35], v[148:151], v[196:199], v[32:35]
	v_mfma_f32_16x16x32_bf16 v[20:23], v[60:63], v[204:207], v[20:23]
	v_mfma_f32_16x16x32_bf16 v[16:19], v[148:151], v[204:207], v[16:19]
	s_setprio 0
	s_barrier
	s_mov_b32 m0, s63
	v_lshl_add_u64 v[56:57], v[166:167], 0, s[82:83]
	global_load_lds_dwordx4 v[56:57], off
	v_lshl_add_u64 v[56:57], v[166:167], 0, s[94:95]
	s_mov_b32 m0, s62
	s_nop 0
	global_load_lds_dwordx4 v[56:57], off
	s_waitcnt vmcnt(6)
	s_barrier
	s_setprio 3
	v_mfma_f32_16x16x32_bf16 v[44:47], v[208:211], v[162:165], v[44:47]
	v_mfma_f32_16x16x32_bf16 v[40:43], v[216:219], v[162:165], v[40:43]
	v_mfma_f32_16x16x32_bf16 v[28:31], v[208:211], v[176:179], v[28:31]
	v_mfma_f32_16x16x32_bf16 v[24:27], v[216:219], v[176:179], v[24:27]
	v_mfma_f32_16x16x32_bf16 v[12:15], v[208:211], v[200:203], v[12:15]
	v_mfma_f32_16x16x32_bf16 v[8:11], v[216:219], v[200:203], v[8:11]
	v_mfma_f32_16x16x32_bf16 v[56:59], v[208:211], v[152:155], v[68:71]
	v_mfma_f32_16x16x32_bf16 v[60:63], v[216:219], v[152:155], v[64:67]
	v_mfma_f32_16x16x32_bf16 v[44:47], v[212:215], v[172:175], v[44:47]
	v_mfma_f32_16x16x32_bf16 v[40:43], v[220:223], v[172:175], v[40:43]
	v_mfma_f32_16x16x32_bf16 v[28:31], v[212:215], v[196:199], v[28:31]
	v_mfma_f32_16x16x32_bf16 v[24:27], v[220:223], v[196:199], v[24:27]
	v_mfma_f32_16x16x32_bf16 v[12:15], v[212:215], v[204:207], v[12:15]
	v_mfma_f32_16x16x32_bf16 v[8:11], v[220:223], v[204:207], v[8:11]
	v_mfma_f32_16x16x32_bf16 v[56:59], v[212:215], v[156:159], v[56:59]
	v_mfma_f32_16x16x32_bf16 v[60:63], v[220:223], v[156:159], v[60:63]
	s_setprio 0
	v_add_u32_e32 v0, s31, v183
	s_barrier
	ds_read_b128 v[64:67], v0
	ds_read_b128 v[68:71], v0 offset:1024
	ds_read_b128 v[144:147], v0 offset:2048
	ds_read_b128 v[148:151], v0 offset:3072
	s_mov_b32 m0, s51
	v_lshl_add_u64 v[208:209], v[180:181], 0, s[86:87]
	ds_read_b128 v[152:155], v184 offset:32768
	ds_read_b128 v[156:159], v184 offset:33792
	ds_read_b128 v[162:165], v184 offset:34816
	ds_read_b128 v[172:175], v184 offset:35840
	ds_read_b128 v[176:179], v184 offset:36864
	ds_read_b128 v[196:199], v184 offset:37888
	ds_read_b128 v[200:203], v184 offset:38912
	ds_read_b128 v[204:207], v184 offset:39936
	global_load_lds_dwordx4 v[208:209], off
	v_lshl_add_u64 v[208:209], v[180:181], 0, s[96:97]
	s_mov_b32 m0, s52
	s_nop 0
	global_load_lds_dwordx4 v[208:209], off
	s_waitcnt lgkmcnt(8)
	s_barrier
; #define G_STAGE(bufoff, gbase, o0, h64) do { \
;         __builtin_amdgcn_global_load_lds((const unsigned*)((const char*)(gbase) + (o0)), (LAS unsigned*)(lds + (bufoff) + ldsw), 16, 0, 0); \
;         __builtin_amdgcn_global_load_lds((const unsigned*)((const char*)(gbase) + (h64) + (o0)), (LAS unsigned*)(lds + (bufoff) + ldsw + 8192), 16, 0, 0); } while (0)
; #define G_LDA(dst, b, h) do { _Pragma("unroll") for (int m = 0; m < 4; ++m) _Pragma("unroll") for (int k = 0; k < 2; ++k) dst[m][k] = *(const LAS bf16x8*)(lds + G_SA(b, h) + aoff + m * 2048 + k * 1024); } while (0)
; #define G_LDB(dst, b, h) do { _Pragma("unroll") for (int n = 0; n < 2; ++n) _Pragma("unroll") for (int k = 0; k < 2; ++k) dst[n][k] = *(const LAS bf16x8*)(lds + G_SB(b, h) + boff + n * 2048 + k * 1024); } while (0)
; #define G_WAIT_V(n) asm volatile("s_waitcnt vmcnt(" #n ")" ::: "memory")
; #define G_WAIT_L(n) asm volatile("s_waitcnt lgkmcnt(" #n ")" ::: "memory")
; #define G_BAR __builtin_amdgcn_s_barrier()
; #define G_SCHED __builtin_amdgcn_sched_barrier(0)
;     ...
;             G_WAIT_L(8); G_BAR; G_WAIT_L(0); G_MMA(0, 0, At, B0); G_BAR; G_SCHED;
;             G_LDB(B1, 1, 1); G_STAGE(G_SB(1, 0), b3, cB0, qB);
;             G_BAR; G_WAIT_L(0); G_MMA(0, 1, At, B1); G_BAR;
;             G_LDA(At, 1, 1); G_STAGE(G_SA(1, 0), a3, cA0, qA);
;             G_BAR; G_WAIT_L(0); G_MMA(1, 0, At, B0); G_BAR; G_SCHED;
;             G_STAGE(G_SB(1, 1), b3 + chB, cB0, qB);
;             G_WAIT_V(6); G_BAR; G_MMA(1, 1, At, B1); G_BAR;
;         }
;         E.template run<cs.kind>(acc, cur, tid);
;         if (!has_next) break;
	s_waitcnt lgkmcnt(0)
	s_setprio 3
	s_waitcnt lgkmcnt(0)
	v_mfma_f32_16x16x32_bf16 v[140:143], v[64:67], v[152:155], v[140:143]
	v_mfma_f32_16x16x32_bf16 v[136:139], v[144:147], v[152:155], v[136:139]
	v_mfma_f32_16x16x32_bf16 v[124:127], v[64:67], v[162:165], v[124:127]
	v_mfma_f32_16x16x32_bf16 v[120:123], v[144:147], v[162:165], v[120:123]
	v_mfma_f32_16x16x32_bf16 v[108:111], v[64:67], v[176:179], v[108:111]
	v_mfma_f32_16x16x32_bf16 v[104:107], v[144:147], v[176:179], v[104:107]
	v_mfma_f32_16x16x32_bf16 v[92:95], v[64:67], v[200:203], v[92:95]
	v_mfma_f32_16x16x32_bf16 v[88:91], v[144:147], v[200:203], v[88:91]
	v_mfma_f32_16x16x32_bf16 v[140:143], v[68:71], v[156:159], v[140:143]
	v_mfma_f32_16x16x32_bf16 v[136:139], v[148:151], v[156:159], v[136:139]
	v_mfma_f32_16x16x32_bf16 v[124:127], v[68:71], v[172:175], v[124:127]
	v_mfma_f32_16x16x32_bf16 v[120:123], v[148:151], v[172:175], v[120:123]
	v_mfma_f32_16x16x32_bf16 v[108:111], v[68:71], v[196:199], v[108:111]
	v_mfma_f32_16x16x32_bf16 v[104:107], v[148:151], v[196:199], v[104:107]
	v_mfma_f32_16x16x32_bf16 v[92:95], v[68:71], v[204:207], v[92:95]
	v_mfma_f32_16x16x32_bf16 v[88:91], v[148:151], v[204:207], v[88:91]
	s_setprio 0
	s_barrier
	s_mov_b32 m0, s30
	v_add_u32_e32 v0, s19, v183
	v_lshl_add_u64 v[224:225], v[166:167], 0, s[46:47]
	ds_read_b128 v[208:211], v0
	ds_read_b128 v[212:215], v0 offset:1024
	ds_read_b128 v[216:219], v0 offset:2048
	ds_read_b128 v[220:223], v0 offset:3072
	global_load_lds_dwordx4 v[224:225], off
	v_lshl_add_u64 v[224:225], v[166:167], 0, s[70:71]
	s_mov_b32 m0, s67
	s_nop 0
	global_load_lds_dwordx4 v[224:225], off
	s_barrier
	s_waitcnt lgkmcnt(0)
	s_setprio 3
	s_waitcnt lgkmcnt(0)
	v_mfma_f32_16x16x32_bf16 v[132:135], v[208:211], v[152:155], v[132:135]
	v_mfma_f32_16x16x32_bf16 v[128:131], v[216:219], v[152:155], v[128:131]
	v_mfma_f32_16x16x32_bf16 v[116:119], v[208:211], v[162:165], v[116:119]
	v_mfma_f32_16x16x32_bf16 v[112:115], v[216:219], v[162:165], v[112:115]
	v_mfma_f32_16x16x32_bf16 v[100:103], v[208:211], v[176:179], v[100:103]
	v_mfma_f32_16x16x32_bf16 v[96:99], v[216:219], v[176:179], v[96:99]
	v_mfma_f32_16x16x32_bf16 v[84:87], v[208:211], v[200:203], v[84:87]
	v_mfma_f32_16x16x32_bf16 v[80:83], v[216:219], v[200:203], v[80:83]
	v_mfma_f32_16x16x32_bf16 v[132:135], v[212:215], v[156:159], v[132:135]
	v_mfma_f32_16x16x32_bf16 v[128:131], v[220:223], v[156:159], v[128:131]
	v_mfma_f32_16x16x32_bf16 v[116:119], v[212:215], v[172:175], v[116:119]
	v_mfma_f32_16x16x32_bf16 v[112:115], v[220:223], v[172:175], v[112:115]
	v_mfma_f32_16x16x32_bf16 v[100:103], v[212:215], v[196:199], v[100:103]
	v_mfma_f32_16x16x32_bf16 v[96:99], v[220:223], v[196:199], v[96:99]
	v_mfma_f32_16x16x32_bf16 v[84:87], v[212:215], v[204:207], v[84:87]
	v_mfma_f32_16x16x32_bf16 v[80:83], v[220:223], v[204:207], v[80:83]
	s_setprio 0
	s_mov_b32 m0, s53
	v_lshl_add_u64 v[224:225], v[180:181], 0, s[46:47]
	s_barrier
	ds_read_b128 v[152:155], v184 offset:49152
	ds_read_b128 v[156:159], v184 offset:50176
	ds_read_b128 v[162:165], v184 offset:51200
	ds_read_b128 v[172:175], v184 offset:52224
	ds_read_b128 v[176:179], v184 offset:53248
	ds_read_b128 v[196:199], v184 offset:54272
	ds_read_b128 v[200:203], v184 offset:55296
	ds_read_b128 v[204:207], v184 offset:56320
	global_load_lds_dwordx4 v[224:225], off
	v_lshl_add_u64 v[180:181], v[180:181], 0, s[68:69]
	s_mov_b32 m0, s54
	s_nop 0
	global_load_lds_dwordx4 v[180:181], off
	s_barrier
	s_waitcnt lgkmcnt(0)
	s_setprio 3
	s_waitcnt lgkmcnt(0)
	v_mfma_f32_16x16x32_bf16 v[76:79], v[64:67], v[152:155], v[76:79]
	v_mfma_f32_16x16x32_bf16 v[72:75], v[144:147], v[152:155], v[72:75]
	v_mfma_f32_16x16x32_bf16 v[52:55], v[64:67], v[162:165], v[52:55]
	v_mfma_f32_16x16x32_bf16 v[48:51], v[144:147], v[162:165], v[48:51]
	v_mfma_f32_16x16x32_bf16 v[36:39], v[64:67], v[176:179], v[36:39]
	v_mfma_f32_16x16x32_bf16 v[32:35], v[144:147], v[176:179], v[32:35]
	v_mfma_f32_16x16x32_bf16 v[20:23], v[64:67], v[200:203], v[20:23]
	v_mfma_f32_16x16x32_bf16 v[16:19], v[144:147], v[200:203], v[16:19]
	v_mfma_f32_16x16x32_bf16 v[76:79], v[68:71], v[156:159], v[76:79]
	v_mfma_f32_16x16x32_bf16 v[72:75], v[148:151], v[156:159], v[72:75]
	v_mfma_f32_16x16x32_bf16 v[52:55], v[68:71], v[172:175], v[52:55]
	v_mfma_f32_16x16x32_bf16 v[48:51], v[148:151], v[172:175], v[48:51]
	v_mfma_f32_16x16x32_bf16 v[36:39], v[68:71], v[196:199], v[36:39]
	v_mfma_f32_16x16x32_bf16 v[32:35], v[148:151], v[196:199], v[32:35]
	v_mfma_f32_16x16x32_bf16 v[20:23], v[68:71], v[204:207], v[20:23]
	v_mfma_f32_16x16x32_bf16 v[16:19], v[148:151], v[204:207], v[16:19]
	s_setprio 0
	s_barrier
	s_mov_b32 m0, s65
	v_lshl_add_u64 v[64:65], v[166:167], 0, s[84:85]
	global_load_lds_dwordx4 v[64:65], off
	v_lshl_add_u64 v[64:65], v[166:167], 0, s[28:29]
	s_mov_b32 m0, s64
	s_nop 0
	global_load_lds_dwordx4 v[64:65], off
	s_waitcnt vmcnt(6)
	s_barrier
	s_setprio 3
	v_mfma_f32_16x16x32_bf16 v[56:59], v[208:211], v[152:155], v[56:59]
	v_mfma_f32_16x16x32_bf16 v[68:71], v[212:215], v[156:159], v[56:59]
	v_mfma_f32_16x16x32_bf16 v[56:59], v[216:219], v[152:155], v[60:63]
	v_mfma_f32_16x16x32_bf16 v[44:47], v[208:211], v[162:165], v[44:47]
	v_mfma_f32_16x16x32_bf16 v[40:43], v[216:219], v[162:165], v[40:43]
	v_mfma_f32_16x16x32_bf16 v[28:31], v[208:211], v[176:179], v[28:31]
	v_mfma_f32_16x16x32_bf16 v[24:27], v[216:219], v[176:179], v[24:27]
	v_mfma_f32_16x16x32_bf16 v[12:15], v[208:211], v[200:203], v[12:15]
	v_mfma_f32_16x16x32_bf16 v[8:11], v[216:219], v[200:203], v[8:11]
	v_mfma_f32_16x16x32_bf16 v[64:67], v[220:223], v[156:159], v[56:59]
	v_mfma_f32_16x16x32_bf16 v[44:47], v[212:215], v[172:175], v[44:47]
	v_mfma_f32_16x16x32_bf16 v[40:43], v[220:223], v[172:175], v[40:43]
	v_mfma_f32_16x16x32_bf16 v[28:31], v[212:215], v[196:199], v[28:31]
	v_mfma_f32_16x16x32_bf16 v[24:27], v[220:223], v[196:199], v[24:27]
	v_mfma_f32_16x16x32_bf16 v[12:15], v[212:215], v[204:207], v[12:15]
	v_mfma_f32_16x16x32_bf16 v[8:11], v[220:223], v[204:207], v[8:11]
	s_setprio 0
	s_andn2_b64 vcc, exec, s[24:25]
	s_mov_b64 s[26:27], -1
	s_mov_b64 s[24:25], 0
	s_mov_b64 s[30:31], 0x100
	s_cbranch_vccz .Ldb_SSM2_cont
	v_readfirstlane_b32 s101, v186
	s_cmpk_gt_u32 s101, 0xff
	s_cbranch_scc1 .Ldb_SSM2_exit
	s_barrier
	s_branch .Ldb_SSM2_exit

; __device__ __forceinline__ float gelu_tanh(float y) { const float z = 1.5957691216057308f * (y + 0.044715f * y * y * y); return y * sigmoidf_(z); }
; __device__ __forceinline__ u32x4 pack8(const f32x4 a, const f32x4 b) { u32x4 w; w.x = cvt_pk_bf16(a[0], a[1]); w.y = cvt_pk_bf16(a[2], a[3]); w.z = cvt_pk_bf16(b[0], b[1]); w.w = cvt_pk_bf16(b[2], b[3]); return w; }
; #define MEMFENCE asm volatile("" ::: "memory")
;     template <int KIND> __device__ __forceinline__ void run(f32x4 (&acc)[2][2][4][2], const Unit& u, int tid_in) const {
;     ...
;         if constexpr (KIND == K_SSM2) { const int g = u.aux; const int ch = g * 16 + 8 * (fq & 1); const f32x4 d0 = *(const f32x4*)(dskip + ch), d1 = *(const f32x4*)(dskip + ch + 4);
; #pragma unroll
;             for (int ai = 0; ai < 2; ++ai)
; #pragma unroll
;                 for (int mh = 0; mh < 2; ++mh) { u32x4 yv[2][2], uv[2][2];
; #pragma unroll
;                     for (int ml = 0; ml < 2; ++ml) { int R = rbase + ai * 128 + (mh * 2 + ml) * 16; asm volatile("" : "+v"(R));
; #pragma unroll
;                         for (int bj = 0; bj < 2; ++bj) { const int t = 16 * u.pn + 8 * bj + 2 * wc + (fq >> 1); const size_t tok = (size_t)R * LCH + t;
;                             yv[ml][bj] = *(const u32x4*)(yi + ((size_t)g * T_TOK + tok) * 16 + 8 * (fq & 1)); uv[ml][bj] = *(const u32x4*)((const bf16_t*)x + ((size_t)g * T_TOK + tok) * 16 + 8 * (fq & 1)); } }
; #pragma unroll
;                     for (int ml = 0; ml < 2; ++ml) { const int m = mh * 2 + ml; int R = rbase + ai * 128 + m * 16; asm volatile("" : "+v"(R));
; #pragma unroll
;                         for (int bj = 0; bj < 2; ++bj) { const int t = 16 * u.pn + 8 * bj + 2 * wc + (fq >> 1); const size_t tok = (size_t)R * LCH + t;
;                             f32x4 y0, y1, u0, u1; unpack8(yv[ml][bj], y0, y1); unpack8(uv[ml][bj], u0, u1);
;                             y0 = acc[ai][bj][m][0] + y0 + d0 * u0; y1 = acc[ai][bj][m][1] + y1 + d1 * u1;
; #pragma unroll
;                             for (int j = 0; j < 4; ++j) { y0[j] = gelu_tanh(y0[j]); y1[j] = gelu_tanh(y1[j]); }
;                             *(u32x4*)(yi + ((size_t)g * T_TOK + tok) * 16 + 8 * (fq & 1)) = pack8(y0, y1); } }
;                     MEMFENCE; }
.Ldb_SSM2_exit:
	v_mov_b32_e32 v0, v182
	s_lshl_b32 s3, s23, 8
	v_readfirstlane_b32 s2, v0
	s_ashr_i32 s4, s2, 2
	v_lshrrev_b32_e32 v56, 1, v0
	s_andn2_b32 s4, s4, 63
	v_and_b32_e32 v144, 8, v56
	s_add_i32 s4, s4, s3
	v_lshl_or_b32 v56, s22, 4, v144
	s_lshr_b32 s2, s2, 5
	v_and_or_b32 v185, v0, 15, s4
	v_ashrrev_i32_e32 v57, 31, v56
	s_and_b32 s2, s2, 6
	v_lshrrev_b32_e32 v0, 5, v0
	v_lshl_add_u64 v[60:61], v[56:57], 2, s[6:7]
	v_and_or_b32 v145, v0, 1, s2
	v_lshlrev_b32_e32 v0, 1, v144
	v_mov_b32_e32 v144, v185
	global_load_dwordx4 v[56:59], v[60:61], off offset:16
	s_nop 0
	global_load_dwordx4 v[60:63], v[60:61], off
	s_ashr_i32 s23, s22, 31
	v_lshl_or_b32 v212, s33, 4, v145
	v_ashrrev_i32_e32 v145, 31, v144
	s_lshl_b64 s[20:21], s[22:23], 19
	v_lshlrev_b64 v[144:145], 9, v[144:145]
	v_ashrrev_i32_e32 v213, 31, v212
	v_lshl_add_u64 v[144:145], v[144:145], 0, s[20:21]
	v_lshlrev_b64 v[172:173], 4, v[212:213]
	v_lshl_add_u64 v[146:147], v[144:145], 0, v[172:173]
	v_lshl_add_u64 v[164:165], s[10:11], 0, v[0:1]
	v_lshlrev_b64 v[146:147], 1, v[146:147]
	v_lshl_add_u64 v[148:149], v[164:165], 0, v[146:147]
	v_lshl_add_u64 v[166:167], s[8:9], 0, v[0:1]
	global_load_dwordx4 v[196:199], v[148:149], off
	v_lshl_add_u64 v[146:147], v[166:167], 0, v[146:147]
	global_load_dwordx4 v[200:203], v[146:147], off
	v_or_b32_e32 v176, 8, v212
	v_ashrrev_i32_e32 v177, 31, v176
	v_lshlrev_b64 v[174:175], 4, v[176:177]
	v_lshl_add_u64 v[144:145], v[174:175], 0, v[144:145]
	v_lshlrev_b64 v[144:145], 1, v[144:145]
	v_lshl_add_u64 v[148:149], v[164:165], 0, v[144:145]
	v_lshl_add_u64 v[144:145], v[166:167], 0, v[144:145]
	global_load_dwordx4 v[204:207], v[148:149], off
	global_load_dwordx4 v[208:211], v[144:145], off
	v_or_b32_e32 v178, 16, v185
	s_lshl_b64 s[2:3], s[22:23], 20
	v_mov_b32_e32 v146, v178
	s_add_u32 s2, s10, s2
	s_addc_u32 s3, s11, s3
	v_ashrrev_i32_e32 v147, 31, v146
	v_lshlrev_b64 v[144:145], 9, v[146:147]
	v_lshl_add_u64 v[162:163], s[2:3], 0, v[0:1]
	v_lshl_add_u64 v[144:145], v[144:145], 0, s[20:21]
	v_lshl_add_u64 v[146:147], v[144:145], 0, v[172:173]
	v_lshl_add_u64 v[144:145], v[144:145], 0, v[174:175]
	v_lshlrev_b64 v[146:147], 1, v[146:147]
	v_lshlrev_b64 v[144:145], 1, v[144:145]
	v_lshl_add_u64 v[148:149], v[164:165], 0, v[146:147]
	v_lshl_add_u64 v[146:147], v[166:167], 0, v[146:147]
	v_lshl_add_u64 v[150:151], v[164:165], 0, v[144:145]
	v_lshl_add_u64 v[144:145], v[166:167], 0, v[144:145]
	global_load_dwordx4 v[156:159], v[148:149], off
	global_load_dwordx4 v[152:155], v[146:147], off
	s_nop 0
	global_load_dwordx4 v[148:151], v[150:151], off
	s_nop 0
	global_load_dwordx4 v[144:147], v[144:145], off
	v_mov_b32_e32 v180, v185
	v_readlane_b32 s48, v230, 5
	v_ashrrev_i32_e32 v181, 31, v180
	v_lshlrev_b64 v[180:181], 10, v[180:181]
	v_lshl_add_u64 v[180:181], v[162:163], 0, v[180:181]
	v_readlane_b32 s49, v230, 6
	v_readlane_b32 s44, v230, 7
	s_and_b64 vcc, exec, s[14:15]
	s_mov_b32 s22, s18
	s_mov_b32 s33, s59
	s_mov_b32 s23, s58
	s_mov_b64 s[2:3], s[12:13]
	v_readlane_b32 s45, v230, 8
	s_movk_i32 s49, 0x4000
	s_mov_b64 s[68:69], 0x18080
	s_mov_b64 s[70:71], 0x800
	s_mov_b64 s[82:83], 0x1800
	s_mov_b64 s[84:85], 0x400800
	s_mov_b64 s[86:87], 0x58000
	s_mov_b64 s[88:89], 0xb0000
	s_mov_b64 s[64:65], 0x108000
	s_mov_b64 s[66:67], 0x58080
	s_mov_b32 s28, s74
	s_waitcnt vmcnt(0)
	v_lshlrev_b32_e32 v214, 16, v196
	v_and_b32_e32 v215, 0xffff0000, v196
	v_lshlrev_b32_e32 v216, 16, v198
	v_and_b32_e32 v217, 0xffff0000, v198
	v_lshlrev_b32_e32 v218, 16, v200
	v_and_b32_e32 v219, 0xffff0000, v200
	v_lshlrev_b32_e32 v220, 16, v202
	v_and_b32_e32 v221, 0xffff0000, v202
	v_pk_add_f32 v[140:141], v[140:141], v[214:215]
	v_pk_add_f32 v[136:137], v[136:137], v[216:217]
	v_pk_fma_f32 v[140:141], v[60:61], v[218:219], v[140:141]
	v_pk_fma_f32 v[136:137], v[56:57], v[220:221], v[136:137]
	v_mul_f32_e32 v0, 0x3d372713, v140
	v_mul_f32_e32 v179, 0x3d372713, v136
	v_mul_f32_e32 v195, 0x3d372713, v141
	v_mul_f32_e32 v0, v140, v0
	v_mul_f32_e32 v179, v136, v179
	v_mul_f32_e32 v195, v141, v195
	v_fma_f32 v0, v140, v0, v140
	v_fma_f32 v179, v136, v179, v136
	v_fma_f32 v195, v141, v195, v141
	v_mul_f32_e32 v0, 0x3fcc422a, v0
	v_mul_f32_e32 v179, 0x3fcc422a, v179
	v_mul_f32_e32 v195, 0x3fcc422a, v195
	v_mul_f32_e32 v0, 0xbfb8aa3b, v0
	v_mul_f32_e32 v179, 0xbfb8aa3b, v179
	v_mul_f32_e32 v195, 0xbfb8aa3b, v195
	v_exp_f32_e32 v0, v0
	v_exp_f32_e32 v179, v179
	v_exp_f32_e32 v195, v195
	v_lshlrev_b32_e32 v196, 16, v197
	v_and_b32_e32 v197, 0xffff0000, v197
	v_pk_add_f32 v[142:143], v[142:143], v[196:197]
	v_add_f32_e32 v0, 1.0, v0
	v_add_f32_e32 v179, 1.0, v179
	v_add_f32_e32 v195, 1.0, v195
	v_mul_f32_e32 v196, 0x3d372713, v137
	v_rcp_f32_e32 v0, v0
	v_rcp_f32_e32 v179, v179
	v_rcp_f32_e32 v195, v195
	v_mul_f32_e32 v196, v137, v196
	v_lshlrev_b32_e32 v198, 16, v199
	v_and_b32_e32 v199, 0xffff0000, v199
	v_fma_f32 v196, v137, v196, v137
	v_lshlrev_b32_e32 v200, 16, v201
	v_and_b32_e32 v201, 0xffff0000, v201
	v_lshlrev_b32_e32 v202, 16, v203
	v_and_b32_e32 v203, 0xffff0000, v203
	v_pk_add_f32 v[138:139], v[138:139], v[198:199]
	v_mul_f32_e32 v196, 0x3fcc422a, v196
	v_pk_fma_f32 v[142:143], v[62:63], v[200:201], v[142:143]
	v_pk_fma_f32 v[138:139], v[58:59], v[202:203], v[138:139]
	v_mul_f32_e32 v196, 0xbfb8aa3b, v196
	v_exp_f32_e32 v196, v196
	v_mul_f32_e32 v0, v140, v0
	v_mul_f32_e32 v136, v136, v179
	v_mul_f32_e32 v140, v141, v195
	v_mul_f32_e32 v179, 0x3d372713, v142
	v_mul_f32_e32 v195, 0x3d372713, v138
	v_mul_f32_e32 v179, v142, v179
	v_mul_f32_e32 v195, v138, v195
	v_fma_f32 v179, v142, v179, v142
	v_fma_f32 v195, v138, v195, v138
	v_mul_f32_e32 v179, 0x3fcc422a, v179
; __device__ __forceinline__ float gelu_tanh(float y) { const float z = 1.5957691216057308f * (y + 0.044715f * y * y * y); return y * sigmoidf_(z); }
; __device__ __forceinline__ u32x4 pack8(const f32x4 a, const f32x4 b) { u32x4 w; w.x = cvt_pk_bf16(a[0], a[1]); w.y = cvt_pk_bf16(a[2], a[3]); w.z = cvt_pk_bf16(b[0], b[1]); w.w = cvt_pk_bf16(b[2], b[3]); return w; }
; #define MEMFENCE asm volatile("" ::: "memory")
;     template <int KIND> __device__ __forceinline__ void run(f32x4 (&acc)[2][2][4][2], const Unit& u, int tid_in) const {
;     ...
;         if constexpr (KIND == K_SSM2) { const int g = u.aux; const int ch = g * 16 + 8 * (fq & 1); const f32x4 d0 = *(const f32x4*)(dskip + ch), d1 = *(const f32x4*)(dskip + ch + 4);
; #pragma unroll
;             for (int ai = 0; ai < 2; ++ai)
; #pragma unroll
;                 for (int mh = 0; mh < 2; ++mh) { u32x4 yv[2][2], uv[2][2];
; #pragma unroll
;                     for (int ml = 0; ml < 2; ++ml) { int R = rbase + ai * 128 + (mh * 2 + ml) * 16; asm volatile("" : "+v"(R));
; #pragma unroll
;                         for (int bj = 0; bj < 2; ++bj) { const int t = 16 * u.pn + 8 * bj + 2 * wc + (fq >> 1); const size_t tok = (size_t)R * LCH + t;
;                             yv[ml][bj] = *(const u32x4*)(yi + ((size_t)g * T_TOK + tok) * 16 + 8 * (fq & 1)); uv[ml][bj] = *(const u32x4*)((const bf16_t*)x + ((size_t)g * T_TOK + tok) * 16 + 8 * (fq & 1)); } }
; #pragma unroll
;                     for (int ml = 0; ml < 2; ++ml) { const int m = mh * 2 + ml; int R = rbase + ai * 128 + m * 16; asm volatile("" : "+v"(R));
; #pragma unroll
;                         for (int bj = 0; bj < 2; ++bj) { const int t = 16 * u.pn + 8 * bj + 2 * wc + (fq >> 1); const size_t tok = (size_t)R * LCH + t;
;                             f32x4 y0, y1, u0, u1; unpack8(yv[ml][bj], y0, y1); unpack8(uv[ml][bj], u0, u1);
;                             y0 = acc[ai][bj][m][0] + y0 + d0 * u0; y1 = acc[ai][bj][m][1] + y1 + d1 * u1;
; #pragma unroll
;                             for (int j = 0; j < 4; ++j) { y0[j] = gelu_tanh(y0[j]); y1[j] = gelu_tanh(y1[j]); }
;                             *(u32x4*)(yi + ((size_t)g * T_TOK + tok) * 16 + 8 * (fq & 1)) = pack8(y0, y1); } }
;                     MEMFENCE; }
	v_mul_f32_e32 v195, 0x3fcc422a, v195
	v_add_f32_e32 v141, 1.0, v196
	v_mul_f32_e32 v179, 0xbfb8aa3b, v179
	v_mul_f32_e32 v195, 0xbfb8aa3b, v195
	v_rcp_f32_e32 v141, v141
	v_exp_f32_e32 v179, v179
	v_exp_f32_e32 v195, v195
	v_mul_f32_e32 v196, 0x3d372713, v139
	v_mul_f32_e32 v137, v137, v141
	v_add_f32_e32 v141, 1.0, v179
	v_add_f32_e32 v179, 1.0, v195
	v_mul_f32_e32 v195, 0x3d372713, v143
	v_mul_f32_e32 v195, v143, v195
	v_mul_f32_e32 v196, v139, v196
	v_fma_f32 v195, v143, v195, v143
	v_fma_f32 v196, v139, v196, v139
	v_mul_f32_e32 v195, 0x3fcc422a, v195
	v_mul_f32_e32 v196, 0x3fcc422a, v196
	v_mul_f32_e32 v195, 0xbfb8aa3b, v195
	v_mul_f32_e32 v196, 0xbfb8aa3b, v196
	v_exp_f32_e32 v195, v195
	v_exp_f32_e32 v196, v196
	v_rcp_f32_e32 v141, v141
	v_rcp_f32_e32 v179, v179
	v_add_f32_e32 v195, 1.0, v195
	v_add_f32_e32 v196, 1.0, v196
	v_rcp_f32_e32 v195, v195
	v_rcp_f32_e32 v196, v196
	v_mul_f32_e32 v141, v142, v141
	v_mul_f32_e32 v142, v138, v179
	v_mul_f32_e32 v143, v143, v195
	v_mul_f32_e32 v179, v139, v196
	v_cvt_pk_bf16_f32 v138, v0, v140
	v_cvt_pk_bf16_f32 v139, v141, v143
	v_cvt_pk_bf16_f32 v140, v136, v137
	v_lshlrev_b64 v[136:137], 5, v[212:213]
	v_cvt_pk_bf16_f32 v141, v142, v179
	v_lshl_add_u64 v[142:143], v[180:181], 0, v[136:137]
	global_store_dwordx4 v[142:143], v[138:141], off
	v_lshlrev_b32_e32 v142, 16, v206
	v_and_b32_e32 v143, 0xffff0000, v206
	v_lshlrev_b32_e32 v138, 16, v204
	v_and_b32_e32 v139, 0xffff0000, v204
	v_lshlrev_b32_e32 v198, 16, v208
	v_and_b32_e32 v199, 0xffff0000, v208
	v_lshlrev_b32_e32 v202, 16, v210
	v_and_b32_e32 v203, 0xffff0000, v210
	v_pk_add_f32 v[132:133], v[132:133], v[138:139]
	v_pk_add_f32 v[128:129], v[128:129], v[142:143]
	v_pk_fma_f32 v[132:133], v[60:61], v[198:199], v[132:133]
	v_pk_fma_f32 v[128:129], v[56:57], v[202:203], v[128:129]
	v_mul_f32_e32 v0, 0x3d372713, v132
	v_mul_f32_e32 v138, 0x3d372713, v128
	v_mul_f32_e32 v139, 0x3d372713, v133
	v_mul_f32_e32 v0, v132, v0
	v_mul_f32_e32 v138, v128, v138
	v_mul_f32_e32 v139, v133, v139
	v_fma_f32 v0, v132, v0, v132
	v_fma_f32 v138, v128, v138, v128
	v_fma_f32 v139, v133, v139, v133
	v_mul_f32_e32 v0, 0x3fcc422a, v0
	v_mul_f32_e32 v138, 0x3fcc422a, v138
	v_mul_f32_e32 v139, 0x3fcc422a, v139
	v_mul_f32_e32 v0, 0xbfb8aa3b, v0
	v_mul_f32_e32 v138, 0xbfb8aa3b, v138
	v_mul_f32_e32 v139, 0xbfb8aa3b, v139
	v_exp_f32_e32 v0, v0
	v_exp_f32_e32 v138, v138
	v_exp_f32_e32 v139, v139
	v_lshlrev_b32_e32 v140, 16, v205
	v_and_b32_e32 v141, 0xffff0000, v205
	v_pk_add_f32 v[134:135], v[134:135], v[140:141]
	v_add_f32_e32 v0, 1.0, v0
	v_add_f32_e32 v138, 1.0, v138
	v_add_f32_e32 v139, 1.0, v139
	v_mul_f32_e32 v140, 0x3d372713, v129
	v_rcp_f32_e32 v0, v0
	v_rcp_f32_e32 v138, v138
	v_rcp_f32_e32 v139, v139
	v_mul_f32_e32 v140, v129, v140
	v_lshlrev_b32_e32 v196, 16, v207
	v_and_b32_e32 v197, 0xffff0000, v207
	v_fma_f32 v140, v129, v140, v129
	v_lshlrev_b32_e32 v200, 16, v209
	v_and_b32_e32 v201, 0xffff0000, v209
	v_lshlrev_b32_e32 v204, 16, v211
	v_and_b32_e32 v205, 0xffff0000, v211
	v_pk_add_f32 v[130:131], v[130:131], v[196:197]
	v_mul_f32_e32 v140, 0x3fcc422a, v140
	v_pk_fma_f32 v[134:135], v[62:63], v[200:201], v[134:135]
	v_pk_fma_f32 v[130:131], v[58:59], v[204:205], v[130:131]
	v_mul_f32_e32 v140, 0xbfb8aa3b, v140
	v_exp_f32_e32 v140, v140
	v_mul_f32_e32 v0, v132, v0
	v_mul_f32_e32 v128, v128, v138
	v_mul_f32_e32 v132, v133, v139
	v_mul_f32_e32 v138, 0x3d372713, v134
	v_mul_f32_e32 v139, 0x3d372713, v130
	v_mul_f32_e32 v138, v134, v138
	v_mul_f32_e32 v139, v130, v139
	v_fma_f32 v138, v134, v138, v134
	v_fma_f32 v139, v130, v139, v130
	v_mul_f32_e32 v138, 0x3fcc422a, v138
	v_mul_f32_e32 v139, 0x3fcc422a, v139
	v_add_f32_e32 v133, 1.0, v140
	v_mul_f32_e32 v138, 0xbfb8aa3b, v138
	v_mul_f32_e32 v139, 0xbfb8aa3b, v139
	v_rcp_f32_e32 v133, v133
	v_exp_f32_e32 v138, v138
	v_exp_f32_e32 v139, v139
	v_mul_f32_e32 v140, 0x3d372713, v131
	v_mul_f32_e32 v129, v129, v133
	v_add_f32_e32 v133, 1.0, v138
	v_add_f32_e32 v138, 1.0, v139
	v_mul_f32_e32 v139, 0x3d372713, v135
	v_mul_f32_e32 v139, v135, v139
	v_mul_f32_e32 v140, v131, v140
	v_fma_f32 v139, v135, v139, v135
	v_fma_f32 v140, v131, v140, v131
	v_mul_f32_e32 v139, 0x3fcc422a, v139
	v_mul_f32_e32 v140, 0x3fcc422a, v140
	v_mul_f32_e32 v139, 0xbfb8aa3b, v139
	v_mul_f32_e32 v140, 0xbfb8aa3b, v140
	v_exp_f32_e32 v139, v139
	v_exp_f32_e32 v140, v140
	v_rcp_f32_e32 v133, v133
	v_rcp_f32_e32 v138, v138
	v_add_f32_e32 v139, 1.0, v139
	v_add_f32_e32 v140, 1.0, v140
	v_rcp_f32_e32 v139, v139
	v_rcp_f32_e32 v140, v140
	v_mul_f32_e32 v133, v134, v133
	v_mul_f32_e32 v134, v130, v138
	v_mul_f32_e32 v135, v135, v139
	v_mul_f32_e32 v138, v131, v140
	v_cvt_pk_bf16_f32 v130, v0, v132
	v_cvt_pk_bf16_f32 v131, v133, v135
	v_cvt_pk_bf16_f32 v132, v128, v129
	v_lshlrev_b64 v[128:129], 5, v[176:177]
	v_cvt_pk_bf16_f32 v133, v134, v138
	v_lshl_add_u64 v[134:135], v[180:181], 0, v[128:129]
	global_store_dwordx4 v[134:135], v[130:133], off
	v_lshlrev_b32_e32 v138, 16, v158
	v_and_b32_e32 v139, 0xffff0000, v158
	v_lshlrev_b32_e32 v132, 16, v156
	v_and_b32_e32 v133, 0xffff0000, v156
	v_lshlrev_b32_e32 v134, 16, v157
	v_and_b32_e32 v135, 0xffff0000, v157
	v_lshlrev_b32_e32 v142, 16, v152
	v_and_b32_e32 v143, 0xffff0000, v152
	v_lshlrev_b32_e32 v156, 16, v154
	v_and_b32_e32 v157, 0xffff0000, v154
	v_pk_add_f32 v[124:125], v[124:125], v[132:133]
	v_pk_add_f32 v[120:121], v[120:121], v[138:139]
	v_pk_fma_f32 v[124:125], v[60:61], v[142:143], v[124:125]
	v_pk_fma_f32 v[120:121], v[56:57], v[156:157], v[120:121]
	v_mul_f32_e32 v0, 0x3d372713, v124
	v_mul_f32_e32 v132, 0x3d372713, v120
	v_mul_f32_e32 v133, 0x3d372713, v125
	v_mul_f32_e32 v0, v124, v0
; __device__ __forceinline__ float gelu_tanh(float y) { const float z = 1.5957691216057308f * (y + 0.044715f * y * y * y); return y * sigmoidf_(z); }
; __device__ __forceinline__ u32x4 pack8(const f32x4 a, const f32x4 b) { u32x4 w; w.x = cvt_pk_bf16(a[0], a[1]); w.y = cvt_pk_bf16(a[2], a[3]); w.z = cvt_pk_bf16(b[0], b[1]); w.w = cvt_pk_bf16(b[2], b[3]); return w; }
; #define MEMFENCE asm volatile("" ::: "memory")
;     template <int KIND> __device__ __forceinline__ void run(f32x4 (&acc)[2][2][4][2], const Unit& u, int tid_in) const {
;     ...
;         if constexpr (KIND == K_SSM2) { const int g = u.aux; const int ch = g * 16 + 8 * (fq & 1); const f32x4 d0 = *(const f32x4*)(dskip + ch), d1 = *(const f32x4*)(dskip + ch + 4);
; #pragma unroll
;             for (int ai = 0; ai < 2; ++ai)
; #pragma unroll
;                 for (int mh = 0; mh < 2; ++mh) { u32x4 yv[2][2], uv[2][2];
; #pragma unroll
;                     for (int ml = 0; ml < 2; ++ml) { int R = rbase + ai * 128 + (mh * 2 + ml) * 16; asm volatile("" : "+v"(R));
; #pragma unroll
;                         for (int bj = 0; bj < 2; ++bj) { const int t = 16 * u.pn + 8 * bj + 2 * wc + (fq >> 1); const size_t tok = (size_t)R * LCH + t;
;                             yv[ml][bj] = *(const u32x4*)(yi + ((size_t)g * T_TOK + tok) * 16 + 8 * (fq & 1)); uv[ml][bj] = *(const u32x4*)((const bf16_t*)x + ((size_t)g * T_TOK + tok) * 16 + 8 * (fq & 1)); } }
; #pragma unroll
;                     for (int ml = 0; ml < 2; ++ml) { const int m = mh * 2 + ml; int R = rbase + ai * 128 + m * 16; asm volatile("" : "+v"(R));
; #pragma unroll
;                         for (int bj = 0; bj < 2; ++bj) { const int t = 16 * u.pn + 8 * bj + 2 * wc + (fq >> 1); const size_t tok = (size_t)R * LCH + t;
;                             f32x4 y0, y1, u0, u1; unpack8(yv[ml][bj], y0, y1); unpack8(uv[ml][bj], u0, u1);
;                             y0 = acc[ai][bj][m][0] + y0 + d0 * u0; y1 = acc[ai][bj][m][1] + y1 + d1 * u1;
; #pragma unroll
;                             for (int j = 0; j < 4; ++j) { y0[j] = gelu_tanh(y0[j]); y1[j] = gelu_tanh(y1[j]); }
;                             *(u32x4*)(yi + ((size_t)g * T_TOK + tok) * 16 + 8 * (fq & 1)) = pack8(y0, y1); } }
;                     MEMFENCE; }
	v_mul_f32_e32 v132, v120, v132
	v_mul_f32_e32 v133, v125, v133
	v_fma_f32 v0, v124, v0, v124
	v_fma_f32 v132, v120, v132, v120
	v_fma_f32 v133, v125, v133, v125
	v_mul_f32_e32 v0, 0x3fcc422a, v0
	v_mul_f32_e32 v132, 0x3fcc422a, v132
	v_mul_f32_e32 v133, 0x3fcc422a, v133
	v_mul_f32_e32 v0, 0xbfb8aa3b, v0
	v_mul_f32_e32 v132, 0xbfb8aa3b, v132
	v_mul_f32_e32 v133, 0xbfb8aa3b, v133
	v_exp_f32_e32 v0, v0
	v_exp_f32_e32 v132, v132
	v_exp_f32_e32 v133, v133
	v_pk_add_f32 v[126:127], v[126:127], v[134:135]
	v_add_f32_e32 v0, 1.0, v0
	v_add_f32_e32 v132, 1.0, v132
	v_add_f32_e32 v133, 1.0, v133
	v_mul_f32_e32 v134, 0x3d372713, v121
	v_rcp_f32_e32 v0, v0
	v_rcp_f32_e32 v132, v132
	v_rcp_f32_e32 v133, v133
	v_mul_f32_e32 v134, v121, v134
	v_lshlrev_b32_e32 v140, 16, v159
	v_and_b32_e32 v141, 0xffff0000, v159
	v_fma_f32 v134, v121, v134, v121
	v_lshlrev_b32_e32 v152, 16, v153
	v_and_b32_e32 v153, 0xffff0000, v153
	v_lshlrev_b32_e32 v154, 16, v155
	v_and_b32_e32 v155, 0xffff0000, v155
	v_pk_add_f32 v[122:123], v[122:123], v[140:141]
	v_mul_f32_e32 v134, 0x3fcc422a, v134
	v_pk_fma_f32 v[126:127], v[62:63], v[152:153], v[126:127]
	v_pk_fma_f32 v[122:123], v[58:59], v[154:155], v[122:123]
	v_mul_f32_e32 v134, 0xbfb8aa3b, v134
	v_exp_f32_e32 v134, v134
	v_mul_f32_e32 v0, v124, v0
	v_mul_f32_e32 v124, v120, v132
	v_mul_f32_e32 v120, v125, v133
	v_mul_f32_e32 v132, 0x3d372713, v126
	v_mul_f32_e32 v133, 0x3d372713, v122
	v_mul_f32_e32 v132, v126, v132
	v_mul_f32_e32 v133, v122, v133
	v_fma_f32 v132, v126, v132, v126
	v_fma_f32 v133, v122, v133, v122
	v_mul_f32_e32 v132, 0x3fcc422a, v132
	v_mul_f32_e32 v133, 0x3fcc422a, v133
	v_add_f32_e32 v125, 1.0, v134
	v_mul_f32_e32 v132, 0xbfb8aa3b, v132
	v_mul_f32_e32 v133, 0xbfb8aa3b, v133
	v_rcp_f32_e32 v125, v125
	v_exp_f32_e32 v132, v132
	v_exp_f32_e32 v133, v133
	v_mul_f32_e32 v134, 0x3d372713, v123
	v_mul_f32_e32 v125, v121, v125
	v_add_f32_e32 v121, 1.0, v132
	v_add_f32_e32 v132, 1.0, v133
	v_mul_f32_e32 v133, 0x3d372713, v127
	v_mul_f32_e32 v133, v127, v133
	v_fma_f32 v133, v127, v133, v127
	v_mul_f32_e32 v134, v123, v134
	v_mul_f32_e32 v133, 0x3fcc422a, v133
	v_fma_f32 v134, v123, v134, v123
	v_mul_f32_e32 v133, 0xbfb8aa3b, v133
	v_mul_f32_e32 v134, 0x3fcc422a, v134
	v_exp_f32_e32 v133, v133
	v_mul_f32_e32 v134, 0xbfb8aa3b, v134
	v_exp_f32_e32 v134, v134
	v_rcp_f32_e32 v121, v121
	v_add_f32_e32 v133, 1.0, v133
	v_rcp_f32_e32 v132, v132
	v_rcp_f32_e32 v133, v133
	v_add_f32_e32 v134, 1.0, v134
	v_rcp_f32_e32 v134, v134
	v_mul_f32_e32 v121, v126, v121
	v_ashrrev_i32_e32 v179, 31, v178
	v_lshlrev_b64 v[130:131], 10, v[178:179]
	v_lshl_add_u64 v[130:131], v[162:163], 0, v[130:131]
	v_mul_f32_e32 v126, v122, v132
	v_mul_f32_e32 v122, v127, v133
	v_mul_f32_e32 v123, v123, v134
	v_cvt_pk_bf16_f32 v120, v0, v120
	v_cvt_pk_bf16_f32 v121, v121, v122
	v_cvt_pk_bf16_f32 v122, v124, v125
	v_lshl_add_u64 v[124:125], v[130:131], 0, v[136:137]
	v_cvt_pk_bf16_f32 v123, v126, v123
	global_store_dwordx4 v[124:125], v[120:123], off
	v_lshlrev_b32_e32 v124, 16, v150
	v_and_b32_e32 v125, 0xffff0000, v150
	v_lshlrev_b32_e32 v120, 16, v148
	v_and_b32_e32 v121, 0xffff0000, v148
	v_lshlrev_b32_e32 v132, 16, v144
	v_and_b32_e32 v133, 0xffff0000, v144
	v_lshlrev_b32_e32 v138, 16, v146
	v_and_b32_e32 v139, 0xffff0000, v146
	v_pk_add_f32 v[116:117], v[116:117], v[120:121]
	v_pk_add_f32 v[112:113], v[112:113], v[124:125]
	v_pk_fma_f32 v[116:117], v[60:61], v[132:133], v[116:117]
	v_pk_fma_f32 v[112:113], v[56:57], v[138:139], v[112:113]
	v_mul_f32_e32 v0, 0x3d372713, v116
	v_mul_f32_e32 v120, 0x3d372713, v112
	v_mul_f32_e32 v121, 0x3d372713, v117
	v_mul_f32_e32 v0, v116, v0
	v_mul_f32_e32 v120, v112, v120
	v_mul_f32_e32 v121, v117, v121
	v_fma_f32 v0, v116, v0, v116
	v_fma_f32 v120, v112, v120, v112
	v_fma_f32 v121, v117, v121, v117
	v_mul_f32_e32 v0, 0x3fcc422a, v0
	v_mul_f32_e32 v120, 0x3fcc422a, v120
	v_mul_f32_e32 v121, 0x3fcc422a, v121
	v_mul_f32_e32 v0, 0xbfb8aa3b, v0
	v_mul_f32_e32 v120, 0xbfb8aa3b, v120
	v_mul_f32_e32 v121, 0xbfb8aa3b, v121
	v_exp_f32_e32 v0, v0
	v_exp_f32_e32 v120, v120
	v_exp_f32_e32 v121, v121
	v_lshlrev_b32_e32 v122, 16, v149
	v_and_b32_e32 v123, 0xffff0000, v149
	v_pk_add_f32 v[118:119], v[118:119], v[122:123]
	v_add_f32_e32 v0, 1.0, v0
	v_add_f32_e32 v120, 1.0, v120
	v_add_f32_e32 v121, 1.0, v121
	v_mul_f32_e32 v122, 0x3d372713, v113
	v_rcp_f32_e32 v0, v0
	v_rcp_f32_e32 v120, v120
	v_rcp_f32_e32 v121, v121
	v_mul_f32_e32 v122, v113, v122
	v_lshlrev_b32_e32 v126, 16, v151
	v_and_b32_e32 v127, 0xffff0000, v151
	v_fma_f32 v122, v113, v122, v113
	v_lshlrev_b32_e32 v134, 16, v145
	v_and_b32_e32 v135, 0xffff0000, v145
	v_lshlrev_b32_e32 v140, 16, v147
	v_and_b32_e32 v141, 0xffff0000, v147
	v_pk_add_f32 v[114:115], v[114:115], v[126:127]
	v_mul_f32_e32 v122, 0x3fcc422a, v122
	v_pk_fma_f32 v[118:119], v[62:63], v[134:135], v[118:119]
	v_pk_fma_f32 v[114:115], v[58:59], v[140:141], v[114:115]
	v_mul_f32_e32 v122, 0xbfb8aa3b, v122
	v_exp_f32_e32 v122, v122
	v_mul_f32_e32 v0, v116, v0
	v_mul_f32_e32 v116, v112, v120
	v_mul_f32_e32 v112, v117, v121
	v_mul_f32_e32 v120, 0x3d372713, v118
	v_mul_f32_e32 v121, 0x3d372713, v114
	v_mul_f32_e32 v120, v118, v120
	v_mul_f32_e32 v121, v114, v121
	v_fma_f32 v120, v118, v120, v118
	v_fma_f32 v121, v114, v121, v114
	v_mul_f32_e32 v120, 0x3fcc422a, v120
	v_mul_f32_e32 v121, 0x3fcc422a, v121
	v_add_f32_e32 v117, 1.0, v122
	v_mul_f32_e32 v120, 0xbfb8aa3b, v120
	v_mul_f32_e32 v121, 0xbfb8aa3b, v121
	v_rcp_f32_e32 v117, v117
	v_exp_f32_e32 v120, v120
	v_exp_f32_e32 v121, v121
	v_mul_f32_e32 v122, 0x3d372713, v115
	v_mul_f32_e32 v117, v113, v117
	v_add_f32_e32 v113, 1.0, v120
; __device__ __forceinline__ float gelu_tanh(float y) { const float z = 1.5957691216057308f * (y + 0.044715f * y * y * y); return y * sigmoidf_(z); }
; __device__ __forceinline__ u32x4 pack8(const f32x4 a, const f32x4 b) { u32x4 w; w.x = cvt_pk_bf16(a[0], a[1]); w.y = cvt_pk_bf16(a[2], a[3]); w.z = cvt_pk_bf16(b[0], b[1]); w.w = cvt_pk_bf16(b[2], b[3]); return w; }
; #define MEMFENCE asm volatile("" ::: "memory")
;     template <int KIND> __device__ __forceinline__ void run(f32x4 (&acc)[2][2][4][2], const Unit& u, int tid_in) const {
;     ...
;         if constexpr (KIND == K_SSM2) { const int g = u.aux; const int ch = g * 16 + 8 * (fq & 1); const f32x4 d0 = *(const f32x4*)(dskip + ch), d1 = *(const f32x4*)(dskip + ch + 4);
; #pragma unroll
;             for (int ai = 0; ai < 2; ++ai)
; #pragma unroll
;                 for (int mh = 0; mh < 2; ++mh) { u32x4 yv[2][2], uv[2][2];
; #pragma unroll
;                     for (int ml = 0; ml < 2; ++ml) { int R = rbase + ai * 128 + (mh * 2 + ml) * 16; asm volatile("" : "+v"(R));
; #pragma unroll
;                         for (int bj = 0; bj < 2; ++bj) { const int t = 16 * u.pn + 8 * bj + 2 * wc + (fq >> 1); const size_t tok = (size_t)R * LCH + t;
;                             yv[ml][bj] = *(const u32x4*)(yi + ((size_t)g * T_TOK + tok) * 16 + 8 * (fq & 1)); uv[ml][bj] = *(const u32x4*)((const bf16_t*)x + ((size_t)g * T_TOK + tok) * 16 + 8 * (fq & 1)); } }
; #pragma unroll
;                     for (int ml = 0; ml < 2; ++ml) { const int m = mh * 2 + ml; int R = rbase + ai * 128 + m * 16; asm volatile("" : "+v"(R));
; #pragma unroll
;                         for (int bj = 0; bj < 2; ++bj) { const int t = 16 * u.pn + 8 * bj + 2 * wc + (fq >> 1); const size_t tok = (size_t)R * LCH + t;
;                             f32x4 y0, y1, u0, u1; unpack8(yv[ml][bj], y0, y1); unpack8(uv[ml][bj], u0, u1);
;                             y0 = acc[ai][bj][m][0] + y0 + d0 * u0; y1 = acc[ai][bj][m][1] + y1 + d1 * u1;
; #pragma unroll
;                             for (int j = 0; j < 4; ++j) { y0[j] = gelu_tanh(y0[j]); y1[j] = gelu_tanh(y1[j]); }
;                             *(u32x4*)(yi + ((size_t)g * T_TOK + tok) * 16 + 8 * (fq & 1)) = pack8(y0, y1); } }
;                     MEMFENCE; }
	v_add_f32_e32 v120, 1.0, v121
	v_mul_f32_e32 v121, 0x3d372713, v119
	v_mul_f32_e32 v121, v119, v121
	v_fma_f32 v121, v119, v121, v119
	v_mul_f32_e32 v122, v115, v122
	v_mul_f32_e32 v121, 0x3fcc422a, v121
	v_fma_f32 v122, v115, v122, v115
	v_mul_f32_e32 v121, 0xbfb8aa3b, v121
	v_mul_f32_e32 v122, 0x3fcc422a, v122
	v_exp_f32_e32 v121, v121
	v_mul_f32_e32 v122, 0xbfb8aa3b, v122
	v_exp_f32_e32 v122, v122
	v_rcp_f32_e32 v113, v113
	v_add_f32_e32 v121, 1.0, v121
	v_rcp_f32_e32 v120, v120
	v_rcp_f32_e32 v121, v121
	v_add_f32_e32 v122, 1.0, v122
	v_rcp_f32_e32 v122, v122
	v_mul_f32_e32 v113, v118, v113
	v_mul_f32_e32 v118, v114, v120
	v_mul_f32_e32 v114, v119, v121
	v_mul_f32_e32 v115, v115, v122
	v_cvt_pk_bf16_f32 v112, v0, v112
	v_cvt_pk_bf16_f32 v113, v113, v114
	v_cvt_pk_bf16_f32 v114, v116, v117
	v_lshl_add_u64 v[116:117], v[130:131], 0, v[128:129]
	v_or_b32_e32 v132, 32, v185
	v_cvt_pk_bf16_f32 v115, v118, v115
	global_store_dwordx4 v[116:117], v[112:115], off
	v_or_b32_e32 v130, 48, v185
	s_nop 0
	v_mov_b32_e32 v112, v132
	s_nop 0
	v_ashrrev_i32_e32 v113, 31, v112
	v_lshlrev_b64 v[112:113], 9, v[112:113]
	v_lshl_add_u64 v[112:113], v[112:113], 0, s[20:21]
	v_lshl_add_u64 v[114:115], v[112:113], 0, v[172:173]
	v_lshlrev_b64 v[114:115], 1, v[114:115]
	v_lshl_add_u64 v[116:117], v[164:165], 0, v[114:115]
	global_load_dwordx4 v[138:141], v[116:117], off
	v_lshl_add_u64 v[114:115], v[166:167], 0, v[114:115]
	global_load_dwordx4 v[142:145], v[114:115], off
	v_lshl_add_u64 v[112:113], v[112:113], 0, v[174:175]
	v_lshlrev_b64 v[112:113], 1, v[112:113]
	v_lshl_add_u64 v[114:115], v[164:165], 0, v[112:113]
	global_load_dwordx4 v[146:149], v[114:115], off
	v_lshl_add_u64 v[112:113], v[166:167], 0, v[112:113]
	global_load_dwordx4 v[150:153], v[112:113], off
	v_mov_b32_e32 v112, v130
	s_waitcnt vmcnt(0)
	v_lshlrev_b32_e32 v134, 16, v138
	v_ashrrev_i32_e32 v113, 31, v112
	v_lshlrev_b64 v[112:113], 9, v[112:113]
	v_lshl_add_u64 v[112:113], v[112:113], 0, s[20:21]
	v_and_b32_e32 v135, 0xffff0000, v138
	v_lshlrev_b32_e32 v154, 16, v140
	v_and_b32_e32 v155, 0xffff0000, v140
	v_lshl_add_u64 v[114:115], v[112:113], 0, v[172:173]
	v_lshlrev_b32_e32 v156, 16, v142
	v_and_b32_e32 v157, 0xffff0000, v142
	v_lshlrev_b32_e32 v158, 16, v144
	v_and_b32_e32 v159, 0xffff0000, v144
	v_pk_add_f32 v[108:109], v[108:109], v[134:135]
	v_pk_add_f32 v[104:105], v[104:105], v[154:155]
	v_lshlrev_b64 v[114:115], 1, v[114:115]
	v_pk_fma_f32 v[108:109], v[60:61], v[156:157], v[108:109]
	v_pk_fma_f32 v[104:105], v[56:57], v[158:159], v[104:105]
	v_lshl_add_u64 v[116:117], v[164:165], 0, v[114:115]
	v_mul_f32_e32 v0, 0x3d372713, v108
	v_mul_f32_e32 v131, 0x3d372713, v104
	v_mul_f32_e32 v134, 0x3d372713, v109
	global_load_dwordx4 v[124:127], v[116:117], off
	v_lshl_add_u64 v[114:115], v[166:167], 0, v[114:115]
	v_mul_f32_e32 v0, v108, v0
	v_mul_f32_e32 v131, v104, v131
	v_mul_f32_e32 v134, v109, v134
	global_load_dwordx4 v[120:123], v[114:115], off
	v_fma_f32 v0, v108, v0, v108
	v_fma_f32 v131, v104, v131, v104
	v_fma_f32 v134, v109, v134, v109
	v_mul_f32_e32 v0, 0x3fcc422a, v0
	v_mul_f32_e32 v131, 0x3fcc422a, v131
	v_mul_f32_e32 v134, 0x3fcc422a, v134
	v_mul_f32_e32 v0, 0xbfb8aa3b, v0
	v_mul_f32_e32 v131, 0xbfb8aa3b, v131
	v_mul_f32_e32 v134, 0xbfb8aa3b, v134
	v_exp_f32_e32 v0, v0
	v_exp_f32_e32 v131, v131
	v_exp_f32_e32 v134, v134
	v_mul_f32_e32 v135, 0x3d372713, v105
	v_add_f32_e32 v0, 1.0, v0
	v_add_f32_e32 v131, 1.0, v131
	v_add_f32_e32 v134, 1.0, v134
	v_rcp_f32_e32 v0, v0
	v_rcp_f32_e32 v131, v131
	v_rcp_f32_e32 v134, v134
	v_mul_f32_e32 v135, v105, v135
	v_lshlrev_b32_e32 v138, 16, v139
	v_and_b32_e32 v139, 0xffff0000, v139
	v_lshlrev_b32_e32 v140, 16, v141
	v_and_b32_e32 v141, 0xffff0000, v141
	v_fma_f32 v135, v105, v135, v105
	v_lshlrev_b32_e32 v142, 16, v143
	v_and_b32_e32 v143, 0xffff0000, v143
	v_lshlrev_b32_e32 v144, 16, v145
	v_and_b32_e32 v145, 0xffff0000, v145
	v_pk_add_f32 v[110:111], v[110:111], v[138:139]
	v_pk_add_f32 v[106:107], v[106:107], v[140:141]
	v_mul_f32_e32 v135, 0x3fcc422a, v135
	v_pk_fma_f32 v[110:111], v[62:63], v[142:143], v[110:111]
	v_pk_fma_f32 v[106:107], v[58:59], v[144:145], v[106:107]
	v_mul_f32_e32 v135, 0xbfb8aa3b, v135
	v_exp_f32_e32 v135, v135
	v_mul_f32_e32 v0, v108, v0
	v_mul_f32_e32 v108, v104, v131
	v_mul_f32_e32 v104, v109, v134
	v_mul_f32_e32 v131, 0x3d372713, v110
	v_mul_f32_e32 v134, 0x3d372713, v106
	v_mul_f32_e32 v131, v110, v131
	v_mul_f32_e32 v134, v106, v134
	v_fma_f32 v131, v110, v131, v110
	v_fma_f32 v134, v106, v134, v106
	v_mul_f32_e32 v131, 0x3fcc422a, v131
	v_mul_f32_e32 v134, 0x3fcc422a, v134
	v_add_f32_e32 v109, 1.0, v135
	v_mul_f32_e32 v131, 0xbfb8aa3b, v131
	v_mul_f32_e32 v134, 0xbfb8aa3b, v134
	v_rcp_f32_e32 v109, v109
	v_exp_f32_e32 v131, v131
	v_exp_f32_e32 v134, v134
	v_mul_f32_e32 v135, 0x3d372713, v107
	v_mul_f32_e32 v109, v105, v109
	v_add_f32_e32 v105, 1.0, v131
	v_add_f32_e32 v131, 1.0, v134
	v_mul_f32_e32 v134, 0x3d372713, v111
	v_mul_f32_e32 v134, v111, v134
	v_fma_f32 v134, v111, v134, v111
	v_mul_f32_e32 v135, v107, v135
	v_mul_f32_e32 v134, 0x3fcc422a, v134
	v_fma_f32 v135, v107, v135, v107
	v_mul_f32_e32 v134, 0xbfb8aa3b, v134
	v_mul_f32_e32 v135, 0x3fcc422a, v135
	v_exp_f32_e32 v134, v134
	v_mul_f32_e32 v135, 0xbfb8aa3b, v135
	v_exp_f32_e32 v135, v135
	v_lshl_add_u64 v[112:113], v[112:113], 0, v[174:175]
	v_add_f32_e32 v134, 1.0, v134
	v_lshlrev_b64 v[112:113], 1, v[112:113]
	v_rcp_f32_e32 v105, v105
	v_rcp_f32_e32 v131, v131
	v_rcp_f32_e32 v134, v134
	v_add_f32_e32 v135, 1.0, v135
	v_lshl_add_u64 v[114:115], v[164:165], 0, v[112:113]
	v_lshl_add_u64 v[112:113], v[166:167], 0, v[112:113]
; __device__ __forceinline__ float gelu_tanh(float y) { const float z = 1.5957691216057308f * (y + 0.044715f * y * y * y); return y * sigmoidf_(z); }
; __device__ __forceinline__ u32x4 pack8(const f32x4 a, const f32x4 b) { u32x4 w; w.x = cvt_pk_bf16(a[0], a[1]); w.y = cvt_pk_bf16(a[2], a[3]); w.z = cvt_pk_bf16(b[0], b[1]); w.w = cvt_pk_bf16(b[2], b[3]); return w; }
; #define MEMFENCE asm volatile("" ::: "memory")
;     template <int KIND> __device__ __forceinline__ void run(f32x4 (&acc)[2][2][4][2], const Unit& u, int tid_in) const {
;     ...
;         if constexpr (KIND == K_SSM2) { const int g = u.aux; const int ch = g * 16 + 8 * (fq & 1); const f32x4 d0 = *(const f32x4*)(dskip + ch), d1 = *(const f32x4*)(dskip + ch + 4);
; #pragma unroll
;             for (int ai = 0; ai < 2; ++ai)
; #pragma unroll
;                 for (int mh = 0; mh < 2; ++mh) { u32x4 yv[2][2], uv[2][2];
; #pragma unroll
;                     for (int ml = 0; ml < 2; ++ml) { int R = rbase + ai * 128 + (mh * 2 + ml) * 16; asm volatile("" : "+v"(R));
; #pragma unroll
;                         for (int bj = 0; bj < 2; ++bj) { const int t = 16 * u.pn + 8 * bj + 2 * wc + (fq >> 1); const size_t tok = (size_t)R * LCH + t;
;                             yv[ml][bj] = *(const u32x4*)(yi + ((size_t)g * T_TOK + tok) * 16 + 8 * (fq & 1)); uv[ml][bj] = *(const u32x4*)((const bf16_t*)x + ((size_t)g * T_TOK + tok) * 16 + 8 * (fq & 1)); } }
; #pragma unroll
;                     for (int ml = 0; ml < 2; ++ml) { const int m = mh * 2 + ml; int R = rbase + ai * 128 + m * 16; asm volatile("" : "+v"(R));
; #pragma unroll
;                         for (int bj = 0; bj < 2; ++bj) { const int t = 16 * u.pn + 8 * bj + 2 * wc + (fq >> 1); const size_t tok = (size_t)R * LCH + t;
;                             f32x4 y0, y1, u0, u1; unpack8(yv[ml][bj], y0, y1); unpack8(uv[ml][bj], u0, u1);
;                             y0 = acc[ai][bj][m][0] + y0 + d0 * u0; y1 = acc[ai][bj][m][1] + y1 + d1 * u1;
; #pragma unroll
;                             for (int j = 0; j < 4; ++j) { y0[j] = gelu_tanh(y0[j]); y1[j] = gelu_tanh(y1[j]); }
;                             *(u32x4*)(yi + ((size_t)g * T_TOK + tok) * 16 + 8 * (fq & 1)) = pack8(y0, y1); } }
;                     MEMFENCE; }
	v_rcp_f32_e32 v135, v135
	global_load_dwordx4 v[116:119], v[114:115], off
	v_mul_f32_e32 v105, v110, v105
	global_load_dwordx4 v[112:115], v[112:113], off
	v_mul_f32_e32 v110, v106, v131
	v_ashrrev_i32_e32 v133, 31, v132
	v_lshlrev_b64 v[132:133], 10, v[132:133]
	v_lshl_add_u64 v[132:133], v[162:163], 0, v[132:133]
	v_mul_f32_e32 v106, v111, v134
	v_mul_f32_e32 v107, v107, v135
	v_cvt_pk_bf16_f32 v104, v0, v104
	v_cvt_pk_bf16_f32 v105, v105, v106
	v_cvt_pk_bf16_f32 v106, v108, v109
	v_lshl_add_u64 v[108:109], v[132:133], 0, v[136:137]
	v_cvt_pk_bf16_f32 v107, v110, v107
	global_store_dwordx4 v[108:109], v[104:107], off
	v_lshlrev_b32_e32 v108, 16, v148
	v_and_b32_e32 v109, 0xffff0000, v148
	v_lshlrev_b32_e32 v104, 16, v146
	v_and_b32_e32 v105, 0xffff0000, v146
	v_lshlrev_b32_e32 v134, 16, v150
	v_and_b32_e32 v135, 0xffff0000, v150
	v_lshlrev_b32_e32 v140, 16, v152
	v_and_b32_e32 v141, 0xffff0000, v152
	v_pk_add_f32 v[100:101], v[100:101], v[104:105]
	v_pk_add_f32 v[96:97], v[96:97], v[108:109]
	v_pk_fma_f32 v[100:101], v[60:61], v[134:135], v[100:101]
	v_pk_fma_f32 v[96:97], v[56:57], v[140:141], v[96:97]
	v_mul_f32_e32 v0, 0x3d372713, v100
	v_mul_f32_e32 v104, 0x3d372713, v96
	v_mul_f32_e32 v105, 0x3d372713, v101
	v_mul_f32_e32 v0, v100, v0
	v_mul_f32_e32 v104, v96, v104
	v_mul_f32_e32 v105, v101, v105
	v_fma_f32 v0, v100, v0, v100
	v_fma_f32 v104, v96, v104, v96
	v_fma_f32 v105, v101, v105, v101
	v_mul_f32_e32 v0, 0x3fcc422a, v0
	v_mul_f32_e32 v104, 0x3fcc422a, v104
	v_mul_f32_e32 v105, 0x3fcc422a, v105
	v_mul_f32_e32 v0, 0xbfb8aa3b, v0
	v_mul_f32_e32 v104, 0xbfb8aa3b, v104
	v_mul_f32_e32 v105, 0xbfb8aa3b, v105
	v_exp_f32_e32 v0, v0
	v_exp_f32_e32 v104, v104
	v_exp_f32_e32 v105, v105
	v_lshlrev_b32_e32 v106, 16, v147
	v_and_b32_e32 v107, 0xffff0000, v147
	v_pk_add_f32 v[102:103], v[102:103], v[106:107]
	v_add_f32_e32 v0, 1.0, v0
	v_add_f32_e32 v104, 1.0, v104
	v_add_f32_e32 v105, 1.0, v105
	v_mul_f32_e32 v106, 0x3d372713, v97
	v_rcp_f32_e32 v0, v0
	v_rcp_f32_e32 v104, v104
	v_rcp_f32_e32 v105, v105
	v_mul_f32_e32 v106, v97, v106
	v_lshlrev_b32_e32 v110, 16, v149
	v_and_b32_e32 v111, 0xffff0000, v149
	v_fma_f32 v106, v97, v106, v97
	v_lshlrev_b32_e32 v138, 16, v151
	v_and_b32_e32 v139, 0xffff0000, v151
	v_lshlrev_b32_e32 v142, 16, v153
	v_and_b32_e32 v143, 0xffff0000, v153
	v_pk_add_f32 v[98:99], v[98:99], v[110:111]
	v_mul_f32_e32 v106, 0x3fcc422a, v106
	v_pk_fma_f32 v[102:103], v[62:63], v[138:139], v[102:103]
	v_pk_fma_f32 v[98:99], v[58:59], v[142:143], v[98:99]
	v_mul_f32_e32 v106, 0xbfb8aa3b, v106
	v_exp_f32_e32 v106, v106
	v_mul_f32_e32 v0, v100, v0
	v_mul_f32_e32 v100, v96, v104
	v_mul_f32_e32 v96, v101, v105
	v_mul_f32_e32 v104, 0x3d372713, v102
	v_mul_f32_e32 v105, 0x3d372713, v98
	v_mul_f32_e32 v104, v102, v104
	v_mul_f32_e32 v105, v98, v105
	v_fma_f32 v104, v102, v104, v102
	v_fma_f32 v105, v98, v105, v98
	v_mul_f32_e32 v104, 0x3fcc422a, v104
	v_mul_f32_e32 v105, 0x3fcc422a, v105
	v_add_f32_e32 v101, 1.0, v106
	v_mul_f32_e32 v104, 0xbfb8aa3b, v104
	v_mul_f32_e32 v105, 0xbfb8aa3b, v105
	v_rcp_f32_e32 v101, v101
	v_exp_f32_e32 v104, v104
	v_exp_f32_e32 v105, v105
	v_mul_f32_e32 v106, 0x3d372713, v99
	v_mul_f32_e32 v101, v97, v101
	v_add_f32_e32 v97, 1.0, v104
	v_add_f32_e32 v104, 1.0, v105
	v_mul_f32_e32 v105, 0x3d372713, v103
	v_mul_f32_e32 v105, v103, v105
	v_mul_f32_e32 v106, v99, v106
	v_fma_f32 v105, v103, v105, v103
	v_fma_f32 v106, v99, v106, v99
	v_mul_f32_e32 v105, 0x3fcc422a, v105
	v_mul_f32_e32 v106, 0x3fcc422a, v106
	v_mul_f32_e32 v105, 0xbfb8aa3b, v105
	v_mul_f32_e32 v106, 0xbfb8aa3b, v106
	v_exp_f32_e32 v105, v105
	v_exp_f32_e32 v106, v106
	v_rcp_f32_e32 v97, v97
	v_rcp_f32_e32 v104, v104
	v_add_f32_e32 v105, 1.0, v105
	v_add_f32_e32 v106, 1.0, v106
	v_rcp_f32_e32 v105, v105
	v_rcp_f32_e32 v106, v106
	v_mul_f32_e32 v97, v102, v97
	v_mul_f32_e32 v102, v98, v104
	v_mul_f32_e32 v98, v103, v105
	v_mul_f32_e32 v99, v99, v106
	v_cvt_pk_bf16_f32 v96, v0, v96
	v_cvt_pk_bf16_f32 v97, v97, v98
	v_cvt_pk_bf16_f32 v98, v100, v101
	v_cvt_pk_bf16_f32 v99, v102, v99
	v_lshl_add_u64 v[100:101], v[132:133], 0, v[128:129]
	global_store_dwordx4 v[100:101], v[96:99], off
	s_waitcnt vmcnt(0)
	v_lshlrev_b32_e32 v102, 16, v126
	v_and_b32_e32 v103, 0xffff0000, v126
	v_lshlrev_b32_e32 v98, 16, v124
	v_and_b32_e32 v99, 0xffff0000, v124
	v_lshlrev_b32_e32 v106, 16, v120
	v_and_b32_e32 v107, 0xffff0000, v120
	v_lshlrev_b32_e32 v110, 16, v122
	v_and_b32_e32 v111, 0xffff0000, v122
	v_pk_add_f32 v[92:93], v[92:93], v[98:99]
	v_pk_add_f32 v[88:89], v[88:89], v[102:103]
	v_pk_fma_f32 v[92:93], v[60:61], v[106:107], v[92:93]
	v_pk_fma_f32 v[88:89], v[56:57], v[110:111], v[88:89]
	v_mul_f32_e32 v0, 0x3d372713, v92
	v_mul_f32_e32 v98, 0x3d372713, v88
	v_mul_f32_e32 v99, 0x3d372713, v93
	v_mul_f32_e32 v0, v92, v0
	v_mul_f32_e32 v98, v88, v98
	v_mul_f32_e32 v99, v93, v99
	v_fma_f32 v0, v92, v0, v92
	v_fma_f32 v98, v88, v98, v88
	v_fma_f32 v99, v93, v99, v93
	v_mul_f32_e32 v0, 0x3fcc422a, v0
	v_mul_f32_e32 v98, 0x3fcc422a, v98
	v_mul_f32_e32 v99, 0x3fcc422a, v99
	v_mul_f32_e32 v0, 0xbfb8aa3b, v0
	v_mul_f32_e32 v98, 0xbfb8aa3b, v98
	v_mul_f32_e32 v99, 0xbfb8aa3b, v99
	v_exp_f32_e32 v0, v0
	v_exp_f32_e32 v98, v98
	v_exp_f32_e32 v99, v99
	v_lshlrev_b32_e32 v100, 16, v125
	v_and_b32_e32 v101, 0xffff0000, v125
	v_pk_add_f32 v[94:95], v[94:95], v[100:101]
	v_add_f32_e32 v0, 1.0, v0
	v_add_f32_e32 v98, 1.0, v98
	v_add_f32_e32 v99, 1.0, v99
	v_mul_f32_e32 v100, 0x3d372713, v89
	v_rcp_f32_e32 v0, v0
	v_rcp_f32_e32 v98, v98
	v_rcp_f32_e32 v99, v99
	v_mul_f32_e32 v100, v89, v100
	v_lshlrev_b32_e32 v104, 16, v127
	v_and_b32_e32 v105, 0xffff0000, v127
; __device__ __forceinline__ float gelu_tanh(float y) { const float z = 1.5957691216057308f * (y + 0.044715f * y * y * y); return y * sigmoidf_(z); }
; __device__ __forceinline__ u32x4 pack8(const f32x4 a, const f32x4 b) { u32x4 w; w.x = cvt_pk_bf16(a[0], a[1]); w.y = cvt_pk_bf16(a[2], a[3]); w.z = cvt_pk_bf16(b[0], b[1]); w.w = cvt_pk_bf16(b[2], b[3]); return w; }
; __device__ __forceinline__ void unpack8(const u32x4 w, f32x4& a, f32x4& b) { a[0] = bf_lo(w.x); a[1] = bf_hi(w.x); a[2] = bf_lo(w.y); a[3] = bf_hi(w.y); b[0] = bf_lo(w.z); b[1] = bf_hi(w.z); b[2] = bf_lo(w.w); b[3] = bf_hi(w.w); }
;     template <int KIND> __device__ __forceinline__ void run(f32x4 (&acc)[2][2][4][2], const Unit& u, int tid_in) const {
;     ...
;                 for (int mh = 0; mh < 2; ++mh) { u32x4 yv[2][2], uv[2][2];
; #pragma unroll
;                     for (int ml = 0; ml < 2; ++ml) { int R = rbase + ai * 128 + (mh * 2 + ml) * 16; asm volatile("" : "+v"(R));
; #pragma unroll
;                         for (int bj = 0; bj < 2; ++bj) { const int t = 16 * u.pn + 8 * bj + 2 * wc + (fq >> 1); const size_t tok = (size_t)R * LCH + t;
;                             yv[ml][bj] = *(const u32x4*)(yi + ((size_t)g * T_TOK + tok) * 16 + 8 * (fq & 1)); uv[ml][bj] = *(const u32x4*)((const bf16_t*)x + ((size_t)g * T_TOK + tok) * 16 + 8 * (fq & 1)); } }
; #pragma unroll
;                     for (int ml = 0; ml < 2; ++ml) { const int m = mh * 2 + ml; int R = rbase + ai * 128 + m * 16; asm volatile("" : "+v"(R));
; #pragma unroll
;                         for (int bj = 0; bj < 2; ++bj) { const int t = 16 * u.pn + 8 * bj + 2 * wc + (fq >> 1); const size_t tok = (size_t)R * LCH + t;
;                             f32x4 y0, y1, u0, u1; unpack8(yv[ml][bj], y0, y1); unpack8(uv[ml][bj], u0, u1);
;                             y0 = acc[ai][bj][m][0] + y0 + d0 * u0; y1 = acc[ai][bj][m][1] + y1 + d1 * u1;
; #pragma unroll
;                             for (int j = 0; j < 4; ++j) { y0[j] = gelu_tanh(y0[j]); y1[j] = gelu_tanh(y1[j]); }
;                             *(u32x4*)(yi + ((size_t)g * T_TOK + tok) * 16 + 8 * (fq & 1)) = pack8(y0, y1); } }
	v_fma_f32 v100, v89, v100, v89
	v_lshlrev_b32_e32 v108, 16, v121
	v_and_b32_e32 v109, 0xffff0000, v121
	v_lshlrev_b32_e32 v120, 16, v123
	v_and_b32_e32 v121, 0xffff0000, v123
	v_pk_add_f32 v[90:91], v[90:91], v[104:105]
	v_mul_f32_e32 v100, 0x3fcc422a, v100
	v_pk_fma_f32 v[94:95], v[62:63], v[108:109], v[94:95]
	v_pk_fma_f32 v[90:91], v[58:59], v[120:121], v[90:91]
	v_mul_f32_e32 v100, 0xbfb8aa3b, v100
	v_exp_f32_e32 v100, v100
	v_mul_f32_e32 v0, v92, v0
	v_mul_f32_e32 v92, v88, v98
	v_mul_f32_e32 v88, v93, v99
	v_mul_f32_e32 v98, 0x3d372713, v94
	v_mul_f32_e32 v99, 0x3d372713, v90
	v_mul_f32_e32 v98, v94, v98
	v_mul_f32_e32 v99, v90, v99
	v_fma_f32 v98, v94, v98, v94
	v_fma_f32 v99, v90, v99, v90
	v_mul_f32_e32 v98, 0x3fcc422a, v98
	v_mul_f32_e32 v99, 0x3fcc422a, v99
	v_add_f32_e32 v93, 1.0, v100
	v_mul_f32_e32 v98, 0xbfb8aa3b, v98
	v_mul_f32_e32 v99, 0xbfb8aa3b, v99
	v_rcp_f32_e32 v93, v93
	v_exp_f32_e32 v98, v98
	v_exp_f32_e32 v99, v99
	v_mul_f32_e32 v100, 0x3d372713, v91
	v_mul_f32_e32 v93, v89, v93
	v_add_f32_e32 v89, 1.0, v98
	v_add_f32_e32 v98, 1.0, v99
	v_mul_f32_e32 v99, 0x3d372713, v95
	v_mul_f32_e32 v99, v95, v99
	v_fma_f32 v99, v95, v99, v95
	v_mul_f32_e32 v100, v91, v100
	v_mul_f32_e32 v99, 0x3fcc422a, v99
	v_fma_f32 v100, v91, v100, v91
	v_mul_f32_e32 v99, 0xbfb8aa3b, v99
	v_mul_f32_e32 v100, 0x3fcc422a, v100
	v_exp_f32_e32 v99, v99
	v_mul_f32_e32 v100, 0xbfb8aa3b, v100
	v_exp_f32_e32 v100, v100
	v_rcp_f32_e32 v89, v89
	v_add_f32_e32 v99, 1.0, v99
	v_rcp_f32_e32 v98, v98
	v_rcp_f32_e32 v99, v99
	v_add_f32_e32 v100, 1.0, v100
	v_rcp_f32_e32 v100, v100
	v_mul_f32_e32 v89, v94, v89
	v_ashrrev_i32_e32 v131, 31, v130
	v_lshlrev_b64 v[96:97], 10, v[130:131]
	v_lshl_add_u64 v[96:97], v[162:163], 0, v[96:97]
	v_mul_f32_e32 v94, v90, v98
	v_mul_f32_e32 v90, v95, v99
	v_mul_f32_e32 v91, v91, v100
	v_cvt_pk_bf16_f32 v88, v0, v88
	v_cvt_pk_bf16_f32 v89, v89, v90
	v_cvt_pk_bf16_f32 v90, v92, v93
	v_lshl_add_u64 v[92:93], v[96:97], 0, v[136:137]
	v_cvt_pk_bf16_f32 v91, v94, v91
	global_store_dwordx4 v[92:93], v[88:91], off
	v_lshlrev_b32_e32 v92, 16, v118
	v_and_b32_e32 v93, 0xffff0000, v118
	v_lshlrev_b32_e32 v88, 16, v116
	v_and_b32_e32 v89, 0xffff0000, v116
	v_lshlrev_b32_e32 v98, 16, v112
	v_and_b32_e32 v99, 0xffff0000, v112
	v_lshlrev_b32_e32 v102, 16, v114
	v_and_b32_e32 v103, 0xffff0000, v114
	v_pk_add_f32 v[84:85], v[84:85], v[88:89]
	v_pk_add_f32 v[80:81], v[80:81], v[92:93]
	v_pk_fma_f32 v[84:85], v[60:61], v[98:99], v[84:85]
	v_pk_fma_f32 v[80:81], v[56:57], v[102:103], v[80:81]
	v_mul_f32_e32 v0, 0x3d372713, v84
	v_mul_f32_e32 v88, 0x3d372713, v80
	v_mul_f32_e32 v89, 0x3d372713, v85
	v_mul_f32_e32 v0, v84, v0
	v_mul_f32_e32 v88, v80, v88
	v_mul_f32_e32 v89, v85, v89
	v_fma_f32 v0, v84, v0, v84
	v_fma_f32 v88, v80, v88, v80
	v_fma_f32 v89, v85, v89, v85
	v_mul_f32_e32 v0, 0x3fcc422a, v0
	v_mul_f32_e32 v88, 0x3fcc422a, v88
	v_mul_f32_e32 v89, 0x3fcc422a, v89
	v_mul_f32_e32 v0, 0xbfb8aa3b, v0
	v_mul_f32_e32 v88, 0xbfb8aa3b, v88
	v_mul_f32_e32 v89, 0xbfb8aa3b, v89
	v_exp_f32_e32 v0, v0
	v_exp_f32_e32 v88, v88
	v_exp_f32_e32 v89, v89
	v_lshlrev_b32_e32 v90, 16, v117
	v_and_b32_e32 v91, 0xffff0000, v117
	v_pk_add_f32 v[86:87], v[86:87], v[90:91]
	v_add_f32_e32 v0, 1.0, v0
	v_add_f32_e32 v88, 1.0, v88
	v_add_f32_e32 v89, 1.0, v89
	v_mul_f32_e32 v90, 0x3d372713, v81
	v_rcp_f32_e32 v0, v0
	v_rcp_f32_e32 v88, v88
	v_rcp_f32_e32 v89, v89
	v_mul_f32_e32 v90, v81, v90
	v_lshlrev_b32_e32 v94, 16, v119
	v_and_b32_e32 v95, 0xffff0000, v119
	v_fma_f32 v90, v81, v90, v81
	v_lshlrev_b32_e32 v100, 16, v113
	v_and_b32_e32 v101, 0xffff0000, v113
	v_lshlrev_b32_e32 v104, 16, v115
	v_and_b32_e32 v105, 0xffff0000, v115
	v_pk_add_f32 v[82:83], v[82:83], v[94:95]
	v_mul_f32_e32 v90, 0x3fcc422a, v90
	v_pk_fma_f32 v[86:87], v[62:63], v[100:101], v[86:87]
	v_pk_fma_f32 v[82:83], v[58:59], v[104:105], v[82:83]
	v_mul_f32_e32 v90, 0xbfb8aa3b, v90
	v_exp_f32_e32 v90, v90
	v_mul_f32_e32 v0, v84, v0
	v_mul_f32_e32 v84, v80, v88
	v_mul_f32_e32 v80, v85, v89
	v_mul_f32_e32 v88, 0x3d372713, v86
	v_mul_f32_e32 v89, 0x3d372713, v82
	v_mul_f32_e32 v88, v86, v88
	v_mul_f32_e32 v89, v82, v89
	v_fma_f32 v88, v86, v88, v86
	v_fma_f32 v89, v82, v89, v82
	v_mul_f32_e32 v88, 0x3fcc422a, v88
	v_mul_f32_e32 v89, 0x3fcc422a, v89
	v_add_f32_e32 v85, 1.0, v90
	v_mul_f32_e32 v88, 0xbfb8aa3b, v88
	v_mul_f32_e32 v89, 0xbfb8aa3b, v89
	v_rcp_f32_e32 v85, v85
	v_exp_f32_e32 v88, v88
	v_exp_f32_e32 v89, v89
	v_mul_f32_e32 v90, 0x3d372713, v83
	v_mul_f32_e32 v85, v81, v85
	v_add_f32_e32 v81, 1.0, v88
	v_add_f32_e32 v88, 1.0, v89
	v_mul_f32_e32 v89, 0x3d372713, v87
	v_mul_f32_e32 v89, v87, v89
	v_fma_f32 v89, v87, v89, v87
	v_mul_f32_e32 v90, v83, v90
	v_mul_f32_e32 v89, 0x3fcc422a, v89
	v_fma_f32 v90, v83, v90, v83
	v_mul_f32_e32 v89, 0xbfb8aa3b, v89
	v_mul_f32_e32 v90, 0x3fcc422a, v90
	v_exp_f32_e32 v89, v89
	v_mul_f32_e32 v90, 0xbfb8aa3b, v90
	v_exp_f32_e32 v90, v90
	v_rcp_f32_e32 v81, v81
	v_add_f32_e32 v89, 1.0, v89
	v_rcp_f32_e32 v88, v88
	v_rcp_f32_e32 v89, v89
	v_add_f32_e32 v90, 1.0, v90
	v_rcp_f32_e32 v90, v90
	v_mul_f32_e32 v81, v86, v81
	v_mul_f32_e32 v86, v82, v88
	v_mul_f32_e32 v82, v87, v89
	v_mul_f32_e32 v83, v83, v90
	v_cvt_pk_bf16_f32 v80, v0, v80
	v_cvt_pk_bf16_f32 v81, v81, v82
	v_cvt_pk_bf16_f32 v82, v84, v85
	v_lshl_add_u64 v[84:85], v[96:97], 0, v[128:129]
	v_add_u32_e32 v98, 0x80, v185
	v_cvt_pk_bf16_f32 v83, v86, v83
	global_store_dwordx4 v[84:85], v[80:83], off
	v_add_u32_e32 v96, 0x90, v185
	s_nop 0
	v_mov_b32_e32 v80, v98
	s_nop 0
	v_ashrrev_i32_e32 v81, 31, v80
	v_lshlrev_b64 v[80:81], 9, v[80:81]
	v_lshl_add_u64 v[80:81], v[80:81], 0, s[20:21]
	v_lshl_add_u64 v[82:83], v[80:81], 0, v[172:173]
	v_lshlrev_b64 v[82:83], 1, v[82:83]
	v_lshl_add_u64 v[84:85], v[164:165], 0, v[82:83]
	global_load_dwordx4 v[100:103], v[84:85], off
	v_lshl_add_u64 v[82:83], v[166:167], 0, v[82:83]
	global_load_dwordx4 v[104:107], v[82:83], off
	v_lshl_add_u64 v[80:81], v[80:81], 0, v[174:175]
	v_lshlrev_b64 v[80:81], 1, v[80:81]
	v_lshl_add_u64 v[82:83], v[164:165], 0, v[80:81]
	global_load_dwordx4 v[108:111], v[82:83], off
	v_lshl_add_u64 v[80:81], v[166:167], 0, v[80:81]
	global_load_dwordx4 v[112:115], v[80:81], off
	v_mov_b32_e32 v80, v96
	s_waitcnt vmcnt(0)
; __device__ __forceinline__ float gelu_tanh(float y) { const float z = 1.5957691216057308f * (y + 0.044715f * y * y * y); return y * sigmoidf_(z); }
; __device__ __forceinline__ u32x4 pack8(const f32x4 a, const f32x4 b) { u32x4 w; w.x = cvt_pk_bf16(a[0], a[1]); w.y = cvt_pk_bf16(a[2], a[3]); w.z = cvt_pk_bf16(b[0], b[1]); w.w = cvt_pk_bf16(b[2], b[3]); return w; }
; __device__ __forceinline__ void unpack8(const u32x4 w, f32x4& a, f32x4& b) { a[0] = bf_lo(w.x); a[1] = bf_hi(w.x); a[2] = bf_lo(w.y); a[3] = bf_hi(w.y); b[0] = bf_lo(w.z); b[1] = bf_hi(w.z); b[2] = bf_lo(w.w); b[3] = bf_hi(w.w); }
;     template <int KIND> __device__ __forceinline__ void run(f32x4 (&acc)[2][2][4][2], const Unit& u, int tid_in) const {
;     ...
;                 for (int mh = 0; mh < 2; ++mh) { u32x4 yv[2][2], uv[2][2];
; #pragma unroll
;                     for (int ml = 0; ml < 2; ++ml) { int R = rbase + ai * 128 + (mh * 2 + ml) * 16; asm volatile("" : "+v"(R));
; #pragma unroll
;                         for (int bj = 0; bj < 2; ++bj) { const int t = 16 * u.pn + 8 * bj + 2 * wc + (fq >> 1); const size_t tok = (size_t)R * LCH + t;
;                             yv[ml][bj] = *(const u32x4*)(yi + ((size_t)g * T_TOK + tok) * 16 + 8 * (fq & 1)); uv[ml][bj] = *(const u32x4*)((const bf16_t*)x + ((size_t)g * T_TOK + tok) * 16 + 8 * (fq & 1)); } }
; #pragma unroll
;                     for (int ml = 0; ml < 2; ++ml) { const int m = mh * 2 + ml; int R = rbase + ai * 128 + m * 16; asm volatile("" : "+v"(R));
; #pragma unroll
;                         for (int bj = 0; bj < 2; ++bj) { const int t = 16 * u.pn + 8 * bj + 2 * wc + (fq >> 1); const size_t tok = (size_t)R * LCH + t;
;                             f32x4 y0, y1, u0, u1; unpack8(yv[ml][bj], y0, y1); unpack8(uv[ml][bj], u0, u1);
;                             y0 = acc[ai][bj][m][0] + y0 + d0 * u0; y1 = acc[ai][bj][m][1] + y1 + d1 * u1;
; #pragma unroll
;                             for (int j = 0; j < 4; ++j) { y0[j] = gelu_tanh(y0[j]); y1[j] = gelu_tanh(y1[j]); }
;                             *(u32x4*)(yi + ((size_t)g * T_TOK + tok) * 16 + 8 * (fq & 1)) = pack8(y0, y1); } }
	v_lshlrev_b32_e32 v116, 16, v100
	v_ashrrev_i32_e32 v81, 31, v80
	v_lshlrev_b64 v[80:81], 9, v[80:81]
	v_lshl_add_u64 v[80:81], v[80:81], 0, s[20:21]
	v_and_b32_e32 v117, 0xffff0000, v100
	v_lshlrev_b32_e32 v118, 16, v102
	v_and_b32_e32 v119, 0xffff0000, v102
	v_lshl_add_u64 v[82:83], v[80:81], 0, v[172:173]
	v_lshlrev_b32_e32 v120, 16, v104
	v_and_b32_e32 v121, 0xffff0000, v104
	v_lshlrev_b32_e32 v122, 16, v106
	v_and_b32_e32 v123, 0xffff0000, v106
	v_pk_add_f32 v[76:77], v[76:77], v[116:117]
	v_pk_add_f32 v[72:73], v[72:73], v[118:119]
	v_lshlrev_b64 v[82:83], 1, v[82:83]
	v_lshlrev_b32_e32 v100, 16, v101
	v_and_b32_e32 v101, 0xffff0000, v101
	v_pk_fma_f32 v[76:77], v[60:61], v[120:121], v[76:77]
	v_pk_fma_f32 v[72:73], v[56:57], v[122:123], v[72:73]
	v_lshl_add_u64 v[84:85], v[164:165], 0, v[82:83]
	v_pk_add_f32 v[78:79], v[78:79], v[100:101]
	v_mul_f32_e32 v0, 0x3d372713, v76
	v_mul_f32_e32 v97, 0x3d372713, v72
	v_mul_f32_e32 v100, 0x3d372713, v77
	global_load_dwordx4 v[92:95], v[84:85], off
	v_lshl_add_u64 v[82:83], v[166:167], 0, v[82:83]
	v_mul_f32_e32 v0, v76, v0
	v_mul_f32_e32 v97, v72, v97
	v_mul_f32_e32 v100, v77, v100
	global_load_dwordx4 v[88:91], v[82:83], off
	v_fma_f32 v0, v76, v0, v76
	v_fma_f32 v97, v72, v97, v72
	v_fma_f32 v100, v77, v100, v77
	v_mul_f32_e32 v0, 0x3fcc422a, v0
	v_mul_f32_e32 v97, 0x3fcc422a, v97
	v_mul_f32_e32 v100, 0x3fcc422a, v100
	v_mul_f32_e32 v0, 0xbfb8aa3b, v0
	v_mul_f32_e32 v97, 0xbfb8aa3b, v97
	v_mul_f32_e32 v100, 0xbfb8aa3b, v100
	v_exp_f32_e32 v0, v0
	v_exp_f32_e32 v97, v97
	v_exp_f32_e32 v100, v100
	v_mul_f32_e32 v101, 0x3d372713, v73
	v_add_f32_e32 v0, 1.0, v0
	v_add_f32_e32 v97, 1.0, v97
	v_add_f32_e32 v100, 1.0, v100
	v_rcp_f32_e32 v0, v0
	v_rcp_f32_e32 v97, v97
	v_rcp_f32_e32 v100, v100
	v_mul_f32_e32 v101, v73, v101
	v_lshlrev_b32_e32 v102, 16, v103
	v_and_b32_e32 v103, 0xffff0000, v103
	v_fma_f32 v101, v73, v101, v73
	v_lshlrev_b32_e32 v104, 16, v105
	v_and_b32_e32 v105, 0xffff0000, v105
	v_lshlrev_b32_e32 v106, 16, v107
	v_and_b32_e32 v107, 0xffff0000, v107
	v_pk_add_f32 v[74:75], v[74:75], v[102:103]
	v_mul_f32_e32 v101, 0x3fcc422a, v101
	v_pk_fma_f32 v[78:79], v[62:63], v[104:105], v[78:79]
	v_pk_fma_f32 v[74:75], v[58:59], v[106:107], v[74:75]
	v_mul_f32_e32 v101, 0xbfb8aa3b, v101
	v_exp_f32_e32 v101, v101
	v_mul_f32_e32 v0, v76, v0
	v_mul_f32_e32 v76, v72, v97
	v_mul_f32_e32 v72, v77, v100
	v_mul_f32_e32 v97, 0x3d372713, v78
	v_mul_f32_e32 v100, 0x3d372713, v74
	v_mul_f32_e32 v97, v78, v97
	v_mul_f32_e32 v100, v74, v100
	v_fma_f32 v97, v78, v97, v78
	v_fma_f32 v100, v74, v100, v74
	v_mul_f32_e32 v97, 0x3fcc422a, v97
	v_mul_f32_e32 v100, 0x3fcc422a, v100
	v_add_f32_e32 v77, 1.0, v101
	v_mul_f32_e32 v97, 0xbfb8aa3b, v97
	v_mul_f32_e32 v100, 0xbfb8aa3b, v100
	v_rcp_f32_e32 v77, v77
	v_exp_f32_e32 v97, v97
	v_exp_f32_e32 v100, v100
	v_mul_f32_e32 v101, 0x3d372713, v75
	v_mul_f32_e32 v77, v73, v77
	v_add_f32_e32 v73, 1.0, v97
	v_add_f32_e32 v97, 1.0, v100
	v_mul_f32_e32 v100, 0x3d372713, v79
	v_mul_f32_e32 v100, v79, v100
	v_fma_f32 v100, v79, v100, v79
	v_mul_f32_e32 v101, v75, v101
	v_mul_f32_e32 v100, 0x3fcc422a, v100
	v_fma_f32 v101, v75, v101, v75
	v_mul_f32_e32 v100, 0xbfb8aa3b, v100
	v_mul_f32_e32 v101, 0x3fcc422a, v101
	v_exp_f32_e32 v100, v100
	v_mul_f32_e32 v101, 0xbfb8aa3b, v101
	v_exp_f32_e32 v101, v101
	v_lshl_add_u64 v[80:81], v[80:81], 0, v[174:175]
	v_add_f32_e32 v100, 1.0, v100
	v_lshlrev_b64 v[80:81], 1, v[80:81]
	v_rcp_f32_e32 v73, v73
	v_rcp_f32_e32 v97, v97
	v_rcp_f32_e32 v100, v100
	v_add_f32_e32 v101, 1.0, v101
	v_lshl_add_u64 v[82:83], v[164:165], 0, v[80:81]
	v_lshl_add_u64 v[80:81], v[166:167], 0, v[80:81]
	v_rcp_f32_e32 v101, v101
	global_load_dwordx4 v[84:87], v[82:83], off
	v_mul_f32_e32 v73, v78, v73
	global_load_dwordx4 v[80:83], v[80:81], off
	v_mul_f32_e32 v78, v74, v97
	v_ashrrev_i32_e32 v99, 31, v98
	v_lshlrev_b64 v[98:99], 10, v[98:99]
	v_lshl_add_u64 v[98:99], v[162:163], 0, v[98:99]
	v_mul_f32_e32 v74, v79, v100
	v_mul_f32_e32 v75, v75, v101
	v_cvt_pk_bf16_f32 v72, v0, v72
	v_cvt_pk_bf16_f32 v73, v73, v74
	v_cvt_pk_bf16_f32 v74, v76, v77
	v_lshl_add_u64 v[76:77], v[98:99], 0, v[136:137]
	v_cvt_pk_bf16_f32 v75, v78, v75
	global_store_dwordx4 v[76:77], v[72:75], off
	v_lshlrev_b32_e32 v76, 16, v110
	v_and_b32_e32 v77, 0xffff0000, v110
	v_lshlrev_b32_e32 v72, 16, v108
	v_and_b32_e32 v73, 0xffff0000, v108
	v_lshlrev_b32_e32 v100, 16, v112
	v_and_b32_e32 v101, 0xffff0000, v112
	v_lshlrev_b32_e32 v104, 16, v114
	v_and_b32_e32 v105, 0xffff0000, v114
	v_pk_add_f32 v[68:69], v[68:69], v[72:73]
	v_pk_add_f32 v[64:65], v[64:65], v[76:77]
	v_pk_fma_f32 v[68:69], v[60:61], v[100:101], v[68:69]
	v_pk_fma_f32 v[64:65], v[56:57], v[104:105], v[64:65]
	v_mul_f32_e32 v0, 0x3d372713, v68
	v_mul_f32_e32 v72, 0x3d372713, v64
	v_mul_f32_e32 v73, 0x3d372713, v69
	v_mul_f32_e32 v0, v68, v0
	v_mul_f32_e32 v72, v64, v72
	v_mul_f32_e32 v73, v69, v73
	v_fma_f32 v0, v68, v0, v68
	v_fma_f32 v72, v64, v72, v64
	v_fma_f32 v73, v69, v73, v69
	v_mul_f32_e32 v0, 0x3fcc422a, v0
	v_mul_f32_e32 v72, 0x3fcc422a, v72
	v_mul_f32_e32 v73, 0x3fcc422a, v73
	v_mul_f32_e32 v0, 0xbfb8aa3b, v0
	v_mul_f32_e32 v72, 0xbfb8aa3b, v72
	v_mul_f32_e32 v73, 0xbfb8aa3b, v73
	v_exp_f32_e32 v0, v0
	v_exp_f32_e32 v72, v72
	v_exp_f32_e32 v73, v73
	v_lshlrev_b32_e32 v74, 16, v109
	v_and_b32_e32 v75, 0xffff0000, v109
	v_pk_add_f32 v[70:71], v[70:71], v[74:75]
	v_add_f32_e32 v0, 1.0, v0
	v_add_f32_e32 v72, 1.0, v72
	v_add_f32_e32 v73, 1.0, v73
	v_mul_f32_e32 v74, 0x3d372713, v65
	v_rcp_f32_e32 v0, v0
	v_rcp_f32_e32 v72, v72
	v_rcp_f32_e32 v73, v73
	v_mul_f32_e32 v74, v65, v74
	v_lshlrev_b32_e32 v78, 16, v111
; __device__ __forceinline__ float gelu_tanh(float y) { const float z = 1.5957691216057308f * (y + 0.044715f * y * y * y); return y * sigmoidf_(z); }
; __device__ __forceinline__ u32x4 pack8(const f32x4 a, const f32x4 b) { u32x4 w; w.x = cvt_pk_bf16(a[0], a[1]); w.y = cvt_pk_bf16(a[2], a[3]); w.z = cvt_pk_bf16(b[0], b[1]); w.w = cvt_pk_bf16(b[2], b[3]); return w; }
; __device__ __forceinline__ void unpack8(const u32x4 w, f32x4& a, f32x4& b) { a[0] = bf_lo(w.x); a[1] = bf_hi(w.x); a[2] = bf_lo(w.y); a[3] = bf_hi(w.y); b[0] = bf_lo(w.z); b[1] = bf_hi(w.z); b[2] = bf_lo(w.w); b[3] = bf_hi(w.w); }
;     template <int KIND> __device__ __forceinline__ void run(f32x4 (&acc)[2][2][4][2], const Unit& u, int tid_in) const {
;     ...
;                 for (int mh = 0; mh < 2; ++mh) { u32x4 yv[2][2], uv[2][2];
; #pragma unroll
;                     for (int ml = 0; ml < 2; ++ml) { int R = rbase + ai * 128 + (mh * 2 + ml) * 16; asm volatile("" : "+v"(R));
; #pragma unroll
;                         for (int bj = 0; bj < 2; ++bj) { const int t = 16 * u.pn + 8 * bj + 2 * wc + (fq >> 1); const size_t tok = (size_t)R * LCH + t;
;                             yv[ml][bj] = *(const u32x4*)(yi + ((size_t)g * T_TOK + tok) * 16 + 8 * (fq & 1)); uv[ml][bj] = *(const u32x4*)((const bf16_t*)x + ((size_t)g * T_TOK + tok) * 16 + 8 * (fq & 1)); } }
; #pragma unroll
;                     for (int ml = 0; ml < 2; ++ml) { const int m = mh * 2 + ml; int R = rbase + ai * 128 + m * 16; asm volatile("" : "+v"(R));
; #pragma unroll
;                         for (int bj = 0; bj < 2; ++bj) { const int t = 16 * u.pn + 8 * bj + 2 * wc + (fq >> 1); const size_t tok = (size_t)R * LCH + t;
;                             f32x4 y0, y1, u0, u1; unpack8(yv[ml][bj], y0, y1); unpack8(uv[ml][bj], u0, u1);
;                             y0 = acc[ai][bj][m][0] + y0 + d0 * u0; y1 = acc[ai][bj][m][1] + y1 + d1 * u1;
; #pragma unroll
;                             for (int j = 0; j < 4; ++j) { y0[j] = gelu_tanh(y0[j]); y1[j] = gelu_tanh(y1[j]); }
;                             *(u32x4*)(yi + ((size_t)g * T_TOK + tok) * 16 + 8 * (fq & 1)) = pack8(y0, y1); } }
	v_and_b32_e32 v79, 0xffff0000, v111
	v_fma_f32 v74, v65, v74, v65
	v_lshlrev_b32_e32 v102, 16, v113
	v_and_b32_e32 v103, 0xffff0000, v113
	v_lshlrev_b32_e32 v106, 16, v115
	v_and_b32_e32 v107, 0xffff0000, v115
	v_pk_add_f32 v[66:67], v[66:67], v[78:79]
	v_mul_f32_e32 v74, 0x3fcc422a, v74
	v_pk_fma_f32 v[70:71], v[62:63], v[102:103], v[70:71]
	v_pk_fma_f32 v[66:67], v[58:59], v[106:107], v[66:67]
	v_mul_f32_e32 v74, 0xbfb8aa3b, v74
	v_exp_f32_e32 v74, v74
	v_mul_f32_e32 v0, v68, v0
	v_mul_f32_e32 v68, v64, v72
	v_mul_f32_e32 v64, v69, v73
	v_mul_f32_e32 v72, 0x3d372713, v70
	v_mul_f32_e32 v73, 0x3d372713, v66
	v_mul_f32_e32 v72, v70, v72
	v_mul_f32_e32 v73, v66, v73
	v_fma_f32 v72, v70, v72, v70
	v_fma_f32 v73, v66, v73, v66
	v_mul_f32_e32 v72, 0x3fcc422a, v72
	v_mul_f32_e32 v73, 0x3fcc422a, v73
	v_add_f32_e32 v69, 1.0, v74
	v_mul_f32_e32 v72, 0xbfb8aa3b, v72
	v_mul_f32_e32 v73, 0xbfb8aa3b, v73
	v_rcp_f32_e32 v69, v69
	v_exp_f32_e32 v72, v72
	v_exp_f32_e32 v73, v73
	v_mul_f32_e32 v74, 0x3d372713, v67
	v_mul_f32_e32 v69, v65, v69
	v_add_f32_e32 v65, 1.0, v72
	v_add_f32_e32 v72, 1.0, v73
	v_mul_f32_e32 v73, 0x3d372713, v71
	v_mul_f32_e32 v73, v71, v73
	v_mul_f32_e32 v74, v67, v74
	v_fma_f32 v73, v71, v73, v71
	v_fma_f32 v74, v67, v74, v67
	v_mul_f32_e32 v73, 0x3fcc422a, v73
	v_mul_f32_e32 v74, 0x3fcc422a, v74
	v_mul_f32_e32 v73, 0xbfb8aa3b, v73
	v_mul_f32_e32 v74, 0xbfb8aa3b, v74
	v_exp_f32_e32 v73, v73
	v_exp_f32_e32 v74, v74
	v_rcp_f32_e32 v65, v65
	v_rcp_f32_e32 v72, v72
	v_add_f32_e32 v73, 1.0, v73
	v_add_f32_e32 v74, 1.0, v74
	v_rcp_f32_e32 v73, v73
	v_rcp_f32_e32 v74, v74
	v_mul_f32_e32 v65, v70, v65
	v_mul_f32_e32 v70, v66, v72
	v_mul_f32_e32 v66, v71, v73
	v_mul_f32_e32 v67, v67, v74
	v_cvt_pk_bf16_f32 v64, v0, v64
	v_cvt_pk_bf16_f32 v65, v65, v66
	v_cvt_pk_bf16_f32 v66, v68, v69
	v_cvt_pk_bf16_f32 v67, v70, v67
	v_lshl_add_u64 v[68:69], v[98:99], 0, v[128:129]
	global_store_dwordx4 v[68:69], v[64:67], off
	s_waitcnt vmcnt(0)
	v_lshlrev_b32_e32 v70, 16, v94
	v_and_b32_e32 v71, 0xffff0000, v94
	v_lshlrev_b32_e32 v66, 16, v92
	v_and_b32_e32 v67, 0xffff0000, v92
	v_lshlrev_b32_e32 v74, 16, v88
	v_and_b32_e32 v75, 0xffff0000, v88
	v_lshlrev_b32_e32 v78, 16, v90
	v_and_b32_e32 v79, 0xffff0000, v90
	v_pk_add_f32 v[52:53], v[52:53], v[66:67]
	v_pk_add_f32 v[48:49], v[48:49], v[70:71]
	v_pk_fma_f32 v[52:53], v[60:61], v[74:75], v[52:53]
	v_pk_fma_f32 v[48:49], v[56:57], v[78:79], v[48:49]
	v_mul_f32_e32 v0, 0x3d372713, v52
	v_mul_f32_e32 v66, 0x3d372713, v48
	v_mul_f32_e32 v67, 0x3d372713, v53
	v_mul_f32_e32 v0, v52, v0
	v_mul_f32_e32 v66, v48, v66
	v_mul_f32_e32 v67, v53, v67
	v_fma_f32 v0, v52, v0, v52
	v_fma_f32 v66, v48, v66, v48
	v_fma_f32 v67, v53, v67, v53
	v_mul_f32_e32 v0, 0x3fcc422a, v0
	v_mul_f32_e32 v66, 0x3fcc422a, v66
	v_mul_f32_e32 v67, 0x3fcc422a, v67
	v_mul_f32_e32 v0, 0xbfb8aa3b, v0
	v_mul_f32_e32 v66, 0xbfb8aa3b, v66
	v_mul_f32_e32 v67, 0xbfb8aa3b, v67
	v_exp_f32_e32 v0, v0
	v_exp_f32_e32 v66, v66
	v_exp_f32_e32 v67, v67
	v_lshlrev_b32_e32 v68, 16, v93
	v_and_b32_e32 v69, 0xffff0000, v93
	v_pk_add_f32 v[54:55], v[54:55], v[68:69]
	v_add_f32_e32 v0, 1.0, v0
	v_add_f32_e32 v66, 1.0, v66
	v_add_f32_e32 v67, 1.0, v67
	v_mul_f32_e32 v68, 0x3d372713, v49
	v_rcp_f32_e32 v0, v0
	v_rcp_f32_e32 v66, v66
	v_rcp_f32_e32 v67, v67
	v_mul_f32_e32 v68, v49, v68
	v_lshlrev_b32_e32 v72, 16, v95
	v_and_b32_e32 v73, 0xffff0000, v95
	v_fma_f32 v68, v49, v68, v49
	v_lshlrev_b32_e32 v76, 16, v89
	v_and_b32_e32 v77, 0xffff0000, v89
	v_lshlrev_b32_e32 v88, 16, v91
	v_and_b32_e32 v89, 0xffff0000, v91
	v_pk_add_f32 v[50:51], v[50:51], v[72:73]
	v_mul_f32_e32 v68, 0x3fcc422a, v68
	v_pk_fma_f32 v[54:55], v[62:63], v[76:77], v[54:55]
	v_pk_fma_f32 v[50:51], v[58:59], v[88:89], v[50:51]
	v_mul_f32_e32 v68, 0xbfb8aa3b, v68
	v_exp_f32_e32 v68, v68
	v_mul_f32_e32 v0, v52, v0
	v_mul_f32_e32 v52, v48, v66
	v_mul_f32_e32 v48, v53, v67
	v_mul_f32_e32 v66, 0x3d372713, v54
	v_mul_f32_e32 v67, 0x3d372713, v50
	v_mul_f32_e32 v66, v54, v66
	v_mul_f32_e32 v67, v50, v67
	v_fma_f32 v66, v54, v66, v54
	v_fma_f32 v67, v50, v67, v50
	v_mul_f32_e32 v66, 0x3fcc422a, v66
	v_mul_f32_e32 v67, 0x3fcc422a, v67
	v_add_f32_e32 v53, 1.0, v68
	v_mul_f32_e32 v66, 0xbfb8aa3b, v66
	v_mul_f32_e32 v67, 0xbfb8aa3b, v67
	v_rcp_f32_e32 v53, v53
	v_exp_f32_e32 v66, v66
	v_exp_f32_e32 v67, v67
	v_mul_f32_e32 v68, 0x3d372713, v51
	v_mul_f32_e32 v53, v49, v53
	v_add_f32_e32 v49, 1.0, v66
	v_add_f32_e32 v66, 1.0, v67
	v_mul_f32_e32 v67, 0x3d372713, v55
	v_mul_f32_e32 v67, v55, v67
	v_fma_f32 v67, v55, v67, v55
	v_mul_f32_e32 v68, v51, v68
	v_mul_f32_e32 v67, 0x3fcc422a, v67
	v_fma_f32 v68, v51, v68, v51
	v_mul_f32_e32 v67, 0xbfb8aa3b, v67
	v_mul_f32_e32 v68, 0x3fcc422a, v68
	v_exp_f32_e32 v67, v67
	v_mul_f32_e32 v68, 0xbfb8aa3b, v68
	v_exp_f32_e32 v68, v68
	v_rcp_f32_e32 v49, v49
	v_add_f32_e32 v67, 1.0, v67
	v_rcp_f32_e32 v66, v66
	v_rcp_f32_e32 v67, v67
	v_add_f32_e32 v68, 1.0, v68
	v_rcp_f32_e32 v68, v68
	v_mul_f32_e32 v49, v54, v49
	v_ashrrev_i32_e32 v97, 31, v96
	v_lshlrev_b64 v[64:65], 10, v[96:97]
	v_lshl_add_u64 v[64:65], v[162:163], 0, v[64:65]
	v_mul_f32_e32 v54, v50, v66
	v_mul_f32_e32 v50, v55, v67
	v_mul_f32_e32 v51, v51, v68
	v_cvt_pk_bf16_f32 v48, v0, v48
	v_cvt_pk_bf16_f32 v49, v49, v50
	v_cvt_pk_bf16_f32 v50, v52, v53
	v_lshl_add_u64 v[52:53], v[64:65], 0, v[136:137]
	v_cvt_pk_bf16_f32 v51, v54, v51
	global_store_dwordx4 v[52:53], v[48:51], off
	v_lshlrev_b32_e32 v52, 16, v86
	v_and_b32_e32 v53, 0xffff0000, v86
	v_lshlrev_b32_e32 v48, 16, v84
	v_and_b32_e32 v49, 0xffff0000, v84
	v_lshlrev_b32_e32 v66, 16, v80
	v_and_b32_e32 v67, 0xffff0000, v80
	v_lshlrev_b32_e32 v70, 16, v82
; __device__ __forceinline__ float gelu_tanh(float y) { const float z = 1.5957691216057308f * (y + 0.044715f * y * y * y); return y * sigmoidf_(z); }
; __device__ __forceinline__ u32x4 pack8(const f32x4 a, const f32x4 b) { u32x4 w; w.x = cvt_pk_bf16(a[0], a[1]); w.y = cvt_pk_bf16(a[2], a[3]); w.z = cvt_pk_bf16(b[0], b[1]); w.w = cvt_pk_bf16(b[2], b[3]); return w; }
; __device__ __forceinline__ void unpack8(const u32x4 w, f32x4& a, f32x4& b) { a[0] = bf_lo(w.x); a[1] = bf_hi(w.x); a[2] = bf_lo(w.y); a[3] = bf_hi(w.y); b[0] = bf_lo(w.z); b[1] = bf_hi(w.z); b[2] = bf_lo(w.w); b[3] = bf_hi(w.w); }
;     template <int KIND> __device__ __forceinline__ void run(f32x4 (&acc)[2][2][4][2], const Unit& u, int tid_in) const {
;     ...
;                 for (int mh = 0; mh < 2; ++mh) { u32x4 yv[2][2], uv[2][2];
; #pragma unroll
;                     for (int ml = 0; ml < 2; ++ml) { int R = rbase + ai * 128 + (mh * 2 + ml) * 16; asm volatile("" : "+v"(R));
; #pragma unroll
;                         for (int bj = 0; bj < 2; ++bj) { const int t = 16 * u.pn + 8 * bj + 2 * wc + (fq >> 1); const size_t tok = (size_t)R * LCH + t;
;                             yv[ml][bj] = *(const u32x4*)(yi + ((size_t)g * T_TOK + tok) * 16 + 8 * (fq & 1)); uv[ml][bj] = *(const u32x4*)((const bf16_t*)x + ((size_t)g * T_TOK + tok) * 16 + 8 * (fq & 1)); } }
; #pragma unroll
;                     for (int ml = 0; ml < 2; ++ml) { const int m = mh * 2 + ml; int R = rbase + ai * 128 + m * 16; asm volatile("" : "+v"(R));
; #pragma unroll
;                         for (int bj = 0; bj < 2; ++bj) { const int t = 16 * u.pn + 8 * bj + 2 * wc + (fq >> 1); const size_t tok = (size_t)R * LCH + t;
;                             f32x4 y0, y1, u0, u1; unpack8(yv[ml][bj], y0, y1); unpack8(uv[ml][bj], u0, u1);
;                             y0 = acc[ai][bj][m][0] + y0 + d0 * u0; y1 = acc[ai][bj][m][1] + y1 + d1 * u1;
; #pragma unroll
;                             for (int j = 0; j < 4; ++j) { y0[j] = gelu_tanh(y0[j]); y1[j] = gelu_tanh(y1[j]); }
;                             *(u32x4*)(yi + ((size_t)g * T_TOK + tok) * 16 + 8 * (fq & 1)) = pack8(y0, y1); } }
	v_and_b32_e32 v71, 0xffff0000, v82
	v_pk_add_f32 v[44:45], v[44:45], v[48:49]
	v_pk_add_f32 v[40:41], v[40:41], v[52:53]
	v_pk_fma_f32 v[44:45], v[60:61], v[66:67], v[44:45]
	v_pk_fma_f32 v[40:41], v[56:57], v[70:71], v[40:41]
	v_mul_f32_e32 v0, 0x3d372713, v44
	v_mul_f32_e32 v48, 0x3d372713, v40
	v_mul_f32_e32 v49, 0x3d372713, v45
	v_mul_f32_e32 v0, v44, v0
	v_mul_f32_e32 v48, v40, v48
	v_mul_f32_e32 v49, v45, v49
	v_fma_f32 v0, v44, v0, v44
	v_fma_f32 v48, v40, v48, v40
	v_fma_f32 v49, v45, v49, v45
	v_mul_f32_e32 v0, 0x3fcc422a, v0
	v_mul_f32_e32 v48, 0x3fcc422a, v48
	v_mul_f32_e32 v49, 0x3fcc422a, v49
	v_mul_f32_e32 v0, 0xbfb8aa3b, v0
	v_mul_f32_e32 v48, 0xbfb8aa3b, v48
	v_mul_f32_e32 v49, 0xbfb8aa3b, v49
	v_exp_f32_e32 v0, v0
	v_exp_f32_e32 v48, v48
	v_exp_f32_e32 v49, v49
	v_lshlrev_b32_e32 v50, 16, v85
	v_and_b32_e32 v51, 0xffff0000, v85
	v_pk_add_f32 v[46:47], v[46:47], v[50:51]
	v_add_f32_e32 v0, 1.0, v0
	v_add_f32_e32 v48, 1.0, v48
	v_add_f32_e32 v49, 1.0, v49
	v_mul_f32_e32 v50, 0x3d372713, v41
	v_rcp_f32_e32 v0, v0
	v_rcp_f32_e32 v48, v48
	v_rcp_f32_e32 v49, v49
	v_mul_f32_e32 v50, v41, v50
	v_lshlrev_b32_e32 v54, 16, v87
	v_and_b32_e32 v55, 0xffff0000, v87
	v_fma_f32 v50, v41, v50, v41
	v_lshlrev_b32_e32 v68, 16, v81
	v_and_b32_e32 v69, 0xffff0000, v81
	v_lshlrev_b32_e32 v72, 16, v83
	v_and_b32_e32 v73, 0xffff0000, v83
	v_pk_add_f32 v[42:43], v[42:43], v[54:55]
	v_mul_f32_e32 v50, 0x3fcc422a, v50
	v_pk_fma_f32 v[46:47], v[62:63], v[68:69], v[46:47]
	v_pk_fma_f32 v[42:43], v[58:59], v[72:73], v[42:43]
	v_mul_f32_e32 v50, 0xbfb8aa3b, v50
	v_exp_f32_e32 v50, v50
	v_mul_f32_e32 v0, v44, v0
	v_mul_f32_e32 v44, v40, v48
	v_mul_f32_e32 v40, v45, v49
	v_mul_f32_e32 v48, 0x3d372713, v46
	v_mul_f32_e32 v49, 0x3d372713, v42
	v_mul_f32_e32 v48, v46, v48
	v_mul_f32_e32 v49, v42, v49
	v_fma_f32 v48, v46, v48, v46
	v_fma_f32 v49, v42, v49, v42
	v_mul_f32_e32 v48, 0x3fcc422a, v48
	v_mul_f32_e32 v49, 0x3fcc422a, v49
	v_add_f32_e32 v45, 1.0, v50
	v_mul_f32_e32 v48, 0xbfb8aa3b, v48
	v_mul_f32_e32 v49, 0xbfb8aa3b, v49
	v_rcp_f32_e32 v45, v45
	v_exp_f32_e32 v48, v48
	v_exp_f32_e32 v49, v49
	v_mul_f32_e32 v50, 0x3d372713, v43
	v_mul_f32_e32 v45, v41, v45
	v_add_f32_e32 v41, 1.0, v48
	v_add_f32_e32 v48, 1.0, v49
	v_mul_f32_e32 v49, 0x3d372713, v47
	v_mul_f32_e32 v49, v47, v49
	v_fma_f32 v49, v47, v49, v47
	v_mul_f32_e32 v50, v43, v50
	v_mul_f32_e32 v49, 0x3fcc422a, v49
	v_fma_f32 v50, v43, v50, v43
	v_mul_f32_e32 v49, 0xbfb8aa3b, v49
	v_mul_f32_e32 v50, 0x3fcc422a, v50
	v_exp_f32_e32 v49, v49
	v_mul_f32_e32 v50, 0xbfb8aa3b, v50
	v_exp_f32_e32 v50, v50
	v_rcp_f32_e32 v41, v41
	v_add_f32_e32 v49, 1.0, v49
	v_rcp_f32_e32 v48, v48
	v_rcp_f32_e32 v49, v49
	v_add_f32_e32 v50, 1.0, v50
	v_rcp_f32_e32 v50, v50
	v_mul_f32_e32 v41, v46, v41
	v_mul_f32_e32 v46, v42, v48
	v_mul_f32_e32 v42, v47, v49
	v_mul_f32_e32 v43, v43, v50
	v_cvt_pk_bf16_f32 v40, v0, v40
	v_cvt_pk_bf16_f32 v41, v41, v42
	v_cvt_pk_bf16_f32 v42, v44, v45
	v_lshl_add_u64 v[44:45], v[64:65], 0, v[128:129]
	v_add_u32_e32 v66, 0xa0, v185
	v_cvt_pk_bf16_f32 v43, v46, v43
	global_store_dwordx4 v[44:45], v[40:43], off
	v_add_u32_e32 v64, 0xb0, v185
	s_nop 0
	v_mov_b32_e32 v40, v66
	s_nop 0
	v_ashrrev_i32_e32 v41, 31, v40
	v_lshlrev_b64 v[40:41], 9, v[40:41]
	v_lshl_add_u64 v[40:41], v[40:41], 0, s[20:21]
	v_lshl_add_u64 v[42:43], v[40:41], 0, v[172:173]
	v_lshlrev_b64 v[42:43], 1, v[42:43]
	v_lshl_add_u64 v[44:45], v[164:165], 0, v[42:43]
	global_load_dwordx4 v[68:71], v[44:45], off
	v_lshl_add_u64 v[42:43], v[166:167], 0, v[42:43]
	global_load_dwordx4 v[72:75], v[42:43], off
	v_lshl_add_u64 v[40:41], v[40:41], 0, v[174:175]
	v_lshlrev_b64 v[40:41], 1, v[40:41]
	v_lshl_add_u64 v[42:43], v[164:165], 0, v[40:41]
	global_load_dwordx4 v[76:79], v[42:43], off
	v_lshl_add_u64 v[40:41], v[166:167], 0, v[40:41]
	global_load_dwordx4 v[80:83], v[40:41], off
	v_mov_b32_e32 v40, v64
	s_waitcnt vmcnt(0)
	v_lshlrev_b32_e32 v84, 16, v68
	v_ashrrev_i32_e32 v41, 31, v40
	v_lshlrev_b64 v[40:41], 9, v[40:41]
	v_lshl_add_u64 v[40:41], v[40:41], 0, s[20:21]
	v_and_b32_e32 v85, 0xffff0000, v68
	v_lshlrev_b32_e32 v86, 16, v70
	v_and_b32_e32 v87, 0xffff0000, v70
	v_lshl_add_u64 v[42:43], v[40:41], 0, v[172:173]
	v_lshlrev_b32_e32 v88, 16, v72
	v_and_b32_e32 v89, 0xffff0000, v72
	v_lshlrev_b32_e32 v90, 16, v74
	v_and_b32_e32 v91, 0xffff0000, v74
	v_pk_add_f32 v[36:37], v[36:37], v[84:85]
	v_pk_add_f32 v[32:33], v[32:33], v[86:87]
	v_lshlrev_b64 v[42:43], 1, v[42:43]
	v_lshlrev_b32_e32 v68, 16, v69
	v_and_b32_e32 v69, 0xffff0000, v69
	v_pk_fma_f32 v[36:37], v[60:61], v[88:89], v[36:37]
	v_pk_fma_f32 v[32:33], v[56:57], v[90:91], v[32:33]
	v_lshl_add_u64 v[44:45], v[164:165], 0, v[42:43]
	v_pk_add_f32 v[38:39], v[38:39], v[68:69]
	v_mul_f32_e32 v0, 0x3d372713, v36
	v_mul_f32_e32 v65, 0x3d372713, v32
	v_mul_f32_e32 v68, 0x3d372713, v37
	global_load_dwordx4 v[52:55], v[44:45], off
	v_lshl_add_u64 v[42:43], v[166:167], 0, v[42:43]
	v_mul_f32_e32 v0, v36, v0
	v_mul_f32_e32 v65, v32, v65
	v_mul_f32_e32 v68, v37, v68
	global_load_dwordx4 v[48:51], v[42:43], off
	v_fma_f32 v0, v36, v0, v36
	v_fma_f32 v65, v32, v65, v32
	v_fma_f32 v68, v37, v68, v37
	v_mul_f32_e32 v0, 0x3fcc422a, v0
	v_mul_f32_e32 v65, 0x3fcc422a, v65
	v_mul_f32_e32 v68, 0x3fcc422a, v68
	v_mul_f32_e32 v0, 0xbfb8aa3b, v0
	v_mul_f32_e32 v65, 0xbfb8aa3b, v65
	v_mul_f32_e32 v68, 0xbfb8aa3b, v68
	v_exp_f32_e32 v0, v0
	v_exp_f32_e32 v65, v65
	v_exp_f32_e32 v68, v68
	v_mul_f32_e32 v69, 0x3d372713, v33
	v_add_f32_e32 v0, 1.0, v0
	v_add_f32_e32 v65, 1.0, v65
	v_add_f32_e32 v68, 1.0, v68
	v_rcp_f32_e32 v0, v0
	v_rcp_f32_e32 v65, v65
	v_rcp_f32_e32 v68, v68
; __device__ __forceinline__ float gelu_tanh(float y) { const float z = 1.5957691216057308f * (y + 0.044715f * y * y * y); return y * sigmoidf_(z); }
; __device__ __forceinline__ u32x4 pack8(const f32x4 a, const f32x4 b) { u32x4 w; w.x = cvt_pk_bf16(a[0], a[1]); w.y = cvt_pk_bf16(a[2], a[3]); w.z = cvt_pk_bf16(b[0], b[1]); w.w = cvt_pk_bf16(b[2], b[3]); return w; }
; __device__ __forceinline__ void unpack8(const u32x4 w, f32x4& a, f32x4& b) { a[0] = bf_lo(w.x); a[1] = bf_hi(w.x); a[2] = bf_lo(w.y); a[3] = bf_hi(w.y); b[0] = bf_lo(w.z); b[1] = bf_hi(w.z); b[2] = bf_lo(w.w); b[3] = bf_hi(w.w); }
;     template <int KIND> __device__ __forceinline__ void run(f32x4 (&acc)[2][2][4][2], const Unit& u, int tid_in) const {
;     ...
;                 for (int mh = 0; mh < 2; ++mh) { u32x4 yv[2][2], uv[2][2];
; #pragma unroll
;                     for (int ml = 0; ml < 2; ++ml) { int R = rbase + ai * 128 + (mh * 2 + ml) * 16; asm volatile("" : "+v"(R));
; #pragma unroll
;                         for (int bj = 0; bj < 2; ++bj) { const int t = 16 * u.pn + 8 * bj + 2 * wc + (fq >> 1); const size_t tok = (size_t)R * LCH + t;
;                             yv[ml][bj] = *(const u32x4*)(yi + ((size_t)g * T_TOK + tok) * 16 + 8 * (fq & 1)); uv[ml][bj] = *(const u32x4*)((const bf16_t*)x + ((size_t)g * T_TOK + tok) * 16 + 8 * (fq & 1)); } }
; #pragma unroll
;                     for (int ml = 0; ml < 2; ++ml) { const int m = mh * 2 + ml; int R = rbase + ai * 128 + m * 16; asm volatile("" : "+v"(R));
; #pragma unroll
;                         for (int bj = 0; bj < 2; ++bj) { const int t = 16 * u.pn + 8 * bj + 2 * wc + (fq >> 1); const size_t tok = (size_t)R * LCH + t;
;                             f32x4 y0, y1, u0, u1; unpack8(yv[ml][bj], y0, y1); unpack8(uv[ml][bj], u0, u1);
;                             y0 = acc[ai][bj][m][0] + y0 + d0 * u0; y1 = acc[ai][bj][m][1] + y1 + d1 * u1;
; #pragma unroll
;                             for (int j = 0; j < 4; ++j) { y0[j] = gelu_tanh(y0[j]); y1[j] = gelu_tanh(y1[j]); }
;                             *(u32x4*)(yi + ((size_t)g * T_TOK + tok) * 16 + 8 * (fq & 1)) = pack8(y0, y1); } }
	v_mul_f32_e32 v69, v33, v69
	v_lshlrev_b32_e32 v70, 16, v71
	v_and_b32_e32 v71, 0xffff0000, v71
	v_fma_f32 v69, v33, v69, v33
	v_lshlrev_b32_e32 v72, 16, v73
	v_and_b32_e32 v73, 0xffff0000, v73
	v_lshlrev_b32_e32 v74, 16, v75
	v_and_b32_e32 v75, 0xffff0000, v75
	v_pk_add_f32 v[34:35], v[34:35], v[70:71]
	v_mul_f32_e32 v69, 0x3fcc422a, v69
	v_pk_fma_f32 v[38:39], v[62:63], v[72:73], v[38:39]
	v_pk_fma_f32 v[34:35], v[58:59], v[74:75], v[34:35]
	v_mul_f32_e32 v69, 0xbfb8aa3b, v69
	v_exp_f32_e32 v69, v69
	v_mul_f32_e32 v0, v36, v0
	v_mul_f32_e32 v36, v32, v65
	v_mul_f32_e32 v32, v37, v68
	v_mul_f32_e32 v65, 0x3d372713, v38
	v_mul_f32_e32 v68, 0x3d372713, v34
	v_mul_f32_e32 v65, v38, v65
	v_mul_f32_e32 v68, v34, v68
	v_fma_f32 v65, v38, v65, v38
	v_fma_f32 v68, v34, v68, v34
	v_mul_f32_e32 v65, 0x3fcc422a, v65
	v_mul_f32_e32 v68, 0x3fcc422a, v68
	v_add_f32_e32 v37, 1.0, v69
	v_mul_f32_e32 v65, 0xbfb8aa3b, v65
	v_mul_f32_e32 v68, 0xbfb8aa3b, v68
	v_rcp_f32_e32 v37, v37
	v_exp_f32_e32 v65, v65
	v_exp_f32_e32 v68, v68
	v_mul_f32_e32 v69, 0x3d372713, v35
	v_mul_f32_e32 v37, v33, v37
	v_add_f32_e32 v33, 1.0, v65
	v_add_f32_e32 v65, 1.0, v68
	v_mul_f32_e32 v68, 0x3d372713, v39
	v_mul_f32_e32 v68, v39, v68
	v_fma_f32 v68, v39, v68, v39
	v_mul_f32_e32 v69, v35, v69
	v_mul_f32_e32 v68, 0x3fcc422a, v68
	v_fma_f32 v69, v35, v69, v35
	v_mul_f32_e32 v68, 0xbfb8aa3b, v68
	v_mul_f32_e32 v69, 0x3fcc422a, v69
	v_exp_f32_e32 v68, v68
	v_mul_f32_e32 v69, 0xbfb8aa3b, v69
	v_exp_f32_e32 v69, v69
	v_lshl_add_u64 v[40:41], v[40:41], 0, v[174:175]
	v_add_f32_e32 v68, 1.0, v68
	v_lshlrev_b64 v[40:41], 1, v[40:41]
	v_rcp_f32_e32 v33, v33
	v_rcp_f32_e32 v65, v65
	v_rcp_f32_e32 v68, v68
	v_add_f32_e32 v69, 1.0, v69
	v_lshl_add_u64 v[42:43], v[164:165], 0, v[40:41]
	v_lshl_add_u64 v[40:41], v[166:167], 0, v[40:41]
	v_rcp_f32_e32 v69, v69
	global_load_dwordx4 v[44:47], v[42:43], off
	v_mul_f32_e32 v33, v38, v33
	global_load_dwordx4 v[40:43], v[40:41], off
	v_mul_f32_e32 v38, v34, v65
	v_ashrrev_i32_e32 v67, 31, v66
	v_lshlrev_b64 v[66:67], 10, v[66:67]
	v_lshl_add_u64 v[66:67], v[162:163], 0, v[66:67]
	v_mul_f32_e32 v34, v39, v68
	v_mul_f32_e32 v35, v35, v69
	v_cvt_pk_bf16_f32 v32, v0, v32
	v_cvt_pk_bf16_f32 v33, v33, v34
	v_cvt_pk_bf16_f32 v34, v36, v37
	v_lshl_add_u64 v[36:37], v[66:67], 0, v[136:137]
	v_cvt_pk_bf16_f32 v35, v38, v35
	global_store_dwordx4 v[36:37], v[32:35], off
	v_lshlrev_b32_e32 v36, 16, v78
	v_and_b32_e32 v37, 0xffff0000, v78
	v_lshlrev_b32_e32 v32, 16, v76
	v_and_b32_e32 v33, 0xffff0000, v76
	v_lshlrev_b32_e32 v68, 16, v80
	v_and_b32_e32 v69, 0xffff0000, v80
	v_lshlrev_b32_e32 v72, 16, v82
	v_and_b32_e32 v73, 0xffff0000, v82
	v_pk_add_f32 v[28:29], v[28:29], v[32:33]
	v_pk_add_f32 v[24:25], v[24:25], v[36:37]
	v_pk_fma_f32 v[28:29], v[60:61], v[68:69], v[28:29]
	v_pk_fma_f32 v[24:25], v[56:57], v[72:73], v[24:25]
	v_mul_f32_e32 v0, 0x3d372713, v28
	v_mul_f32_e32 v32, 0x3d372713, v24
	v_mul_f32_e32 v33, 0x3d372713, v29
	v_mul_f32_e32 v0, v28, v0
	v_mul_f32_e32 v32, v24, v32
	v_mul_f32_e32 v33, v29, v33
	v_fma_f32 v0, v28, v0, v28
	v_fma_f32 v32, v24, v32, v24
	v_fma_f32 v33, v29, v33, v29
	v_mul_f32_e32 v0, 0x3fcc422a, v0
	v_mul_f32_e32 v32, 0x3fcc422a, v32
	v_mul_f32_e32 v33, 0x3fcc422a, v33
	v_mul_f32_e32 v0, 0xbfb8aa3b, v0
	v_mul_f32_e32 v32, 0xbfb8aa3b, v32
	v_mul_f32_e32 v33, 0xbfb8aa3b, v33
	v_exp_f32_e32 v0, v0
	v_exp_f32_e32 v32, v32
	v_exp_f32_e32 v33, v33
	v_lshlrev_b32_e32 v34, 16, v77
	v_and_b32_e32 v35, 0xffff0000, v77
	v_pk_add_f32 v[30:31], v[30:31], v[34:35]
	v_add_f32_e32 v0, 1.0, v0
	v_add_f32_e32 v32, 1.0, v32
	v_add_f32_e32 v33, 1.0, v33
	v_mul_f32_e32 v34, 0x3d372713, v25
	v_rcp_f32_e32 v0, v0
	v_rcp_f32_e32 v32, v32
	v_rcp_f32_e32 v33, v33
	v_mul_f32_e32 v34, v25, v34
	v_lshlrev_b32_e32 v38, 16, v79
	v_and_b32_e32 v39, 0xffff0000, v79
	v_fma_f32 v34, v25, v34, v25
	v_lshlrev_b32_e32 v70, 16, v81
	v_and_b32_e32 v71, 0xffff0000, v81
	v_lshlrev_b32_e32 v74, 16, v83
	v_and_b32_e32 v75, 0xffff0000, v83
	v_pk_add_f32 v[26:27], v[26:27], v[38:39]
	v_mul_f32_e32 v34, 0x3fcc422a, v34
	v_pk_fma_f32 v[30:31], v[62:63], v[70:71], v[30:31]
	v_pk_fma_f32 v[26:27], v[58:59], v[74:75], v[26:27]
	v_mul_f32_e32 v34, 0xbfb8aa3b, v34
	v_exp_f32_e32 v34, v34
	v_mul_f32_e32 v0, v28, v0
	v_mul_f32_e32 v28, v24, v32
	v_mul_f32_e32 v24, v29, v33
	v_mul_f32_e32 v32, 0x3d372713, v30
	v_mul_f32_e32 v33, 0x3d372713, v26
	v_mul_f32_e32 v32, v30, v32
	v_mul_f32_e32 v33, v26, v33
	v_fma_f32 v32, v30, v32, v30
	v_fma_f32 v33, v26, v33, v26
	v_mul_f32_e32 v32, 0x3fcc422a, v32
	v_mul_f32_e32 v33, 0x3fcc422a, v33
	v_add_f32_e32 v29, 1.0, v34
	v_mul_f32_e32 v32, 0xbfb8aa3b, v32
	v_mul_f32_e32 v33, 0xbfb8aa3b, v33
	v_rcp_f32_e32 v29, v29
	v_exp_f32_e32 v32, v32
	v_exp_f32_e32 v33, v33
	v_mul_f32_e32 v34, 0x3d372713, v27
	v_mul_f32_e32 v29, v25, v29
	v_add_f32_e32 v25, 1.0, v32
	v_add_f32_e32 v32, 1.0, v33
	v_mul_f32_e32 v33, 0x3d372713, v31
	v_mul_f32_e32 v33, v31, v33
	v_mul_f32_e32 v34, v27, v34
	v_fma_f32 v33, v31, v33, v31
	v_fma_f32 v34, v27, v34, v27
	v_mul_f32_e32 v33, 0x3fcc422a, v33
	v_mul_f32_e32 v34, 0x3fcc422a, v34
	v_mul_f32_e32 v33, 0xbfb8aa3b, v33
	v_mul_f32_e32 v34, 0xbfb8aa3b, v34
	v_exp_f32_e32 v33, v33
	v_exp_f32_e32 v34, v34
	v_rcp_f32_e32 v25, v25
	v_rcp_f32_e32 v32, v32
	v_add_f32_e32 v33, 1.0, v33
	v_add_f32_e32 v34, 1.0, v34
	v_rcp_f32_e32 v33, v33
	v_rcp_f32_e32 v34, v34
	v_mul_f32_e32 v25, v30, v25
	v_mul_f32_e32 v30, v26, v32
	v_mul_f32_e32 v26, v31, v33
	v_mul_f32_e32 v27, v27, v34
	v_cvt_pk_bf16_f32 v24, v0, v24
	v_cvt_pk_bf16_f32 v25, v25, v26
	v_cvt_pk_bf16_f32 v26, v28, v29
	v_cvt_pk_bf16_f32 v27, v30, v27
	v_lshl_add_u64 v[28:29], v[66:67], 0, v[128:129]
	global_store_dwordx4 v[28:29], v[24:27], off
	s_waitcnt vmcnt(0)
; __device__ __forceinline__ float gelu_tanh(float y) { const float z = 1.5957691216057308f * (y + 0.044715f * y * y * y); return y * sigmoidf_(z); }
; __device__ __forceinline__ u32x4 pack8(const f32x4 a, const f32x4 b) { u32x4 w; w.x = cvt_pk_bf16(a[0], a[1]); w.y = cvt_pk_bf16(a[2], a[3]); w.z = cvt_pk_bf16(b[0], b[1]); w.w = cvt_pk_bf16(b[2], b[3]); return w; }
; __device__ __forceinline__ void unpack8(const u32x4 w, f32x4& a, f32x4& b) { a[0] = bf_lo(w.x); a[1] = bf_hi(w.x); a[2] = bf_lo(w.y); a[3] = bf_hi(w.y); b[0] = bf_lo(w.z); b[1] = bf_hi(w.z); b[2] = bf_lo(w.w); b[3] = bf_hi(w.w); }
; #define MEMFENCE asm volatile("" ::: "memory")
; #define G_WAIT_V(n) asm volatile("s_waitcnt vmcnt(" #n ")" ::: "memory")
; #define G_BAR __builtin_amdgcn_s_barrier()
;     template <int KIND> __device__ __forceinline__ void run(f32x4 (&acc)[2][2][4][2], const Unit& u, int tid_in) const {
;     ...
;                     for (int ml = 0; ml < 2; ++ml) { const int m = mh * 2 + ml; int R = rbase + ai * 128 + m * 16; asm volatile("" : "+v"(R));
; #pragma unroll
;                         for (int bj = 0; bj < 2; ++bj) { const int t = 16 * u.pn + 8 * bj + 2 * wc + (fq >> 1); const size_t tok = (size_t)R * LCH + t;
;                             f32x4 y0, y1, u0, u1; unpack8(yv[ml][bj], y0, y1); unpack8(uv[ml][bj], u0, u1);
;                             y0 = acc[ai][bj][m][0] + y0 + d0 * u0; y1 = acc[ai][bj][m][1] + y1 + d1 * u1;
; #pragma unroll
;                             for (int j = 0; j < 4; ++j) { y0[j] = gelu_tanh(y0[j]); y1[j] = gelu_tanh(y1[j]); }
;                             *(u32x4*)(yi + ((size_t)g * T_TOK + tok) * 16 + 8 * (fq & 1)) = pack8(y0, y1); } }
;                     MEMFENCE; }
;     ...
;         E.template run<cs.kind>(acc, cur, tid);
;         if (!has_next) break;
;         if (!(cs.kind == K_MG_B && cur.aux < 2))
; #pragma unroll
;         for (int a = 0; a < 2; ++a)
; #pragma unroll
;             for (int b = 0; b < 2; ++b)
; #pragma unroll
;                 for (int m = 0; m < 4; ++m)
; #pragma unroll
;                     for (int n = 0; n < 2; ++n) acc[a][b][m][n] = (f32x4){0.f, 0.f, 0.f, 0.f};
;         cur = nxt; cA = nA; cB = nB; ++ui;
;     }
;     G_WAIT_V(0);
;     if (wr == 0) G_BAR;
;     G_BAR;
	v_lshlrev_b32_e32 v30, 16, v54
	v_and_b32_e32 v31, 0xffff0000, v54
	v_lshlrev_b32_e32 v26, 16, v52
	v_and_b32_e32 v27, 0xffff0000, v52
	v_lshlrev_b32_e32 v34, 16, v48
	v_and_b32_e32 v35, 0xffff0000, v48
	v_lshlrev_b32_e32 v38, 16, v50
	v_and_b32_e32 v39, 0xffff0000, v50
	v_pk_add_f32 v[20:21], v[20:21], v[26:27]
	v_pk_add_f32 v[16:17], v[16:17], v[30:31]
	v_pk_fma_f32 v[20:21], v[60:61], v[34:35], v[20:21]
	v_pk_fma_f32 v[16:17], v[56:57], v[38:39], v[16:17]
	v_mul_f32_e32 v0, 0x3d372713, v20
	v_mul_f32_e32 v26, 0x3d372713, v16
	v_mul_f32_e32 v27, 0x3d372713, v21
	v_mul_f32_e32 v0, v20, v0
	v_mul_f32_e32 v26, v16, v26
	v_mul_f32_e32 v27, v21, v27
	v_fma_f32 v0, v20, v0, v20
	v_fma_f32 v26, v16, v26, v16
	v_fma_f32 v27, v21, v27, v21
	v_mul_f32_e32 v0, 0x3fcc422a, v0
	v_mul_f32_e32 v26, 0x3fcc422a, v26
	v_mul_f32_e32 v27, 0x3fcc422a, v27
	v_mul_f32_e32 v0, 0xbfb8aa3b, v0
	v_mul_f32_e32 v26, 0xbfb8aa3b, v26
	v_mul_f32_e32 v27, 0xbfb8aa3b, v27
	v_exp_f32_e32 v0, v0
	v_exp_f32_e32 v26, v26
	v_exp_f32_e32 v27, v27
	v_lshlrev_b32_e32 v28, 16, v53
	v_and_b32_e32 v29, 0xffff0000, v53
	v_pk_add_f32 v[22:23], v[22:23], v[28:29]
	v_add_f32_e32 v0, 1.0, v0
	v_add_f32_e32 v26, 1.0, v26
	v_add_f32_e32 v27, 1.0, v27
	v_mul_f32_e32 v28, 0x3d372713, v17
	v_rcp_f32_e32 v0, v0
	v_rcp_f32_e32 v26, v26
	v_rcp_f32_e32 v27, v27
	v_mul_f32_e32 v28, v17, v28
	v_lshlrev_b32_e32 v32, 16, v55
	v_and_b32_e32 v33, 0xffff0000, v55
	v_fma_f32 v28, v17, v28, v17
	v_lshlrev_b32_e32 v36, 16, v49
	v_and_b32_e32 v37, 0xffff0000, v49
	v_lshlrev_b32_e32 v48, 16, v51
	v_and_b32_e32 v49, 0xffff0000, v51
	v_pk_add_f32 v[18:19], v[18:19], v[32:33]
	v_mul_f32_e32 v28, 0x3fcc422a, v28
	v_pk_fma_f32 v[22:23], v[62:63], v[36:37], v[22:23]
	v_pk_fma_f32 v[18:19], v[58:59], v[48:49], v[18:19]
	v_mul_f32_e32 v28, 0xbfb8aa3b, v28
	v_exp_f32_e32 v28, v28
	v_mul_f32_e32 v0, v20, v0
	v_mul_f32_e32 v20, v16, v26
	v_mul_f32_e32 v16, v21, v27
	v_mul_f32_e32 v26, 0x3d372713, v22
	v_mul_f32_e32 v27, 0x3d372713, v18
	v_mul_f32_e32 v26, v22, v26
	v_mul_f32_e32 v27, v18, v27
	v_fma_f32 v26, v22, v26, v22
	v_fma_f32 v27, v18, v27, v18
	v_mul_f32_e32 v26, 0x3fcc422a, v26
	v_mul_f32_e32 v27, 0x3fcc422a, v27
	v_add_f32_e32 v21, 1.0, v28
	v_mul_f32_e32 v26, 0xbfb8aa3b, v26
	v_mul_f32_e32 v27, 0xbfb8aa3b, v27
	v_rcp_f32_e32 v21, v21
	v_exp_f32_e32 v26, v26
	v_exp_f32_e32 v27, v27
	v_mul_f32_e32 v28, 0x3d372713, v19
	v_mul_f32_e32 v21, v17, v21
	v_add_f32_e32 v17, 1.0, v26
	v_add_f32_e32 v26, 1.0, v27
	v_mul_f32_e32 v27, 0x3d372713, v23
	v_mul_f32_e32 v27, v23, v27
	v_fma_f32 v27, v23, v27, v23
	v_mul_f32_e32 v28, v19, v28
	v_mul_f32_e32 v27, 0x3fcc422a, v27
	v_fma_f32 v28, v19, v28, v19
	v_mul_f32_e32 v27, 0xbfb8aa3b, v27
	v_mul_f32_e32 v28, 0x3fcc422a, v28
	v_exp_f32_e32 v27, v27
	v_mul_f32_e32 v28, 0xbfb8aa3b, v28
	v_exp_f32_e32 v28, v28
	v_rcp_f32_e32 v17, v17
	v_add_f32_e32 v27, 1.0, v27
	v_rcp_f32_e32 v26, v26
	v_rcp_f32_e32 v27, v27
	v_add_f32_e32 v28, 1.0, v28
	v_rcp_f32_e32 v28, v28
	v_mul_f32_e32 v17, v22, v17
	v_ashrrev_i32_e32 v65, 31, v64
	v_lshlrev_b64 v[24:25], 10, v[64:65]
	v_lshl_add_u64 v[24:25], v[162:163], 0, v[24:25]
	v_mul_f32_e32 v22, v18, v26
	v_mul_f32_e32 v18, v23, v27
	v_mul_f32_e32 v19, v19, v28
	v_cvt_pk_bf16_f32 v16, v0, v16
	v_cvt_pk_bf16_f32 v17, v17, v18
	v_cvt_pk_bf16_f32 v18, v20, v21
	v_lshl_add_u64 v[20:21], v[24:25], 0, v[136:137]
	v_cvt_pk_bf16_f32 v19, v22, v19
	global_store_dwordx4 v[20:21], v[16:19], off
	v_lshlrev_b32_e32 v20, 16, v46
	v_and_b32_e32 v21, 0xffff0000, v46
	v_lshlrev_b32_e32 v16, 16, v44
	v_and_b32_e32 v17, 0xffff0000, v44
	v_lshlrev_b32_e32 v26, 16, v40
	v_and_b32_e32 v27, 0xffff0000, v40
	v_lshlrev_b32_e32 v30, 16, v42
	v_and_b32_e32 v31, 0xffff0000, v42
	v_pk_add_f32 v[12:13], v[12:13], v[16:17]
	v_pk_add_f32 v[8:9], v[8:9], v[20:21]
	v_pk_fma_f32 v[12:13], v[60:61], v[26:27], v[12:13]
	v_pk_fma_f32 v[8:9], v[56:57], v[30:31], v[8:9]
	v_mul_f32_e32 v0, 0x3d372713, v12
	v_mul_f32_e32 v16, 0x3d372713, v8
	v_mul_f32_e32 v17, 0x3d372713, v13
	v_mul_f32_e32 v0, v12, v0
	v_mul_f32_e32 v16, v8, v16
	v_mul_f32_e32 v17, v13, v17
	v_fma_f32 v0, v12, v0, v12
	v_fma_f32 v16, v8, v16, v8
	v_fma_f32 v17, v13, v17, v13
	v_mul_f32_e32 v0, 0x3fcc422a, v0
	v_mul_f32_e32 v16, 0x3fcc422a, v16
	v_mul_f32_e32 v17, 0x3fcc422a, v17
	v_mul_f32_e32 v0, 0xbfb8aa3b, v0
	v_mul_f32_e32 v16, 0xbfb8aa3b, v16
	v_mul_f32_e32 v17, 0xbfb8aa3b, v17
	v_exp_f32_e32 v0, v0
	v_exp_f32_e32 v16, v16
	v_exp_f32_e32 v17, v17
	v_lshlrev_b32_e32 v18, 16, v45
	v_and_b32_e32 v19, 0xffff0000, v45
	v_pk_add_f32 v[14:15], v[14:15], v[18:19]
	v_add_f32_e32 v0, 1.0, v0
	v_add_f32_e32 v16, 1.0, v16
	v_add_f32_e32 v17, 1.0, v17
	v_mul_f32_e32 v18, 0x3d372713, v9
	v_rcp_f32_e32 v0, v0
	v_rcp_f32_e32 v16, v16
	v_rcp_f32_e32 v17, v17
	v_mul_f32_e32 v18, v9, v18
	v_lshlrev_b32_e32 v22, 16, v47
	v_and_b32_e32 v23, 0xffff0000, v47
	v_fma_f32 v18, v9, v18, v9
	v_lshlrev_b32_e32 v28, 16, v41
	v_and_b32_e32 v29, 0xffff0000, v41
	v_lshlrev_b32_e32 v32, 16, v43
	v_and_b32_e32 v33, 0xffff0000, v43
	v_pk_add_f32 v[10:11], v[10:11], v[22:23]
	v_mul_f32_e32 v18, 0x3fcc422a, v18
	v_pk_fma_f32 v[14:15], v[62:63], v[28:29], v[14:15]
	v_pk_fma_f32 v[10:11], v[58:59], v[32:33], v[10:11]
	v_mul_f32_e32 v18, 0xbfb8aa3b, v18
	v_exp_f32_e32 v18, v18
	v_mul_f32_e32 v0, v12, v0
	v_mul_f32_e32 v12, v8, v16
	v_mul_f32_e32 v8, v13, v17
	v_mul_f32_e32 v16, 0x3d372713, v14
	v_mul_f32_e32 v17, 0x3d372713, v10
	v_mul_f32_e32 v16, v14, v16
	v_mul_f32_e32 v17, v10, v17
	v_fma_f32 v16, v14, v16, v14
	v_fma_f32 v17, v10, v17, v10
	v_mul_f32_e32 v16, 0x3fcc422a, v16
	v_mul_f32_e32 v17, 0x3fcc422a, v17
	v_add_f32_e32 v13, 1.0, v18
	v_mul_f32_e32 v16, 0xbfb8aa3b, v16
	v_mul_f32_e32 v17, 0xbfb8aa3b, v17
	v_rcp_f32_e32 v13, v13
	v_exp_f32_e32 v16, v16
	v_exp_f32_e32 v17, v17
	v_mul_f32_e32 v18, 0x3d372713, v11
	v_mul_f32_e32 v13, v9, v13
	v_add_f32_e32 v9, 1.0, v16
	v_add_f32_e32 v16, 1.0, v17
	v_mul_f32_e32 v17, 0x3d372713, v15
	v_mul_f32_e32 v17, v15, v17
	v_fma_f32 v17, v15, v17, v15
	v_mul_f32_e32 v18, v11, v18
	v_mul_f32_e32 v17, 0x3fcc422a, v17
	v_fma_f32 v18, v11, v18, v11
	v_mul_f32_e32 v17, 0xbfb8aa3b, v17
	v_mul_f32_e32 v18, 0x3fcc422a, v18
	v_exp_f32_e32 v17, v17
	v_mul_f32_e32 v18, 0xbfb8aa3b, v18
	v_exp_f32_e32 v18, v18
	v_rcp_f32_e32 v9, v9
	v_add_f32_e32 v17, 1.0, v17
	v_rcp_f32_e32 v16, v16
	v_rcp_f32_e32 v17, v17
	v_add_f32_e32 v18, 1.0, v18
	v_rcp_f32_e32 v18, v18
	v_mul_f32_e32 v9, v14, v9
	v_mul_f32_e32 v14, v10, v16
	v_mul_f32_e32 v10, v15, v17
	v_mul_f32_e32 v11, v11, v18
	v_cvt_pk_bf16_f32 v8, v0, v8
	v_cvt_pk_bf16_f32 v9, v9, v10
	v_cvt_pk_bf16_f32 v10, v12, v13
	v_lshl_add_u64 v[12:13], v[24:25], 0, v[128:129]
	v_cvt_pk_bf16_f32 v11, v14, v11
	global_store_dwordx4 v[12:13], v[8:11], off
	s_mov_b64 s[20:21], s[16:17]
	s_cbranch_vccz .LBB0_737
	s_cmpk_gt_u32 s101, 0xff
	s_cbranch_scc0 .Ldbj_SSM2_pe
	s_barrier
	s_mov_b32 s101, 0
.Ldbj_SSM2_pe:
	s_waitcnt vmcnt(0)
	s_cmpk_gt_u32 s61, 0xff
	s_cbranch_scc1 .LBB0_746
	s_barrier

; #define G_STAGE(bufoff, gbase, o0, h64) do { \
;         __builtin_amdgcn_global_load_lds((const unsigned*)((const char*)(gbase) + (o0)), (LAS unsigned*)(lds + (bufoff) + ldsw), 16, 0, 0); \
;         __builtin_amdgcn_global_load_lds((const unsigned*)((const char*)(gbase) + (h64) + (o0)), (LAS unsigned*)(lds + (bufoff) + ldsw + 8192), 16, 0, 0); } while (0)
; #define G_LDA(dst, b, h) do { _Pragma("unroll") for (int m = 0; m < 4; ++m) _Pragma("unroll") for (int k = 0; k < 2; ++k) dst[m][k] = *(const LAS bf16x8*)(lds + G_SA(b, h) + aoff + m * 2048 + k * 1024); } while (0)
; #define G_LDB(dst, b, h) do { _Pragma("unroll") for (int n = 0; n < 2; ++n) _Pragma("unroll") for (int k = 0; k < 2; ++k) dst[n][k] = *(const LAS bf16x8*)(lds + G_SB(b, h) + boff + n * 2048 + k * 1024); } while (0)
; #define G_WAIT_L(n) asm volatile("s_waitcnt lgkmcnt(" #n ")" ::: "memory")
; #define G_BAR __builtin_amdgcn_s_barrier()
; #define G_SCHED __builtin_amdgcn_sched_barrier(0)
;     ...
;     for (;;) {
;         const bool has_next = sched_next<PH, SUB>(E.ws, E.layer, ui + 1, nxt, E.x);
;         if (!has_next) nxt = cur;
;         const char* nA = nxt.A; const char* nB = nxt.B;
; #pragma unroll 1
;         for (int t = 0; t < nt; t += 2) {
;             const bool last = (t == nt - 2);
;             const char* a1 = cA + (size_t)(t + 1) * ckA;
;             const char* a2 = last ? nA : cA + (size_t)(t + 2) * ckA; const char* b2 = last ? nB : cB + (size_t)(t + 2) * kB;
;             const char* a3 = a2 + ckA; const char* b3 = b2 + kB;
;             G_LDB(B0, 0, 0); G_SCHED; G_LDA(At, 0, 0); G_STAGE(G_SA(1, 1), a1 + chA, cA0, qA);
;             G_WAIT_L(8); G_BAR; G_WAIT_L(0); G_MMA(0, 0, At, B0); G_BAR; G_SCHED;
;             G_LDB(B1, 0, 1); G_STAGE(G_SB(0, 0), b2, cB0, qB);
;             G_BAR; G_WAIT_L(0); G_MMA(0, 1, At, B1); G_BAR;
;             G_LDA(At, 0, 1); G_STAGE(G_SA(0, 0), a2, cA0, qA);
;             G_BAR; G_WAIT_L(0); G_MMA(1, 0, At, B0); G_BAR; G_SCHED;
;     ...
;         if (!(cs.kind == K_MG_B && cur.aux < 2))
; #pragma unroll
;         for (int a = 0; a < 2; ++a)
; #pragma unroll
;             for (int b = 0; b < 2; ++b)
; #pragma unroll
;                 for (int m = 0; m < 4; ++m)
; #pragma unroll
;                     for (int n = 0; n < 2; ++n) acc[a][b][m][n] = (f32x4){0.f, 0.f, 0.f, 0.f};
;         cur = nxt; cA = nA; cB = nB; ++ui;
.LBB0_803:
	s_add_u32 s13, s18, 0x100
	s_addc_u32 s18, s19, 0
	s_add_u32 s2, s2, 0x800000
	v_mov_b64_e32 v[8:9], 0
	s_addc_u32 s3, s3, 0
	s_mov_b32 s19, -2
	v_mov_b64_e32 v[10:11], 0
	v_mov_b64_e32 v[12:13], 0
	v_mov_b64_e32 v[14:15], 0
	v_mov_b64_e32 v[24:25], 0
	v_mov_b64_e32 v[26:27], 0
	v_mov_b64_e32 v[28:29], 0
	v_mov_b64_e32 v[30:31], 0
	v_mov_b64_e32 v[40:41], 0
	v_mov_b64_e32 v[42:43], 0
	v_mov_b64_e32 v[44:45], 0
	v_mov_b64_e32 v[46:47], 0
	v_mov_b64_e32 v[56:57], 0
	v_mov_b64_e32 v[58:59], 0
	v_mov_b64_e32 v[60:61], 0
	v_mov_b64_e32 v[62:63], 0
	v_mov_b64_e32 v[16:17], 0
	v_mov_b64_e32 v[18:19], 0
	v_mov_b64_e32 v[20:21], 0
	v_mov_b64_e32 v[22:23], 0
	v_mov_b64_e32 v[32:33], 0
	v_mov_b64_e32 v[34:35], 0
	v_mov_b64_e32 v[36:37], 0
	v_mov_b64_e32 v[38:39], 0
	v_mov_b64_e32 v[48:49], 0
	v_mov_b64_e32 v[50:51], 0
	v_mov_b64_e32 v[52:53], 0
	v_mov_b64_e32 v[54:55], 0
	v_mov_b64_e32 v[64:65], 0
	v_mov_b64_e32 v[66:67], 0
	v_mov_b64_e32 v[68:69], 0
	v_mov_b64_e32 v[70:71], 0
	v_mov_b64_e32 v[72:73], 0
	v_mov_b64_e32 v[74:75], 0
	v_mov_b64_e32 v[76:77], 0
	v_mov_b64_e32 v[78:79], 0
	v_mov_b64_e32 v[88:89], 0
	v_mov_b64_e32 v[90:91], 0
	v_mov_b64_e32 v[92:93], 0
	v_mov_b64_e32 v[94:95], 0
	v_mov_b64_e32 v[104:105], 0
	v_mov_b64_e32 v[106:107], 0
	v_mov_b64_e32 v[108:109], 0
	v_mov_b64_e32 v[110:111], 0
	v_mov_b64_e32 v[128:129], 0
	v_mov_b64_e32 v[130:131], 0
	v_mov_b64_e32 v[132:133], 0
	v_mov_b64_e32 v[134:135], 0
	v_mov_b64_e32 v[80:81], 0
	v_mov_b64_e32 v[82:83], 0
	v_mov_b64_e32 v[84:85], 0
	v_mov_b64_e32 v[86:87], 0
	v_mov_b64_e32 v[96:97], 0
	v_mov_b64_e32 v[98:99], 0
	v_mov_b64_e32 v[100:101], 0
	v_mov_b64_e32 v[102:103], 0
	v_mov_b64_e32 v[116:117], 0
	v_mov_b64_e32 v[118:119], 0
	v_mov_b64_e32 v[120:121], 0
	v_mov_b64_e32 v[122:123], 0
	v_mov_b64_e32 v[140:141], 0
	v_mov_b64_e32 v[142:143], 0
	v_mov_b64_e32 v[144:145], 0
	v_mov_b64_e32 v[146:147], 0
	s_mov_b64 s[42:43], 0x20080
	s_mov_b64 s[50:51], 0x10000
	s_mov_b64 s[52:53], 0x30000
	s_mov_b64 s[54:55], 0x10080
	s_mov_b64 s[58:59], 0x30080
	s_mov_b64 s[62:63], 0x400000
	s_cmpk_gt_u32 s101, 0xff
	s_cbranch_scc0 .Ldbj_GLU_in
	s_barrier
	s_mov_b32 s101, 0
.Ldbj_GLU_in:
.LBB0_804:
	s_add_i32 s40, 0, 0x10000
	v_add_u32_e32 v0, s40, v196
	ds_read_b128 v[112:115], v0
	ds_read_b128 v[124:127], v0 offset:1024
	ds_read_b128 v[136:139], v0 offset:2048
	ds_read_b128 v[148:151], v0 offset:3072
	s_cmp_eq_u32 s19, 4
	s_cselect_b32 s5, s15, s3
	s_cselect_b32 s4, s14, s2
	s_cselect_b32 s37, s17, s18
	s_cselect_b32 s36, s16, s13
	s_mov_b32 s38, 0xffc01000
	v_lshl_add_u64 v[184:185], s[2:3], 0, v[166:167]
	s_mov_b32 s39, -1
	v_lshl_add_u64 v[206:207], v[184:185], 0, s[38:39]
	s_mov_b32 s38, 0xffc01800
	s_add_i32 m0, s24, 0xc000
	s_mov_b32 s39, -1
	ds_read_b128 v[152:155], v197
	ds_read_b128 v[156:159], v197 offset:1024
	ds_read_b128 v[160:163], v197 offset:2048
	ds_read_b128 v[172:175], v197 offset:3072
	ds_read_b128 v[176:179], v197 offset:4096
	ds_read_b128 v[180:183], v197 offset:5120
	ds_read_b128 v[198:201], v197 offset:6144
	ds_read_b128 v[202:205], v197 offset:7168
	global_load_lds_dwordx4 v[206:207], off
	v_lshl_add_u64 v[184:185], v[184:185], 0, s[38:39]
	s_add_i32 m0, s24, 0xe000
	s_nop 0
	global_load_lds_dwordx4 v[184:185], off
	s_waitcnt lgkmcnt(8)
	s_barrier
	s_waitcnt lgkmcnt(0)
	s_setprio 3
	s_waitcnt lgkmcnt(0)
	v_mfma_f32_16x16x32_bf16 v[144:147], v[112:115], v[152:155], v[144:147]
	v_mfma_f32_16x16x32_bf16 v[140:143], v[136:139], v[152:155], v[140:143]
	v_mfma_f32_16x16x32_bf16 v[120:123], v[112:115], v[160:163], v[120:123]
	v_mfma_f32_16x16x32_bf16 v[116:119], v[136:139], v[160:163], v[116:119]
	v_mfma_f32_16x16x32_bf16 v[100:103], v[112:115], v[176:179], v[100:103]
	v_mfma_f32_16x16x32_bf16 v[96:99], v[136:139], v[176:179], v[96:99]
	v_mfma_f32_16x16x32_bf16 v[84:87], v[112:115], v[198:201], v[84:87]
	v_mfma_f32_16x16x32_bf16 v[80:83], v[136:139], v[198:201], v[80:83]
	v_mfma_f32_16x16x32_bf16 v[144:147], v[124:127], v[156:159], v[144:147]
	v_mfma_f32_16x16x32_bf16 v[140:143], v[148:151], v[156:159], v[140:143]
	v_mfma_f32_16x16x32_bf16 v[120:123], v[124:127], v[172:175], v[120:123]
	v_mfma_f32_16x16x32_bf16 v[116:119], v[148:151], v[172:175], v[116:119]
	v_mfma_f32_16x16x32_bf16 v[100:103], v[124:127], v[180:183], v[100:103]
	v_mfma_f32_16x16x32_bf16 v[96:99], v[148:151], v[180:183], v[96:99]
	v_mfma_f32_16x16x32_bf16 v[84:87], v[124:127], v[202:205], v[84:87]
	v_mfma_f32_16x16x32_bf16 v[80:83], v[148:151], v[202:205], v[80:83]
	s_setprio 0
	s_barrier
	s_add_i32 s38, 0, 0x14000
	v_lshl_add_u64 v[184:185], s[36:37], 0, v[2:3]
	s_add_i32 s36, s40, s21
	v_add_u32_e32 v0, s38, v196
	s_mov_b32 m0, s36
	ds_read_b128 v[206:209], v0
	ds_read_b128 v[210:213], v0 offset:1024
	ds_read_b128 v[214:217], v0 offset:2048
	ds_read_b128 v[218:221], v0 offset:3072
	global_load_lds_dwordx4 v[184:185], off
	v_lshl_add_u64 v[222:223], v[184:185], 0, s[50:51]
	s_add_i32 m0, s36, 0x2000
	s_nop 0
	global_load_lds_dwordx4 v[222:223], off
	s_barrier
	s_waitcnt lgkmcnt(0)
	s_setprio 3
	s_waitcnt lgkmcnt(0)
	v_mfma_f32_16x16x32_bf16 v[132:135], v[206:209], v[152:155], v[132:135]
	v_mfma_f32_16x16x32_bf16 v[128:131], v[214:217], v[152:155], v[128:131]
	v_mfma_f32_16x16x32_bf16 v[108:111], v[206:209], v[160:163], v[108:111]
	v_mfma_f32_16x16x32_bf16 v[104:107], v[214:217], v[160:163], v[104:107]
	v_mfma_f32_16x16x32_bf16 v[92:95], v[206:209], v[176:179], v[92:95]
	v_mfma_f32_16x16x32_bf16 v[88:91], v[214:217], v[176:179], v[88:91]
	v_mfma_f32_16x16x32_bf16 v[76:79], v[206:209], v[198:201], v[76:79]
	v_mfma_f32_16x16x32_bf16 v[72:75], v[214:217], v[198:201], v[72:75]
	v_mfma_f32_16x16x32_bf16 v[132:135], v[210:213], v[156:159], v[132:135]
	v_mfma_f32_16x16x32_bf16 v[128:131], v[218:221], v[156:159], v[128:131]
	v_mfma_f32_16x16x32_bf16 v[108:111], v[210:213], v[172:175], v[108:111]
	v_mfma_f32_16x16x32_bf16 v[104:107], v[218:221], v[172:175], v[104:107]
	v_mfma_f32_16x16x32_bf16 v[92:95], v[210:213], v[180:183], v[92:95]
	v_mfma_f32_16x16x32_bf16 v[88:91], v[218:221], v[180:183], v[88:91]
	v_mfma_f32_16x16x32_bf16 v[76:79], v[210:213], v[202:205], v[76:79]
	v_mfma_f32_16x16x32_bf16 v[72:75], v[218:221], v[202:205], v[72:75]
	s_setprio 0
	s_mov_b32 m0, s24
	v_lshl_add_u64 v[222:223], s[4:5], 0, v[164:165]
	s_barrier
; #define G_STAGE(bufoff, gbase, o0, h64) do { \
;         __builtin_amdgcn_global_load_lds((const unsigned*)((const char*)(gbase) + (o0)), (LAS unsigned*)(lds + (bufoff) + ldsw), 16, 0, 0); \
;         __builtin_amdgcn_global_load_lds((const unsigned*)((const char*)(gbase) + (h64) + (o0)), (LAS unsigned*)(lds + (bufoff) + ldsw + 8192), 16, 0, 0); } while (0)
; #define G_LDA(dst, b, h) do { _Pragma("unroll") for (int m = 0; m < 4; ++m) _Pragma("unroll") for (int k = 0; k < 2; ++k) dst[m][k] = *(const LAS bf16x8*)(lds + G_SA(b, h) + aoff + m * 2048 + k * 1024); } while (0)
; #define G_LDB(dst, b, h) do { _Pragma("unroll") for (int n = 0; n < 2; ++n) _Pragma("unroll") for (int k = 0; k < 2; ++k) dst[n][k] = *(const LAS bf16x8*)(lds + G_SB(b, h) + boff + n * 2048 + k * 1024); } while (0)
; #define G_WAIT_V(n) asm volatile("s_waitcnt vmcnt(" #n ")" ::: "memory")
; #define G_WAIT_L(n) asm volatile("s_waitcnt lgkmcnt(" #n ")" ::: "memory")
; #define G_BAR __builtin_amdgcn_s_barrier()
; #define G_SCHED __builtin_amdgcn_sched_barrier(0)
;     ...
;             G_BAR; G_WAIT_L(0); G_MMA(1, 0, At, B0); G_BAR; G_SCHED;
;             G_STAGE(G_SB(0, 1), b2 + chB, cB0, qB);
;             G_WAIT_V(6); G_BAR; G_MMA(1, 1, At, B1); G_BAR;
;             G_LDB(B0, 1, 0); G_SCHED; G_LDA(At, 1, 0); G_STAGE(G_SA(0, 1), a2 + chA, cA0, qA);
;             G_WAIT_L(8); G_BAR; G_WAIT_L(0); G_MMA(0, 0, At, B0); G_BAR; G_SCHED;
;             G_LDB(B1, 1, 1); G_STAGE(G_SB(1, 0), b3, cB0, qB);
;             G_BAR; G_WAIT_L(0); G_MMA(0, 1, At, B1); G_BAR;
;             G_LDA(At, 1, 1); G_STAGE(G_SA(1, 0), a3, cA0, qA);
;             G_BAR; G_WAIT_L(0); G_MMA(1, 0, At, B0); G_BAR; G_SCHED;
	ds_read_b128 v[152:155], v197 offset:16384
	ds_read_b128 v[156:159], v197 offset:17408
	ds_read_b128 v[160:163], v197 offset:18432
	ds_read_b128 v[172:175], v197 offset:19456
	ds_read_b128 v[176:179], v197 offset:20480
	ds_read_b128 v[180:183], v197 offset:21504
	ds_read_b128 v[198:201], v197 offset:22528
	ds_read_b128 v[202:205], v197 offset:23552
	global_load_lds_dwordx4 v[222:223], off
	v_lshl_add_u64 v[224:225], v[222:223], 0, s[70:71]
	s_mov_b32 m0, s25
	s_nop 0
	global_load_lds_dwordx4 v[224:225], off
	s_barrier
	s_waitcnt lgkmcnt(0)
	s_setprio 3
	s_waitcnt lgkmcnt(0)
	v_mfma_f32_16x16x32_bf16 v[68:71], v[112:115], v[152:155], v[68:71]
	v_mfma_f32_16x16x32_bf16 v[64:67], v[136:139], v[152:155], v[64:67]
	v_mfma_f32_16x16x32_bf16 v[52:55], v[112:115], v[160:163], v[52:55]
	v_mfma_f32_16x16x32_bf16 v[48:51], v[136:139], v[160:163], v[48:51]
	v_mfma_f32_16x16x32_bf16 v[36:39], v[112:115], v[176:179], v[36:39]
	v_mfma_f32_16x16x32_bf16 v[32:35], v[136:139], v[176:179], v[32:35]
	v_mfma_f32_16x16x32_bf16 v[20:23], v[112:115], v[198:201], v[20:23]
	v_mfma_f32_16x16x32_bf16 v[16:19], v[136:139], v[198:201], v[16:19]
	v_mfma_f32_16x16x32_bf16 v[68:71], v[124:127], v[156:159], v[68:71]
	v_mfma_f32_16x16x32_bf16 v[64:67], v[148:151], v[156:159], v[64:67]
	v_mfma_f32_16x16x32_bf16 v[52:55], v[124:127], v[172:175], v[52:55]
	v_mfma_f32_16x16x32_bf16 v[48:51], v[148:151], v[172:175], v[48:51]
	v_mfma_f32_16x16x32_bf16 v[36:39], v[124:127], v[180:183], v[36:39]
	v_mfma_f32_16x16x32_bf16 v[32:35], v[148:151], v[180:183], v[32:35]
	v_mfma_f32_16x16x32_bf16 v[20:23], v[124:127], v[202:205], v[20:23]
	v_mfma_f32_16x16x32_bf16 v[16:19], v[148:151], v[202:205], v[16:19]
	s_setprio 0
	s_barrier
	s_add_i32 s4, s38, s21
	v_lshl_add_u64 v[112:113], v[184:185], 0, s[0:1]
	s_mov_b32 m0, s4
	s_nop 0
	global_load_lds_dwordx4 v[112:113], off
	v_lshl_add_u64 v[112:113], v[184:185], 0, s[52:53]
	s_add_i32 m0, s4, 0x2000
	s_nop 0
	global_load_lds_dwordx4 v[112:113], off
	s_waitcnt vmcnt(6)
	s_barrier
	s_setprio 3
	v_mfma_f32_16x16x32_bf16 v[60:63], v[206:209], v[152:155], v[60:63]
	v_mfma_f32_16x16x32_bf16 v[56:59], v[214:217], v[152:155], v[56:59]
	v_mfma_f32_16x16x32_bf16 v[44:47], v[206:209], v[160:163], v[44:47]
	v_mfma_f32_16x16x32_bf16 v[40:43], v[214:217], v[160:163], v[40:43]
	v_mfma_f32_16x16x32_bf16 v[28:31], v[206:209], v[176:179], v[28:31]
	v_mfma_f32_16x16x32_bf16 v[24:27], v[214:217], v[176:179], v[24:27]
	v_mfma_f32_16x16x32_bf16 v[12:15], v[206:209], v[198:201], v[12:15]
	v_mfma_f32_16x16x32_bf16 v[8:11], v[214:217], v[198:201], v[8:11]
	v_mfma_f32_16x16x32_bf16 v[60:63], v[210:213], v[156:159], v[60:63]
	v_mfma_f32_16x16x32_bf16 v[56:59], v[218:221], v[156:159], v[56:59]
	v_mfma_f32_16x16x32_bf16 v[44:47], v[210:213], v[172:175], v[44:47]
	v_mfma_f32_16x16x32_bf16 v[40:43], v[218:221], v[172:175], v[40:43]
	v_mfma_f32_16x16x32_bf16 v[28:31], v[210:213], v[180:183], v[28:31]
	v_mfma_f32_16x16x32_bf16 v[24:27], v[218:221], v[180:183], v[24:27]
	v_mfma_f32_16x16x32_bf16 v[12:15], v[210:213], v[202:205], v[12:15]
	v_mfma_f32_16x16x32_bf16 v[8:11], v[218:221], v[202:205], v[8:11]
	s_setprio 0
	s_add_i32 s4, 0, 0x18000
	v_add_u32_e32 v0, s4, v196
	s_barrier
	ds_read_b128 v[112:115], v0
	ds_read_b128 v[124:127], v0 offset:1024
	ds_read_b128 v[136:139], v0 offset:2048
	ds_read_b128 v[148:151], v0 offset:3072
	s_mov_b32 m0, s26
	v_lshl_add_u64 v[206:207], v[222:223], 0, s[80:81]
	ds_read_b128 v[152:155], v197 offset:32768
	ds_read_b128 v[156:159], v197 offset:33792
	ds_read_b128 v[160:163], v197 offset:34816
	ds_read_b128 v[172:175], v197 offset:35840
	ds_read_b128 v[176:179], v197 offset:36864
	ds_read_b128 v[180:183], v197 offset:37888
	ds_read_b128 v[198:201], v197 offset:38912
	ds_read_b128 v[202:205], v197 offset:39936
	global_load_lds_dwordx4 v[206:207], off
	v_lshl_add_u64 v[206:207], v[222:223], 0, s[82:83]
	s_mov_b32 m0, s27
	s_nop 0
	global_load_lds_dwordx4 v[206:207], off
	s_waitcnt lgkmcnt(8)
	s_barrier
	s_waitcnt lgkmcnt(0)
	s_setprio 3
	s_waitcnt lgkmcnt(0)
	v_mfma_f32_16x16x32_bf16 v[144:147], v[112:115], v[152:155], v[144:147]
	v_mfma_f32_16x16x32_bf16 v[140:143], v[136:139], v[152:155], v[140:143]
	v_mfma_f32_16x16x32_bf16 v[120:123], v[112:115], v[160:163], v[120:123]
	v_mfma_f32_16x16x32_bf16 v[116:119], v[136:139], v[160:163], v[116:119]
	v_mfma_f32_16x16x32_bf16 v[100:103], v[112:115], v[176:179], v[100:103]
	v_mfma_f32_16x16x32_bf16 v[96:99], v[136:139], v[176:179], v[96:99]
	v_mfma_f32_16x16x32_bf16 v[84:87], v[112:115], v[198:201], v[84:87]
	v_mfma_f32_16x16x32_bf16 v[80:83], v[136:139], v[198:201], v[80:83]
	v_mfma_f32_16x16x32_bf16 v[144:147], v[124:127], v[156:159], v[144:147]
	v_mfma_f32_16x16x32_bf16 v[140:143], v[148:151], v[156:159], v[140:143]
	v_mfma_f32_16x16x32_bf16 v[120:123], v[124:127], v[172:175], v[120:123]
	v_mfma_f32_16x16x32_bf16 v[116:119], v[148:151], v[172:175], v[116:119]
	v_mfma_f32_16x16x32_bf16 v[100:103], v[124:127], v[180:183], v[100:103]
	v_mfma_f32_16x16x32_bf16 v[96:99], v[148:151], v[180:183], v[96:99]
	v_mfma_f32_16x16x32_bf16 v[84:87], v[124:127], v[202:205], v[84:87]
	v_mfma_f32_16x16x32_bf16 v[80:83], v[148:151], v[202:205], v[80:83]
	s_setprio 0
	s_barrier
; #define G_STAGE(bufoff, gbase, o0, h64) do { \
;         __builtin_amdgcn_global_load_lds((const unsigned*)((const char*)(gbase) + (o0)), (LAS unsigned*)(lds + (bufoff) + ldsw), 16, 0, 0); \
;         __builtin_amdgcn_global_load_lds((const unsigned*)((const char*)(gbase) + (h64) + (o0)), (LAS unsigned*)(lds + (bufoff) + ldsw + 8192), 16, 0, 0); } while (0)
; #define G_LDA(dst, b, h) do { _Pragma("unroll") for (int m = 0; m < 4; ++m) _Pragma("unroll") for (int k = 0; k < 2; ++k) dst[m][k] = *(const LAS bf16x8*)(lds + G_SA(b, h) + aoff + m * 2048 + k * 1024); } while (0)
; #define G_LDB(dst, b, h) do { _Pragma("unroll") for (int n = 0; n < 2; ++n) _Pragma("unroll") for (int k = 0; k < 2; ++k) dst[n][k] = *(const LAS bf16x8*)(lds + G_SB(b, h) + boff + n * 2048 + k * 1024); } while (0)
; #define G_WAIT_V(n) asm volatile("s_waitcnt vmcnt(" #n ")" ::: "memory")
; #define G_WAIT_L(n) asm volatile("s_waitcnt lgkmcnt(" #n ")" ::: "memory")
; #define G_BAR __builtin_amdgcn_s_barrier()
; #define G_SCHED __builtin_amdgcn_sched_barrier(0)
;     ...
;             G_WAIT_V(6); G_BAR; G_MMA(1, 1, At, B1); G_BAR;
;             G_LDB(B0, 1, 0); G_SCHED; G_LDA(At, 1, 0); G_STAGE(G_SA(0, 1), a2 + chA, cA0, qA);
;             G_WAIT_L(8); G_BAR; G_WAIT_L(0); G_MMA(0, 0, At, B0); G_BAR; G_SCHED;
;             G_LDB(B1, 1, 1); G_STAGE(G_SB(1, 0), b3, cB0, qB);
;             G_BAR; G_WAIT_L(0); G_MMA(0, 1, At, B1); G_BAR;
;             G_LDA(At, 1, 1); G_STAGE(G_SA(1, 0), a3, cA0, qA);
;             G_BAR; G_WAIT_L(0); G_MMA(1, 0, At, B0); G_BAR; G_SCHED;
;             G_STAGE(G_SB(1, 1), b3 + chB, cB0, qB);
;             G_WAIT_V(6); G_BAR; G_MMA(1, 1, At, B1); G_BAR;
;         }
	s_add_i32 s5, 0, 0x1c000
	s_add_i32 s4, s4, s21
	v_add_u32_e32 v0, s5, v196
	v_lshl_add_u64 v[224:225], v[184:185], 0, s[46:47]
	s_mov_b32 m0, s4
	ds_read_b128 v[206:209], v0
	ds_read_b128 v[210:213], v0 offset:1024
	ds_read_b128 v[214:217], v0 offset:2048
	ds_read_b128 v[218:221], v0 offset:3072
	global_load_lds_dwordx4 v[224:225], off
	v_lshl_add_u64 v[224:225], v[184:185], 0, s[54:55]
	s_add_i32 m0, s4, 0x2000
	s_nop 0
	global_load_lds_dwordx4 v[224:225], off
	s_barrier
	s_waitcnt lgkmcnt(0)
	s_setprio 3
	s_waitcnt lgkmcnt(0)
	v_mfma_f32_16x16x32_bf16 v[132:135], v[206:209], v[152:155], v[132:135]
	v_mfma_f32_16x16x32_bf16 v[128:131], v[214:217], v[152:155], v[128:131]
	v_mfma_f32_16x16x32_bf16 v[108:111], v[206:209], v[160:163], v[108:111]
	v_mfma_f32_16x16x32_bf16 v[104:107], v[214:217], v[160:163], v[104:107]
	v_mfma_f32_16x16x32_bf16 v[92:95], v[206:209], v[176:179], v[92:95]
	v_mfma_f32_16x16x32_bf16 v[88:91], v[214:217], v[176:179], v[88:91]
	v_mfma_f32_16x16x32_bf16 v[76:79], v[206:209], v[198:201], v[76:79]
	v_mfma_f32_16x16x32_bf16 v[72:75], v[214:217], v[198:201], v[72:75]
	v_mfma_f32_16x16x32_bf16 v[132:135], v[210:213], v[156:159], v[132:135]
	v_mfma_f32_16x16x32_bf16 v[128:131], v[218:221], v[156:159], v[128:131]
	v_mfma_f32_16x16x32_bf16 v[108:111], v[210:213], v[172:175], v[108:111]
	v_mfma_f32_16x16x32_bf16 v[104:107], v[218:221], v[172:175], v[104:107]
	v_mfma_f32_16x16x32_bf16 v[92:95], v[210:213], v[180:183], v[92:95]
	v_mfma_f32_16x16x32_bf16 v[88:91], v[218:221], v[180:183], v[88:91]
	v_mfma_f32_16x16x32_bf16 v[76:79], v[210:213], v[202:205], v[76:79]
	v_mfma_f32_16x16x32_bf16 v[72:75], v[218:221], v[202:205], v[72:75]
	s_setprio 0
	s_mov_b32 m0, s29
	v_lshl_add_u64 v[224:225], v[222:223], 0, s[62:63]
	s_barrier
	ds_read_b128 v[152:155], v197 offset:49152
	ds_read_b128 v[156:159], v197 offset:50176
	ds_read_b128 v[160:163], v197 offset:51200
	ds_read_b128 v[172:175], v197 offset:52224
	ds_read_b128 v[176:179], v197 offset:53248
	ds_read_b128 v[180:183], v197 offset:54272
	ds_read_b128 v[198:201], v197 offset:55296
	ds_read_b128 v[202:205], v197 offset:56320
	global_load_lds_dwordx4 v[224:225], off
	v_lshl_add_u64 v[222:223], v[222:223], 0, s[84:85]
	s_mov_b32 m0, s30
	s_nop 0
	global_load_lds_dwordx4 v[222:223], off
	s_barrier
	s_waitcnt lgkmcnt(0)
	s_setprio 3
	s_waitcnt lgkmcnt(0)
	v_mfma_f32_16x16x32_bf16 v[68:71], v[112:115], v[152:155], v[68:71]
	v_mfma_f32_16x16x32_bf16 v[64:67], v[136:139], v[152:155], v[64:67]
	v_mfma_f32_16x16x32_bf16 v[52:55], v[112:115], v[160:163], v[52:55]
	v_mfma_f32_16x16x32_bf16 v[48:51], v[136:139], v[160:163], v[48:51]
	v_mfma_f32_16x16x32_bf16 v[36:39], v[112:115], v[176:179], v[36:39]
	v_mfma_f32_16x16x32_bf16 v[32:35], v[136:139], v[176:179], v[32:35]
	v_mfma_f32_16x16x32_bf16 v[20:23], v[112:115], v[198:201], v[20:23]
	v_mfma_f32_16x16x32_bf16 v[16:19], v[136:139], v[198:201], v[16:19]
	v_mfma_f32_16x16x32_bf16 v[68:71], v[124:127], v[156:159], v[68:71]
	v_mfma_f32_16x16x32_bf16 v[64:67], v[148:151], v[156:159], v[64:67]
	v_mfma_f32_16x16x32_bf16 v[52:55], v[124:127], v[172:175], v[52:55]
	v_mfma_f32_16x16x32_bf16 v[48:51], v[148:151], v[172:175], v[48:51]
	v_mfma_f32_16x16x32_bf16 v[36:39], v[124:127], v[180:183], v[36:39]
	v_mfma_f32_16x16x32_bf16 v[32:35], v[148:151], v[180:183], v[32:35]
	v_mfma_f32_16x16x32_bf16 v[20:23], v[124:127], v[202:205], v[20:23]
	v_mfma_f32_16x16x32_bf16 v[16:19], v[148:151], v[202:205], v[16:19]
	s_setprio 0
	s_barrier
	s_add_i32 s4, s5, s21
	v_lshl_add_u64 v[112:113], v[184:185], 0, s[42:43]
	s_mov_b32 m0, s4
	s_nop 0
	global_load_lds_dwordx4 v[112:113], off
	v_lshl_add_u64 v[112:113], v[184:185], 0, s[58:59]
	s_add_i32 m0, s4, 0x2000
	s_nop 0
	global_load_lds_dwordx4 v[112:113], off
	s_waitcnt vmcnt(6)
	s_barrier
	s_setprio 3
	v_mfma_f32_16x16x32_bf16 v[60:63], v[206:209], v[152:155], v[60:63]
	v_mfma_f32_16x16x32_bf16 v[56:59], v[214:217], v[152:155], v[56:59]
	v_mfma_f32_16x16x32_bf16 v[44:47], v[206:209], v[160:163], v[44:47]
	v_mfma_f32_16x16x32_bf16 v[40:43], v[214:217], v[160:163], v[40:43]
	v_mfma_f32_16x16x32_bf16 v[28:31], v[206:209], v[176:179], v[28:31]
	v_mfma_f32_16x16x32_bf16 v[24:27], v[214:217], v[176:179], v[24:27]
	v_mfma_f32_16x16x32_bf16 v[12:15], v[206:209], v[198:201], v[12:15]
	v_mfma_f32_16x16x32_bf16 v[8:11], v[214:217], v[198:201], v[8:11]
	v_mfma_f32_16x16x32_bf16 v[60:63], v[210:213], v[156:159], v[60:63]
	v_mfma_f32_16x16x32_bf16 v[56:59], v[218:221], v[156:159], v[56:59]
	v_mfma_f32_16x16x32_bf16 v[44:47], v[210:213], v[172:175], v[44:47]
	v_mfma_f32_16x16x32_bf16 v[40:43], v[218:221], v[172:175], v[40:43]
	v_mfma_f32_16x16x32_bf16 v[28:31], v[210:213], v[180:183], v[28:31]
	v_mfma_f32_16x16x32_bf16 v[24:27], v[218:221], v[180:183], v[24:27]
	v_mfma_f32_16x16x32_bf16 v[12:15], v[210:213], v[202:205], v[12:15]
	v_mfma_f32_16x16x32_bf16 v[8:11], v[218:221], v[202:205], v[8:11]
	s_setprio 0
	s_add_i32 s19, s19, 2
	s_add_u32 s13, s13, 0x100
	s_addc_u32 s18, s18, 0
	s_add_u32 s2, s2, 0x800000
	s_addc_u32 s3, s3, 0
	s_cmp_gt_u32 s19, 5
	s_cbranch_scc0 .Ldb_GLU_cont
	v_readfirstlane_b32 s101, v186
	s_cmpk_gt_u32 s101, 0xff
	s_cbranch_scc1 .Ldb_GLU_exit
	s_barrier
	s_branch .Ldb_GLU_exit

; __device__ __forceinline__ float sigmoidf_(float v) { return __builtin_amdgcn_rcpf(1.0f + __expf(-v)); }
; __device__ __forceinline__ u32x4 pack8(const f32x4 a, const f32x4 b) { u32x4 w; w.x = cvt_pk_bf16(a[0], a[1]); w.y = cvt_pk_bf16(a[2], a[3]); w.z = cvt_pk_bf16(b[0], b[1]); w.w = cvt_pk_bf16(b[2], b[3]); return w; }
; __device__ __forceinline__ void unpack8(const u32x4 w, f32x4& a, f32x4& b) { a[0] = bf_lo(w.x); a[1] = bf_hi(w.x); a[2] = bf_lo(w.y); a[3] = bf_hi(w.y); b[0] = bf_lo(w.z); b[1] = bf_hi(w.z); b[2] = bf_lo(w.w); b[3] = bf_hi(w.w); }
; #define MEMFENCE asm volatile("" ::: "memory")
;     template <int KIND> __device__ __forceinline__ void run(f32x4 (&acc)[2][2][4][2], const Unit& u, int tid_in) const {
;     ...
;         if constexpr (KIND == K_GLU) {
; #pragma unroll
;             for (int ai = 0; ai < 2; ++ai) { u32x4 yv[4][2];
; #pragma unroll
;                 for (int m = 0; m < 4; ++m) { int row = rbase + ai * 128 + m * 16; asm volatile("" : "+v"(row));
; #pragma unroll
;                     for (int bj = 0; bj < 2; ++bj) { const int col = u.pn * 256 + bj * 128 + cl; yv[m][bj] = *(const u32x4*)(yi + ((size_t)(col >> 4) * T_TOK + row) * 16 + (col & 15)); } }
; #pragma unroll
;                 for (int m = 0; m < 4; ++m) { int row = rbase + ai * 128 + m * 16; asm volatile("" : "+v"(row));
; #pragma unroll
;                     for (int bj = 0; bj < 2; ++bj) { const int col = u.pn * 256 + bj * 128 + cl; f32x4 y0, y1; unpack8(yv[m][bj], y0, y1);
; #pragma unroll
;                         for (int j = 0; j < 4; ++j) { y0[j] *= sigmoidf_(acc[ai][bj][m][0][j]); y1[j] *= sigmoidf_(acc[ai][bj][m][1][j]); }
;                         *(u32x4*)(zb + (size_t)row * ZW + 1024 + col) = pack8(y0, y1); } }
;                 MEMFENCE; }
.Ldb_GLU_exit:
	v_mov_b32_e32 v0, v195
	s_lshl_b32 s3, s35, 8
	v_readfirstlane_b32 s2, v0
	s_ashr_i32 s4, s2, 2
	s_lshr_b32 s2, s2, 1
	s_and_b32 s2, s2, 0x60
	v_lshrrev_b32_e32 v112, 1, v0
	v_and_or_b32 v112, v112, 24, s2
	s_andn2_b32 s4, s4, 63
	v_lshl_or_b32 v182, s33, 8, v112
	s_add_i32 s4, s4, s3
	v_ashrrev_i32_e32 v112, 4, v182
	v_and_or_b32 v198, v0, 15, s4
	v_ashrrev_i32_e32 v113, 31, v112
	v_lshlrev_b64 v[176:177], 20, v[112:113]
	v_mov_b32_e32 v112, v198
	v_and_b32_e32 v0, 16, v0
	v_lshl_add_u64 v[174:175], s[8:9], 0, v[0:1]
	v_ashrrev_i32_e32 v113, 31, v112
	v_lshlrev_b64 v[112:113], 5, v[112:113]
	v_lshl_add_u64 v[112:113], v[174:175], 0, v[112:113]
	v_lshl_add_u64 v[114:115], v[112:113], 0, v[176:177]
	global_load_dwordx4 v[202:205], v[114:115], off
	v_or_b32_e32 v180, 0x80, v182
	v_ashrrev_i32_e32 v114, 4, v180
	v_ashrrev_i32_e32 v115, 31, v114
	v_lshlrev_b64 v[178:179], 20, v[114:115]
	v_lshl_add_u64 v[112:113], v[112:113], 0, v[178:179]
	global_load_dwordx4 v[160:163], v[112:113], off
	v_or_b32_e32 v200, 16, v198
	v_mov_b32_e32 v112, v200
	v_or_b32_e32 v199, 32, v198
	v_ashrrev_i32_e32 v113, 31, v112
	v_lshlrev_b64 v[112:113], 5, v[112:113]
	v_lshl_add_u64 v[112:113], v[174:175], 0, v[112:113]
	v_lshl_add_u64 v[114:115], v[112:113], 0, v[176:177]
	global_load_dwordx4 v[156:159], v[114:115], off
	v_lshl_add_u64 v[112:113], v[112:113], 0, v[178:179]
	global_load_dwordx4 v[152:155], v[112:113], off
	v_mov_b32_e32 v112, v199
	v_mul_f32_e32 v144, 0xbfb8aa3b, v144
	v_ashrrev_i32_e32 v113, 31, v112
	v_lshlrev_b64 v[112:113], 5, v[112:113]
	v_mul_f32_e32 v142, 0xbfb8aa3b, v142
	v_lshl_add_u64 v[112:113], v[174:175], 0, v[112:113]
	v_exp_f32_e32 v144, v144
	v_exp_f32_e32 v142, v142
	v_lshl_add_u64 v[114:115], v[112:113], 0, v[176:177]
	v_lshl_add_u64 v[112:113], v[112:113], 0, v[178:179]
	v_or_b32_e32 v0, 48, v198
	global_load_dwordx4 v[148:151], v[114:115], off
	global_load_dwordx4 v[136:139], v[112:113], off
	v_mov_b32_e32 v112, v0
	v_add_f32_e32 v144, 1.0, v144
	v_ashrrev_i32_e32 v113, 31, v112
	v_lshlrev_b64 v[112:113], 5, v[112:113]
	v_add_f32_e32 v142, 1.0, v142
	v_lshl_add_u64 v[112:113], v[174:175], 0, v[112:113]
	v_rcp_f32_e32 v144, v144
	v_rcp_f32_e32 v142, v142
	v_lshl_add_u64 v[114:115], v[112:113], 0, v[176:177]
	v_lshl_add_u64 v[112:113], v[112:113], 0, v[178:179]
	v_mov_b32_e32 v181, v198
	global_load_dwordx4 v[124:127], v[114:115], off
	v_mov_b64_e32 v[172:173], s[6:7]
	global_load_dwordx4 v[112:115], v[112:113], off
	v_mul_f32_e32 v145, 0xbfb8aa3b, v145
	v_mad_i64_i32 v[184:185], s[2:3], v181, s76, v[172:173]
	v_mul_f32_e32 v140, 0xbfb8aa3b, v140
	v_exp_f32_e32 v145, v145
	v_mul_f32_e32 v141, 0xbfb8aa3b, v141
	v_mul_f32_e32 v146, 0xbfb8aa3b, v146
	v_exp_f32_e32 v140, v140
	v_exp_f32_e32 v141, v141
	v_exp_f32_e32 v146, v146
	v_add_f32_e32 v145, 1.0, v145
	v_mul_f32_e32 v132, 0xbfb8aa3b, v132
	v_mul_f32_e32 v130, 0xbfb8aa3b, v130
	v_add_f32_e32 v140, 1.0, v140
	v_rcp_f32_e32 v145, v145
	v_add_f32_e32 v141, 1.0, v141
	v_add_f32_e32 v146, 1.0, v146
	v_exp_f32_e32 v132, v132
	v_exp_f32_e32 v130, v130
	v_rcp_f32_e32 v140, v140
	v_rcp_f32_e32 v141, v141
	v_rcp_f32_e32 v146, v146
	v_add_f32_e32 v132, 1.0, v132
	v_add_f32_e32 v130, 1.0, v130
	s_mov_b64 s[4:5], 0xae00800
	v_rcp_f32_e32 v132, v132
	v_rcp_f32_e32 v130, v130
	v_lshl_add_u64 v[184:185], v[184:185], 0, s[4:5]
	v_mul_f32_e32 v128, 0xbfb8aa3b, v128
	v_mul_f32_e32 v129, 0xbfb8aa3b, v129
	v_exp_f32_e32 v128, v128
	v_mul_f32_e32 v133, 0xbfb8aa3b, v133
	s_waitcnt vmcnt(0)
	v_lshlrev_b32_e32 v181, 16, v202
	v_lshlrev_b32_e32 v206, 16, v205
	v_mul_f32_e32 v144, v144, v181
	v_mul_f32_e32 v181, v142, v206
	v_mul_f32_e32 v142, 0xbfb8aa3b, v147
	v_exp_f32_e32 v142, v142
	v_and_b32_e32 v183, 0xffff0000, v202
	v_and_b32_e32 v202, 0xffff0000, v203
	v_and_b32_e32 v205, 0xffff0000, v205
	v_add_f32_e32 v142, 1.0, v142
	v_rcp_f32_e32 v142, v142
	v_lshlrev_b32_e32 v201, 16, v203
	v_lshlrev_b32_e32 v203, 16, v204
	v_and_b32_e32 v204, 0xffff0000, v204
	v_mul_f32_e32 v147, v142, v202
	v_mul_f32_e32 v142, 0xbfb8aa3b, v143
	v_exp_f32_e32 v142, v142
	v_mul_f32_e32 v145, v145, v183
	v_mul_f32_e32 v140, v140, v203
	v_mul_f32_e32 v141, v141, v204
	v_add_f32_e32 v142, 1.0, v142
	v_rcp_f32_e32 v142, v142
	v_mul_f32_e32 v146, v146, v201
	v_exp_f32_e32 v129, v129
	v_mul_f32_e32 v134, 0xbfb8aa3b, v134
	v_mul_f32_e32 v183, v142, v205
	v_cvt_pk_bf16_f32 v142, v144, v145
	v_cvt_pk_bf16_f32 v143, v146, v147
	v_cvt_pk_bf16_f32 v144, v140, v141
	v_cvt_pk_bf16_f32 v145, v181, v183
	v_ashrrev_i32_e32 v183, 31, v182
	v_lshlrev_b64 v[140:141], 1, v[182:183]
	v_lshl_add_u64 v[146:147], v[184:185], 0, v[140:141]
	global_store_dwordx4 v[146:147], v[142:145], off
	v_exp_f32_e32 v133, v133
	v_exp_f32_e32 v134, v134
	v_lshlrev_b32_e32 v142, 16, v160
	v_and_b32_e32 v143, 0xffff0000, v160
	v_lshlrev_b32_e32 v160, 16, v163
	v_mul_f32_e32 v132, v132, v142
	v_mul_f32_e32 v142, v130, v160
	v_mul_f32_e32 v130, 0xbfb8aa3b, v135
	v_exp_f32_e32 v130, v130
	v_and_b32_e32 v145, 0xffff0000, v161
	v_mul_f32_e32 v120, 0xbfb8aa3b, v120
	v_mul_f32_e32 v116, 0xbfb8aa3b, v116
	v_add_f32_e32 v130, 1.0, v130
	v_rcp_f32_e32 v130, v130
	v_mul_f32_e32 v117, 0xbfb8aa3b, v117
	v_mul_f32_e32 v118, 0xbfb8aa3b, v118
	v_add_f32_e32 v128, 1.0, v128
	v_mul_f32_e32 v135, v130, v145
	v_mul_f32_e32 v130, 0xbfb8aa3b, v131
	v_exp_f32_e32 v130, v130
	v_add_f32_e32 v129, 1.0, v129
	v_exp_f32_e32 v120, v120
	v_exp_f32_e32 v116, v116
	v_exp_f32_e32 v117, v117
	v_exp_f32_e32 v118, v118
	v_rcp_f32_e32 v128, v128
	v_add_f32_e32 v133, 1.0, v133
	v_rcp_f32_e32 v129, v129
	v_add_f32_e32 v134, 1.0, v134
	v_add_f32_e32 v130, 1.0, v130
	v_rcp_f32_e32 v133, v133
; __device__ __forceinline__ float sigmoidf_(float v) { return __builtin_amdgcn_rcpf(1.0f + __expf(-v)); }
; __device__ __forceinline__ u32x4 pack8(const f32x4 a, const f32x4 b) { u32x4 w; w.x = cvt_pk_bf16(a[0], a[1]); w.y = cvt_pk_bf16(a[2], a[3]); w.z = cvt_pk_bf16(b[0], b[1]); w.w = cvt_pk_bf16(b[2], b[3]); return w; }
; __device__ __forceinline__ void unpack8(const u32x4 w, f32x4& a, f32x4& b) { a[0] = bf_lo(w.x); a[1] = bf_hi(w.x); a[2] = bf_lo(w.y); a[3] = bf_hi(w.y); b[0] = bf_lo(w.z); b[1] = bf_hi(w.z); b[2] = bf_lo(w.w); b[3] = bf_hi(w.w); }
; #define MEMFENCE asm volatile("" ::: "memory")
;     template <int KIND> __device__ __forceinline__ void run(f32x4 (&acc)[2][2][4][2], const Unit& u, int tid_in) const {
;     ...
;         if constexpr (KIND == K_GLU) {
; #pragma unroll
;             for (int ai = 0; ai < 2; ++ai) { u32x4 yv[4][2];
; #pragma unroll
;                 for (int m = 0; m < 4; ++m) { int row = rbase + ai * 128 + m * 16; asm volatile("" : "+v"(row));
; #pragma unroll
;                     for (int bj = 0; bj < 2; ++bj) { const int col = u.pn * 256 + bj * 128 + cl; yv[m][bj] = *(const u32x4*)(yi + ((size_t)(col >> 4) * T_TOK + row) * 16 + (col & 15)); } }
; #pragma unroll
;                 for (int m = 0; m < 4; ++m) { int row = rbase + ai * 128 + m * 16; asm volatile("" : "+v"(row));
; #pragma unroll
;                     for (int bj = 0; bj < 2; ++bj) { const int col = u.pn * 256 + bj * 128 + cl; f32x4 y0, y1; unpack8(yv[m][bj], y0, y1);
; #pragma unroll
;                         for (int j = 0; j < 4; ++j) { y0[j] *= sigmoidf_(acc[ai][bj][m][0][j]); y1[j] *= sigmoidf_(acc[ai][bj][m][1][j]); }
;                         *(u32x4*)(zb + (size_t)row * ZW + 1024 + col) = pack8(y0, y1); } }
;                 MEMFENCE; }
	v_rcp_f32_e32 v134, v134
	v_rcp_f32_e32 v130, v130
	v_lshlrev_b32_e32 v146, 16, v162
	v_and_b32_e32 v147, 0xffff0000, v162
	v_add_f32_e32 v120, 1.0, v120
	v_add_f32_e32 v116, 1.0, v116
	v_add_f32_e32 v117, 1.0, v117
	v_add_f32_e32 v118, 1.0, v118
	v_lshlrev_b32_e32 v144, 16, v161
	v_and_b32_e32 v161, 0xffff0000, v163
	v_mul_f32_e32 v128, v128, v146
	v_mul_f32_e32 v129, v129, v147
	v_ashrrev_i32_e32 v181, 31, v180
	v_rcp_f32_e32 v120, v120
	v_rcp_f32_e32 v116, v116
	v_rcp_f32_e32 v117, v117
	v_rcp_f32_e32 v118, v118
	v_mul_f32_e32 v133, v133, v143
	v_mul_f32_e32 v134, v134, v144
	v_mul_f32_e32 v143, v130, v161
	v_cvt_pk_bf16_f32 v130, v132, v133
	v_cvt_pk_bf16_f32 v131, v134, v135
	v_cvt_pk_bf16_f32 v132, v128, v129
	v_lshlrev_b64 v[128:129], 1, v[180:181]
	v_lshl_add_u64 v[134:135], v[184:185], 0, v[128:129]
	v_cvt_pk_bf16_f32 v133, v142, v143
	global_store_dwordx4 v[134:135], v[130:133], off
	v_lshlrev_b32_e32 v142, 16, v158
	v_and_b32_e32 v143, 0xffff0000, v158
	v_lshlrev_b32_e32 v132, 16, v156
	v_lshlrev_b32_e32 v144, 16, v159
	v_mul_f32_e32 v120, v120, v132
	v_mul_f32_e32 v132, v116, v142
	v_mul_f32_e32 v116, 0xbfb8aa3b, v121
	v_mul_f32_e32 v121, v117, v143
	v_mul_f32_e32 v117, 0xbfb8aa3b, v122
	v_mul_f32_e32 v122, v118, v144
	v_mul_f32_e32 v118, 0xbfb8aa3b, v123
	v_exp_f32_e32 v116, v116
	v_exp_f32_e32 v117, v117
	v_exp_f32_e32 v118, v118
	v_mul_f32_e32 v119, 0xbfb8aa3b, v119
	v_exp_f32_e32 v119, v119
	v_mul_f32_e32 v108, 0xbfb8aa3b, v108
	v_mul_f32_e32 v104, 0xbfb8aa3b, v104
	v_mul_f32_e32 v105, 0xbfb8aa3b, v105
	v_mul_f32_e32 v106, 0xbfb8aa3b, v106
	v_exp_f32_e32 v108, v108
	v_exp_f32_e32 v104, v104
	v_exp_f32_e32 v105, v105
	v_exp_f32_e32 v106, v106
	v_add_f32_e32 v116, 1.0, v116
	v_add_f32_e32 v117, 1.0, v117
	v_add_f32_e32 v118, 1.0, v118
	v_rcp_f32_e32 v116, v116
	v_rcp_f32_e32 v117, v117
	v_rcp_f32_e32 v118, v118
	v_add_f32_e32 v119, 1.0, v119
	v_rcp_f32_e32 v119, v119
	v_add_f32_e32 v108, 1.0, v108
	v_add_f32_e32 v104, 1.0, v104
	v_add_f32_e32 v105, 1.0, v105
	v_add_f32_e32 v106, 1.0, v106
	v_and_b32_e32 v133, 0xffff0000, v156
	v_mad_i64_i32 v[130:131], s[2:3], v200, s76, v[172:173]
	v_lshlrev_b32_e32 v134, 16, v157
	v_and_b32_e32 v135, 0xffff0000, v157
	v_rcp_f32_e32 v108, v108
	v_rcp_f32_e32 v104, v104
	v_rcp_f32_e32 v105, v105
	v_rcp_f32_e32 v106, v106
	v_lshl_add_u64 v[130:131], v[130:131], 0, s[4:5]
	v_and_b32_e32 v145, 0xffff0000, v159
	v_mul_f32_e32 v116, v116, v133
	v_mul_f32_e32 v117, v117, v134
	v_mul_f32_e32 v118, v118, v135
	v_mul_f32_e32 v119, v119, v145
	v_cvt_pk_bf16_f32 v116, v120, v116
	v_cvt_pk_bf16_f32 v117, v117, v118
	v_cvt_pk_bf16_f32 v118, v132, v121
	v_lshl_add_u64 v[120:121], v[130:131], 0, v[140:141]
	v_cvt_pk_bf16_f32 v119, v122, v119
	global_store_dwordx4 v[120:121], v[116:119], off
	v_lshlrev_b32_e32 v120, 16, v154
	v_and_b32_e32 v121, 0xffff0000, v154
	v_lshlrev_b32_e32 v116, 16, v152
	v_lshlrev_b32_e32 v122, 16, v155
	v_mul_f32_e32 v108, v108, v116
	v_mul_f32_e32 v116, v104, v120
	v_mul_f32_e32 v104, 0xbfb8aa3b, v109
	v_mul_f32_e32 v109, v105, v121
	v_mul_f32_e32 v105, 0xbfb8aa3b, v110
	v_mul_f32_e32 v110, v106, v122
	v_mul_f32_e32 v106, 0xbfb8aa3b, v111
	v_exp_f32_e32 v104, v104
	v_exp_f32_e32 v105, v105
	v_exp_f32_e32 v106, v106
	v_mul_f32_e32 v107, 0xbfb8aa3b, v107
	v_exp_f32_e32 v107, v107
	v_mul_f32_e32 v100, 0xbfb8aa3b, v100
	v_mul_f32_e32 v96, 0xbfb8aa3b, v96
	v_mul_f32_e32 v97, 0xbfb8aa3b, v97
	v_mul_f32_e32 v98, 0xbfb8aa3b, v98
	v_exp_f32_e32 v100, v100
	v_exp_f32_e32 v96, v96
	v_exp_f32_e32 v97, v97
	v_exp_f32_e32 v98, v98
	v_add_f32_e32 v104, 1.0, v104
	v_add_f32_e32 v105, 1.0, v105
	v_add_f32_e32 v106, 1.0, v106
	v_rcp_f32_e32 v104, v104
	v_rcp_f32_e32 v105, v105
	v_rcp_f32_e32 v106, v106
	v_add_f32_e32 v107, 1.0, v107
	v_rcp_f32_e32 v107, v107
	v_add_f32_e32 v100, 1.0, v100
	v_add_f32_e32 v96, 1.0, v96
	v_add_f32_e32 v97, 1.0, v97
	v_add_f32_e32 v98, 1.0, v98
	v_and_b32_e32 v117, 0xffff0000, v152
	v_lshlrev_b32_e32 v118, 16, v153
	v_and_b32_e32 v119, 0xffff0000, v153
	v_rcp_f32_e32 v100, v100
	v_rcp_f32_e32 v96, v96
	v_rcp_f32_e32 v97, v97
	v_rcp_f32_e32 v98, v98
	v_and_b32_e32 v123, 0xffff0000, v155
	v_mul_f32_e32 v104, v104, v117
	v_mul_f32_e32 v105, v105, v118
	v_mul_f32_e32 v106, v106, v119
	v_mul_f32_e32 v107, v107, v123
	v_cvt_pk_bf16_f32 v104, v108, v104
	v_cvt_pk_bf16_f32 v105, v105, v106
	v_cvt_pk_bf16_f32 v106, v116, v109
	v_lshl_add_u64 v[108:109], v[130:131], 0, v[128:129]
	v_cvt_pk_bf16_f32 v107, v110, v107
	global_store_dwordx4 v[108:109], v[104:107], off
	v_lshlrev_b32_e32 v110, 16, v150
	v_and_b32_e32 v111, 0xffff0000, v150
	v_lshlrev_b32_e32 v106, 16, v148
	v_lshlrev_b32_e32 v116, 16, v151
	v_mul_f32_e32 v100, v100, v106
	v_mul_f32_e32 v106, v96, v110
	v_mul_f32_e32 v96, 0xbfb8aa3b, v101
	v_mul_f32_e32 v101, v97, v111
	v_mul_f32_e32 v97, 0xbfb8aa3b, v102
	v_mul_f32_e32 v102, v98, v116
	v_mul_f32_e32 v98, 0xbfb8aa3b, v103
	v_exp_f32_e32 v96, v96
	v_exp_f32_e32 v97, v97
	v_exp_f32_e32 v98, v98
	v_mul_f32_e32 v99, 0xbfb8aa3b, v99
	v_exp_f32_e32 v99, v99
	v_mul_f32_e32 v92, 0xbfb8aa3b, v92
	v_mul_f32_e32 v88, 0xbfb8aa3b, v88
	v_mul_f32_e32 v89, 0xbfb8aa3b, v89
	v_mul_f32_e32 v90, 0xbfb8aa3b, v90
	v_exp_f32_e32 v92, v92
	v_exp_f32_e32 v88, v88
	v_exp_f32_e32 v89, v89
	v_exp_f32_e32 v90, v90
	v_add_f32_e32 v96, 1.0, v96
	v_add_f32_e32 v97, 1.0, v97
	v_add_f32_e32 v98, 1.0, v98
	v_rcp_f32_e32 v96, v96
	v_rcp_f32_e32 v97, v97
	v_rcp_f32_e32 v98, v98
	v_add_f32_e32 v99, 1.0, v99
	v_rcp_f32_e32 v99, v99
	v_add_f32_e32 v92, 1.0, v92
	v_add_f32_e32 v88, 1.0, v88
	v_add_f32_e32 v89, 1.0, v89
	v_add_f32_e32 v90, 1.0, v90
	v_and_b32_e32 v107, 0xffff0000, v148
; __device__ __forceinline__ float sigmoidf_(float v) { return __builtin_amdgcn_rcpf(1.0f + __expf(-v)); }
; __device__ __forceinline__ u32x4 pack8(const f32x4 a, const f32x4 b) { u32x4 w; w.x = cvt_pk_bf16(a[0], a[1]); w.y = cvt_pk_bf16(a[2], a[3]); w.z = cvt_pk_bf16(b[0], b[1]); w.w = cvt_pk_bf16(b[2], b[3]); return w; }
; __device__ __forceinline__ void unpack8(const u32x4 w, f32x4& a, f32x4& b) { a[0] = bf_lo(w.x); a[1] = bf_hi(w.x); a[2] = bf_lo(w.y); a[3] = bf_hi(w.y); b[0] = bf_lo(w.z); b[1] = bf_hi(w.z); b[2] = bf_lo(w.w); b[3] = bf_hi(w.w); }
; #define MEMFENCE asm volatile("" ::: "memory")
;     template <int KIND> __device__ __forceinline__ void run(f32x4 (&acc)[2][2][4][2], const Unit& u, int tid_in) const {
;     ...
;         if constexpr (KIND == K_GLU) {
; #pragma unroll
;             for (int ai = 0; ai < 2; ++ai) { u32x4 yv[4][2];
; #pragma unroll
;                 for (int m = 0; m < 4; ++m) { int row = rbase + ai * 128 + m * 16; asm volatile("" : "+v"(row));
; #pragma unroll
;                     for (int bj = 0; bj < 2; ++bj) { const int col = u.pn * 256 + bj * 128 + cl; yv[m][bj] = *(const u32x4*)(yi + ((size_t)(col >> 4) * T_TOK + row) * 16 + (col & 15)); } }
; #pragma unroll
;                 for (int m = 0; m < 4; ++m) { int row = rbase + ai * 128 + m * 16; asm volatile("" : "+v"(row));
; #pragma unroll
;                     for (int bj = 0; bj < 2; ++bj) { const int col = u.pn * 256 + bj * 128 + cl; f32x4 y0, y1; unpack8(yv[m][bj], y0, y1);
; #pragma unroll
;                         for (int j = 0; j < 4; ++j) { y0[j] *= sigmoidf_(acc[ai][bj][m][0][j]); y1[j] *= sigmoidf_(acc[ai][bj][m][1][j]); }
;                         *(u32x4*)(zb + (size_t)row * ZW + 1024 + col) = pack8(y0, y1); } }
;                 MEMFENCE; }
	v_mad_i64_i32 v[104:105], s[2:3], v199, s76, v[172:173]
	v_lshlrev_b32_e32 v108, 16, v149
	v_and_b32_e32 v109, 0xffff0000, v149
	v_rcp_f32_e32 v92, v92
	v_rcp_f32_e32 v88, v88
	v_rcp_f32_e32 v89, v89
	v_rcp_f32_e32 v90, v90
	v_lshl_add_u64 v[104:105], v[104:105], 0, s[4:5]
	v_and_b32_e32 v117, 0xffff0000, v151
	v_mul_f32_e32 v96, v96, v107
	v_mul_f32_e32 v97, v97, v108
	v_mul_f32_e32 v98, v98, v109
	v_mul_f32_e32 v99, v99, v117
	v_cvt_pk_bf16_f32 v96, v100, v96
	v_cvt_pk_bf16_f32 v97, v97, v98
	v_cvt_pk_bf16_f32 v98, v106, v101
	v_lshl_add_u64 v[100:101], v[104:105], 0, v[140:141]
	v_cvt_pk_bf16_f32 v99, v102, v99
	global_store_dwordx4 v[100:101], v[96:99], off
	v_lshlrev_b32_e32 v100, 16, v138
	v_and_b32_e32 v101, 0xffff0000, v138
	v_lshlrev_b32_e32 v96, 16, v136
	v_lshlrev_b32_e32 v102, 16, v139
	v_mul_f32_e32 v92, v92, v96
	v_mul_f32_e32 v96, v88, v100
	v_mul_f32_e32 v88, 0xbfb8aa3b, v93
	v_mul_f32_e32 v93, v89, v101
	v_mul_f32_e32 v89, 0xbfb8aa3b, v94
	v_mul_f32_e32 v94, v90, v102
	v_mul_f32_e32 v90, 0xbfb8aa3b, v95
	v_exp_f32_e32 v88, v88
	v_exp_f32_e32 v89, v89
	v_exp_f32_e32 v90, v90
	v_mul_f32_e32 v91, 0xbfb8aa3b, v91
	v_exp_f32_e32 v91, v91
	v_mul_f32_e32 v84, 0xbfb8aa3b, v84
	v_mul_f32_e32 v80, 0xbfb8aa3b, v80
	v_mul_f32_e32 v81, 0xbfb8aa3b, v81
	v_mul_f32_e32 v82, 0xbfb8aa3b, v82
	v_add_f32_e32 v88, 1.0, v88
	v_add_f32_e32 v89, 1.0, v89
	v_add_f32_e32 v90, 1.0, v90
	v_exp_f32_e32 v84, v84
	v_exp_f32_e32 v80, v80
	v_exp_f32_e32 v81, v81
	v_exp_f32_e32 v82, v82
	v_rcp_f32_e32 v88, v88
	v_rcp_f32_e32 v89, v89
	v_rcp_f32_e32 v90, v90
	v_add_f32_e32 v91, 1.0, v91
	v_rcp_f32_e32 v91, v91
	v_and_b32_e32 v97, 0xffff0000, v136
	v_lshlrev_b32_e32 v98, 16, v137
	v_and_b32_e32 v99, 0xffff0000, v137
	v_add_f32_e32 v84, 1.0, v84
	v_add_f32_e32 v80, 1.0, v80
	v_add_f32_e32 v81, 1.0, v81
	v_add_f32_e32 v82, 1.0, v82
	v_and_b32_e32 v103, 0xffff0000, v139
	v_mul_f32_e32 v88, v88, v97
	v_mul_f32_e32 v89, v89, v98
	v_mul_f32_e32 v90, v90, v99
	v_rcp_f32_e32 v84, v84
	v_rcp_f32_e32 v80, v80
	v_rcp_f32_e32 v81, v81
	v_rcp_f32_e32 v82, v82
	v_mul_f32_e32 v91, v91, v103
	v_cvt_pk_bf16_f32 v88, v92, v88
	v_cvt_pk_bf16_f32 v89, v89, v90
	v_cvt_pk_bf16_f32 v90, v96, v93
	v_lshl_add_u64 v[92:93], v[104:105], 0, v[128:129]
	v_cvt_pk_bf16_f32 v91, v94, v91
	global_store_dwordx4 v[92:93], v[88:91], off
	v_lshlrev_b32_e32 v93, 16, v126
	v_and_b32_e32 v94, 0xffff0000, v126
	v_mad_i64_i32 v[88:89], s[2:3], v0, s76, v[172:173]
	v_lshlrev_b32_e32 v0, 16, v124
	v_lshlrev_b32_e32 v95, 16, v127
	v_mul_f32_e32 v0, v84, v0
	v_mul_f32_e32 v84, v80, v93
	v_mul_f32_e32 v80, 0xbfb8aa3b, v85
	v_mul_f32_e32 v85, v81, v94
	v_mul_f32_e32 v81, 0xbfb8aa3b, v86
	v_mul_f32_e32 v86, v82, v95
	v_mul_f32_e32 v82, 0xbfb8aa3b, v87
	v_mul_f32_e32 v83, 0xbfb8aa3b, v83
	v_exp_f32_e32 v80, v80
	v_exp_f32_e32 v81, v81
	v_exp_f32_e32 v82, v82
	v_exp_f32_e32 v83, v83
	v_mul_f32_e32 v76, 0xbfb8aa3b, v76
	v_mul_f32_e32 v72, 0xbfb8aa3b, v72
	v_mul_f32_e32 v73, 0xbfb8aa3b, v73
	v_mul_f32_e32 v74, 0xbfb8aa3b, v74
	v_exp_f32_e32 v76, v76
	v_exp_f32_e32 v72, v72
	v_exp_f32_e32 v73, v73
	v_exp_f32_e32 v74, v74
	v_add_f32_e32 v80, 1.0, v80
	v_add_f32_e32 v81, 1.0, v81
	v_add_f32_e32 v82, 1.0, v82
	v_add_f32_e32 v83, 1.0, v83
	v_rcp_f32_e32 v80, v80
	v_rcp_f32_e32 v81, v81
	v_rcp_f32_e32 v82, v82
	v_rcp_f32_e32 v83, v83
	v_add_f32_e32 v76, 1.0, v76
	v_add_f32_e32 v72, 1.0, v72
	v_add_f32_e32 v73, 1.0, v73
	v_add_f32_e32 v74, 1.0, v74
	v_and_b32_e32 v90, 0xffff0000, v124
	v_lshlrev_b32_e32 v91, 16, v125
	v_and_b32_e32 v92, 0xffff0000, v125
	v_and_b32_e32 v96, 0xffff0000, v127
	v_rcp_f32_e32 v76, v76
	v_rcp_f32_e32 v72, v72
	v_rcp_f32_e32 v73, v73
	v_rcp_f32_e32 v74, v74
	v_lshl_add_u64 v[88:89], v[88:89], 0, s[4:5]
	v_mul_f32_e32 v80, v80, v90
	v_mul_f32_e32 v81, v81, v91
	v_mul_f32_e32 v82, v82, v92
	v_mul_f32_e32 v83, v83, v96
	v_cvt_pk_bf16_f32 v80, v0, v80
	v_cvt_pk_bf16_f32 v81, v81, v82
	v_cvt_pk_bf16_f32 v82, v84, v85
	v_cvt_pk_bf16_f32 v83, v86, v83
	v_lshl_add_u64 v[84:85], v[88:89], 0, v[140:141]
	global_store_dwordx4 v[84:85], v[80:83], off
	v_lshlrev_b32_e32 v0, 16, v112
	v_and_b32_e32 v84, 0xffff0000, v114
	v_lshlrev_b32_e32 v83, 16, v114
	v_lshlrev_b32_e32 v85, 16, v115
	v_mul_f32_e32 v0, v76, v0
	v_mul_f32_e32 v76, v72, v83
	v_mul_f32_e32 v72, 0xbfb8aa3b, v77
	v_mul_f32_e32 v77, v73, v84
	v_mul_f32_e32 v73, 0xbfb8aa3b, v78
	v_mul_f32_e32 v78, v74, v85
	v_mul_f32_e32 v74, 0xbfb8aa3b, v79
	v_exp_f32_e32 v72, v72
	v_exp_f32_e32 v73, v73
	v_exp_f32_e32 v74, v74
	v_mul_f32_e32 v75, 0xbfb8aa3b, v75
	v_exp_f32_e32 v75, v75
	v_add_f32_e32 v72, 1.0, v72
	v_add_f32_e32 v73, 1.0, v73
	v_add_f32_e32 v74, 1.0, v74
	v_rcp_f32_e32 v72, v72
	v_rcp_f32_e32 v73, v73
	v_rcp_f32_e32 v74, v74
	v_add_f32_e32 v75, 1.0, v75
	v_rcp_f32_e32 v75, v75
	v_and_b32_e32 v80, 0xffff0000, v112
	v_lshlrev_b32_e32 v81, 16, v113
	v_and_b32_e32 v82, 0xffff0000, v113
	v_and_b32_e32 v86, 0xffff0000, v115
	v_mul_f32_e32 v72, v72, v80
	v_mul_f32_e32 v73, v73, v81
	v_mul_f32_e32 v74, v74, v82
	v_mul_f32_e32 v75, v75, v86
	v_cvt_pk_bf16_f32 v72, v0, v72
	v_cvt_pk_bf16_f32 v73, v73, v74
	v_cvt_pk_bf16_f32 v74, v76, v77
	v_lshl_add_u64 v[76:77], v[88:89], 0, v[128:129]
	v_add_u32_e32 v100, 0x80, v198
	v_cvt_pk_bf16_f32 v75, v78, v75
	global_store_dwordx4 v[76:77], v[72:75], off
	v_add_u32_e32 v103, 0x90, v198
	v_add_u32_e32 v102, 0xa0, v198
	v_mov_b32_e32 v72, v100
	v_mul_f32_e32 v68, 0xbfb8aa3b, v68
	v_ashrrev_i32_e32 v73, 31, v72
	v_lshlrev_b64 v[72:73], 5, v[72:73]
	v_lshl_add_u64 v[72:73], v[174:175], 0, v[72:73]
	v_lshl_add_u64 v[74:75], v[72:73], 0, v[176:177]
	global_load_dwordx4 v[104:107], v[74:75], off
; __device__ __forceinline__ float sigmoidf_(float v) { return __builtin_amdgcn_rcpf(1.0f + __expf(-v)); }
; __device__ __forceinline__ u32x4 pack8(const f32x4 a, const f32x4 b) { u32x4 w; w.x = cvt_pk_bf16(a[0], a[1]); w.y = cvt_pk_bf16(a[2], a[3]); w.z = cvt_pk_bf16(b[0], b[1]); w.w = cvt_pk_bf16(b[2], b[3]); return w; }
; __device__ __forceinline__ void unpack8(const u32x4 w, f32x4& a, f32x4& b) { a[0] = bf_lo(w.x); a[1] = bf_hi(w.x); a[2] = bf_lo(w.y); a[3] = bf_hi(w.y); b[0] = bf_lo(w.z); b[1] = bf_hi(w.z); b[2] = bf_lo(w.w); b[3] = bf_hi(w.w); }
; #define MEMFENCE asm volatile("" ::: "memory")
;     template <int KIND> __device__ __forceinline__ void run(f32x4 (&acc)[2][2][4][2], const Unit& u, int tid_in) const {
;     ...
;         if constexpr (KIND == K_GLU) {
; #pragma unroll
;             for (int ai = 0; ai < 2; ++ai) { u32x4 yv[4][2];
; #pragma unroll
;                 for (int m = 0; m < 4; ++m) { int row = rbase + ai * 128 + m * 16; asm volatile("" : "+v"(row));
; #pragma unroll
;                     for (int bj = 0; bj < 2; ++bj) { const int col = u.pn * 256 + bj * 128 + cl; yv[m][bj] = *(const u32x4*)(yi + ((size_t)(col >> 4) * T_TOK + row) * 16 + (col & 15)); } }
; #pragma unroll
;                 for (int m = 0; m < 4; ++m) { int row = rbase + ai * 128 + m * 16; asm volatile("" : "+v"(row));
; #pragma unroll
;                     for (int bj = 0; bj < 2; ++bj) { const int col = u.pn * 256 + bj * 128 + cl; f32x4 y0, y1; unpack8(yv[m][bj], y0, y1);
; #pragma unroll
;                         for (int j = 0; j < 4; ++j) { y0[j] *= sigmoidf_(acc[ai][bj][m][0][j]); y1[j] *= sigmoidf_(acc[ai][bj][m][1][j]); }
;                         *(u32x4*)(zb + (size_t)row * ZW + 1024 + col) = pack8(y0, y1); } }
;                 MEMFENCE; }
	v_lshl_add_u64 v[72:73], v[72:73], 0, v[178:179]
	global_load_dwordx4 v[96:99], v[72:73], off
	v_mov_b32_e32 v72, v103
	v_mul_f32_e32 v64, 0xbfb8aa3b, v64
	v_ashrrev_i32_e32 v73, 31, v72
	v_lshlrev_b64 v[72:73], 5, v[72:73]
	v_lshl_add_u64 v[72:73], v[174:175], 0, v[72:73]
	v_lshl_add_u64 v[74:75], v[72:73], 0, v[176:177]
	global_load_dwordx4 v[92:95], v[74:75], off
	v_lshl_add_u64 v[72:73], v[72:73], 0, v[178:179]
	global_load_dwordx4 v[88:91], v[72:73], off
	v_mov_b32_e32 v72, v102
	v_mul_f32_e32 v65, 0xbfb8aa3b, v65
	v_ashrrev_i32_e32 v73, 31, v72
	v_lshlrev_b64 v[72:73], 5, v[72:73]
	v_lshl_add_u64 v[72:73], v[174:175], 0, v[72:73]
	v_lshl_add_u64 v[74:75], v[72:73], 0, v[176:177]
	global_load_dwordx4 v[84:87], v[74:75], off
	v_lshl_add_u64 v[72:73], v[72:73], 0, v[178:179]
	global_load_dwordx4 v[80:83], v[72:73], off
	v_mul_f32_e32 v66, 0xbfb8aa3b, v66
	v_exp_f32_e32 v68, v68
	v_exp_f32_e32 v64, v64
	v_exp_f32_e32 v65, v65
	v_exp_f32_e32 v66, v66
	v_add_u32_e32 v0, 0xb0, v198
	v_mov_b32_e32 v72, v0
	v_add_f32_e32 v68, 1.0, v68
	v_ashrrev_i32_e32 v73, 31, v72
	v_lshlrev_b64 v[72:73], 5, v[72:73]
	v_add_f32_e32 v64, 1.0, v64
	v_add_f32_e32 v65, 1.0, v65
	v_add_f32_e32 v66, 1.0, v66
	v_lshl_add_u64 v[72:73], v[174:175], 0, v[72:73]
	v_rcp_f32_e32 v68, v68
	v_rcp_f32_e32 v64, v64
	v_rcp_f32_e32 v65, v65
	v_rcp_f32_e32 v66, v66
	v_lshl_add_u64 v[74:75], v[72:73], 0, v[176:177]
	global_load_dwordx4 v[76:79], v[74:75], off
	v_mul_f32_e32 v67, 0xbfb8aa3b, v67
	v_exp_f32_e32 v67, v67
	v_mul_f32_e32 v60, 0xbfb8aa3b, v60
	v_mul_f32_e32 v56, 0xbfb8aa3b, v56
	v_mul_f32_e32 v57, 0xbfb8aa3b, v57
	v_mul_f32_e32 v58, 0xbfb8aa3b, v58
	v_exp_f32_e32 v60, v60
	v_exp_f32_e32 v56, v56
	v_exp_f32_e32 v57, v57
	v_exp_f32_e32 v58, v58
	v_add_f32_e32 v67, 1.0, v67
	v_lshl_add_u64 v[72:73], v[72:73], 0, v[178:179]
	v_rcp_f32_e32 v67, v67
	global_load_dwordx4 v[72:75], v[72:73], off
	v_add_f32_e32 v60, 1.0, v60
	v_add_f32_e32 v56, 1.0, v56
	v_add_f32_e32 v57, 1.0, v57
	v_add_f32_e32 v58, 1.0, v58
	v_mad_i64_i32 v[100:101], s[2:3], v100, s76, v[172:173]
	v_rcp_f32_e32 v60, v60
	v_rcp_f32_e32 v56, v56
	v_rcp_f32_e32 v57, v57
	v_rcp_f32_e32 v58, v58
	v_lshl_add_u64 v[100:101], v[100:101], 0, s[4:5]
	v_mul_f32_e32 v59, 0xbfb8aa3b, v59
	v_exp_f32_e32 v59, v59
	v_mul_f32_e32 v52, 0xbfb8aa3b, v52
	v_mul_f32_e32 v48, 0xbfb8aa3b, v48
	v_mul_f32_e32 v49, 0xbfb8aa3b, v49
	v_mul_f32_e32 v50, 0xbfb8aa3b, v50
	v_exp_f32_e32 v52, v52
	v_exp_f32_e32 v48, v48
	v_exp_f32_e32 v49, v49
	v_exp_f32_e32 v50, v50
	s_waitcnt vmcnt(0)
	v_lshlrev_b32_e32 v108, 16, v104
	v_lshlrev_b32_e32 v110, 16, v106
	v_and_b32_e32 v106, 0xffff0000, v106
	v_lshlrev_b32_e32 v111, 16, v107
	v_mul_f32_e32 v68, v68, v108
	v_mul_f32_e32 v108, v64, v110
	v_mul_f32_e32 v64, 0xbfb8aa3b, v69
	v_mul_f32_e32 v69, v65, v106
	v_mul_f32_e32 v65, 0xbfb8aa3b, v70
	v_mul_f32_e32 v70, v66, v111
	v_mul_f32_e32 v66, 0xbfb8aa3b, v71
	v_exp_f32_e32 v64, v64
	v_exp_f32_e32 v65, v65
	v_exp_f32_e32 v66, v66
	v_and_b32_e32 v104, 0xffff0000, v104
	v_add_f32_e32 v64, 1.0, v64
	v_add_f32_e32 v65, 1.0, v65
	v_add_f32_e32 v66, 1.0, v66
	v_rcp_f32_e32 v64, v64
	v_rcp_f32_e32 v65, v65
	v_rcp_f32_e32 v66, v66
	v_lshlrev_b32_e32 v109, 16, v105
	v_and_b32_e32 v105, 0xffff0000, v105
	v_and_b32_e32 v107, 0xffff0000, v107
	v_mul_f32_e32 v64, v64, v104
	v_mul_f32_e32 v65, v65, v109
	v_mul_f32_e32 v66, v66, v105
	v_mul_f32_e32 v67, v67, v107
	v_cvt_pk_bf16_f32 v64, v68, v64
	v_cvt_pk_bf16_f32 v65, v65, v66
	v_cvt_pk_bf16_f32 v66, v108, v69
	v_lshl_add_u64 v[68:69], v[100:101], 0, v[140:141]
	v_cvt_pk_bf16_f32 v67, v70, v67
	global_store_dwordx4 v[68:69], v[64:67], off
	v_lshlrev_b32_e32 v68, 16, v98
	v_and_b32_e32 v69, 0xffff0000, v98
	v_lshlrev_b32_e32 v64, 16, v96
	v_lshlrev_b32_e32 v70, 16, v99
	v_mul_f32_e32 v60, v60, v64
	v_mul_f32_e32 v64, v56, v68
	v_mul_f32_e32 v56, 0xbfb8aa3b, v61
	v_mul_f32_e32 v61, v57, v69
	v_mul_f32_e32 v57, 0xbfb8aa3b, v62
	v_mul_f32_e32 v62, v58, v70
	v_mul_f32_e32 v58, 0xbfb8aa3b, v63
	v_exp_f32_e32 v56, v56
	v_exp_f32_e32 v57, v57
	v_exp_f32_e32 v58, v58
	v_add_f32_e32 v59, 1.0, v59
	v_add_f32_e32 v56, 1.0, v56
	v_add_f32_e32 v57, 1.0, v57
	v_add_f32_e32 v58, 1.0, v58
	v_rcp_f32_e32 v56, v56
	v_rcp_f32_e32 v57, v57
	v_rcp_f32_e32 v58, v58
	v_rcp_f32_e32 v59, v59
	v_add_f32_e32 v52, 1.0, v52
	v_add_f32_e32 v48, 1.0, v48
	v_add_f32_e32 v49, 1.0, v49
	v_add_f32_e32 v50, 1.0, v50
	v_and_b32_e32 v65, 0xffff0000, v96
	v_lshlrev_b32_e32 v66, 16, v97
	v_and_b32_e32 v67, 0xffff0000, v97
	v_rcp_f32_e32 v52, v52
	v_rcp_f32_e32 v48, v48
	v_rcp_f32_e32 v49, v49
	v_rcp_f32_e32 v50, v50
	v_and_b32_e32 v71, 0xffff0000, v99
	v_mul_f32_e32 v56, v56, v65
	v_mul_f32_e32 v57, v57, v66
	v_mul_f32_e32 v58, v58, v67
	v_mul_f32_e32 v59, v59, v71
	v_cvt_pk_bf16_f32 v56, v60, v56
	v_cvt_pk_bf16_f32 v57, v57, v58
	v_cvt_pk_bf16_f32 v58, v64, v61
	v_lshl_add_u64 v[60:61], v[100:101], 0, v[128:129]
	v_cvt_pk_bf16_f32 v59, v62, v59
	global_store_dwordx4 v[60:61], v[56:59], off
	v_lshlrev_b32_e32 v62, 16, v94
	v_and_b32_e32 v63, 0xffff0000, v94
	v_lshlrev_b32_e32 v58, 16, v92
	v_lshlrev_b32_e32 v64, 16, v95
	v_mul_f32_e32 v52, v52, v58
	v_mul_f32_e32 v58, v48, v62
	v_mul_f32_e32 v48, 0xbfb8aa3b, v53
	v_mul_f32_e32 v53, v49, v63
	v_mul_f32_e32 v49, 0xbfb8aa3b, v54
	v_mul_f32_e32 v54, v50, v64
	v_mul_f32_e32 v50, 0xbfb8aa3b, v55
	v_exp_f32_e32 v48, v48
	v_exp_f32_e32 v49, v49
	v_exp_f32_e32 v50, v50
	v_mul_f32_e32 v51, 0xbfb8aa3b, v51
	v_exp_f32_e32 v51, v51
	v_mul_f32_e32 v44, 0xbfb8aa3b, v44
	v_mul_f32_e32 v40, 0xbfb8aa3b, v40
	v_mul_f32_e32 v41, 0xbfb8aa3b, v41
	v_mul_f32_e32 v42, 0xbfb8aa3b, v42
	v_exp_f32_e32 v44, v44
	v_exp_f32_e32 v40, v40
; __device__ __forceinline__ float sigmoidf_(float v) { return __builtin_amdgcn_rcpf(1.0f + __expf(-v)); }
; __device__ __forceinline__ u32x4 pack8(const f32x4 a, const f32x4 b) { u32x4 w; w.x = cvt_pk_bf16(a[0], a[1]); w.y = cvt_pk_bf16(a[2], a[3]); w.z = cvt_pk_bf16(b[0], b[1]); w.w = cvt_pk_bf16(b[2], b[3]); return w; }
; __device__ __forceinline__ void unpack8(const u32x4 w, f32x4& a, f32x4& b) { a[0] = bf_lo(w.x); a[1] = bf_hi(w.x); a[2] = bf_lo(w.y); a[3] = bf_hi(w.y); b[0] = bf_lo(w.z); b[1] = bf_hi(w.z); b[2] = bf_lo(w.w); b[3] = bf_hi(w.w); }
; #define MEMFENCE asm volatile("" ::: "memory")
;     template <int KIND> __device__ __forceinline__ void run(f32x4 (&acc)[2][2][4][2], const Unit& u, int tid_in) const {
;     ...
;         if constexpr (KIND == K_GLU) {
; #pragma unroll
;             for (int ai = 0; ai < 2; ++ai) { u32x4 yv[4][2];
; #pragma unroll
;                 for (int m = 0; m < 4; ++m) { int row = rbase + ai * 128 + m * 16; asm volatile("" : "+v"(row));
; #pragma unroll
;                     for (int bj = 0; bj < 2; ++bj) { const int col = u.pn * 256 + bj * 128 + cl; yv[m][bj] = *(const u32x4*)(yi + ((size_t)(col >> 4) * T_TOK + row) * 16 + (col & 15)); } }
; #pragma unroll
;                 for (int m = 0; m < 4; ++m) { int row = rbase + ai * 128 + m * 16; asm volatile("" : "+v"(row));
; #pragma unroll
;                     for (int bj = 0; bj < 2; ++bj) { const int col = u.pn * 256 + bj * 128 + cl; f32x4 y0, y1; unpack8(yv[m][bj], y0, y1);
; #pragma unroll
;                         for (int j = 0; j < 4; ++j) { y0[j] *= sigmoidf_(acc[ai][bj][m][0][j]); y1[j] *= sigmoidf_(acc[ai][bj][m][1][j]); }
;                         *(u32x4*)(zb + (size_t)row * ZW + 1024 + col) = pack8(y0, y1); } }
;                 MEMFENCE; }
	v_exp_f32_e32 v41, v41
	v_exp_f32_e32 v42, v42
	v_add_f32_e32 v48, 1.0, v48
	v_add_f32_e32 v49, 1.0, v49
	v_add_f32_e32 v50, 1.0, v50
	v_rcp_f32_e32 v48, v48
	v_rcp_f32_e32 v49, v49
	v_rcp_f32_e32 v50, v50
	v_add_f32_e32 v51, 1.0, v51
	v_rcp_f32_e32 v51, v51
	v_add_f32_e32 v44, 1.0, v44
	v_add_f32_e32 v40, 1.0, v40
	v_add_f32_e32 v41, 1.0, v41
	v_add_f32_e32 v42, 1.0, v42
	v_and_b32_e32 v59, 0xffff0000, v92
	v_mad_i64_i32 v[56:57], s[2:3], v103, s76, v[172:173]
	v_lshlrev_b32_e32 v60, 16, v93
	v_and_b32_e32 v61, 0xffff0000, v93
	v_rcp_f32_e32 v44, v44
	v_rcp_f32_e32 v40, v40
	v_rcp_f32_e32 v41, v41
	v_rcp_f32_e32 v42, v42
	v_lshl_add_u64 v[56:57], v[56:57], 0, s[4:5]
	v_and_b32_e32 v65, 0xffff0000, v95
	v_mul_f32_e32 v48, v48, v59
	v_mul_f32_e32 v49, v49, v60
	v_mul_f32_e32 v50, v50, v61
	v_mul_f32_e32 v51, v51, v65
	v_cvt_pk_bf16_f32 v48, v52, v48
	v_cvt_pk_bf16_f32 v49, v49, v50
	v_cvt_pk_bf16_f32 v50, v58, v53
	v_lshl_add_u64 v[52:53], v[56:57], 0, v[140:141]
	v_cvt_pk_bf16_f32 v51, v54, v51
	global_store_dwordx4 v[52:53], v[48:51], off
	v_lshlrev_b32_e32 v52, 16, v90
	v_and_b32_e32 v53, 0xffff0000, v90
	v_lshlrev_b32_e32 v48, 16, v88
	v_lshlrev_b32_e32 v54, 16, v91
	v_mul_f32_e32 v44, v44, v48
	v_mul_f32_e32 v48, v40, v52
	v_mul_f32_e32 v40, 0xbfb8aa3b, v45
	v_mul_f32_e32 v45, v41, v53
	v_mul_f32_e32 v41, 0xbfb8aa3b, v46
	v_mul_f32_e32 v46, v42, v54
	v_mul_f32_e32 v42, 0xbfb8aa3b, v47
	v_exp_f32_e32 v40, v40
	v_exp_f32_e32 v41, v41
	v_exp_f32_e32 v42, v42
	v_mul_f32_e32 v43, 0xbfb8aa3b, v43
	v_exp_f32_e32 v43, v43
	v_mul_f32_e32 v36, 0xbfb8aa3b, v36
	v_mul_f32_e32 v32, 0xbfb8aa3b, v32
	v_mul_f32_e32 v33, 0xbfb8aa3b, v33
	v_mul_f32_e32 v34, 0xbfb8aa3b, v34
	v_exp_f32_e32 v36, v36
	v_exp_f32_e32 v32, v32
	v_exp_f32_e32 v33, v33
	v_exp_f32_e32 v34, v34
	v_add_f32_e32 v40, 1.0, v40
	v_add_f32_e32 v41, 1.0, v41
	v_add_f32_e32 v42, 1.0, v42
	v_rcp_f32_e32 v40, v40
	v_rcp_f32_e32 v41, v41
	v_rcp_f32_e32 v42, v42
	v_add_f32_e32 v43, 1.0, v43
	v_rcp_f32_e32 v43, v43
	v_add_f32_e32 v36, 1.0, v36
	v_add_f32_e32 v32, 1.0, v32
	v_add_f32_e32 v33, 1.0, v33
	v_add_f32_e32 v34, 1.0, v34
	v_and_b32_e32 v49, 0xffff0000, v88
	v_lshlrev_b32_e32 v50, 16, v89
	v_and_b32_e32 v51, 0xffff0000, v89
	v_rcp_f32_e32 v36, v36
	v_rcp_f32_e32 v32, v32
	v_rcp_f32_e32 v33, v33
	v_rcp_f32_e32 v34, v34
	v_and_b32_e32 v55, 0xffff0000, v91
	v_mul_f32_e32 v40, v40, v49
	v_mul_f32_e32 v41, v41, v50
	v_mul_f32_e32 v42, v42, v51
	v_mul_f32_e32 v43, v43, v55
	v_cvt_pk_bf16_f32 v40, v44, v40
	v_cvt_pk_bf16_f32 v41, v41, v42
	v_cvt_pk_bf16_f32 v42, v48, v45
	v_lshl_add_u64 v[44:45], v[56:57], 0, v[128:129]
	v_cvt_pk_bf16_f32 v43, v46, v43
	global_store_dwordx4 v[44:45], v[40:43], off
	v_lshlrev_b32_e32 v46, 16, v86
	v_and_b32_e32 v47, 0xffff0000, v86
	v_lshlrev_b32_e32 v42, 16, v84
	v_lshlrev_b32_e32 v48, 16, v87
	v_mul_f32_e32 v36, v36, v42
	v_mul_f32_e32 v42, v32, v46
	v_mul_f32_e32 v32, 0xbfb8aa3b, v37
	v_mul_f32_e32 v37, v33, v47
	v_mul_f32_e32 v33, 0xbfb8aa3b, v38
	v_mul_f32_e32 v38, v34, v48
	v_mul_f32_e32 v34, 0xbfb8aa3b, v39
	v_exp_f32_e32 v32, v32
	v_exp_f32_e32 v33, v33
	v_exp_f32_e32 v34, v34
	v_mul_f32_e32 v35, 0xbfb8aa3b, v35
	v_exp_f32_e32 v35, v35
	v_mul_f32_e32 v28, 0xbfb8aa3b, v28
	v_mul_f32_e32 v24, 0xbfb8aa3b, v24
	v_mul_f32_e32 v25, 0xbfb8aa3b, v25
	v_mul_f32_e32 v26, 0xbfb8aa3b, v26
	v_exp_f32_e32 v28, v28
	v_exp_f32_e32 v24, v24
	v_exp_f32_e32 v25, v25
	v_exp_f32_e32 v26, v26
	v_add_f32_e32 v32, 1.0, v32
	v_add_f32_e32 v33, 1.0, v33
	v_add_f32_e32 v34, 1.0, v34
	v_rcp_f32_e32 v32, v32
	v_rcp_f32_e32 v33, v33
	v_rcp_f32_e32 v34, v34
	v_add_f32_e32 v35, 1.0, v35
	v_rcp_f32_e32 v35, v35
	v_add_f32_e32 v28, 1.0, v28
	v_add_f32_e32 v24, 1.0, v24
	v_add_f32_e32 v25, 1.0, v25
	v_add_f32_e32 v26, 1.0, v26
	v_and_b32_e32 v43, 0xffff0000, v84
	v_mad_i64_i32 v[40:41], s[2:3], v102, s76, v[172:173]
	v_lshlrev_b32_e32 v44, 16, v85
	v_and_b32_e32 v45, 0xffff0000, v85
	v_rcp_f32_e32 v28, v28
	v_rcp_f32_e32 v24, v24
	v_rcp_f32_e32 v25, v25
	v_rcp_f32_e32 v26, v26
	v_lshl_add_u64 v[40:41], v[40:41], 0, s[4:5]
	v_and_b32_e32 v49, 0xffff0000, v87
	v_mul_f32_e32 v32, v32, v43
	v_mul_f32_e32 v33, v33, v44
	v_mul_f32_e32 v34, v34, v45
	v_mul_f32_e32 v35, v35, v49
	v_cvt_pk_bf16_f32 v32, v36, v32
	v_cvt_pk_bf16_f32 v33, v33, v34
	v_cvt_pk_bf16_f32 v34, v42, v37
	v_lshl_add_u64 v[36:37], v[40:41], 0, v[140:141]
	v_cvt_pk_bf16_f32 v35, v38, v35
	global_store_dwordx4 v[36:37], v[32:35], off
	v_lshlrev_b32_e32 v36, 16, v82
	v_and_b32_e32 v37, 0xffff0000, v82
	v_lshlrev_b32_e32 v32, 16, v80
	v_lshlrev_b32_e32 v38, 16, v83
	v_mul_f32_e32 v28, v28, v32
; __device__ __forceinline__ float sigmoidf_(float v) { return __builtin_amdgcn_rcpf(1.0f + __expf(-v)); }
; __device__ __forceinline__ u32x4 pack8(const f32x4 a, const f32x4 b) { u32x4 w; w.x = cvt_pk_bf16(a[0], a[1]); w.y = cvt_pk_bf16(a[2], a[3]); w.z = cvt_pk_bf16(b[0], b[1]); w.w = cvt_pk_bf16(b[2], b[3]); return w; }
; __device__ __forceinline__ void unpack8(const u32x4 w, f32x4& a, f32x4& b) { a[0] = bf_lo(w.x); a[1] = bf_hi(w.x); a[2] = bf_lo(w.y); a[3] = bf_hi(w.y); b[0] = bf_lo(w.z); b[1] = bf_hi(w.z); b[2] = bf_lo(w.w); b[3] = bf_hi(w.w); }
; #define MEMFENCE asm volatile("" ::: "memory")
;     template <int KIND> __device__ __forceinline__ void run(f32x4 (&acc)[2][2][4][2], const Unit& u, int tid_in) const {
;     ...
;         if constexpr (KIND == K_GLU) {
; #pragma unroll
;             for (int ai = 0; ai < 2; ++ai) { u32x4 yv[4][2];
; #pragma unroll
;                 for (int m = 0; m < 4; ++m) { int row = rbase + ai * 128 + m * 16; asm volatile("" : "+v"(row));
; #pragma unroll
;                     for (int bj = 0; bj < 2; ++bj) { const int col = u.pn * 256 + bj * 128 + cl; yv[m][bj] = *(const u32x4*)(yi + ((size_t)(col >> 4) * T_TOK + row) * 16 + (col & 15)); } }
; #pragma unroll
;                 for (int m = 0; m < 4; ++m) { int row = rbase + ai * 128 + m * 16; asm volatile("" : "+v"(row));
; #pragma unroll
;                     for (int bj = 0; bj < 2; ++bj) { const int col = u.pn * 256 + bj * 128 + cl; f32x4 y0, y1; unpack8(yv[m][bj], y0, y1);
; #pragma unroll
;                         for (int j = 0; j < 4; ++j) { y0[j] *= sigmoidf_(acc[ai][bj][m][0][j]); y1[j] *= sigmoidf_(acc[ai][bj][m][1][j]); }
;                         *(u32x4*)(zb + (size_t)row * ZW + 1024 + col) = pack8(y0, y1); } }
;                 MEMFENCE; }
;     ...
;         E.template run<cs.kind>(acc, cur, tid);
;         if (!has_next) break;
;         if (!(cs.kind == K_MG_B && cur.aux < 2))
	v_mul_f32_e32 v32, v24, v36
	v_mul_f32_e32 v24, 0xbfb8aa3b, v29
	v_mul_f32_e32 v29, v25, v37
	v_mul_f32_e32 v25, 0xbfb8aa3b, v30
	v_mul_f32_e32 v30, v26, v38
	v_mul_f32_e32 v26, 0xbfb8aa3b, v31
	v_exp_f32_e32 v24, v24
	v_exp_f32_e32 v25, v25
	v_exp_f32_e32 v26, v26
	v_mul_f32_e32 v27, 0xbfb8aa3b, v27
	v_exp_f32_e32 v27, v27
	v_mul_f32_e32 v20, 0xbfb8aa3b, v20
	v_mul_f32_e32 v16, 0xbfb8aa3b, v16
	v_mul_f32_e32 v17, 0xbfb8aa3b, v17
	v_mul_f32_e32 v18, 0xbfb8aa3b, v18
	v_add_f32_e32 v24, 1.0, v24
	v_add_f32_e32 v25, 1.0, v25
	v_add_f32_e32 v26, 1.0, v26
	v_exp_f32_e32 v20, v20
	v_exp_f32_e32 v16, v16
	v_exp_f32_e32 v17, v17
	v_exp_f32_e32 v18, v18
	v_rcp_f32_e32 v24, v24
	v_rcp_f32_e32 v25, v25
	v_rcp_f32_e32 v26, v26
	v_add_f32_e32 v27, 1.0, v27
	v_rcp_f32_e32 v27, v27
	v_and_b32_e32 v33, 0xffff0000, v80
	v_lshlrev_b32_e32 v34, 16, v81
	v_and_b32_e32 v35, 0xffff0000, v81
	v_add_f32_e32 v20, 1.0, v20
	v_add_f32_e32 v16, 1.0, v16
	v_add_f32_e32 v17, 1.0, v17
	v_add_f32_e32 v18, 1.0, v18
	v_and_b32_e32 v39, 0xffff0000, v83
	v_mul_f32_e32 v24, v24, v33
	v_mul_f32_e32 v25, v25, v34
	v_mul_f32_e32 v26, v26, v35
	v_rcp_f32_e32 v20, v20
	v_rcp_f32_e32 v16, v16
	v_rcp_f32_e32 v17, v17
	v_rcp_f32_e32 v18, v18
	v_mul_f32_e32 v27, v27, v39
	v_cvt_pk_bf16_f32 v24, v28, v24
	v_cvt_pk_bf16_f32 v25, v25, v26
	v_cvt_pk_bf16_f32 v26, v32, v29
	v_lshl_add_u64 v[28:29], v[40:41], 0, v[128:129]
	v_cvt_pk_bf16_f32 v27, v30, v27
	global_store_dwordx4 v[28:29], v[24:27], off
	v_lshlrev_b32_e32 v29, 16, v78
	v_and_b32_e32 v30, 0xffff0000, v78
	v_mad_i64_i32 v[24:25], s[2:3], v0, s76, v[172:173]
	v_lshlrev_b32_e32 v0, 16, v76
	v_lshlrev_b32_e32 v31, 16, v79
	v_mul_f32_e32 v0, v20, v0
	v_mul_f32_e32 v20, v16, v29
	v_mul_f32_e32 v16, 0xbfb8aa3b, v21
	v_mul_f32_e32 v21, v17, v30
	v_mul_f32_e32 v17, 0xbfb8aa3b, v22
	v_mul_f32_e32 v22, v18, v31
	v_mul_f32_e32 v18, 0xbfb8aa3b, v23
	v_mul_f32_e32 v19, 0xbfb8aa3b, v19
	v_exp_f32_e32 v16, v16
	v_exp_f32_e32 v17, v17
	v_exp_f32_e32 v18, v18
	v_exp_f32_e32 v19, v19
	v_mul_f32_e32 v12, 0xbfb8aa3b, v12
	v_mul_f32_e32 v8, 0xbfb8aa3b, v8
	v_mul_f32_e32 v9, 0xbfb8aa3b, v9
	v_mul_f32_e32 v10, 0xbfb8aa3b, v10
	v_exp_f32_e32 v12, v12
	v_exp_f32_e32 v8, v8
	v_exp_f32_e32 v9, v9
	v_exp_f32_e32 v10, v10
	v_add_f32_e32 v16, 1.0, v16
	v_add_f32_e32 v17, 1.0, v17
	v_add_f32_e32 v18, 1.0, v18
	v_add_f32_e32 v19, 1.0, v19
	v_rcp_f32_e32 v16, v16
	v_rcp_f32_e32 v17, v17
	v_rcp_f32_e32 v18, v18
	v_rcp_f32_e32 v19, v19
	v_add_f32_e32 v12, 1.0, v12
	v_add_f32_e32 v8, 1.0, v8
	v_add_f32_e32 v9, 1.0, v9
	v_add_f32_e32 v10, 1.0, v10
	v_and_b32_e32 v26, 0xffff0000, v76
	v_lshlrev_b32_e32 v27, 16, v77
	v_and_b32_e32 v28, 0xffff0000, v77
	v_and_b32_e32 v32, 0xffff0000, v79
	v_rcp_f32_e32 v12, v12
	v_rcp_f32_e32 v8, v8
	v_rcp_f32_e32 v9, v9
	v_rcp_f32_e32 v10, v10
	v_lshl_add_u64 v[24:25], v[24:25], 0, s[4:5]
	v_mul_f32_e32 v16, v16, v26
	v_mul_f32_e32 v17, v17, v27
	v_mul_f32_e32 v18, v18, v28
	v_mul_f32_e32 v19, v19, v32
	v_cvt_pk_bf16_f32 v16, v0, v16
	v_cvt_pk_bf16_f32 v17, v17, v18
	v_cvt_pk_bf16_f32 v18, v20, v21
	v_cvt_pk_bf16_f32 v19, v22, v19
	v_lshl_add_u64 v[20:21], v[24:25], 0, v[140:141]
	global_store_dwordx4 v[20:21], v[16:19], off
	v_lshlrev_b32_e32 v0, 16, v72
	v_and_b32_e32 v20, 0xffff0000, v74
	v_lshlrev_b32_e32 v19, 16, v74
	v_lshlrev_b32_e32 v21, 16, v75
	v_mul_f32_e32 v0, v12, v0
	v_mul_f32_e32 v12, v8, v19
	v_mul_f32_e32 v8, 0xbfb8aa3b, v13
	v_mul_f32_e32 v13, v9, v20
	v_mul_f32_e32 v9, 0xbfb8aa3b, v14
	v_mul_f32_e32 v14, v10, v21
	v_mul_f32_e32 v10, 0xbfb8aa3b, v15
	v_exp_f32_e32 v8, v8
	v_exp_f32_e32 v9, v9
	v_exp_f32_e32 v10, v10
	v_mul_f32_e32 v11, 0xbfb8aa3b, v11
	v_exp_f32_e32 v11, v11
	v_add_f32_e32 v8, 1.0, v8
	v_add_f32_e32 v9, 1.0, v9
	v_add_f32_e32 v10, 1.0, v10
	v_rcp_f32_e32 v8, v8
	v_rcp_f32_e32 v9, v9
	v_rcp_f32_e32 v10, v10
	v_add_f32_e32 v11, 1.0, v11
	v_rcp_f32_e32 v11, v11
	v_and_b32_e32 v16, 0xffff0000, v72
	v_lshlrev_b32_e32 v17, 16, v73
	v_and_b32_e32 v18, 0xffff0000, v73
	v_and_b32_e32 v22, 0xffff0000, v75
	v_mul_f32_e32 v8, v8, v16
	v_mul_f32_e32 v9, v9, v17
	v_mul_f32_e32 v10, v10, v18
	v_mul_f32_e32 v11, v11, v22
	v_cvt_pk_bf16_f32 v8, v0, v8
	v_cvt_pk_bf16_f32 v9, v9, v10
	v_cvt_pk_bf16_f32 v10, v12, v13
	v_lshl_add_u64 v[12:13], v[24:25], 0, v[128:129]
	v_cvt_pk_bf16_f32 v11, v14, v11
	global_store_dwordx4 v[12:13], v[8:11], off
	s_and_b64 vcc, exec, s[10:11]
	s_mov_b32 s33, s34
	s_mov_b32 s35, s12
	s_mov_b64 s[18:19], s[16:17]
	s_mov_b64 s[2:3], s[14:15]
	s_cbranch_vccz .LBB0_799
	s_cmpk_gt_u32 s101, 0xff
	s_cbranch_scc0 .Ldbj_GLU_pe
	s_barrier
	s_mov_b32 s101, 0

; #define G_STAGE(bufoff, gbase, o0, h64) do { \
;         __builtin_amdgcn_global_load_lds((const unsigned*)((const char*)(gbase) + (o0)), (LAS unsigned*)(lds + (bufoff) + ldsw), 16, 0, 0); \
;         __builtin_amdgcn_global_load_lds((const unsigned*)((const char*)(gbase) + (h64) + (o0)), (LAS unsigned*)(lds + (bufoff) + ldsw + 8192), 16, 0, 0); } while (0)
; #define G_LDA(dst, b, h) do { _Pragma("unroll") for (int m = 0; m < 4; ++m) _Pragma("unroll") for (int k = 0; k < 2; ++k) dst[m][k] = *(const LAS bf16x8*)(lds + G_SA(b, h) + aoff + m * 2048 + k * 1024); } while (0)
; #define G_LDB(dst, b, h) do { _Pragma("unroll") for (int n = 0; n < 2; ++n) _Pragma("unroll") for (int k = 0; k < 2; ++k) dst[n][k] = *(const LAS bf16x8*)(lds + G_SB(b, h) + boff + n * 2048 + k * 1024); } while (0)
; #define G_WAIT_L(n) asm volatile("s_waitcnt lgkmcnt(" #n ")" ::: "memory")
; #define G_BAR __builtin_amdgcn_s_barrier()
; #define G_SCHED __builtin_amdgcn_sched_barrier(0)
;     ...
;     for (;;) {
;         const bool has_next = sched_next<PH, SUB>(E.ws, E.layer, ui + 1, nxt, E.x);
;         if (!has_next) nxt = cur;
;         const char* nA = nxt.A; const char* nB = nxt.B;
; #pragma unroll 1
;         for (int t = 0; t < nt; t += 2) {
;             const bool last = (t == nt - 2);
;             const char* a1 = cA + (size_t)(t + 1) * ckA;
;             const char* a2 = last ? nA : cA + (size_t)(t + 2) * ckA; const char* b2 = last ? nB : cB + (size_t)(t + 2) * kB;
;             const char* a3 = a2 + ckA; const char* b3 = b2 + kB;
;             G_LDB(B0, 0, 0); G_SCHED; G_LDA(At, 0, 0); G_STAGE(G_SA(1, 1), a1 + chA, cA0, qA);
;             G_WAIT_L(8); G_BAR; G_WAIT_L(0); G_MMA(0, 0, At, B0); G_BAR; G_SCHED;
;             G_LDB(B1, 0, 1); G_STAGE(G_SB(0, 0), b2, cB0, qB);
;             G_BAR; G_WAIT_L(0); G_MMA(0, 1, At, B1); G_BAR;
;             G_LDA(At, 0, 1); G_STAGE(G_SA(0, 0), a2, cA0, qA);
;             G_BAR; G_WAIT_L(0); G_MMA(1, 0, At, B0); G_BAR; G_SCHED;
;     ...
;         if (!(cs.kind == K_MG_B && cur.aux < 2))
; #pragma unroll
;         for (int a = 0; a < 2; ++a)
; #pragma unroll
;             for (int b = 0; b < 2; ++b)
; #pragma unroll
;                 for (int m = 0; m < 4; ++m)
; #pragma unroll
;                     for (int n = 0; n < 2; ++n) acc[a][b][m][n] = (f32x4){0.f, 0.f, 0.f, 0.f};
;         cur = nxt; cA = nA; cB = nB; ++ui;
.LBB0_871:
	s_add_u32 s2, s2, 0xb0080
	s_addc_u32 s3, s3, 0
	s_add_u32 s37, s12, 0x100
	v_mov_b64_e32 v[8:9], 0
	s_addc_u32 s38, s13, 0
	s_mov_b32 s39, -2
	v_mov_b64_e32 v[10:11], 0
	v_mov_b64_e32 v[12:13], 0
	v_mov_b64_e32 v[14:15], 0
	v_mov_b64_e32 v[24:25], 0
	v_mov_b64_e32 v[26:27], 0
	v_mov_b64_e32 v[28:29], 0
	v_mov_b64_e32 v[30:31], 0
	v_mov_b64_e32 v[40:41], 0
	v_mov_b64_e32 v[42:43], 0
	v_mov_b64_e32 v[44:45], 0
	v_mov_b64_e32 v[46:47], 0
	v_mov_b64_e32 v[56:57], 0
	v_mov_b64_e32 v[58:59], 0
	v_mov_b64_e32 v[60:61], 0
	v_mov_b64_e32 v[62:63], 0
	v_mov_b64_e32 v[16:17], 0
	v_mov_b64_e32 v[18:19], 0
	v_mov_b64_e32 v[20:21], 0
	v_mov_b64_e32 v[22:23], 0
	v_mov_b64_e32 v[36:37], 0
	v_mov_b64_e32 v[38:39], 0
	v_mov_b64_e32 v[32:33], 0
	v_mov_b64_e32 v[34:35], 0
	v_mov_b64_e32 v[52:53], 0
	v_mov_b64_e32 v[54:55], 0
	v_mov_b64_e32 v[48:49], 0
	v_mov_b64_e32 v[50:51], 0
	v_mov_b64_e32 v[68:69], 0
	v_mov_b64_e32 v[70:71], 0
	v_mov_b64_e32 v[64:65], 0
	v_mov_b64_e32 v[66:67], 0
	v_mov_b64_e32 v[72:73], 0
	v_mov_b64_e32 v[74:75], 0
	v_mov_b64_e32 v[76:77], 0
	v_mov_b64_e32 v[78:79], 0
	v_mov_b64_e32 v[88:89], 0
	v_mov_b64_e32 v[90:91], 0
	v_mov_b64_e32 v[92:93], 0
	v_mov_b64_e32 v[94:95], 0
	v_mov_b64_e32 v[104:105], 0
	v_mov_b64_e32 v[106:107], 0
	v_mov_b64_e32 v[108:109], 0
	v_mov_b64_e32 v[110:111], 0
	v_mov_b64_e32 v[120:121], 0
	v_mov_b64_e32 v[122:123], 0
	v_mov_b64_e32 v[124:125], 0
	v_mov_b64_e32 v[126:127], 0
	v_mov_b64_e32 v[84:85], 0
	v_mov_b64_e32 v[86:87], 0
	v_mov_b64_e32 v[80:81], 0
	v_mov_b64_e32 v[82:83], 0
	v_mov_b64_e32 v[100:101], 0
	v_mov_b64_e32 v[102:103], 0
	v_mov_b64_e32 v[96:97], 0
	v_mov_b64_e32 v[98:99], 0
	v_mov_b64_e32 v[116:117], 0
	v_mov_b64_e32 v[118:119], 0
	v_mov_b64_e32 v[112:113], 0
	v_mov_b64_e32 v[114:115], 0
	v_mov_b64_e32 v[132:133], 0
	v_mov_b64_e32 v[134:135], 0
	v_mov_b64_e32 v[128:129], 0
	v_mov_b64_e32 v[130:131], 0
	s_mov_b64 s[42:43], 0x20080
	s_mov_b64 s[50:51], 0x10000
	s_mov_b64 s[52:53], 0x30000
	s_mov_b64 s[54:55], 0x10080
	s_mov_b64 s[58:59], 0x30080
	s_cmpk_gt_u32 s101, 0xff
	s_cbranch_scc0 .Ldbj_MG0_in
	s_barrier
	s_mov_b32 s101, 0
.Ldbj_MG0_in:
.LBB0_872:
	s_add_u32 s4, s2, 0xfff50080
	s_addc_u32 s5, s3, -1
	s_add_i32 s40, 0, 0x10000
	v_add_u32_e32 v140, s40, v159
	ds_read_b128 v[144:147], v140
	ds_read_b128 v[148:151], v140 offset:1024
	ds_read_b128 v[136:139], v140 offset:2048
	ds_read_b128 v[140:143], v140 offset:3072
	s_cmp_eq_u32 s39, 4
	s_cselect_b32 s13, s9, s5
	s_cselect_b32 s12, s8, s4
	s_cselect_b32 s15, s11, s38
	s_cselect_b32 s14, s10, s37
	v_lshl_add_u64 v[154:155], s[2:3], 0, v[152:153]
	s_add_i32 m0, s22, 0xc000
	ds_read_b128 v[160:163], v236
	ds_read_b128 v[164:167], v236 offset:1024
	ds_read_b128 v[176:179], v236 offset:2048
	ds_read_b128 v[180:183], v236 offset:3072
	ds_read_b128 v[196:199], v236 offset:4096
	ds_read_b128 v[200:203], v236 offset:5120
	ds_read_b128 v[204:207], v236 offset:6144
	ds_read_b128 v[208:211], v236 offset:7168
	global_load_lds_dwordx4 v[154:155], off
	v_lshl_add_u64 v[154:155], v[154:155], 0, s[86:87]
	s_add_i32 m0, s22, 0xe000
	s_nop 0
	global_load_lds_dwordx4 v[154:155], off
	s_waitcnt lgkmcnt(8)
	s_barrier
	s_waitcnt lgkmcnt(0)
	s_setprio 3
	s_waitcnt lgkmcnt(0)
	v_mfma_f32_16x16x128_f8f6f4 v[128:131], v[144:151], v[160:167], v[128:131]
	v_mfma_f32_16x16x128_f8f6f4 v[132:135], v[136:143], v[160:167], v[132:135]
	v_mfma_f32_16x16x128_f8f6f4 v[112:115], v[144:151], v[176:183], v[112:115]
	v_mfma_f32_16x16x128_f8f6f4 v[116:119], v[136:143], v[176:183], v[116:119]
	v_mfma_f32_16x16x128_f8f6f4 v[96:99], v[144:151], v[196:203], v[96:99]
	v_mfma_f32_16x16x128_f8f6f4 v[100:103], v[136:143], v[196:203], v[100:103]
	v_mfma_f32_16x16x128_f8f6f4 v[80:83], v[144:151], v[204:211], v[80:83]
	v_mfma_f32_16x16x128_f8f6f4 v[84:87], v[136:143], v[204:211], v[84:87]
	s_setprio 0
	s_barrier
	s_add_i32 s4, 0, 0x14000
	v_add_u32_e32 v154, s4, v159
	s_add_i32 s5, s40, s17
	ds_read_b128 v[212:215], v154
	ds_read_b128 v[216:219], v154 offset:1024
	ds_read_b128 v[220:223], v154 offset:2048
	ds_read_b128 v[224:227], v154 offset:3072
	v_lshl_add_u64 v[154:155], s[14:15], 0, v[0:1]
	s_mov_b32 m0, s5
	v_lshl_add_u64 v[156:157], v[154:155], 0, s[50:51]
	global_load_lds_dwordx4 v[154:155], off
	s_add_i32 m0, s5, 0x2000
	s_nop 0
	global_load_lds_dwordx4 v[156:157], off
	s_barrier
	s_waitcnt lgkmcnt(0)
	s_setprio 3
	s_waitcnt lgkmcnt(0)
	v_mfma_f32_16x16x128_f8f6f4 v[124:127], v[212:219], v[160:167], v[124:127]
	v_mfma_f32_16x16x128_f8f6f4 v[120:123], v[220:227], v[160:167], v[120:123]
	v_mfma_f32_16x16x128_f8f6f4 v[108:111], v[212:219], v[176:183], v[108:111]
	v_mfma_f32_16x16x128_f8f6f4 v[104:107], v[220:227], v[176:183], v[104:107]
	v_mfma_f32_16x16x128_f8f6f4 v[92:95], v[212:219], v[196:203], v[92:95]
	v_mfma_f32_16x16x128_f8f6f4 v[88:91], v[220:227], v[196:203], v[88:91]
	v_mfma_f32_16x16x128_f8f6f4 v[76:79], v[212:219], v[204:211], v[76:79]
	v_mfma_f32_16x16x128_f8f6f4 v[72:75], v[220:227], v[204:211], v[72:75]
	s_setprio 0
	s_mov_b32 m0, s22
	v_lshl_add_u64 v[156:157], s[12:13], 0, v[2:3]
	s_barrier
	ds_read_b128 v[160:163], v236 offset:16384
	ds_read_b128 v[164:167], v236 offset:17408
	ds_read_b128 v[176:179], v236 offset:18432
	ds_read_b128 v[180:183], v236 offset:19456
	ds_read_b128 v[196:199], v236 offset:20480
	ds_read_b128 v[200:203], v236 offset:21504
	ds_read_b128 v[204:207], v236 offset:22528
	ds_read_b128 v[208:211], v236 offset:23552
	global_load_lds_dwordx4 v[156:157], off
	v_lshl_add_u64 v[234:235], v[156:157], 0, s[86:87]
	s_mov_b32 m0, s23
	s_nop 0
	global_load_lds_dwordx4 v[234:235], off
	s_barrier
; #define G_STAGE(bufoff, gbase, o0, h64) do { \
;         __builtin_amdgcn_global_load_lds((const unsigned*)((const char*)(gbase) + (o0)), (LAS unsigned*)(lds + (bufoff) + ldsw), 16, 0, 0); \
;         __builtin_amdgcn_global_load_lds((const unsigned*)((const char*)(gbase) + (h64) + (o0)), (LAS unsigned*)(lds + (bufoff) + ldsw + 8192), 16, 0, 0); } while (0)
; #define G_LDA(dst, b, h) do { _Pragma("unroll") for (int m = 0; m < 4; ++m) _Pragma("unroll") for (int k = 0; k < 2; ++k) dst[m][k] = *(const LAS bf16x8*)(lds + G_SA(b, h) + aoff + m * 2048 + k * 1024); } while (0)
; #define G_LDB(dst, b, h) do { _Pragma("unroll") for (int n = 0; n < 2; ++n) _Pragma("unroll") for (int k = 0; k < 2; ++k) dst[n][k] = *(const LAS bf16x8*)(lds + G_SB(b, h) + boff + n * 2048 + k * 1024); } while (0)
; #define G_WAIT_V(n) asm volatile("s_waitcnt vmcnt(" #n ")" ::: "memory")
; #define G_WAIT_L(n) asm volatile("s_waitcnt lgkmcnt(" #n ")" ::: "memory")
; #define G_BAR __builtin_amdgcn_s_barrier()
; #define G_SCHED __builtin_amdgcn_sched_barrier(0)
;     ...
;             G_BAR; G_WAIT_L(0); G_MMA(1, 0, At, B0); G_BAR; G_SCHED;
;             G_STAGE(G_SB(0, 1), b2 + chB, cB0, qB);
;             G_WAIT_V(6); G_BAR; G_MMA(1, 1, At, B1); G_BAR;
;             G_LDB(B0, 1, 0); G_SCHED; G_LDA(At, 1, 0); G_STAGE(G_SA(0, 1), a2 + chA, cA0, qA);
;             G_WAIT_L(8); G_BAR; G_WAIT_L(0); G_MMA(0, 0, At, B0); G_BAR; G_SCHED;
;             G_LDB(B1, 1, 1); G_STAGE(G_SB(1, 0), b3, cB0, qB);
;             G_BAR; G_WAIT_L(0); G_MMA(0, 1, At, B1); G_BAR;
;             G_LDA(At, 1, 1); G_STAGE(G_SA(1, 0), a3, cA0, qA);
;             G_BAR; G_WAIT_L(0); G_MMA(1, 0, At, B0); G_BAR; G_SCHED;
;             G_STAGE(G_SB(1, 1), b3 + chB, cB0, qB);
;             G_WAIT_V(6); G_BAR; G_MMA(1, 1, At, B1); G_BAR;
;         }
	s_waitcnt lgkmcnt(0)
	s_setprio 3
	s_waitcnt lgkmcnt(0)
	v_mfma_f32_16x16x128_f8f6f4 v[64:67], v[144:151], v[160:167], v[64:67]
	v_mfma_f32_16x16x128_f8f6f4 v[68:71], v[136:143], v[160:167], v[68:71]
	v_mfma_f32_16x16x128_f8f6f4 v[48:51], v[144:151], v[176:183], v[48:51]
	v_mfma_f32_16x16x128_f8f6f4 v[52:55], v[136:143], v[176:183], v[52:55]
	v_mfma_f32_16x16x128_f8f6f4 v[32:35], v[144:151], v[196:203], v[32:35]
	v_mfma_f32_16x16x128_f8f6f4 v[36:39], v[136:143], v[196:203], v[36:39]
	v_mfma_f32_16x16x128_f8f6f4 v[20:23], v[144:151], v[204:211], v[20:23]
	v_mfma_f32_16x16x128_f8f6f4 v[16:19], v[136:143], v[204:211], v[16:19]
	s_setprio 0
	s_barrier
	s_add_i32 s4, s4, s17
	v_lshl_add_u64 v[140:141], v[154:155], 0, s[0:1]
	s_mov_b32 m0, s4
	s_nop 0
	global_load_lds_dwordx4 v[140:141], off
	v_lshl_add_u64 v[140:141], v[154:155], 0, s[52:53]
	s_add_i32 m0, s4, 0x2000
	s_nop 0
	global_load_lds_dwordx4 v[140:141], off
	s_waitcnt vmcnt(6)
	s_barrier
	s_setprio 3
	v_mfma_f32_16x16x128_f8f6f4 v[60:63], v[212:219], v[160:167], v[60:63]
	v_mfma_f32_16x16x128_f8f6f4 v[56:59], v[220:227], v[160:167], v[56:59]
	v_mfma_f32_16x16x128_f8f6f4 v[44:47], v[212:219], v[176:183], v[44:47]
	v_mfma_f32_16x16x128_f8f6f4 v[40:43], v[220:227], v[176:183], v[40:43]
	v_mfma_f32_16x16x128_f8f6f4 v[28:31], v[212:219], v[196:203], v[28:31]
	v_mfma_f32_16x16x128_f8f6f4 v[24:27], v[220:227], v[196:203], v[24:27]
	v_mfma_f32_16x16x128_f8f6f4 v[12:15], v[212:219], v[204:211], v[12:15]
	v_mfma_f32_16x16x128_f8f6f4 v[8:11], v[220:227], v[204:211], v[8:11]
	s_setprio 0
	s_add_i32 s4, 0, 0x18000
	v_add_u32_e32 v140, s4, v159
	s_barrier
	ds_read_b128 v[144:147], v140
	ds_read_b128 v[148:151], v140 offset:1024
	ds_read_b128 v[136:139], v140 offset:2048
	ds_read_b128 v[140:143], v140 offset:3072
	s_mov_b32 m0, s24
	v_lshl_add_u64 v[234:235], v[156:157], 0, s[88:89]
	ds_read_b128 v[160:163], v236 offset:32768
	ds_read_b128 v[164:167], v236 offset:33792
	ds_read_b128 v[176:179], v236 offset:34816
	ds_read_b128 v[180:183], v236 offset:35840
	ds_read_b128 v[196:199], v236 offset:36864
	ds_read_b128 v[200:203], v236 offset:37888
	ds_read_b128 v[204:207], v236 offset:38912
	ds_read_b128 v[208:211], v236 offset:39936
	global_load_lds_dwordx4 v[234:235], off
	v_lshl_add_u64 v[234:235], v[156:157], 0, s[64:65]
	s_mov_b32 m0, s25
	s_nop 0
	global_load_lds_dwordx4 v[234:235], off
	s_waitcnt lgkmcnt(8)
	s_barrier
	s_waitcnt lgkmcnt(0)
	s_setprio 3
	s_waitcnt lgkmcnt(0)
	v_mfma_f32_16x16x128_f8f6f4 v[128:131], v[144:151], v[160:167], v[128:131]
	v_mfma_f32_16x16x128_f8f6f4 v[132:135], v[136:143], v[160:167], v[132:135]
	v_mfma_f32_16x16x128_f8f6f4 v[112:115], v[144:151], v[176:183], v[112:115]
	v_mfma_f32_16x16x128_f8f6f4 v[116:119], v[136:143], v[176:183], v[116:119]
	v_mfma_f32_16x16x128_f8f6f4 v[96:99], v[144:151], v[196:203], v[96:99]
	v_mfma_f32_16x16x128_f8f6f4 v[100:103], v[136:143], v[196:203], v[100:103]
	v_mfma_f32_16x16x128_f8f6f4 v[80:83], v[144:151], v[204:211], v[80:83]
	v_mfma_f32_16x16x128_f8f6f4 v[84:87], v[136:143], v[204:211], v[84:87]
	s_setprio 0
	s_barrier
	s_add_i32 s5, 0, 0x1c000
	s_add_i32 s4, s4, s17
	v_add_u32_e32 v237, s5, v159
	v_lshl_add_u64 v[234:235], v[154:155], 0, s[46:47]
	s_mov_b32 m0, s4
	ds_read_b128 v[212:215], v237
	ds_read_b128 v[216:219], v237 offset:1024
	ds_read_b128 v[220:223], v237 offset:2048
	ds_read_b128 v[224:227], v237 offset:3072
	global_load_lds_dwordx4 v[234:235], off
	v_lshl_add_u64 v[234:235], v[154:155], 0, s[54:55]
	s_add_i32 m0, s4, 0x2000
	s_nop 0
	global_load_lds_dwordx4 v[234:235], off
	s_barrier
	s_waitcnt lgkmcnt(0)
	s_setprio 3
	s_waitcnt lgkmcnt(0)
	v_mfma_f32_16x16x128_f8f6f4 v[124:127], v[212:219], v[160:167], v[124:127]
	v_mfma_f32_16x16x128_f8f6f4 v[120:123], v[220:227], v[160:167], v[120:123]
	v_mfma_f32_16x16x128_f8f6f4 v[108:111], v[212:219], v[176:183], v[108:111]
	v_mfma_f32_16x16x128_f8f6f4 v[104:107], v[220:227], v[176:183], v[104:107]
	v_mfma_f32_16x16x128_f8f6f4 v[92:95], v[212:219], v[196:203], v[92:95]
	v_mfma_f32_16x16x128_f8f6f4 v[88:91], v[220:227], v[196:203], v[88:91]
	v_mfma_f32_16x16x128_f8f6f4 v[76:79], v[212:219], v[204:211], v[76:79]
	v_mfma_f32_16x16x128_f8f6f4 v[72:75], v[220:227], v[204:211], v[72:75]
	s_setprio 0
	s_mov_b32 m0, s26
	v_lshl_add_u64 v[234:235], v[156:157], 0, s[46:47]
	s_barrier
	ds_read_b128 v[160:163], v236 offset:49152
	ds_read_b128 v[164:167], v236 offset:50176
	ds_read_b128 v[176:179], v236 offset:51200
	ds_read_b128 v[180:183], v236 offset:52224
	ds_read_b128 v[196:199], v236 offset:53248
	ds_read_b128 v[200:203], v236 offset:54272
	ds_read_b128 v[204:207], v236 offset:55296
	ds_read_b128 v[208:211], v236 offset:56320
	global_load_lds_dwordx4 v[234:235], off
	v_lshl_add_u64 v[156:157], v[156:157], 0, s[66:67]
	s_mov_b32 m0, s27
	s_nop 0
	global_load_lds_dwordx4 v[156:157], off
	s_barrier
	s_waitcnt lgkmcnt(0)
	s_setprio 3
	s_waitcnt lgkmcnt(0)
	v_mfma_f32_16x16x128_f8f6f4 v[64:67], v[144:151], v[160:167], v[64:67]
	v_mfma_f32_16x16x128_f8f6f4 v[68:71], v[136:143], v[160:167], v[68:71]
	v_mfma_f32_16x16x128_f8f6f4 v[48:51], v[144:151], v[176:183], v[48:51]
	v_mfma_f32_16x16x128_f8f6f4 v[52:55], v[136:143], v[176:183], v[52:55]
	v_mfma_f32_16x16x128_f8f6f4 v[32:35], v[144:151], v[196:203], v[32:35]
	v_mfma_f32_16x16x128_f8f6f4 v[36:39], v[136:143], v[196:203], v[36:39]
	v_mfma_f32_16x16x128_f8f6f4 v[20:23], v[144:151], v[204:211], v[20:23]
	v_mfma_f32_16x16x128_f8f6f4 v[16:19], v[136:143], v[204:211], v[16:19]
	s_setprio 0
	s_barrier
	s_add_i32 s4, s5, s17
	v_lshl_add_u64 v[140:141], v[154:155], 0, s[42:43]
	s_mov_b32 m0, s4
	s_nop 0
	global_load_lds_dwordx4 v[140:141], off
	v_lshl_add_u64 v[140:141], v[154:155], 0, s[58:59]
	s_add_i32 m0, s4, 0x2000
	s_nop 0
	global_load_lds_dwordx4 v[140:141], off
	s_waitcnt vmcnt(6)
	s_barrier
	s_setprio 3
	v_mfma_f32_16x16x128_f8f6f4 v[60:63], v[212:219], v[160:167], v[60:63]
	v_mfma_f32_16x16x128_f8f6f4 v[56:59], v[220:227], v[160:167], v[56:59]
	v_mfma_f32_16x16x128_f8f6f4 v[44:47], v[212:219], v[176:183], v[44:47]
	v_mfma_f32_16x16x128_f8f6f4 v[40:43], v[220:227], v[176:183], v[40:43]
	v_mfma_f32_16x16x128_f8f6f4 v[28:31], v[212:219], v[196:203], v[28:31]
	v_mfma_f32_16x16x128_f8f6f4 v[24:27], v[220:227], v[196:203], v[24:27]
	v_mfma_f32_16x16x128_f8f6f4 v[12:15], v[212:219], v[204:211], v[12:15]
	v_mfma_f32_16x16x128_f8f6f4 v[8:11], v[220:227], v[204:211], v[8:11]
	s_setprio 0
	s_add_i32 s39, s39, 2
	s_add_u32 s2, s2, 0x100
	s_addc_u32 s3, s3, 0
	s_add_u32 s37, s37, 0x100
	s_addc_u32 s38, s38, 0
	s_cmp_gt_u32 s39, 5
	s_cbranch_scc0 .Ldb_MG0_cont
	v_readfirstlane_b32 s101, v186
	s_cmpk_gt_u32 s101, 0xff
	s_cbranch_scc1 .Ldb_MG0_exit
	s_barrier
	s_branch .Ldb_MG0_exit

; __device__ __forceinline__ float sigmoidf_(float v) { return __builtin_amdgcn_rcpf(1.0f + __expf(-v)); }
; #define MEMFENCE asm volatile("" ::: "memory")
;     __device__ __forceinline__ void get_rs(const Unit& u, int wr, int fr, float (&rs)[8]) const {
; #pragma unroll
;         for (int r8 = 0; r8 < 8; ++r8) rs[r8] = rstab[u.ord * 256 + (r8 >> 2) * 128 + wr * 64 + (r8 & 3) * 16 + fr];
;     }
;     template <int KIND> __device__ __forceinline__ void run(f32x4 (&acc)[2][2][4][2], const Unit& u, int tid_in) const {
;     ...
;         if constexpr (KIND == K_MG_G) { float rs[8]; get_rs(u, wr, fr, rs);
;             u32x4* gst = (u32x4*)((unsigned char*)x + 32 * MiB) + ((size_t)(blockIdx.x * 2 + (u.ord & 1)) * 3 + u.aux) * 4096;
; #pragma unroll
;             for (int ai = 0; ai < 2; ++ai)
; #pragma unroll
;                 for (int m = 0; m < 4; ++m) { const float r = rs[ai * 4 + m] * (1.0f / GATE_WSCALE); u32x4 w;
; #pragma unroll
;                     for (int bj = 0; bj < 2; ++bj) { f32x4 a = acc[ai][bj][m][0] * r, b = acc[ai][bj][m][1] * r;
; #pragma unroll
;                         for (int j = 0; j < 4; ++j) { a[j] = sigmoidf_(a[j]); b[j] = sigmoidf_(b[j]); }
;                         if (bj == 0) { w.x = pack4_u8c(a); w.y = pack4_u8c(b); } else { w.z = pack4_u8c(a); w.w = pack4_u8c(b); } }
;                     gst[(ai * 4 + m) * 512 + tid] = w; MEMFENCE; }
.Ldb_MG0_exit:
	v_mov_b32_e32 v142, v158
	s_lshl_b32 s3, s33, 10
	v_readfirstlane_b32 s2, v142
	s_add_i32 s3, s3, 0
	s_and_b32 s2, s2, 0xffffff00
	v_and_b32_e32 v136, 15, v142
	s_add_i32 s3, s3, s2
	v_lshl_add_u32 v136, v136, 2, s3
	v_add_u32_e32 v136, 0x20010, v136
	ds_read2_b32 v[144:145], v136 offset1:16
	ds_read2_b32 v[140:141], v136 offset0:32 offset1:48
	ds_read2_b32 v[138:139], v136 offset0:128 offset1:144
	ds_read2_b32 v[136:137], v136 offset0:160 offset1:176
	s_and_b32 s2, s33, 1
	s_waitcnt lgkmcnt(0)
	v_mul_f32_e32 v144, 0x3c800000, v144
	v_pk_mul_f32 v[128:129], v[128:129], v[144:145] op_sel_hi:[1,0]
	v_pk_mul_f32 v[130:131], v[130:131], v[144:145] op_sel_hi:[1,0]
	v_mul_f32_e32 v128, 0xbfb8aa3b, v128
	v_mul_f32_e32 v129, 0xbfb8aa3b, v129
	v_mul_f32_e32 v131, 0xbfb8aa3b, v131
	v_exp_f32_e32 v128, v128
	v_exp_f32_e32 v129, v129
	v_mul_f32_e32 v130, 0xbfb8aa3b, v130
	v_exp_f32_e32 v131, v131
	v_exp_f32_e32 v130, v130
	v_add_f32_e32 v128, 1.0, v128
	v_add_f32_e32 v129, 1.0, v129
	s_or_b32 s2, s2, s60
	v_pk_mul_f32 v[132:133], v[132:133], v[144:145] op_sel_hi:[1,0]
	v_add_f32_e32 v131, 1.0, v131
	v_rcp_f32_e32 v128, v128
	v_rcp_f32_e32 v129, v129
	v_add_f32_e32 v130, 1.0, v130
	s_mul_hi_u32 s3, s2, 3
	s_mul_i32 s2, s2, 3
	s_ashr_i32 s4, s36, 31
	v_pk_mul_f32 v[134:135], v[134:135], v[144:145] op_sel_hi:[1,0]
	v_mul_f32_e32 v132, 0xbfb8aa3b, v132
	v_mul_f32_e32 v133, 0xbfb8aa3b, v133
	v_rcp_f32_e32 v131, v131
	v_rcp_f32_e32 v130, v130
	s_add_u32 s2, s2, s36
	v_mul_f32_e32 v135, 0xbfb8aa3b, v135
	v_exp_f32_e32 v132, v132
	v_exp_f32_e32 v133, v133
	v_mul_f32_e32 v134, 0xbfb8aa3b, v134
	s_addc_u32 s3, s3, s4
	v_exp_f32_e32 v135, v135
	v_exp_f32_e32 v134, v134
	s_mov_b32 s4, 0x437f0000
	v_fma_f32 v128, v128, s4, 0.5
	v_fma_f32 v129, v129, s4, 0.5
	v_max_f32_e32 v128, 1.0, v128
	v_max_f32_e32 v129, 1.0, v129
	v_fma_f32 v130, v130, s4, 0.5
	v_fma_f32 v131, v131, s4, 0.5
	v_add_f32_e32 v132, 1.0, v132
	v_add_f32_e32 v133, 1.0, v133
	v_cvt_u32_f32_e32 v128, v128
	v_cvt_u32_f32_e32 v129, v129
	v_max_f32_e32 v130, 1.0, v130
	v_max_f32_e32 v131, 1.0, v131
	v_add_f32_e32 v135, 1.0, v135
	v_rcp_f32_e32 v132, v132
	v_rcp_f32_e32 v133, v133
	v_cvt_u32_f32_sdwa v130, v130 dst_sel:WORD_1 dst_unused:UNUSED_PAD src0_sel:DWORD
	v_cvt_u32_f32_sdwa v131, v131 dst_sel:BYTE_3 dst_unused:UNUSED_PAD src0_sel:DWORD
	v_add_f32_e32 v134, 1.0, v134
	v_rcp_f32_e32 v135, v135
	v_rcp_f32_e32 v134, v134
	v_lshl_or_b32 v128, v129, 8, v128
	v_or3_b32 v128, v128, v130, v131
	v_fma_f32 v129, v132, s4, 0.5
	v_fma_f32 v130, v133, s4, 0.5
	v_pk_mul_f32 v[124:125], v[124:125], v[144:145] op_sel_hi:[1,0]
	v_max_f32_e32 v129, 1.0, v129
	v_max_f32_e32 v130, 1.0, v130
	v_fma_f32 v131, v134, s4, 0.5
	v_fma_f32 v132, v135, s4, 0.5
	v_mul_f32_e32 v125, 0xbfb8aa3b, v125
	v_cvt_u32_f32_e32 v129, v129
	v_cvt_u32_f32_e32 v130, v130
	v_max_f32_e32 v131, 1.0, v131
	v_max_f32_e32 v132, 1.0, v132
	v_exp_f32_e32 v125, v125
	v_cvt_u32_f32_sdwa v131, v131 dst_sel:WORD_1 dst_unused:UNUSED_PAD src0_sel:DWORD
	v_cvt_u32_f32_sdwa v132, v132 dst_sel:BYTE_3 dst_unused:UNUSED_PAD src0_sel:DWORD
	v_pk_mul_f32 v[120:121], v[120:121], v[144:145] op_sel_hi:[1,0]
	v_mul_f32_e32 v124, 0xbfb8aa3b, v124
	v_mul_f32_e32 v121, 0xbfb8aa3b, v121
	v_lshl_or_b32 v129, v130, 8, v129
	v_exp_f32_e32 v130, v124
	v_add_f32_e32 v124, 1.0, v125
	v_exp_f32_e32 v121, v121
	v_or3_b32 v129, v129, v131, v132
	v_rcp_f32_e32 v131, v124
	v_mul_f32_e32 v120, 0xbfb8aa3b, v120
	v_pk_mul_f32 v[124:125], v[126:127], v[144:145] op_sel_hi:[1,0]
	v_add_f32_e32 v126, 1.0, v130
	v_exp_f32_e32 v130, v120
	v_add_f32_e32 v120, 1.0, v121
	v_fma_f32 v127, v131, s4, 0.5
	v_rcp_f32_e32 v131, v120
	v_pk_mul_f32 v[120:121], v[122:123], v[144:145] op_sel_hi:[1,0]
	v_add_f32_e32 v122, 1.0, v130
	v_mul_f32_e32 v120, 0xbfb8aa3b, v120
	v_mul_f32_e32 v121, 0xbfb8aa3b, v121
	v_exp_f32_e32 v120, v120
	v_exp_f32_e32 v121, v121
	v_rcp_f32_e32 v122, v122
	v_fma_f32 v123, v131, s4, 0.5
	v_add_f32_e32 v120, 1.0, v120
	v_add_f32_e32 v121, 1.0, v121
	v_rcp_f32_e32 v120, v120
	v_rcp_f32_e32 v121, v121
	v_fma_f32 v122, v122, s4, 0.5
	v_max_f32_e32 v123, 1.0, v123
	v_max_f32_e32 v122, 1.0, v122
	v_fma_f32 v120, v120, s4, 0.5
	v_fma_f32 v121, v121, s4, 0.5
	v_cvt_u32_f32_e32 v123, v123
	v_cvt_u32_f32_e32 v122, v122
	v_max_f32_e32 v120, 1.0, v120
	v_max_f32_e32 v121, 1.0, v121
	v_cvt_u32_f32_sdwa v120, v120 dst_sel:WORD_1 dst_unused:UNUSED_PAD src0_sel:DWORD
	v_cvt_u32_f32_sdwa v121, v121 dst_sel:BYTE_3 dst_unused:UNUSED_PAD src0_sel:DWORD
	v_lshl_or_b32 v122, v123, 8, v122
	v_mul_f32_e32 v124, 0xbfb8aa3b, v124
	v_mul_f32_e32 v125, 0xbfb8aa3b, v125
	v_or3_b32 v131, v122, v120, v121
	v_mul_f32_e32 v122, 0x3c800000, v145
	v_pk_mul_f32 v[112:113], v[112:113], v[122:123] op_sel_hi:[1,0]
	v_pk_mul_f32 v[114:115], v[114:115], v[122:123] op_sel_hi:[1,0]
	v_mul_f32_e32 v112, 0xbfb8aa3b, v112
	v_mul_f32_e32 v113, 0xbfb8aa3b, v113
	v_mul_f32_e32 v115, 0xbfb8aa3b, v115
	v_exp_f32_e32 v112, v112
	v_exp_f32_e32 v113, v113
	v_mul_f32_e32 v114, 0xbfb8aa3b, v114
	v_exp_f32_e32 v115, v115
	v_exp_f32_e32 v114, v114
	v_add_f32_e32 v112, 1.0, v112
	v_add_f32_e32 v113, 1.0, v113
	v_pk_mul_f32 v[116:117], v[116:117], v[122:123] op_sel_hi:[1,0]
	v_add_f32_e32 v115, 1.0, v115
	v_rcp_f32_e32 v112, v112
	v_rcp_f32_e32 v113, v113
	v_add_f32_e32 v114, 1.0, v114
	v_pk_mul_f32 v[118:119], v[118:119], v[122:123] op_sel_hi:[1,0]
	v_mul_f32_e32 v116, 0xbfb8aa3b, v116
	v_mul_f32_e32 v117, 0xbfb8aa3b, v117
	v_rcp_f32_e32 v115, v115
	v_rcp_f32_e32 v114, v114
	v_mul_f32_e32 v119, 0xbfb8aa3b, v119
	v_exp_f32_e32 v116, v116
	v_exp_f32_e32 v117, v117
	v_mul_f32_e32 v118, 0xbfb8aa3b, v118
; __device__ __forceinline__ float sigmoidf_(float v) { return __builtin_amdgcn_rcpf(1.0f + __expf(-v)); }
; #define MEMFENCE asm volatile("" ::: "memory")
;     template <int KIND> __device__ __forceinline__ void run(f32x4 (&acc)[2][2][4][2], const Unit& u, int tid_in) const {
;     ...
;         if constexpr (KIND == K_MG_G) { float rs[8]; get_rs(u, wr, fr, rs);
;             u32x4* gst = (u32x4*)((unsigned char*)x + 32 * MiB) + ((size_t)(blockIdx.x * 2 + (u.ord & 1)) * 3 + u.aux) * 4096;
; #pragma unroll
;             for (int ai = 0; ai < 2; ++ai)
; #pragma unroll
;                 for (int m = 0; m < 4; ++m) { const float r = rs[ai * 4 + m] * (1.0f / GATE_WSCALE); u32x4 w;
; #pragma unroll
;                     for (int bj = 0; bj < 2; ++bj) { f32x4 a = acc[ai][bj][m][0] * r, b = acc[ai][bj][m][1] * r;
; #pragma unroll
;                         for (int j = 0; j < 4; ++j) { a[j] = sigmoidf_(a[j]); b[j] = sigmoidf_(b[j]); }
;                         if (bj == 0) { w.x = pack4_u8c(a); w.y = pack4_u8c(b); } else { w.z = pack4_u8c(a); w.w = pack4_u8c(b); } }
;                     gst[(ai * 4 + m) * 512 + tid] = w; MEMFENCE; }
	v_exp_f32_e32 v119, v119
	v_exp_f32_e32 v118, v118
	v_fma_f32 v112, v112, s4, 0.5
	v_fma_f32 v113, v113, s4, 0.5
	v_max_f32_e32 v112, 1.0, v112
	v_max_f32_e32 v113, 1.0, v113
	v_fma_f32 v114, v114, s4, 0.5
	v_fma_f32 v115, v115, s4, 0.5
	v_add_f32_e32 v116, 1.0, v116
	v_add_f32_e32 v117, 1.0, v117
	v_cvt_u32_f32_e32 v112, v112
	v_cvt_u32_f32_e32 v113, v113
	v_max_f32_e32 v114, 1.0, v114
	v_max_f32_e32 v115, 1.0, v115
	v_add_f32_e32 v119, 1.0, v119
	v_rcp_f32_e32 v116, v116
	v_rcp_f32_e32 v117, v117
	v_cvt_u32_f32_sdwa v114, v114 dst_sel:WORD_1 dst_unused:UNUSED_PAD src0_sel:DWORD
	v_cvt_u32_f32_sdwa v115, v115 dst_sel:BYTE_3 dst_unused:UNUSED_PAD src0_sel:DWORD
	v_add_f32_e32 v118, 1.0, v118
	v_rcp_f32_e32 v119, v119
	v_rcp_f32_e32 v118, v118
	v_lshl_or_b32 v112, v113, 8, v112
	v_or3_b32 v112, v112, v114, v115
	v_fma_f32 v113, v116, s4, 0.5
	v_fma_f32 v114, v117, s4, 0.5
	v_pk_mul_f32 v[108:109], v[108:109], v[122:123] op_sel_hi:[1,0]
	v_max_f32_e32 v113, 1.0, v113
	v_max_f32_e32 v114, 1.0, v114
	v_fma_f32 v115, v118, s4, 0.5
	v_fma_f32 v116, v119, s4, 0.5
	v_mul_f32_e32 v109, 0xbfb8aa3b, v109
	v_cvt_u32_f32_e32 v113, v113
	v_cvt_u32_f32_e32 v114, v114
	v_max_f32_e32 v115, 1.0, v115
	v_max_f32_e32 v116, 1.0, v116
	v_exp_f32_e32 v109, v109
	v_cvt_u32_f32_sdwa v115, v115 dst_sel:WORD_1 dst_unused:UNUSED_PAD src0_sel:DWORD
	v_cvt_u32_f32_sdwa v116, v116 dst_sel:BYTE_3 dst_unused:UNUSED_PAD src0_sel:DWORD
	v_pk_mul_f32 v[104:105], v[104:105], v[122:123] op_sel_hi:[1,0]
	v_mul_f32_e32 v108, 0xbfb8aa3b, v108
	v_mul_f32_e32 v105, 0xbfb8aa3b, v105
	v_lshl_or_b32 v113, v114, 8, v113
	v_exp_f32_e32 v114, v108
	v_add_f32_e32 v108, 1.0, v109
	v_exp_f32_e32 v105, v105
	v_or3_b32 v113, v113, v115, v116
	v_rcp_f32_e32 v115, v108
	v_mul_f32_e32 v104, 0xbfb8aa3b, v104
	v_pk_mul_f32 v[108:109], v[110:111], v[122:123] op_sel_hi:[1,0]
	v_add_f32_e32 v110, 1.0, v114
	v_exp_f32_e32 v114, v104
	v_add_f32_e32 v104, 1.0, v105
	v_fma_f32 v111, v115, s4, 0.5
	v_rcp_f32_e32 v115, v104
	v_pk_mul_f32 v[104:105], v[106:107], v[122:123] op_sel_hi:[1,0]
	v_add_f32_e32 v106, 1.0, v114
	v_mul_f32_e32 v104, 0xbfb8aa3b, v104
	v_mul_f32_e32 v105, 0xbfb8aa3b, v105
	v_exp_f32_e32 v104, v104
	v_exp_f32_e32 v105, v105
	v_rcp_f32_e32 v106, v106
	v_fma_f32 v107, v115, s4, 0.5
	v_add_f32_e32 v104, 1.0, v104
	v_add_f32_e32 v105, 1.0, v105
	v_rcp_f32_e32 v104, v104
	v_rcp_f32_e32 v105, v105
	v_fma_f32 v106, v106, s4, 0.5
	v_max_f32_e32 v107, 1.0, v107
	v_max_f32_e32 v106, 1.0, v106
	v_fma_f32 v104, v104, s4, 0.5
	v_fma_f32 v105, v105, s4, 0.5
	v_cvt_u32_f32_e32 v107, v107
	v_cvt_u32_f32_e32 v106, v106
	v_max_f32_e32 v104, 1.0, v104
	v_max_f32_e32 v105, 1.0, v105
	v_cvt_u32_f32_sdwa v104, v104 dst_sel:WORD_1 dst_unused:UNUSED_PAD src0_sel:DWORD
	v_cvt_u32_f32_sdwa v105, v105 dst_sel:BYTE_3 dst_unused:UNUSED_PAD src0_sel:DWORD
	v_lshl_or_b32 v106, v107, 8, v106
	v_exp_f32_e32 v124, v124
	v_exp_f32_e32 v125, v125
	v_or3_b32 v115, v106, v104, v105
	v_mul_f32_e32 v106, 0x3c800000, v140
	v_pk_mul_f32 v[96:97], v[96:97], v[106:107] op_sel_hi:[1,0]
	v_pk_mul_f32 v[98:99], v[98:99], v[106:107] op_sel_hi:[1,0]
	v_mul_f32_e32 v96, 0xbfb8aa3b, v96
	v_mul_f32_e32 v97, 0xbfb8aa3b, v97
	v_mul_f32_e32 v99, 0xbfb8aa3b, v99
	v_exp_f32_e32 v96, v96
	v_exp_f32_e32 v97, v97
	v_mul_f32_e32 v98, 0xbfb8aa3b, v98
	v_exp_f32_e32 v99, v99
	v_exp_f32_e32 v98, v98
	v_add_f32_e32 v96, 1.0, v96
	v_add_f32_e32 v97, 1.0, v97
	v_pk_mul_f32 v[100:101], v[100:101], v[106:107] op_sel_hi:[1,0]
	v_add_f32_e32 v99, 1.0, v99
	v_rcp_f32_e32 v96, v96
	v_rcp_f32_e32 v97, v97
	v_add_f32_e32 v98, 1.0, v98
	v_pk_mul_f32 v[102:103], v[102:103], v[106:107] op_sel_hi:[1,0]
	v_mul_f32_e32 v100, 0xbfb8aa3b, v100
	v_mul_f32_e32 v101, 0xbfb8aa3b, v101
	v_rcp_f32_e32 v99, v99
	v_rcp_f32_e32 v98, v98
	v_mul_f32_e32 v103, 0xbfb8aa3b, v103
	v_exp_f32_e32 v100, v100
	v_exp_f32_e32 v101, v101
	v_mul_f32_e32 v102, 0xbfb8aa3b, v102
	v_exp_f32_e32 v103, v103
	v_exp_f32_e32 v102, v102
	v_fma_f32 v96, v96, s4, 0.5
	v_fma_f32 v97, v97, s4, 0.5
	v_max_f32_e32 v96, 1.0, v96
	v_max_f32_e32 v97, 1.0, v97
	v_fma_f32 v98, v98, s4, 0.5
	v_fma_f32 v99, v99, s4, 0.5
	v_add_f32_e32 v100, 1.0, v100
	v_add_f32_e32 v101, 1.0, v101
	v_cvt_u32_f32_e32 v96, v96
	v_cvt_u32_f32_e32 v97, v97
	v_max_f32_e32 v98, 1.0, v98
	v_max_f32_e32 v99, 1.0, v99
	v_add_f32_e32 v103, 1.0, v103
	v_rcp_f32_e32 v100, v100
	v_rcp_f32_e32 v101, v101
	v_cvt_u32_f32_sdwa v98, v98 dst_sel:WORD_1 dst_unused:UNUSED_PAD src0_sel:DWORD
	v_cvt_u32_f32_sdwa v99, v99 dst_sel:BYTE_3 dst_unused:UNUSED_PAD src0_sel:DWORD
	v_add_f32_e32 v102, 1.0, v102
	v_rcp_f32_e32 v103, v103
	v_rcp_f32_e32 v102, v102
	v_lshl_or_b32 v96, v97, 8, v96
	v_or3_b32 v96, v96, v98, v99
	v_fma_f32 v97, v100, s4, 0.5
	v_fma_f32 v98, v101, s4, 0.5
	v_pk_mul_f32 v[92:93], v[92:93], v[106:107] op_sel_hi:[1,0]
	v_max_f32_e32 v97, 1.0, v97
	v_max_f32_e32 v98, 1.0, v98
	v_fma_f32 v99, v102, s4, 0.5
	v_fma_f32 v100, v103, s4, 0.5
	v_mul_f32_e32 v93, 0xbfb8aa3b, v93
	v_cvt_u32_f32_e32 v97, v97
	v_cvt_u32_f32_e32 v98, v98
	v_max_f32_e32 v99, 1.0, v99
	v_max_f32_e32 v100, 1.0, v100
	v_exp_f32_e32 v93, v93
	v_cvt_u32_f32_sdwa v99, v99 dst_sel:WORD_1 dst_unused:UNUSED_PAD src0_sel:DWORD
	v_cvt_u32_f32_sdwa v100, v100 dst_sel:BYTE_3 dst_unused:UNUSED_PAD src0_sel:DWORD
	v_pk_mul_f32 v[88:89], v[88:89], v[106:107] op_sel_hi:[1,0]
	v_mul_f32_e32 v92, 0xbfb8aa3b, v92
	v_mul_f32_e32 v89, 0xbfb8aa3b, v89
	v_lshl_or_b32 v97, v98, 8, v97
	v_exp_f32_e32 v98, v92
	v_add_f32_e32 v92, 1.0, v93
	v_exp_f32_e32 v89, v89
	v_or3_b32 v97, v97, v99, v100
	v_rcp_f32_e32 v99, v92
	v_mul_f32_e32 v88, 0xbfb8aa3b, v88
	v_pk_mul_f32 v[92:93], v[94:95], v[106:107] op_sel_hi:[1,0]
; __device__ __forceinline__ float sigmoidf_(float v) { return __builtin_amdgcn_rcpf(1.0f + __expf(-v)); }
; #define MEMFENCE asm volatile("" ::: "memory")
;     template <int KIND> __device__ __forceinline__ void run(f32x4 (&acc)[2][2][4][2], const Unit& u, int tid_in) const {
;     ...
;         if constexpr (KIND == K_MG_G) { float rs[8]; get_rs(u, wr, fr, rs);
;             u32x4* gst = (u32x4*)((unsigned char*)x + 32 * MiB) + ((size_t)(blockIdx.x * 2 + (u.ord & 1)) * 3 + u.aux) * 4096;
; #pragma unroll
;             for (int ai = 0; ai < 2; ++ai)
; #pragma unroll
;                 for (int m = 0; m < 4; ++m) { const float r = rs[ai * 4 + m] * (1.0f / GATE_WSCALE); u32x4 w;
; #pragma unroll
;                     for (int bj = 0; bj < 2; ++bj) { f32x4 a = acc[ai][bj][m][0] * r, b = acc[ai][bj][m][1] * r;
; #pragma unroll
;                         for (int j = 0; j < 4; ++j) { a[j] = sigmoidf_(a[j]); b[j] = sigmoidf_(b[j]); }
;                         if (bj == 0) { w.x = pack4_u8c(a); w.y = pack4_u8c(b); } else { w.z = pack4_u8c(a); w.w = pack4_u8c(b); } }
;                     gst[(ai * 4 + m) * 512 + tid] = w; MEMFENCE; }
	v_add_f32_e32 v94, 1.0, v98
	v_exp_f32_e32 v98, v88
	v_add_f32_e32 v88, 1.0, v89
	v_fma_f32 v95, v99, s4, 0.5
	v_rcp_f32_e32 v99, v88
	v_pk_mul_f32 v[88:89], v[90:91], v[106:107] op_sel_hi:[1,0]
	v_add_f32_e32 v90, 1.0, v98
	v_mul_f32_e32 v88, 0xbfb8aa3b, v88
	v_mul_f32_e32 v89, 0xbfb8aa3b, v89
	v_exp_f32_e32 v88, v88
	v_exp_f32_e32 v89, v89
	v_rcp_f32_e32 v90, v90
	v_fma_f32 v91, v99, s4, 0.5
	v_add_f32_e32 v88, 1.0, v88
	v_add_f32_e32 v89, 1.0, v89
	v_rcp_f32_e32 v88, v88
	v_rcp_f32_e32 v89, v89
	v_fma_f32 v90, v90, s4, 0.5
	v_max_f32_e32 v91, 1.0, v91
	v_max_f32_e32 v90, 1.0, v90
	v_fma_f32 v88, v88, s4, 0.5
	v_fma_f32 v89, v89, s4, 0.5
	v_cvt_u32_f32_e32 v91, v91
	v_cvt_u32_f32_e32 v90, v90
	v_max_f32_e32 v88, 1.0, v88
	v_max_f32_e32 v89, 1.0, v89
	v_cvt_u32_f32_sdwa v88, v88 dst_sel:WORD_1 dst_unused:UNUSED_PAD src0_sel:DWORD
	v_cvt_u32_f32_sdwa v89, v89 dst_sel:BYTE_3 dst_unused:UNUSED_PAD src0_sel:DWORD
	v_lshl_or_b32 v90, v91, 8, v90
	v_mul_f32_e32 v108, 0xbfb8aa3b, v108
	v_mul_f32_e32 v109, 0xbfb8aa3b, v109
	v_or3_b32 v99, v90, v88, v89
	v_mul_f32_e32 v90, 0x3c800000, v141
	v_pk_mul_f32 v[80:81], v[80:81], v[90:91] op_sel_hi:[1,0]
	v_pk_mul_f32 v[82:83], v[82:83], v[90:91] op_sel_hi:[1,0]
	v_mul_f32_e32 v80, 0xbfb8aa3b, v80
	v_mul_f32_e32 v81, 0xbfb8aa3b, v81
	v_mul_f32_e32 v83, 0xbfb8aa3b, v83
	v_exp_f32_e32 v80, v80
	v_exp_f32_e32 v81, v81
	v_mul_f32_e32 v82, 0xbfb8aa3b, v82
	v_exp_f32_e32 v83, v83
	v_exp_f32_e32 v82, v82
	v_add_f32_e32 v80, 1.0, v80
	v_add_f32_e32 v81, 1.0, v81
	v_pk_mul_f32 v[84:85], v[84:85], v[90:91] op_sel_hi:[1,0]
	v_add_f32_e32 v83, 1.0, v83
	v_rcp_f32_e32 v80, v80
	v_rcp_f32_e32 v81, v81
	v_add_f32_e32 v82, 1.0, v82
	v_pk_mul_f32 v[86:87], v[86:87], v[90:91] op_sel_hi:[1,0]
	v_mul_f32_e32 v84, 0xbfb8aa3b, v84
	v_mul_f32_e32 v85, 0xbfb8aa3b, v85
	v_rcp_f32_e32 v83, v83
	v_rcp_f32_e32 v82, v82
	v_mul_f32_e32 v87, 0xbfb8aa3b, v87
	v_exp_f32_e32 v84, v84
	v_exp_f32_e32 v85, v85
	v_mul_f32_e32 v86, 0xbfb8aa3b, v86
	v_exp_f32_e32 v87, v87
	v_exp_f32_e32 v86, v86
	v_fma_f32 v80, v80, s4, 0.5
	v_fma_f32 v81, v81, s4, 0.5
	v_max_f32_e32 v80, 1.0, v80
	v_max_f32_e32 v81, 1.0, v81
	v_fma_f32 v82, v82, s4, 0.5
	v_fma_f32 v83, v83, s4, 0.5
	v_add_f32_e32 v84, 1.0, v84
	v_add_f32_e32 v85, 1.0, v85
	v_cvt_u32_f32_e32 v80, v80
	v_cvt_u32_f32_e32 v81, v81
	v_max_f32_e32 v82, 1.0, v82
	v_max_f32_e32 v83, 1.0, v83
	v_add_f32_e32 v87, 1.0, v87
	v_rcp_f32_e32 v84, v84
	v_rcp_f32_e32 v85, v85
	v_cvt_u32_f32_sdwa v82, v82 dst_sel:WORD_1 dst_unused:UNUSED_PAD src0_sel:DWORD
	v_cvt_u32_f32_sdwa v83, v83 dst_sel:BYTE_3 dst_unused:UNUSED_PAD src0_sel:DWORD
	v_add_f32_e32 v86, 1.0, v86
	v_rcp_f32_e32 v87, v87
	v_rcp_f32_e32 v86, v86
	v_lshl_or_b32 v80, v81, 8, v80
	v_or3_b32 v80, v80, v82, v83
	v_fma_f32 v81, v84, s4, 0.5
	v_fma_f32 v82, v85, s4, 0.5
	v_pk_mul_f32 v[76:77], v[76:77], v[90:91] op_sel_hi:[1,0]
	v_max_f32_e32 v81, 1.0, v81
	v_max_f32_e32 v82, 1.0, v82
	v_fma_f32 v83, v86, s4, 0.5
	v_fma_f32 v84, v87, s4, 0.5
	v_mul_f32_e32 v77, 0xbfb8aa3b, v77
	v_cvt_u32_f32_e32 v81, v81
	v_cvt_u32_f32_e32 v82, v82
	v_max_f32_e32 v83, 1.0, v83
	v_max_f32_e32 v84, 1.0, v84
	v_exp_f32_e32 v77, v77
	v_cvt_u32_f32_sdwa v83, v83 dst_sel:WORD_1 dst_unused:UNUSED_PAD src0_sel:DWORD
	v_cvt_u32_f32_sdwa v84, v84 dst_sel:BYTE_3 dst_unused:UNUSED_PAD src0_sel:DWORD
	v_pk_mul_f32 v[72:73], v[72:73], v[90:91] op_sel_hi:[1,0]
	v_mul_f32_e32 v76, 0xbfb8aa3b, v76
	v_mul_f32_e32 v73, 0xbfb8aa3b, v73
	v_lshl_or_b32 v81, v82, 8, v81
	v_exp_f32_e32 v82, v76
	v_add_f32_e32 v76, 1.0, v77
	v_exp_f32_e32 v73, v73
	v_or3_b32 v81, v81, v83, v84
	v_rcp_f32_e32 v83, v76
	v_mul_f32_e32 v72, 0xbfb8aa3b, v72
	v_pk_mul_f32 v[76:77], v[78:79], v[90:91] op_sel_hi:[1,0]
	v_add_f32_e32 v78, 1.0, v82
	v_exp_f32_e32 v82, v72
	v_add_f32_e32 v72, 1.0, v73
	v_fma_f32 v79, v83, s4, 0.5
	v_rcp_f32_e32 v83, v72
	v_pk_mul_f32 v[72:73], v[74:75], v[90:91] op_sel_hi:[1,0]
	v_add_f32_e32 v74, 1.0, v82
	v_mul_f32_e32 v72, 0xbfb8aa3b, v72
	v_mul_f32_e32 v73, 0xbfb8aa3b, v73
	v_exp_f32_e32 v72, v72
	v_exp_f32_e32 v73, v73
	v_rcp_f32_e32 v74, v74
	v_fma_f32 v75, v83, s4, 0.5
	v_add_f32_e32 v72, 1.0, v72
	v_add_f32_e32 v73, 1.0, v73
	v_rcp_f32_e32 v72, v72
	v_rcp_f32_e32 v73, v73
	v_fma_f32 v74, v74, s4, 0.5
	v_max_f32_e32 v75, 1.0, v75
	v_max_f32_e32 v74, 1.0, v74
	v_fma_f32 v72, v72, s4, 0.5
	v_fma_f32 v73, v73, s4, 0.5
	v_cvt_u32_f32_e32 v75, v75
	v_cvt_u32_f32_e32 v74, v74
	v_max_f32_e32 v72, 1.0, v72
	v_max_f32_e32 v73, 1.0, v73
	v_cvt_u32_f32_sdwa v72, v72 dst_sel:WORD_1 dst_unused:UNUSED_PAD src0_sel:DWORD
	v_cvt_u32_f32_sdwa v73, v73 dst_sel:BYTE_3 dst_unused:UNUSED_PAD src0_sel:DWORD
	v_lshl_or_b32 v74, v75, 8, v74
	v_exp_f32_e32 v108, v108
	v_exp_f32_e32 v109, v109
	v_or3_b32 v83, v74, v72, v73
	v_mul_f32_e32 v74, 0x3c800000, v138
	v_pk_mul_f32 v[64:65], v[64:65], v[74:75] op_sel_hi:[1,0]
	v_pk_mul_f32 v[66:67], v[66:67], v[74:75] op_sel_hi:[1,0]
	v_mul_f32_e32 v64, 0xbfb8aa3b, v64
	v_mul_f32_e32 v65, 0xbfb8aa3b, v65
	v_mul_f32_e32 v67, 0xbfb8aa3b, v67
	v_exp_f32_e32 v64, v64
	v_exp_f32_e32 v65, v65
	v_mul_f32_e32 v66, 0xbfb8aa3b, v66
	v_exp_f32_e32 v67, v67
	v_exp_f32_e32 v66, v66
	v_add_f32_e32 v64, 1.0, v64
	v_add_f32_e32 v65, 1.0, v65
	v_pk_mul_f32 v[68:69], v[68:69], v[74:75] op_sel_hi:[1,0]
	v_add_f32_e32 v67, 1.0, v67
	v_rcp_f32_e32 v64, v64
	v_rcp_f32_e32 v65, v65
	v_add_f32_e32 v66, 1.0, v66
	v_pk_mul_f32 v[70:71], v[70:71], v[74:75] op_sel_hi:[1,0]
	v_mul_f32_e32 v68, 0xbfb8aa3b, v68
	v_mul_f32_e32 v69, 0xbfb8aa3b, v69
	v_rcp_f32_e32 v67, v67
	v_rcp_f32_e32 v66, v66
	v_mul_f32_e32 v71, 0xbfb8aa3b, v71
	v_exp_f32_e32 v68, v68
	v_exp_f32_e32 v69, v69
; __device__ __forceinline__ float sigmoidf_(float v) { return __builtin_amdgcn_rcpf(1.0f + __expf(-v)); }
; #define MEMFENCE asm volatile("" ::: "memory")
;     template <int KIND> __device__ __forceinline__ void run(f32x4 (&acc)[2][2][4][2], const Unit& u, int tid_in) const {
;     ...
;         if constexpr (KIND == K_MG_G) { float rs[8]; get_rs(u, wr, fr, rs);
;             u32x4* gst = (u32x4*)((unsigned char*)x + 32 * MiB) + ((size_t)(blockIdx.x * 2 + (u.ord & 1)) * 3 + u.aux) * 4096;
; #pragma unroll
;             for (int ai = 0; ai < 2; ++ai)
; #pragma unroll
;                 for (int m = 0; m < 4; ++m) { const float r = rs[ai * 4 + m] * (1.0f / GATE_WSCALE); u32x4 w;
; #pragma unroll
;                     for (int bj = 0; bj < 2; ++bj) { f32x4 a = acc[ai][bj][m][0] * r, b = acc[ai][bj][m][1] * r;
; #pragma unroll
;                         for (int j = 0; j < 4; ++j) { a[j] = sigmoidf_(a[j]); b[j] = sigmoidf_(b[j]); }
;                         if (bj == 0) { w.x = pack4_u8c(a); w.y = pack4_u8c(b); } else { w.z = pack4_u8c(a); w.w = pack4_u8c(b); } }
;                     gst[(ai * 4 + m) * 512 + tid] = w; MEMFENCE; }
	v_mul_f32_e32 v70, 0xbfb8aa3b, v70
	v_exp_f32_e32 v71, v71
	v_exp_f32_e32 v70, v70
	v_fma_f32 v64, v64, s4, 0.5
	v_fma_f32 v65, v65, s4, 0.5
	v_max_f32_e32 v64, 1.0, v64
	v_max_f32_e32 v65, 1.0, v65
	v_fma_f32 v66, v66, s4, 0.5
	v_fma_f32 v67, v67, s4, 0.5
	v_add_f32_e32 v68, 1.0, v68
	v_add_f32_e32 v69, 1.0, v69
	v_cvt_u32_f32_e32 v64, v64
	v_cvt_u32_f32_e32 v65, v65
	v_max_f32_e32 v66, 1.0, v66
	v_max_f32_e32 v67, 1.0, v67
	v_add_f32_e32 v71, 1.0, v71
	v_rcp_f32_e32 v68, v68
	v_rcp_f32_e32 v69, v69
	v_cvt_u32_f32_sdwa v66, v66 dst_sel:WORD_1 dst_unused:UNUSED_PAD src0_sel:DWORD
	v_cvt_u32_f32_sdwa v67, v67 dst_sel:BYTE_3 dst_unused:UNUSED_PAD src0_sel:DWORD
	v_add_f32_e32 v70, 1.0, v70
	v_rcp_f32_e32 v71, v71
	v_rcp_f32_e32 v70, v70
	v_lshl_or_b32 v64, v65, 8, v64
	v_or3_b32 v64, v64, v66, v67
	v_fma_f32 v65, v68, s4, 0.5
	v_fma_f32 v66, v69, s4, 0.5
	v_pk_mul_f32 v[60:61], v[60:61], v[74:75] op_sel_hi:[1,0]
	v_max_f32_e32 v65, 1.0, v65
	v_max_f32_e32 v66, 1.0, v66
	v_fma_f32 v67, v70, s4, 0.5
	v_fma_f32 v68, v71, s4, 0.5
	v_mul_f32_e32 v61, 0xbfb8aa3b, v61
	v_cvt_u32_f32_e32 v65, v65
	v_cvt_u32_f32_e32 v66, v66
	v_max_f32_e32 v67, 1.0, v67
	v_max_f32_e32 v68, 1.0, v68
	v_exp_f32_e32 v61, v61
	v_cvt_u32_f32_sdwa v67, v67 dst_sel:WORD_1 dst_unused:UNUSED_PAD src0_sel:DWORD
	v_cvt_u32_f32_sdwa v68, v68 dst_sel:BYTE_3 dst_unused:UNUSED_PAD src0_sel:DWORD
	v_pk_mul_f32 v[56:57], v[56:57], v[74:75] op_sel_hi:[1,0]
	v_mul_f32_e32 v60, 0xbfb8aa3b, v60
	v_mul_f32_e32 v57, 0xbfb8aa3b, v57
	v_lshl_or_b32 v65, v66, 8, v65
	v_exp_f32_e32 v66, v60
	v_add_f32_e32 v60, 1.0, v61
	v_exp_f32_e32 v57, v57
	v_or3_b32 v65, v65, v67, v68
	v_rcp_f32_e32 v67, v60
	v_mul_f32_e32 v56, 0xbfb8aa3b, v56
	v_pk_mul_f32 v[60:61], v[62:63], v[74:75] op_sel_hi:[1,0]
	v_add_f32_e32 v62, 1.0, v66
	v_exp_f32_e32 v66, v56
	v_add_f32_e32 v56, 1.0, v57
	v_fma_f32 v63, v67, s4, 0.5
	v_rcp_f32_e32 v67, v56
	v_pk_mul_f32 v[56:57], v[58:59], v[74:75] op_sel_hi:[1,0]
	v_add_f32_e32 v58, 1.0, v66
	v_mul_f32_e32 v56, 0xbfb8aa3b, v56
	v_mul_f32_e32 v57, 0xbfb8aa3b, v57
	v_exp_f32_e32 v56, v56
	v_exp_f32_e32 v57, v57
	v_rcp_f32_e32 v58, v58
	v_fma_f32 v59, v67, s4, 0.5
	v_add_f32_e32 v56, 1.0, v56
	v_add_f32_e32 v57, 1.0, v57
	v_rcp_f32_e32 v56, v56
	v_rcp_f32_e32 v57, v57
	v_fma_f32 v58, v58, s4, 0.5
	v_max_f32_e32 v59, 1.0, v59
	v_max_f32_e32 v58, 1.0, v58
	v_fma_f32 v56, v56, s4, 0.5
	v_fma_f32 v57, v57, s4, 0.5
	v_cvt_u32_f32_e32 v59, v59
	v_cvt_u32_f32_e32 v58, v58
	v_max_f32_e32 v56, 1.0, v56
	v_max_f32_e32 v57, 1.0, v57
	v_cvt_u32_f32_sdwa v56, v56 dst_sel:WORD_1 dst_unused:UNUSED_PAD src0_sel:DWORD
	v_cvt_u32_f32_sdwa v57, v57 dst_sel:BYTE_3 dst_unused:UNUSED_PAD src0_sel:DWORD
	v_lshl_or_b32 v58, v59, 8, v58
	v_mul_f32_e32 v92, 0xbfb8aa3b, v92
	v_mul_f32_e32 v93, 0xbfb8aa3b, v93
	v_or3_b32 v67, v58, v56, v57
	v_mul_f32_e32 v58, 0x3c800000, v139
	v_pk_mul_f32 v[48:49], v[48:49], v[58:59] op_sel_hi:[1,0]
	v_pk_mul_f32 v[50:51], v[50:51], v[58:59] op_sel_hi:[1,0]
	v_mul_f32_e32 v48, 0xbfb8aa3b, v48
	v_mul_f32_e32 v49, 0xbfb8aa3b, v49
	v_mul_f32_e32 v51, 0xbfb8aa3b, v51
	v_exp_f32_e32 v48, v48
	v_exp_f32_e32 v49, v49
	v_mul_f32_e32 v50, 0xbfb8aa3b, v50
	v_exp_f32_e32 v51, v51
	v_exp_f32_e32 v50, v50
	v_add_f32_e32 v48, 1.0, v48
	v_add_f32_e32 v49, 1.0, v49
	v_pk_mul_f32 v[52:53], v[52:53], v[58:59] op_sel_hi:[1,0]
	v_add_f32_e32 v51, 1.0, v51
	v_rcp_f32_e32 v48, v48
	v_rcp_f32_e32 v49, v49
	v_add_f32_e32 v50, 1.0, v50
	v_pk_mul_f32 v[54:55], v[54:55], v[58:59] op_sel_hi:[1,0]
	v_mul_f32_e32 v52, 0xbfb8aa3b, v52
	v_mul_f32_e32 v53, 0xbfb8aa3b, v53
	v_rcp_f32_e32 v51, v51
	v_rcp_f32_e32 v50, v50
	v_mul_f32_e32 v55, 0xbfb8aa3b, v55
	v_exp_f32_e32 v52, v52
	v_exp_f32_e32 v53, v53
	v_mul_f32_e32 v54, 0xbfb8aa3b, v54
	v_exp_f32_e32 v55, v55
	v_exp_f32_e32 v54, v54
	v_fma_f32 v48, v48, s4, 0.5
	v_fma_f32 v49, v49, s4, 0.5
	v_max_f32_e32 v48, 1.0, v48
	v_max_f32_e32 v49, 1.0, v49
	v_fma_f32 v50, v50, s4, 0.5
	v_fma_f32 v51, v51, s4, 0.5
	v_add_f32_e32 v52, 1.0, v52
	v_add_f32_e32 v53, 1.0, v53
	v_cvt_u32_f32_e32 v48, v48
	v_cvt_u32_f32_e32 v49, v49
	v_max_f32_e32 v50, 1.0, v50
	v_max_f32_e32 v51, 1.0, v51
	v_add_f32_e32 v55, 1.0, v55
	v_rcp_f32_e32 v52, v52
	v_rcp_f32_e32 v53, v53
	v_cvt_u32_f32_sdwa v50, v50 dst_sel:WORD_1 dst_unused:UNUSED_PAD src0_sel:DWORD
	v_cvt_u32_f32_sdwa v51, v51 dst_sel:BYTE_3 dst_unused:UNUSED_PAD src0_sel:DWORD
	v_add_f32_e32 v54, 1.0, v54
	v_rcp_f32_e32 v55, v55
	v_rcp_f32_e32 v54, v54
	v_lshl_or_b32 v48, v49, 8, v48
	v_or3_b32 v48, v48, v50, v51
	v_fma_f32 v49, v52, s4, 0.5
	v_fma_f32 v50, v53, s4, 0.5
	v_pk_mul_f32 v[44:45], v[44:45], v[58:59] op_sel_hi:[1,0]
	v_max_f32_e32 v49, 1.0, v49
	v_max_f32_e32 v50, 1.0, v50
	v_fma_f32 v51, v54, s4, 0.5
	v_fma_f32 v52, v55, s4, 0.5
	v_mul_f32_e32 v45, 0xbfb8aa3b, v45
	v_cvt_u32_f32_e32 v49, v49
	v_cvt_u32_f32_e32 v50, v50
	v_max_f32_e32 v51, 1.0, v51
	v_max_f32_e32 v52, 1.0, v52
	v_exp_f32_e32 v45, v45
	v_cvt_u32_f32_sdwa v51, v51 dst_sel:WORD_1 dst_unused:UNUSED_PAD src0_sel:DWORD
	v_cvt_u32_f32_sdwa v52, v52 dst_sel:BYTE_3 dst_unused:UNUSED_PAD src0_sel:DWORD
	v_pk_mul_f32 v[40:41], v[40:41], v[58:59] op_sel_hi:[1,0]
	v_mul_f32_e32 v44, 0xbfb8aa3b, v44
	v_mul_f32_e32 v41, 0xbfb8aa3b, v41
	v_lshl_or_b32 v49, v50, 8, v49
	v_exp_f32_e32 v50, v44
	v_add_f32_e32 v44, 1.0, v45
	v_exp_f32_e32 v41, v41
	v_or3_b32 v49, v49, v51, v52
	v_rcp_f32_e32 v51, v44
	v_mul_f32_e32 v40, 0xbfb8aa3b, v40
	v_pk_mul_f32 v[44:45], v[46:47], v[58:59] op_sel_hi:[1,0]
	v_add_f32_e32 v46, 1.0, v50
	v_exp_f32_e32 v50, v40
	v_add_f32_e32 v40, 1.0, v41
	v_fma_f32 v47, v51, s4, 0.5
	v_rcp_f32_e32 v51, v40
	v_pk_mul_f32 v[40:41], v[42:43], v[58:59] op_sel_hi:[1,0]
; __device__ __forceinline__ float sigmoidf_(float v) { return __builtin_amdgcn_rcpf(1.0f + __expf(-v)); }
; #define MEMFENCE asm volatile("" ::: "memory")
; __device__ __forceinline__ unsigned pack4_u8c(const f32x4 v) { const unsigned q0 = (unsigned)fmaxf(v[0] * 255.0f + 0.5f, 1.0f), q1 = (unsigned)fmaxf(v[1] * 255.0f + 0.5f, 1.0f), q2 = (unsigned)fmaxf(v[2] * 255.0f + 0.5f, 1.0f), q3 = (unsigned)fmaxf(v[3] * 255.0f + 0.5f, 1.0f);
;     return q0 | (q1 << 8) | (q2 << 16) | (q3 << 24); }
;     template <int KIND> __device__ __forceinline__ void run(f32x4 (&acc)[2][2][4][2], const Unit& u, int tid_in) const {
;     ...
;                 for (int m = 0; m < 4; ++m) { const float r = rs[ai * 4 + m] * (1.0f / GATE_WSCALE); u32x4 w;
; #pragma unroll
;                     for (int bj = 0; bj < 2; ++bj) { f32x4 a = acc[ai][bj][m][0] * r, b = acc[ai][bj][m][1] * r;
; #pragma unroll
;                         for (int j = 0; j < 4; ++j) { a[j] = sigmoidf_(a[j]); b[j] = sigmoidf_(b[j]); }
;                         if (bj == 0) { w.x = pack4_u8c(a); w.y = pack4_u8c(b); } else { w.z = pack4_u8c(a); w.w = pack4_u8c(b); } }
;                     gst[(ai * 4 + m) * 512 + tid] = w; MEMFENCE; }
	v_add_f32_e32 v42, 1.0, v50
	v_mul_f32_e32 v40, 0xbfb8aa3b, v40
	v_mul_f32_e32 v41, 0xbfb8aa3b, v41
	v_exp_f32_e32 v40, v40
	v_exp_f32_e32 v41, v41
	v_rcp_f32_e32 v42, v42
	v_fma_f32 v43, v51, s4, 0.5
	v_add_f32_e32 v40, 1.0, v40
	v_add_f32_e32 v41, 1.0, v41
	v_rcp_f32_e32 v40, v40
	v_rcp_f32_e32 v41, v41
	v_fma_f32 v42, v42, s4, 0.5
	v_max_f32_e32 v43, 1.0, v43
	v_max_f32_e32 v42, 1.0, v42
	v_fma_f32 v40, v40, s4, 0.5
	v_fma_f32 v41, v41, s4, 0.5
	v_cvt_u32_f32_e32 v43, v43
	v_cvt_u32_f32_e32 v42, v42
	v_max_f32_e32 v40, 1.0, v40
	v_max_f32_e32 v41, 1.0, v41
	v_cvt_u32_f32_sdwa v40, v40 dst_sel:WORD_1 dst_unused:UNUSED_PAD src0_sel:DWORD
	v_cvt_u32_f32_sdwa v41, v41 dst_sel:BYTE_3 dst_unused:UNUSED_PAD src0_sel:DWORD
	v_lshl_or_b32 v42, v43, 8, v42
	v_exp_f32_e32 v92, v92
	v_exp_f32_e32 v93, v93
	v_or3_b32 v51, v42, v40, v41
	v_mul_f32_e32 v42, 0x3c800000, v136
	v_pk_mul_f32 v[32:33], v[32:33], v[42:43] op_sel_hi:[1,0]
	v_pk_mul_f32 v[34:35], v[34:35], v[42:43] op_sel_hi:[1,0]
	v_mul_f32_e32 v32, 0xbfb8aa3b, v32
	v_mul_f32_e32 v33, 0xbfb8aa3b, v33
	v_mul_f32_e32 v35, 0xbfb8aa3b, v35
	v_exp_f32_e32 v32, v32
	v_exp_f32_e32 v33, v33
	v_mul_f32_e32 v34, 0xbfb8aa3b, v34
	v_exp_f32_e32 v35, v35
	v_exp_f32_e32 v34, v34
	v_add_f32_e32 v32, 1.0, v32
	v_add_f32_e32 v33, 1.0, v33
	v_pk_mul_f32 v[36:37], v[36:37], v[42:43] op_sel_hi:[1,0]
	v_add_f32_e32 v35, 1.0, v35
	v_rcp_f32_e32 v32, v32
	v_rcp_f32_e32 v33, v33
	v_add_f32_e32 v34, 1.0, v34
	v_pk_mul_f32 v[38:39], v[38:39], v[42:43] op_sel_hi:[1,0]
	v_mul_f32_e32 v36, 0xbfb8aa3b, v36
	v_mul_f32_e32 v37, 0xbfb8aa3b, v37
	v_rcp_f32_e32 v35, v35
	v_rcp_f32_e32 v34, v34
	v_mul_f32_e32 v39, 0xbfb8aa3b, v39
	v_exp_f32_e32 v36, v36
	v_exp_f32_e32 v37, v37
	v_mul_f32_e32 v38, 0xbfb8aa3b, v38
	v_exp_f32_e32 v39, v39
	v_exp_f32_e32 v38, v38
	v_fma_f32 v32, v32, s4, 0.5
	v_fma_f32 v33, v33, s4, 0.5
	v_max_f32_e32 v32, 1.0, v32
	v_max_f32_e32 v33, 1.0, v33
	v_fma_f32 v34, v34, s4, 0.5
	v_fma_f32 v35, v35, s4, 0.5
	v_add_f32_e32 v36, 1.0, v36
	v_add_f32_e32 v37, 1.0, v37
	v_cvt_u32_f32_e32 v32, v32
	v_cvt_u32_f32_e32 v33, v33
	v_max_f32_e32 v34, 1.0, v34
	v_max_f32_e32 v35, 1.0, v35
	v_add_f32_e32 v39, 1.0, v39
	v_rcp_f32_e32 v36, v36
	v_rcp_f32_e32 v37, v37
	v_cvt_u32_f32_sdwa v34, v34 dst_sel:WORD_1 dst_unused:UNUSED_PAD src0_sel:DWORD
	v_cvt_u32_f32_sdwa v35, v35 dst_sel:BYTE_3 dst_unused:UNUSED_PAD src0_sel:DWORD
	v_add_f32_e32 v38, 1.0, v38
	v_rcp_f32_e32 v39, v39
	v_rcp_f32_e32 v38, v38
	v_lshl_or_b32 v32, v33, 8, v32
	v_or3_b32 v32, v32, v34, v35
	v_fma_f32 v33, v36, s4, 0.5
	v_fma_f32 v34, v37, s4, 0.5
	v_pk_mul_f32 v[28:29], v[28:29], v[42:43] op_sel_hi:[1,0]
	v_max_f32_e32 v33, 1.0, v33
	v_max_f32_e32 v34, 1.0, v34
	v_fma_f32 v35, v38, s4, 0.5
	v_fma_f32 v36, v39, s4, 0.5
	v_mul_f32_e32 v29, 0xbfb8aa3b, v29
	v_cvt_u32_f32_e32 v33, v33
	v_cvt_u32_f32_e32 v34, v34
	v_max_f32_e32 v35, 1.0, v35
	v_max_f32_e32 v36, 1.0, v36
	v_exp_f32_e32 v29, v29
	v_cvt_u32_f32_sdwa v35, v35 dst_sel:WORD_1 dst_unused:UNUSED_PAD src0_sel:DWORD
	v_cvt_u32_f32_sdwa v36, v36 dst_sel:BYTE_3 dst_unused:UNUSED_PAD src0_sel:DWORD
	v_pk_mul_f32 v[24:25], v[24:25], v[42:43] op_sel_hi:[1,0]
	v_mul_f32_e32 v28, 0xbfb8aa3b, v28
	v_mul_f32_e32 v25, 0xbfb8aa3b, v25
	v_lshl_or_b32 v33, v34, 8, v33
	v_exp_f32_e32 v34, v28
	v_add_f32_e32 v28, 1.0, v29
	v_exp_f32_e32 v25, v25
	v_or3_b32 v33, v33, v35, v36
	v_rcp_f32_e32 v35, v28
	v_mul_f32_e32 v24, 0xbfb8aa3b, v24
	v_mul_f32_e32 v76, 0xbfb8aa3b, v76
	v_mul_f32_e32 v77, 0xbfb8aa3b, v77
	v_pk_mul_f32 v[28:29], v[30:31], v[42:43] op_sel_hi:[1,0]
	v_add_f32_e32 v30, 1.0, v34
	v_exp_f32_e32 v34, v24
	v_add_f32_e32 v24, 1.0, v25
	v_exp_f32_e32 v76, v76
	v_exp_f32_e32 v77, v77
	v_mul_f32_e32 v60, 0xbfb8aa3b, v60
	v_mul_f32_e32 v61, 0xbfb8aa3b, v61
	v_fma_f32 v31, v35, s4, 0.5
	v_rcp_f32_e32 v35, v24
	v_pk_mul_f32 v[24:25], v[26:27], v[42:43] op_sel_hi:[1,0]
	v_rcp_f32_e32 v126, v126
	v_add_f32_e32 v124, 1.0, v124
	v_add_f32_e32 v125, 1.0, v125
	v_exp_f32_e32 v60, v60
	v_exp_f32_e32 v61, v61
	v_mul_f32_e32 v44, 0xbfb8aa3b, v44
	v_mul_f32_e32 v45, 0xbfb8aa3b, v45
	v_mul_f32_e32 v24, 0xbfb8aa3b, v24
	v_mul_f32_e32 v25, 0xbfb8aa3b, v25
	v_rcp_f32_e32 v124, v124
	v_rcp_f32_e32 v125, v125
	v_rcp_f32_e32 v110, v110
	v_add_f32_e32 v108, 1.0, v108
	v_add_f32_e32 v109, 1.0, v109
	v_exp_f32_e32 v44, v44
	v_exp_f32_e32 v45, v45
	v_mul_f32_e32 v28, 0xbfb8aa3b, v28
	v_mul_f32_e32 v29, 0xbfb8aa3b, v29
	v_exp_f32_e32 v24, v24
	v_exp_f32_e32 v25, v25
	s_lshl_b64 s[2:3], s[2:3], 16
	v_rcp_f32_e32 v108, v108
	v_rcp_f32_e32 v109, v109
	v_rcp_f32_e32 v94, v94
	v_add_f32_e32 v92, 1.0, v92
	v_add_f32_e32 v93, 1.0, v93
	v_exp_f32_e32 v28, v28
	v_exp_f32_e32 v29, v29
	s_add_u32 s2, s29, s2
	v_rcp_f32_e32 v92, v92
	v_rcp_f32_e32 v93, v93
	v_rcp_f32_e32 v78, v78
	v_add_f32_e32 v76, 1.0, v76
	v_add_f32_e32 v77, 1.0, v77
	s_addc_u32 s3, s30, s3
	v_fma_f32 v126, v126, s4, 0.5
	v_ashrrev_i32_e32 v143, 31, v142
	v_rcp_f32_e32 v76, v76
	v_rcp_f32_e32 v77, v77
	v_rcp_f32_e32 v62, v62
	v_add_f32_e32 v60, 1.0, v60
	v_add_f32_e32 v61, 1.0, v61
	v_add_f32_e32 v26, 1.0, v34
	v_max_f32_e32 v127, 1.0, v127
	v_max_f32_e32 v126, 1.0, v126
	v_fma_f32 v124, v124, s4, 0.5
	v_fma_f32 v125, v125, s4, 0.5
	v_lshl_add_u64 v[120:121], v[142:143], 4, s[2:3]
	v_fma_f32 v110, v110, s4, 0.5
	s_movk_i32 s2, 0x2000
	v_rcp_f32_e32 v60, v60
	v_rcp_f32_e32 v61, v61
	v_rcp_f32_e32 v46, v46
	v_add_f32_e32 v44, 1.0, v44
	v_add_f32_e32 v45, 1.0, v45
	v_rcp_f32_e32 v26, v26
	v_add_f32_e32 v24, 1.0, v24
	v_add_f32_e32 v25, 1.0, v25
	v_cvt_u32_f32_e32 v127, v127
	v_cvt_u32_f32_e32 v126, v126
	v_max_f32_e32 v124, 1.0, v124
	v_max_f32_e32 v125, 1.0, v125
; __device__ __forceinline__ float sigmoidf_(float v) { return __builtin_amdgcn_rcpf(1.0f + __expf(-v)); }
; #define MEMFENCE asm volatile("" ::: "memory")
;     template <int KIND> __device__ __forceinline__ void run(f32x4 (&acc)[2][2][4][2], const Unit& u, int tid_in) const {
;     ...
;                 for (int m = 0; m < 4; ++m) { const float r = rs[ai * 4 + m] * (1.0f / GATE_WSCALE); u32x4 w;
; #pragma unroll
;                     for (int bj = 0; bj < 2; ++bj) { f32x4 a = acc[ai][bj][m][0] * r, b = acc[ai][bj][m][1] * r;
; #pragma unroll
;                         for (int j = 0; j < 4; ++j) { a[j] = sigmoidf_(a[j]); b[j] = sigmoidf_(b[j]); }
;                         if (bj == 0) { w.x = pack4_u8c(a); w.y = pack4_u8c(b); } else { w.z = pack4_u8c(a); w.w = pack4_u8c(b); } }
;                     gst[(ai * 4 + m) * 512 + tid] = w; MEMFENCE; }
	v_max_f32_e32 v111, 1.0, v111
	v_max_f32_e32 v110, 1.0, v110
	v_fma_f32 v108, v108, s4, 0.5
	v_fma_f32 v109, v109, s4, 0.5
	v_add_co_u32_e32 v104, vcc, s2, v120
	v_fma_f32 v94, v94, s4, 0.5
	v_rcp_f32_e32 v44, v44
	v_rcp_f32_e32 v45, v45
	v_rcp_f32_e32 v30, v30
	v_add_f32_e32 v28, 1.0, v28
	v_add_f32_e32 v29, 1.0, v29
	v_rcp_f32_e32 v24, v24
	v_rcp_f32_e32 v25, v25
	v_cvt_u32_f32_sdwa v124, v124 dst_sel:WORD_1 dst_unused:UNUSED_PAD src0_sel:DWORD
	v_cvt_u32_f32_sdwa v125, v125 dst_sel:BYTE_3 dst_unused:UNUSED_PAD src0_sel:DWORD
	v_cvt_u32_f32_e32 v111, v111
	v_cvt_u32_f32_e32 v110, v110
	v_max_f32_e32 v108, 1.0, v108
	v_max_f32_e32 v109, 1.0, v109
	v_addc_co_u32_e32 v105, vcc, 0, v121, vcc
	v_max_f32_e32 v95, 1.0, v95
	v_max_f32_e32 v94, 1.0, v94
	v_fma_f32 v92, v92, s4, 0.5
	v_fma_f32 v93, v93, s4, 0.5
	v_fma_f32 v78, v78, s4, 0.5
	v_rcp_f32_e32 v28, v28
	v_rcp_f32_e32 v29, v29
	v_cvt_u32_f32_sdwa v108, v108 dst_sel:WORD_1 dst_unused:UNUSED_PAD src0_sel:DWORD
	v_cvt_u32_f32_sdwa v109, v109 dst_sel:BYTE_3 dst_unused:UNUSED_PAD src0_sel:DWORD
	v_cvt_u32_f32_e32 v95, v95
	v_cvt_u32_f32_e32 v94, v94
	v_max_f32_e32 v92, 1.0, v92
	v_max_f32_e32 v93, 1.0, v93
	v_add_co_u32_e32 v88, vcc, s49, v120
	v_max_f32_e32 v79, 1.0, v79
	v_max_f32_e32 v78, 1.0, v78
	v_fma_f32 v76, v76, s4, 0.5
	v_fma_f32 v77, v77, s4, 0.5
	v_fma_f32 v62, v62, s4, 0.5
	v_cvt_u32_f32_sdwa v92, v92 dst_sel:WORD_1 dst_unused:UNUSED_PAD src0_sel:DWORD
	v_cvt_u32_f32_sdwa v93, v93 dst_sel:BYTE_3 dst_unused:UNUSED_PAD src0_sel:DWORD
	v_addc_co_u32_e32 v89, vcc, 0, v121, vcc
	v_cvt_u32_f32_e32 v79, v79
	v_cvt_u32_f32_e32 v78, v78
	v_max_f32_e32 v76, 1.0, v76
	v_max_f32_e32 v77, 1.0, v77
	s_movk_i32 s2, 0x6000
	v_max_f32_e32 v63, 1.0, v63
	v_max_f32_e32 v62, 1.0, v62
	v_fma_f32 v60, v60, s4, 0.5
	v_fma_f32 v61, v61, s4, 0.5
	v_fma_f32 v46, v46, s4, 0.5
	v_fma_f32 v27, v35, s4, 0.5
	v_fma_f32 v26, v26, s4, 0.5
	v_lshl_or_b32 v126, v127, 8, v126
	v_cvt_u32_f32_sdwa v76, v76 dst_sel:WORD_1 dst_unused:UNUSED_PAD src0_sel:DWORD
	v_cvt_u32_f32_sdwa v77, v77 dst_sel:BYTE_3 dst_unused:UNUSED_PAD src0_sel:DWORD
	v_add_co_u32_e32 v72, vcc, s2, v120
	v_cvt_u32_f32_e32 v63, v63
	v_cvt_u32_f32_e32 v62, v62
	v_max_f32_e32 v60, 1.0, v60
	v_max_f32_e32 v61, 1.0, v61
	v_max_f32_e32 v47, 1.0, v47
	v_max_f32_e32 v46, 1.0, v46
	v_fma_f32 v44, v44, s4, 0.5
	v_fma_f32 v45, v45, s4, 0.5
	v_fma_f32 v30, v30, s4, 0.5
	v_max_f32_e32 v27, 1.0, v27
	v_max_f32_e32 v26, 1.0, v26
	v_fma_f32 v24, v24, s4, 0.5
	v_fma_f32 v25, v25, s4, 0.5
	v_or3_b32 v130, v126, v124, v125
	v_lshl_or_b32 v110, v111, 8, v110
	v_addc_co_u32_e32 v73, vcc, 0, v121, vcc
	v_cvt_u32_f32_sdwa v60, v60 dst_sel:WORD_1 dst_unused:UNUSED_PAD src0_sel:DWORD
	v_cvt_u32_f32_sdwa v61, v61 dst_sel:BYTE_3 dst_unused:UNUSED_PAD src0_sel:DWORD
	v_cvt_u32_f32_e32 v47, v47
	v_cvt_u32_f32_e32 v46, v46
	v_max_f32_e32 v44, 1.0, v44
	v_max_f32_e32 v45, 1.0, v45
	v_max_f32_e32 v31, 1.0, v31
	v_max_f32_e32 v30, 1.0, v30
	v_fma_f32 v28, v28, s4, 0.5
	v_fma_f32 v29, v29, s4, 0.5
	v_cvt_u32_f32_e32 v27, v27
	v_cvt_u32_f32_e32 v26, v26
	v_max_f32_e32 v24, 1.0, v24
	v_max_f32_e32 v25, 1.0, v25
	global_store_dwordx4 v[120:121], v[128:131], off
	v_or3_b32 v114, v110, v108, v109
	v_lshl_or_b32 v94, v95, 8, v94
	v_add_co_u32_e32 v56, vcc, s77, v120
	v_cvt_u32_f32_sdwa v44, v44 dst_sel:WORD_1 dst_unused:UNUSED_PAD src0_sel:DWORD
	v_cvt_u32_f32_sdwa v45, v45 dst_sel:BYTE_3 dst_unused:UNUSED_PAD src0_sel:DWORD
	v_cvt_u32_f32_e32 v31, v31
	v_cvt_u32_f32_e32 v30, v30
	v_max_f32_e32 v28, 1.0, v28
	v_max_f32_e32 v29, 1.0, v29
	v_cvt_u32_f32_sdwa v24, v24 dst_sel:WORD_1 dst_unused:UNUSED_PAD src0_sel:DWORD
	v_cvt_u32_f32_sdwa v25, v25 dst_sel:BYTE_3 dst_unused:UNUSED_PAD src0_sel:DWORD
	global_store_dwordx4 v[104:105], v[112:115], off
	v_or3_b32 v98, v94, v92, v93
	v_lshl_or_b32 v78, v79, 8, v78
	v_addc_co_u32_e32 v57, vcc, 0, v121, vcc
	s_mov_b32 s2, 0xa000
	v_cvt_u32_f32_sdwa v28, v28 dst_sel:WORD_1 dst_unused:UNUSED_PAD src0_sel:DWORD
	v_cvt_u32_f32_sdwa v29, v29 dst_sel:BYTE_3 dst_unused:UNUSED_PAD src0_sel:DWORD
	global_store_dwordx4 v[88:89], v[96:99], off
	v_or3_b32 v82, v78, v76, v77
	v_lshl_or_b32 v62, v63, 8, v62
	v_add_co_u32_e32 v40, vcc, s2, v120
	global_store_dwordx4 v[72:73], v[80:83], off
	v_or3_b32 v66, v62, v60, v61
	v_lshl_or_b32 v46, v47, 8, v46
	v_addc_co_u32_e32 v41, vcc, 0, v121, vcc
	v_lshl_or_b32 v26, v27, 8, v26
	s_mov_b32 s2, 0xc000
	global_store_dwordx4 v[56:57], v[64:67], off
	v_or3_b32 v50, v46, v44, v45
	v_lshl_or_b32 v30, v31, 8, v30
	v_or3_b32 v35, v26, v24, v25
	v_add_co_u32_e32 v24, vcc, s2, v120
	global_store_dwordx4 v[40:41], v[48:51], off
	v_or3_b32 v34, v30, v28, v29
	v_addc_co_u32_e32 v25, vcc, 0, v121, vcc
	global_store_dwordx4 v[24:25], v[32:35], off
	v_mul_f32_e32 v24, 0x3c800000, v137
; __device__ __forceinline__ float sigmoidf_(float v) { return __builtin_amdgcn_rcpf(1.0f + __expf(-v)); }
; #define MEMFENCE asm volatile("" ::: "memory")
;     template <int KIND> __device__ __forceinline__ void run(f32x4 (&acc)[2][2][4][2], const Unit& u, int tid_in) const {
;     ...
;                     for (int bj = 0; bj < 2; ++bj) { f32x4 a = acc[ai][bj][m][0] * r, b = acc[ai][bj][m][1] * r;
; #pragma unroll
;                         for (int j = 0; j < 4; ++j) { a[j] = sigmoidf_(a[j]); b[j] = sigmoidf_(b[j]); }
;                         if (bj == 0) { w.x = pack4_u8c(a); w.y = pack4_u8c(b); } else { w.z = pack4_u8c(a); w.w = pack4_u8c(b); } }
;                     gst[(ai * 4 + m) * 512 + tid] = w; MEMFENCE; }
;     ...
;         E.template run<cs.kind>(acc, cur, tid);
;         if (!has_next) break;
;         if (!(cs.kind == K_MG_B && cur.aux < 2))
	v_pk_mul_f32 v[20:21], v[20:21], v[24:25] op_sel_hi:[1,0]
	s_mov_b32 s33, s35
	v_mul_f32_e32 v21, 0xbfb8aa3b, v21
	v_exp_f32_e32 v21, v21
	v_mul_f32_e32 v20, 0xbfb8aa3b, v20
	v_exp_f32_e32 v25, v20
	s_mov_b32 s36, s34
	v_add_f32_e32 v20, 1.0, v21
	v_rcp_f32_e32 v26, v20
	v_pk_mul_f32 v[20:21], v[22:23], v[24:25] op_sel_hi:[1,0]
	v_add_f32_e32 v22, 1.0, v25
	v_mul_f32_e32 v20, 0xbfb8aa3b, v20
	v_exp_f32_e32 v20, v20
	v_rcp_f32_e32 v22, v22
	v_mul_f32_e32 v21, 0xbfb8aa3b, v21
	v_exp_f32_e32 v21, v21
	v_add_f32_e32 v20, 1.0, v20
	v_fma_f32 v23, v26, s4, 0.5
	v_fma_f32 v22, v22, s4, 0.5
	v_rcp_f32_e32 v20, v20
	v_max_f32_e32 v23, 1.0, v23
	v_max_f32_e32 v22, 1.0, v22
	v_add_f32_e32 v21, 1.0, v21
	v_cvt_u32_f32_e32 v23, v23
	v_cvt_u32_f32_e32 v22, v22
	v_rcp_f32_e32 v21, v21
	v_fma_f32 v20, v20, s4, 0.5
	v_max_f32_e32 v20, 1.0, v20
	v_lshl_or_b32 v22, v23, 8, v22
	v_cvt_u32_f32_sdwa v23, v20 dst_sel:WORD_1 dst_unused:UNUSED_PAD src0_sel:DWORD
	v_fma_f32 v20, v21, s4, 0.5
	v_max_f32_e32 v20, 1.0, v20
	v_cvt_u32_f32_sdwa v25, v20 dst_sel:BYTE_3 dst_unused:UNUSED_PAD src0_sel:DWORD
	s_mov_b64 s[12:13], s[10:11]
	s_mov_b64 s[2:3], s[8:9]
	v_pk_mul_f32 v[20:21], v[16:17], v[24:25] op_sel_hi:[1,0]
	s_nop 0
	v_mul_f32_e32 v16, 0xbfb8aa3b, v21
	v_mul_f32_e32 v20, 0xbfb8aa3b, v20
	v_pk_mul_f32 v[18:19], v[18:19], v[24:25] op_sel_hi:[1,0]
	v_exp_f32_e32 v17, v16
	v_exp_f32_e32 v20, v20
	v_mul_f32_e32 v18, 0xbfb8aa3b, v18
	v_mul_f32_e32 v19, 0xbfb8aa3b, v19
	v_exp_f32_e32 v18, v18
	v_exp_f32_e32 v19, v19
	v_add_f32_e32 v17, 1.0, v17
	v_add_f32_e32 v20, 1.0, v20
	v_rcp_f32_e32 v17, v17
	v_rcp_f32_e32 v20, v20
	v_add_f32_e32 v18, 1.0, v18
	v_add_f32_e32 v19, 1.0, v19
	v_rcp_f32_e32 v18, v18
	v_rcp_f32_e32 v19, v19
	v_fma_f32 v17, v17, s4, 0.5
	v_fma_f32 v20, v20, s4, 0.5
	v_max_f32_e32 v17, 1.0, v17
	v_max_f32_e32 v20, 1.0, v20
	v_fma_f32 v18, v18, s4, 0.5
	v_fma_f32 v19, v19, s4, 0.5
	v_pk_mul_f32 v[12:13], v[12:13], v[24:25] op_sel_hi:[1,0]
	v_cvt_u32_f32_e32 v17, v17
	v_cvt_u32_f32_e32 v20, v20
	v_max_f32_e32 v18, 1.0, v18
	v_max_f32_e32 v19, 1.0, v19
	v_mul_f32_e32 v13, 0xbfb8aa3b, v13
	v_cvt_u32_f32_sdwa v18, v18 dst_sel:WORD_1 dst_unused:UNUSED_PAD src0_sel:DWORD
	v_cvt_u32_f32_sdwa v19, v19 dst_sel:BYTE_3 dst_unused:UNUSED_PAD src0_sel:DWORD
	v_exp_f32_e32 v13, v13
	v_pk_mul_f32 v[8:9], v[8:9], v[24:25] op_sel_hi:[1,0]
	v_lshl_or_b32 v17, v17, 8, v20
	v_mul_f32_e32 v12, 0xbfb8aa3b, v12
	v_mul_f32_e32 v9, 0xbfb8aa3b, v9
	v_or3_b32 v17, v17, v18, v19
	v_exp_f32_e32 v18, v12
	v_add_f32_e32 v12, 1.0, v13
	v_exp_f32_e32 v9, v9
	v_rcp_f32_e32 v19, v12
	v_mul_f32_e32 v8, 0xbfb8aa3b, v8
	v_pk_mul_f32 v[12:13], v[14:15], v[24:25] op_sel_hi:[1,0]
	v_add_f32_e32 v14, 1.0, v18
	v_exp_f32_e32 v18, v8
	v_add_f32_e32 v8, 1.0, v9
	v_fma_f32 v15, v19, s4, 0.5
	v_rcp_f32_e32 v19, v8
	v_pk_mul_f32 v[8:9], v[10:11], v[24:25] op_sel_hi:[1,0]
	v_mul_f32_e32 v12, 0xbfb8aa3b, v12
	v_mul_f32_e32 v8, 0xbfb8aa3b, v8
	v_mul_f32_e32 v9, 0xbfb8aa3b, v9
	v_mul_f32_e32 v13, 0xbfb8aa3b, v13
	v_exp_f32_e32 v8, v8
	v_exp_f32_e32 v9, v9
	v_exp_f32_e32 v12, v12
	v_exp_f32_e32 v13, v13
	v_add_f32_e32 v10, 1.0, v18
	v_rcp_f32_e32 v10, v10
	v_add_f32_e32 v8, 1.0, v8
	v_add_f32_e32 v9, 1.0, v9
	v_rcp_f32_e32 v14, v14
	v_add_f32_e32 v12, 1.0, v12
	v_add_f32_e32 v13, 1.0, v13
	v_rcp_f32_e32 v8, v8
	v_rcp_f32_e32 v9, v9
	v_rcp_f32_e32 v12, v12
	v_rcp_f32_e32 v13, v13
	v_fma_f32 v11, v19, s4, 0.5
	v_fma_f32 v10, v10, s4, 0.5
	v_fma_f32 v14, v14, s4, 0.5
	v_max_f32_e32 v11, 1.0, v11
	v_max_f32_e32 v10, 1.0, v10
	v_fma_f32 v8, v8, s4, 0.5
	v_fma_f32 v9, v9, s4, 0.5
	v_max_f32_e32 v15, 1.0, v15
	v_max_f32_e32 v14, 1.0, v14
	v_fma_f32 v12, v12, s4, 0.5
	v_fma_f32 v13, v13, s4, 0.5
	v_cvt_u32_f32_e32 v11, v11
	v_cvt_u32_f32_e32 v10, v10
	v_max_f32_e32 v8, 1.0, v8
	v_max_f32_e32 v9, 1.0, v9
	v_cvt_u32_f32_e32 v15, v15
	v_cvt_u32_f32_e32 v14, v14
	v_max_f32_e32 v12, 1.0, v12
	v_max_f32_e32 v13, 1.0, v13
	v_cvt_u32_f32_sdwa v8, v8 dst_sel:WORD_1 dst_unused:UNUSED_PAD src0_sel:DWORD
	v_cvt_u32_f32_sdwa v9, v9 dst_sel:BYTE_3 dst_unused:UNUSED_PAD src0_sel:DWORD
	v_cvt_u32_f32_sdwa v12, v12 dst_sel:WORD_1 dst_unused:UNUSED_PAD src0_sel:DWORD
	v_cvt_u32_f32_sdwa v13, v13 dst_sel:BYTE_3 dst_unused:UNUSED_PAD src0_sel:DWORD
	v_lshl_or_b32 v10, v11, 8, v10
	v_lshl_or_b32 v14, v15, 8, v14
	v_or3_b32 v19, v10, v8, v9
	v_add_co_u32_e32 v8, vcc, 0xe000, v120
	v_or3_b32 v16, v22, v23, v25
	v_or3_b32 v18, v14, v12, v13
	v_addc_co_u32_e32 v9, vcc, 0, v121, vcc
	global_store_dwordx4 v[8:9], v[16:19], off
	s_and_b64 vcc, exec, s[6:7]
	s_cbranch_vccz .LBB0_867
	s_cmpk_gt_u32 s101, 0xff
	s_cbranch_scc0 .Ldbj_MG0_pe
	s_barrier
	s_mov_b32 s101, 0
.Ldbj_MG0_pe:
	s_waitcnt vmcnt(0)
	s_cmpk_gt_u32 s16, 0xff
	s_cbranch_scc1 .LBB0_876
	s_barrier

; #define G_STAGE(bufoff, gbase, o0, h64) do { \
;         __builtin_amdgcn_global_load_lds((const unsigned*)((const char*)(gbase) + (o0)), (LAS unsigned*)(lds + (bufoff) + ldsw), 16, 0, 0); \
;         __builtin_amdgcn_global_load_lds((const unsigned*)((const char*)(gbase) + (h64) + (o0)), (LAS unsigned*)(lds + (bufoff) + ldsw + 8192), 16, 0, 0); } while (0)
; #define G_LDA(dst, b, h) do { _Pragma("unroll") for (int m = 0; m < 4; ++m) _Pragma("unroll") for (int k = 0; k < 2; ++k) dst[m][k] = *(const LAS bf16x8*)(lds + G_SA(b, h) + aoff + m * 2048 + k * 1024); } while (0)
; #define G_WAIT_V(n) asm volatile("s_waitcnt vmcnt(" #n ")" ::: "memory")
; #define G_BAR __builtin_amdgcn_s_barrier()
;     ...
;         const bool has_next = sched_next<PH, SUB>(E.ws, E.layer, ui + 1, nxt, E.x);
;         if (!has_next) nxt = cur;
;         const char* nA = nxt.A; const char* nB = nxt.B;
; #pragma unroll 1
;         for (int t = 0; t < nt; t += 2) {
;             const bool last = (t == nt - 2);
;             const char* a1 = cA + (size_t)(t + 1) * ckA;
;             const char* a2 = last ? nA : cA + (size_t)(t + 2) * ckA; const char* b2 = last ? nB : cB + (size_t)(t + 2) * kB;
;             const char* a3 = a2 + ckA; const char* b3 = b2 + kB;
;             G_LDB(B0, 0, 0); G_SCHED; G_LDA(At, 0, 0); G_STAGE(G_SA(1, 1), a1 + chA, cA0, qA);
;             G_WAIT_L(8); G_BAR; G_WAIT_L(0); G_MMA(0, 0, At, B0); G_BAR; G_SCHED;
;             G_LDB(B1, 0, 1); G_STAGE(G_SB(0, 0), b2, cB0, qB);
;             G_BAR; G_WAIT_L(0); G_MMA(0, 1, At, B1); G_BAR;
;             G_LDA(At, 0, 1); G_STAGE(G_SA(0, 0), a2, cA0, qA);
;             G_BAR; G_WAIT_L(0); G_MMA(1, 0, At, B0); G_BAR; G_SCHED;
;             G_STAGE(G_SB(0, 1), b2 + chB, cB0, qB);
;             G_WAIT_V(6); G_BAR; G_MMA(1, 1, At, B1); G_BAR;
;             G_LDB(B0, 1, 0); G_SCHED; G_LDA(At, 1, 0); G_STAGE(G_SA(0, 1), a2 + chA, cA0, qA);
;             G_WAIT_L(8); G_BAR; G_WAIT_L(0); G_MMA(0, 0, At, B0); G_BAR; G_SCHED;
;             G_LDB(B1, 1, 1); G_STAGE(G_SB(1, 0), b3, cB0, qB);
;             G_BAR; G_WAIT_L(0); G_MMA(0, 1, At, B1); G_BAR;
;             G_LDA(At, 1, 1); G_STAGE(G_SA(1, 0), a3, cA0, qA);
;             G_BAR; G_WAIT_L(0); G_MMA(1, 0, At, B0); G_BAR; G_SCHED;
;             G_STAGE(G_SB(1, 1), b3 + chB, cB0, qB);
;             G_WAIT_V(6); G_BAR; G_MMA(1, 1, At, B1); G_BAR;
;         }
.LBB0_889:
	s_add_u32 s6, s6, 0xb0080
	s_addc_u32 s7, s7, 0
	s_add_u32 s8, s18, 0x100
	s_addc_u32 s9, s19, 0
	s_mov_b32 s18, -2
	s_mov_b64 s[50:51], 0x20080
	s_mov_b64 s[52:53], 0x30000
	s_mov_b64 s[54:55], 0x10080
	s_mov_b64 s[58:59], 0x30080
	s_cmpk_gt_u32 s101, 0xff
	s_cbranch_scc0 .Ldbj_MG1_in
	s_barrier
	s_mov_b32 s101, 0
.Ldbj_MG1_in:
.LBB0_890:
	s_add_u32 s4, s6, 0xfff50080
	s_addc_u32 s5, s7, -1
	s_add_i32 s19, 0, 0x10000
	v_add_u32_e32 v0, s19, v175
	ds_read_b128 v[136:139], v0
	ds_read_b128 v[140:143], v0 offset:1024
	ds_read_b128 v[144:147], v0 offset:2048
	ds_read_b128 v[148:151], v0 offset:3072
	s_cmp_eq_u32 s18, 4
	s_cselect_b32 s45, s15, s9
	s_cselect_b32 s44, s14, s8
	s_cselect_b32 s5, s13, s5
	s_cselect_b32 s4, s12, s4
	v_lshl_add_u64 v[2:3], s[6:7], 0, v[156:157]
	s_add_i32 m0, s22, 0xc000
	ds_read_b128 v[158:161], v176
	ds_read_b128 v[162:165], v176 offset:1024
	ds_read_b128 v[178:181], v176 offset:2048
	ds_read_b128 v[182:185], v176 offset:3072
	ds_read_b128 v[196:199], v176 offset:4096
	ds_read_b128 v[200:203], v176 offset:5120
	ds_read_b128 v[204:207], v176 offset:6144
	ds_read_b128 v[208:211], v176 offset:7168
	global_load_lds_dwordx4 v[2:3], off
	v_lshl_add_u64 v[2:3], v[2:3], 0, s[86:87]
	s_add_i32 m0, s22, 0xe000
	s_nop 0
	global_load_lds_dwordx4 v[2:3], off
	s_waitcnt lgkmcnt(8)
	s_barrier
	s_waitcnt lgkmcnt(0)
	s_setprio 3
	s_waitcnt lgkmcnt(0)
	v_mfma_f32_16x16x32_bf16 v[104:107], v[136:139], v[158:161], v[104:107]
	v_mfma_f32_16x16x32_bf16 v[108:111], v[144:147], v[158:161], v[108:111]
	v_mfma_f32_16x16x32_bf16 v[132:135], v[136:139], v[178:181], v[132:135]
	v_mfma_f32_16x16x32_bf16 v[128:131], v[144:147], v[178:181], v[128:131]
	v_mfma_f32_16x16x32_bf16 v[124:127], v[136:139], v[196:199], v[124:127]
	v_mfma_f32_16x16x32_bf16 v[120:123], v[144:147], v[196:199], v[120:123]
	v_mfma_f32_16x16x32_bf16 v[116:119], v[136:139], v[204:207], v[116:119]
	v_mfma_f32_16x16x32_bf16 v[112:115], v[144:147], v[204:207], v[112:115]
	v_mfma_f32_16x16x32_bf16 v[104:107], v[140:143], v[162:165], v[104:107]
	v_mfma_f32_16x16x32_bf16 v[108:111], v[148:151], v[162:165], v[108:111]
	v_mfma_f32_16x16x32_bf16 v[132:135], v[140:143], v[182:185], v[132:135]
	v_mfma_f32_16x16x32_bf16 v[128:131], v[148:151], v[182:185], v[128:131]
	v_mfma_f32_16x16x32_bf16 v[124:127], v[140:143], v[200:203], v[124:127]
	v_mfma_f32_16x16x32_bf16 v[120:123], v[148:151], v[200:203], v[120:123]
	v_mfma_f32_16x16x32_bf16 v[116:119], v[140:143], v[208:211], v[116:119]
	v_mfma_f32_16x16x32_bf16 v[112:115], v[148:151], v[208:211], v[112:115]
	s_setprio 0
	s_barrier
	s_add_i32 s43, 0, 0x14000
	s_add_i32 s19, s19, s21
	v_add_u32_e32 v0, s43, v175
	v_lshl_add_u64 v[2:3], s[44:45], 0, v[154:155]
	s_mov_b64 s[44:45], 0x10000
	s_mov_b32 m0, s19
	ds_read_b128 v[212:215], v0
	ds_read_b128 v[216:219], v0 offset:1024
	ds_read_b128 v[220:223], v0 offset:2048
	ds_read_b128 v[224:227], v0 offset:3072
	global_load_lds_dwordx4 v[2:3], off
	v_lshl_add_u64 v[166:167], v[2:3], 0, s[44:45]
	s_add_i32 m0, s19, 0x2000
	s_nop 0
	global_load_lds_dwordx4 v[166:167], off
	s_barrier
	s_waitcnt lgkmcnt(0)
	s_setprio 3
	s_waitcnt lgkmcnt(0)
	v_mfma_f32_16x16x32_bf16 v[100:103], v[212:215], v[158:161], v[100:103]
	v_mfma_f32_16x16x32_bf16 v[96:99], v[220:223], v[158:161], v[96:99]
	v_mfma_f32_16x16x32_bf16 v[92:95], v[212:215], v[178:181], v[92:95]
	v_mfma_f32_16x16x32_bf16 v[88:91], v[220:223], v[178:181], v[88:91]
	v_mfma_f32_16x16x32_bf16 v[84:87], v[212:215], v[196:199], v[84:87]
	v_mfma_f32_16x16x32_bf16 v[80:83], v[220:223], v[196:199], v[80:83]
	v_mfma_f32_16x16x32_bf16 v[76:79], v[212:215], v[204:207], v[76:79]
	v_mfma_f32_16x16x32_bf16 v[72:75], v[220:223], v[204:207], v[72:75]
	v_mfma_f32_16x16x32_bf16 v[100:103], v[216:219], v[162:165], v[100:103]
	v_mfma_f32_16x16x32_bf16 v[96:99], v[224:227], v[162:165], v[96:99]
	v_mfma_f32_16x16x32_bf16 v[92:95], v[216:219], v[182:185], v[92:95]
	v_mfma_f32_16x16x32_bf16 v[88:91], v[224:227], v[182:185], v[88:91]
	v_mfma_f32_16x16x32_bf16 v[84:87], v[216:219], v[200:203], v[84:87]
	v_mfma_f32_16x16x32_bf16 v[80:83], v[224:227], v[200:203], v[80:83]
	v_mfma_f32_16x16x32_bf16 v[76:79], v[216:219], v[208:211], v[76:79]
	v_mfma_f32_16x16x32_bf16 v[72:75], v[224:227], v[208:211], v[72:75]
	s_setprio 0
	s_mov_b32 m0, s22
	v_lshl_add_u64 v[166:167], s[4:5], 0, v[152:153]
	s_barrier
	ds_read_b128 v[158:161], v176 offset:16384
	ds_read_b128 v[162:165], v176 offset:17408
	ds_read_b128 v[178:181], v176 offset:18432
	ds_read_b128 v[182:185], v176 offset:19456
	ds_read_b128 v[196:199], v176 offset:20480
	ds_read_b128 v[200:203], v176 offset:21504
	ds_read_b128 v[204:207], v176 offset:22528
	ds_read_b128 v[208:211], v176 offset:23552
	global_load_lds_dwordx4 v[166:167], off
	v_lshl_add_u64 v[172:173], v[166:167], 0, s[86:87]
	s_mov_b32 m0, s23
	s_nop 0
	global_load_lds_dwordx4 v[172:173], off
	s_barrier
	s_waitcnt lgkmcnt(0)
	s_setprio 3
	s_waitcnt lgkmcnt(0)
	v_mfma_f32_16x16x32_bf16 v[68:71], v[136:139], v[158:161], v[68:71]
	v_mfma_f32_16x16x32_bf16 v[64:67], v[144:147], v[158:161], v[64:67]
	v_mfma_f32_16x16x32_bf16 v[60:63], v[136:139], v[178:181], v[60:63]
	v_mfma_f32_16x16x32_bf16 v[56:59], v[144:147], v[178:181], v[56:59]
	v_mfma_f32_16x16x32_bf16 v[52:55], v[136:139], v[196:199], v[52:55]
	v_mfma_f32_16x16x32_bf16 v[48:51], v[144:147], v[196:199], v[48:51]
	v_mfma_f32_16x16x32_bf16 v[44:47], v[136:139], v[204:207], v[44:47]
	v_mfma_f32_16x16x32_bf16 v[40:43], v[144:147], v[204:207], v[40:43]
	v_mfma_f32_16x16x32_bf16 v[68:71], v[140:143], v[162:165], v[68:71]
	v_mfma_f32_16x16x32_bf16 v[64:67], v[148:151], v[162:165], v[64:67]
	v_mfma_f32_16x16x32_bf16 v[60:63], v[140:143], v[182:185], v[60:63]
	v_mfma_f32_16x16x32_bf16 v[56:59], v[148:151], v[182:185], v[56:59]
	v_mfma_f32_16x16x32_bf16 v[52:55], v[140:143], v[200:203], v[52:55]
	v_mfma_f32_16x16x32_bf16 v[48:51], v[148:151], v[200:203], v[48:51]
	v_mfma_f32_16x16x32_bf16 v[44:47], v[140:143], v[208:211], v[44:47]
	v_mfma_f32_16x16x32_bf16 v[40:43], v[148:151], v[208:211], v[40:43]
	s_setprio 0
	s_barrier
; #define G_STAGE(bufoff, gbase, o0, h64) do { \
;         __builtin_amdgcn_global_load_lds((const unsigned*)((const char*)(gbase) + (o0)), (LAS unsigned*)(lds + (bufoff) + ldsw), 16, 0, 0); \
;         __builtin_amdgcn_global_load_lds((const unsigned*)((const char*)(gbase) + (h64) + (o0)), (LAS unsigned*)(lds + (bufoff) + ldsw + 8192), 16, 0, 0); } while (0)
; #define G_LDA(dst, b, h) do { _Pragma("unroll") for (int m = 0; m < 4; ++m) _Pragma("unroll") for (int k = 0; k < 2; ++k) dst[m][k] = *(const LAS bf16x8*)(lds + G_SA(b, h) + aoff + m * 2048 + k * 1024); } while (0)
; #define G_LDB(dst, b, h) do { _Pragma("unroll") for (int n = 0; n < 2; ++n) _Pragma("unroll") for (int k = 0; k < 2; ++k) dst[n][k] = *(const LAS bf16x8*)(lds + G_SB(b, h) + boff + n * 2048 + k * 1024); } while (0)
; #define G_WAIT_V(n) asm volatile("s_waitcnt vmcnt(" #n ")" ::: "memory")
; #define G_WAIT_L(n) asm volatile("s_waitcnt lgkmcnt(" #n ")" ::: "memory")
; #define G_BAR __builtin_amdgcn_s_barrier()
; #define G_SCHED __builtin_amdgcn_sched_barrier(0)
;     ...
;             G_LDB(B0, 0, 0); G_SCHED; G_LDA(At, 0, 0); G_STAGE(G_SA(1, 1), a1 + chA, cA0, qA);
;             G_WAIT_L(8); G_BAR; G_WAIT_L(0); G_MMA(0, 0, At, B0); G_BAR; G_SCHED;
;             G_LDB(B1, 0, 1); G_STAGE(G_SB(0, 0), b2, cB0, qB);
;             G_BAR; G_WAIT_L(0); G_MMA(0, 1, At, B1); G_BAR;
;             G_LDA(At, 0, 1); G_STAGE(G_SA(0, 0), a2, cA0, qA);
;             G_BAR; G_WAIT_L(0); G_MMA(1, 0, At, B0); G_BAR; G_SCHED;
;             G_STAGE(G_SB(0, 1), b2 + chB, cB0, qB);
;             G_WAIT_V(6); G_BAR; G_MMA(1, 1, At, B1); G_BAR;
;             G_LDB(B0, 1, 0); G_SCHED; G_LDA(At, 1, 0); G_STAGE(G_SA(0, 1), a2 + chA, cA0, qA);
;             G_WAIT_L(8); G_BAR; G_WAIT_L(0); G_MMA(0, 0, At, B0); G_BAR; G_SCHED;
;             G_LDB(B1, 1, 1); G_STAGE(G_SB(1, 0), b3, cB0, qB);
;             G_BAR; G_WAIT_L(0); G_MMA(0, 1, At, B1); G_BAR;
;             G_LDA(At, 1, 1); G_STAGE(G_SA(1, 0), a3, cA0, qA);
;             G_BAR; G_WAIT_L(0); G_MMA(1, 0, At, B0); G_BAR; G_SCHED;
;             G_STAGE(G_SB(1, 1), b3 + chB, cB0, qB);
;             G_WAIT_V(6); G_BAR; G_MMA(1, 1, At, B1); G_BAR;
	s_add_i32 s4, s43, s21
	v_lshl_add_u64 v[136:137], v[2:3], 0, s[0:1]
	s_mov_b32 m0, s4
	s_nop 0
	global_load_lds_dwordx4 v[136:137], off
	v_lshl_add_u64 v[136:137], v[2:3], 0, s[52:53]
	s_add_i32 m0, s4, 0x2000
	s_nop 0
	global_load_lds_dwordx4 v[136:137], off
	s_waitcnt vmcnt(6)
	s_barrier
	s_setprio 3
	v_mfma_f32_16x16x32_bf16 v[36:39], v[212:215], v[158:161], v[36:39]
	v_mfma_f32_16x16x32_bf16 v[32:35], v[220:223], v[158:161], v[32:35]
	v_mfma_f32_16x16x32_bf16 v[28:31], v[212:215], v[178:181], v[28:31]
	v_mfma_f32_16x16x32_bf16 v[24:27], v[220:223], v[178:181], v[24:27]
	v_mfma_f32_16x16x32_bf16 v[20:23], v[212:215], v[196:199], v[20:23]
	v_mfma_f32_16x16x32_bf16 v[16:19], v[220:223], v[196:199], v[16:19]
	v_mfma_f32_16x16x32_bf16 v[12:15], v[212:215], v[204:207], v[12:15]
	v_mfma_f32_16x16x32_bf16 v[8:11], v[220:223], v[204:207], v[8:11]
	v_mfma_f32_16x16x32_bf16 v[36:39], v[216:219], v[162:165], v[36:39]
	v_mfma_f32_16x16x32_bf16 v[32:35], v[224:227], v[162:165], v[32:35]
	v_mfma_f32_16x16x32_bf16 v[28:31], v[216:219], v[182:185], v[28:31]
	v_mfma_f32_16x16x32_bf16 v[24:27], v[224:227], v[182:185], v[24:27]
	v_mfma_f32_16x16x32_bf16 v[20:23], v[216:219], v[200:203], v[20:23]
	v_mfma_f32_16x16x32_bf16 v[16:19], v[224:227], v[200:203], v[16:19]
	v_mfma_f32_16x16x32_bf16 v[12:15], v[216:219], v[208:211], v[12:15]
	v_mfma_f32_16x16x32_bf16 v[8:11], v[224:227], v[208:211], v[8:11]
	s_setprio 0
	s_add_i32 s4, 0, 0x18000
	v_add_u32_e32 v0, s4, v175
	s_barrier
	ds_read_b128 v[136:139], v0
	ds_read_b128 v[140:143], v0 offset:1024
	ds_read_b128 v[144:147], v0 offset:2048
	ds_read_b128 v[148:151], v0 offset:3072
	s_mov_b32 m0, s24
	v_lshl_add_u64 v[172:173], v[166:167], 0, s[88:89]
	ds_read_b128 v[158:161], v176 offset:32768
	ds_read_b128 v[162:165], v176 offset:33792
	ds_read_b128 v[178:181], v176 offset:34816
	ds_read_b128 v[182:185], v176 offset:35840
	ds_read_b128 v[196:199], v176 offset:36864
	ds_read_b128 v[200:203], v176 offset:37888
	ds_read_b128 v[204:207], v176 offset:38912
	ds_read_b128 v[208:211], v176 offset:39936
	global_load_lds_dwordx4 v[172:173], off
	v_lshl_add_u64 v[172:173], v[166:167], 0, s[64:65]
	s_mov_b32 m0, s25
	s_nop 0
	global_load_lds_dwordx4 v[172:173], off
	s_waitcnt lgkmcnt(8)
	s_barrier
	s_waitcnt lgkmcnt(0)
	s_setprio 3
	s_waitcnt lgkmcnt(0)
	v_mfma_f32_16x16x32_bf16 v[104:107], v[136:139], v[158:161], v[104:107]
	v_mfma_f32_16x16x32_bf16 v[108:111], v[144:147], v[158:161], v[108:111]
	v_mfma_f32_16x16x32_bf16 v[132:135], v[136:139], v[178:181], v[132:135]
	v_mfma_f32_16x16x32_bf16 v[128:131], v[144:147], v[178:181], v[128:131]
	v_mfma_f32_16x16x32_bf16 v[124:127], v[136:139], v[196:199], v[124:127]
	v_mfma_f32_16x16x32_bf16 v[120:123], v[144:147], v[196:199], v[120:123]
	v_mfma_f32_16x16x32_bf16 v[116:119], v[136:139], v[204:207], v[116:119]
	v_mfma_f32_16x16x32_bf16 v[112:115], v[144:147], v[204:207], v[112:115]
	v_mfma_f32_16x16x32_bf16 v[104:107], v[140:143], v[162:165], v[104:107]
	v_mfma_f32_16x16x32_bf16 v[108:111], v[148:151], v[162:165], v[108:111]
	v_mfma_f32_16x16x32_bf16 v[132:135], v[140:143], v[182:185], v[132:135]
	v_mfma_f32_16x16x32_bf16 v[128:131], v[148:151], v[182:185], v[128:131]
	v_mfma_f32_16x16x32_bf16 v[124:127], v[140:143], v[200:203], v[124:127]
	v_mfma_f32_16x16x32_bf16 v[120:123], v[148:151], v[200:203], v[120:123]
	v_mfma_f32_16x16x32_bf16 v[116:119], v[140:143], v[208:211], v[116:119]
	v_mfma_f32_16x16x32_bf16 v[112:115], v[148:151], v[208:211], v[112:115]
	s_setprio 0
	s_barrier
	s_add_i32 s5, 0, 0x1c000
	s_add_i32 s4, s4, s21
	v_add_u32_e32 v0, s5, v175
	v_lshl_add_u64 v[172:173], v[2:3], 0, s[46:47]
	s_mov_b32 m0, s4
	ds_read_b128 v[212:215], v0
	ds_read_b128 v[216:219], v0 offset:1024
	ds_read_b128 v[220:223], v0 offset:2048
	ds_read_b128 v[224:227], v0 offset:3072
	global_load_lds_dwordx4 v[172:173], off
	v_lshl_add_u64 v[172:173], v[2:3], 0, s[54:55]
	s_add_i32 m0, s4, 0x2000
	s_nop 0
	global_load_lds_dwordx4 v[172:173], off
	s_barrier
; #define G_STAGE(bufoff, gbase, o0, h64) do { \
;         __builtin_amdgcn_global_load_lds((const unsigned*)((const char*)(gbase) + (o0)), (LAS unsigned*)(lds + (bufoff) + ldsw), 16, 0, 0); \
;         __builtin_amdgcn_global_load_lds((const unsigned*)((const char*)(gbase) + (h64) + (o0)), (LAS unsigned*)(lds + (bufoff) + ldsw + 8192), 16, 0, 0); } while (0)
; #define G_LDA(dst, b, h) do { _Pragma("unroll") for (int m = 0; m < 4; ++m) _Pragma("unroll") for (int k = 0; k < 2; ++k) dst[m][k] = *(const LAS bf16x8*)(lds + G_SA(b, h) + aoff + m * 2048 + k * 1024); } while (0)
; #define G_LDB(dst, b, h) do { _Pragma("unroll") for (int n = 0; n < 2; ++n) _Pragma("unroll") for (int k = 0; k < 2; ++k) dst[n][k] = *(const LAS bf16x8*)(lds + G_SB(b, h) + boff + n * 2048 + k * 1024); } while (0)
; #define G_WAIT_V(n) asm volatile("s_waitcnt vmcnt(" #n ")" ::: "memory")
; #define G_WAIT_L(n) asm volatile("s_waitcnt lgkmcnt(" #n ")" ::: "memory")
; #define G_BAR __builtin_amdgcn_s_barrier()
; #define G_SCHED __builtin_amdgcn_sched_barrier(0)
;     ...
;             G_WAIT_L(8); G_BAR; G_WAIT_L(0); G_MMA(0, 0, At, B0); G_BAR; G_SCHED;
;             G_LDB(B1, 1, 1); G_STAGE(G_SB(1, 0), b3, cB0, qB);
;             G_BAR; G_WAIT_L(0); G_MMA(0, 1, At, B1); G_BAR;
;             G_LDA(At, 1, 1); G_STAGE(G_SA(1, 0), a3, cA0, qA);
;             G_BAR; G_WAIT_L(0); G_MMA(1, 0, At, B0); G_BAR; G_SCHED;
;             G_STAGE(G_SB(1, 1), b3 + chB, cB0, qB);
;             G_WAIT_V(6); G_BAR; G_MMA(1, 1, At, B1); G_BAR;
;         }
	s_waitcnt lgkmcnt(0)
	s_setprio 3
	s_waitcnt lgkmcnt(0)
	v_mfma_f32_16x16x32_bf16 v[100:103], v[212:215], v[158:161], v[100:103]
	v_mfma_f32_16x16x32_bf16 v[96:99], v[220:223], v[158:161], v[96:99]
	v_mfma_f32_16x16x32_bf16 v[92:95], v[212:215], v[178:181], v[92:95]
	v_mfma_f32_16x16x32_bf16 v[88:91], v[220:223], v[178:181], v[88:91]
	v_mfma_f32_16x16x32_bf16 v[84:87], v[212:215], v[196:199], v[84:87]
	v_mfma_f32_16x16x32_bf16 v[80:83], v[220:223], v[196:199], v[80:83]
	v_mfma_f32_16x16x32_bf16 v[76:79], v[212:215], v[204:207], v[76:79]
	v_mfma_f32_16x16x32_bf16 v[72:75], v[220:223], v[204:207], v[72:75]
	v_mfma_f32_16x16x32_bf16 v[100:103], v[216:219], v[162:165], v[100:103]
	v_mfma_f32_16x16x32_bf16 v[96:99], v[224:227], v[162:165], v[96:99]
	v_mfma_f32_16x16x32_bf16 v[92:95], v[216:219], v[182:185], v[92:95]
	v_mfma_f32_16x16x32_bf16 v[88:91], v[224:227], v[182:185], v[88:91]
	v_mfma_f32_16x16x32_bf16 v[84:87], v[216:219], v[200:203], v[84:87]
	v_mfma_f32_16x16x32_bf16 v[80:83], v[224:227], v[200:203], v[80:83]
	v_mfma_f32_16x16x32_bf16 v[76:79], v[216:219], v[208:211], v[76:79]
	v_mfma_f32_16x16x32_bf16 v[72:75], v[224:227], v[208:211], v[72:75]
	s_setprio 0
	s_mov_b32 m0, s26
	v_lshl_add_u64 v[172:173], v[166:167], 0, s[46:47]
	s_barrier
	ds_read_b128 v[158:161], v176 offset:49152
	ds_read_b128 v[162:165], v176 offset:50176
	ds_read_b128 v[178:181], v176 offset:51200
	ds_read_b128 v[182:185], v176 offset:52224
	ds_read_b128 v[196:199], v176 offset:53248
	ds_read_b128 v[200:203], v176 offset:54272
	ds_read_b128 v[204:207], v176 offset:55296
	ds_read_b128 v[208:211], v176 offset:56320
	global_load_lds_dwordx4 v[172:173], off
	v_lshl_add_u64 v[166:167], v[166:167], 0, s[66:67]
	s_mov_b32 m0, s27
	s_nop 0
	global_load_lds_dwordx4 v[166:167], off
	s_barrier
	s_waitcnt lgkmcnt(0)
	s_setprio 3
	s_waitcnt lgkmcnt(0)
	v_mfma_f32_16x16x32_bf16 v[68:71], v[136:139], v[158:161], v[68:71]
	v_mfma_f32_16x16x32_bf16 v[64:67], v[144:147], v[158:161], v[64:67]
	v_mfma_f32_16x16x32_bf16 v[60:63], v[136:139], v[178:181], v[60:63]
	v_mfma_f32_16x16x32_bf16 v[56:59], v[144:147], v[178:181], v[56:59]
	v_mfma_f32_16x16x32_bf16 v[52:55], v[136:139], v[196:199], v[52:55]
	v_mfma_f32_16x16x32_bf16 v[48:51], v[144:147], v[196:199], v[48:51]
	v_mfma_f32_16x16x32_bf16 v[44:47], v[136:139], v[204:207], v[44:47]
	v_mfma_f32_16x16x32_bf16 v[40:43], v[144:147], v[204:207], v[40:43]
	v_mfma_f32_16x16x32_bf16 v[68:71], v[140:143], v[162:165], v[68:71]
	v_mfma_f32_16x16x32_bf16 v[64:67], v[148:151], v[162:165], v[64:67]
	v_mfma_f32_16x16x32_bf16 v[60:63], v[140:143], v[182:185], v[60:63]
	v_mfma_f32_16x16x32_bf16 v[56:59], v[148:151], v[182:185], v[56:59]
	v_mfma_f32_16x16x32_bf16 v[52:55], v[140:143], v[200:203], v[52:55]
	v_mfma_f32_16x16x32_bf16 v[48:51], v[148:151], v[200:203], v[48:51]
	v_mfma_f32_16x16x32_bf16 v[44:47], v[140:143], v[208:211], v[44:47]
	v_mfma_f32_16x16x32_bf16 v[40:43], v[148:151], v[208:211], v[40:43]
	s_setprio 0
	s_barrier
	s_add_i32 s4, s5, s21
	v_lshl_add_u64 v[136:137], v[2:3], 0, s[50:51]
	s_mov_b32 m0, s4
	v_lshl_add_u64 v[2:3], v[2:3], 0, s[58:59]
	global_load_lds_dwordx4 v[136:137], off
	s_add_i32 m0, s4, 0x2000
	s_nop 0
	global_load_lds_dwordx4 v[2:3], off
	s_waitcnt vmcnt(6)
	s_barrier
	s_setprio 3
	v_mfma_f32_16x16x32_bf16 v[36:39], v[212:215], v[158:161], v[36:39]
	v_mfma_f32_16x16x32_bf16 v[32:35], v[220:223], v[158:161], v[32:35]
	v_mfma_f32_16x16x32_bf16 v[28:31], v[212:215], v[178:181], v[28:31]
	v_mfma_f32_16x16x32_bf16 v[24:27], v[220:223], v[178:181], v[24:27]
	v_mfma_f32_16x16x32_bf16 v[20:23], v[212:215], v[196:199], v[20:23]
	v_mfma_f32_16x16x32_bf16 v[16:19], v[220:223], v[196:199], v[16:19]
	v_mfma_f32_16x16x32_bf16 v[12:15], v[212:215], v[204:207], v[12:15]
	v_mfma_f32_16x16x32_bf16 v[8:11], v[220:223], v[204:207], v[8:11]
	v_mfma_f32_16x16x32_bf16 v[36:39], v[216:219], v[162:165], v[36:39]
	v_mfma_f32_16x16x32_bf16 v[32:35], v[224:227], v[162:165], v[32:35]
	v_mfma_f32_16x16x32_bf16 v[28:31], v[216:219], v[182:185], v[28:31]
	v_mfma_f32_16x16x32_bf16 v[24:27], v[224:227], v[182:185], v[24:27]
	v_mfma_f32_16x16x32_bf16 v[20:23], v[216:219], v[200:203], v[20:23]
	v_mfma_f32_16x16x32_bf16 v[16:19], v[224:227], v[200:203], v[16:19]
	v_mfma_f32_16x16x32_bf16 v[12:15], v[216:219], v[208:211], v[12:15]
	v_mfma_f32_16x16x32_bf16 v[8:11], v[224:227], v[208:211], v[8:11]
	s_setprio 0
	s_add_i32 s18, s18, 2
	s_add_u32 s6, s6, 0x100
	s_addc_u32 s7, s7, 0
	s_add_u32 s8, s8, 0x100
	s_addc_u32 s9, s9, 0
	s_cmp_gt_u32 s18, 5
	s_cbranch_scc0 .Ldb_MG1_cont
	v_readfirstlane_b32 s101, v186
	s_cmpk_gt_u32 s101, 0xff
	s_cbranch_scc1 .Ldb_MG1_exit
	s_barrier
	s_branch .Ldb_MG1_exit

; #define G_STAGE(bufoff, gbase, o0, h64) do { \
;         __builtin_amdgcn_global_load_lds((const unsigned*)((const char*)(gbase) + (o0)), (LAS unsigned*)(lds + (bufoff) + ldsw), 16, 0, 0); \
;         __builtin_amdgcn_global_load_lds((const unsigned*)((const char*)(gbase) + (h64) + (o0)), (LAS unsigned*)(lds + (bufoff) + ldsw + 8192), 16, 0, 0); } while (0)
; #define G_LDA(dst, b, h) do { _Pragma("unroll") for (int m = 0; m < 4; ++m) _Pragma("unroll") for (int k = 0; k < 2; ++k) dst[m][k] = *(const LAS bf16x8*)(lds + G_SA(b, h) + aoff + m * 2048 + k * 1024); } while (0)
; #define G_LDB(dst, b, h) do { _Pragma("unroll") for (int n = 0; n < 2; ++n) _Pragma("unroll") for (int k = 0; k < 2; ++k) dst[n][k] = *(const LAS bf16x8*)(lds + G_SB(b, h) + boff + n * 2048 + k * 1024); } while (0)
; #define G_WAIT_L(n) asm volatile("s_waitcnt lgkmcnt(" #n ")" ::: "memory")
; #define G_BAR __builtin_amdgcn_s_barrier()
; #define G_SCHED __builtin_amdgcn_sched_barrier(0)
;     ...
;         for (int t = 0; t < nt; t += 2) {
;             const bool last = (t == nt - 2);
;             const char* a1 = cA + (size_t)(t + 1) * ckA;
;             const char* a2 = last ? nA : cA + (size_t)(t + 2) * ckA; const char* b2 = last ? nB : cB + (size_t)(t + 2) * kB;
;             const char* a3 = a2 + ckA; const char* b3 = b2 + kB;
;             G_LDB(B0, 0, 0); G_SCHED; G_LDA(At, 0, 0); G_STAGE(G_SA(1, 1), a1 + chA, cA0, qA);
;             G_WAIT_L(8); G_BAR; G_WAIT_L(0); G_MMA(0, 0, At, B0); G_BAR; G_SCHED;
;             G_LDB(B1, 0, 1); G_STAGE(G_SB(0, 0), b2, cB0, qB);
;             G_BAR; G_WAIT_L(0); G_MMA(0, 1, At, B1); G_BAR;
;     ...
;         if (!(cs.kind == K_MG_B && cur.aux < 2))
; #pragma unroll
;         for (int a = 0; a < 2; ++a)
; #pragma unroll
;             for (int b = 0; b < 2; ++b)
; #pragma unroll
;                 for (int m = 0; m < 4; ++m)
; #pragma unroll
;                     for (int n = 0; n < 2; ++n) acc[a][b][m][n] = (f32x4){0.f, 0.f, 0.f, 0.f};
;         cur = nxt; cA = nA; cB = nB; ++ui;
.LBB0_1036:
	s_add_u32 s2, s2, 0x40080
	s_addc_u32 s3, s3, 0
	s_add_u32 s6, s6, 0x100
	s_waitcnt lgkmcnt(0)
	v_mov_b64_e32 v[8:9], 0
	s_addc_u32 s7, s7, 0
	s_mov_b32 s15, -2
	v_mov_b64_e32 v[10:11], 0
	v_mov_b64_e32 v[12:13], 0
	v_mov_b64_e32 v[14:15], 0
	v_mov_b64_e32 v[24:25], 0
	v_mov_b64_e32 v[26:27], 0
	v_mov_b64_e32 v[28:29], 0
	v_mov_b64_e32 v[30:31], 0
	v_mov_b64_e32 v[40:41], 0
	v_mov_b64_e32 v[42:43], 0
	v_mov_b64_e32 v[44:45], 0
	v_mov_b64_e32 v[46:47], 0
	v_mov_b64_e32 v[56:57], 0
	v_mov_b64_e32 v[58:59], 0
	v_mov_b64_e32 v[60:61], 0
	v_mov_b64_e32 v[62:63], 0
	v_mov_b64_e32 v[16:17], 0
	v_mov_b64_e32 v[18:19], 0
	v_mov_b64_e32 v[20:21], 0
	v_mov_b64_e32 v[22:23], 0
	v_mov_b64_e32 v[32:33], 0
	v_mov_b64_e32 v[34:35], 0
	v_mov_b64_e32 v[36:37], 0
	v_mov_b64_e32 v[38:39], 0
	v_mov_b64_e32 v[48:49], 0
	v_mov_b64_e32 v[50:51], 0
	v_mov_b64_e32 v[52:53], 0
	v_mov_b64_e32 v[54:55], 0
	v_mov_b64_e32 v[64:65], 0
	v_mov_b64_e32 v[66:67], 0
	v_mov_b64_e32 v[68:69], 0
	v_mov_b64_e32 v[70:71], 0
	v_mov_b64_e32 v[72:73], 0
	v_mov_b64_e32 v[74:75], 0
	v_mov_b64_e32 v[76:77], 0
	v_mov_b64_e32 v[78:79], 0
	v_mov_b64_e32 v[88:89], 0
	v_mov_b64_e32 v[90:91], 0
	v_mov_b64_e32 v[92:93], 0
	v_mov_b64_e32 v[94:95], 0
	v_mov_b64_e32 v[104:105], 0
	v_mov_b64_e32 v[106:107], 0
	v_mov_b64_e32 v[108:109], 0
	v_mov_b64_e32 v[110:111], 0
	v_mov_b64_e32 v[120:121], 0
	v_mov_b64_e32 v[122:123], 0
	v_mov_b64_e32 v[124:125], 0
	v_mov_b64_e32 v[126:127], 0
	v_mov_b64_e32 v[80:81], 0
	v_mov_b64_e32 v[82:83], 0
	v_mov_b64_e32 v[84:85], 0
	v_mov_b64_e32 v[86:87], 0
	v_mov_b64_e32 v[96:97], 0
	v_mov_b64_e32 v[98:99], 0
	v_mov_b64_e32 v[100:101], 0
	v_mov_b64_e32 v[102:103], 0
	v_mov_b64_e32 v[112:113], 0
	v_mov_b64_e32 v[114:115], 0
	v_mov_b64_e32 v[116:117], 0
	v_mov_b64_e32 v[118:119], 0
	v_mov_b64_e32 v[128:129], 0
	v_mov_b64_e32 v[130:131], 0
	v_mov_b64_e32 v[132:133], 0
	v_mov_b64_e32 v[134:135], 0
	s_mov_b64 s[42:43], 0x40000
	s_mov_b64 s[50:51], 0x60000
	s_mov_b64 s[52:53], 0x20080
	s_mov_b64 s[54:55], 0x40080
	s_mov_b64 s[58:59], 0x60080
	s_cmpk_gt_u32 s101, 0xff
	s_cbranch_scc0 .Ldbj_WOUT_in
	s_barrier
	s_mov_b32 s101, 0
.Ldbj_WOUT_in:
.LBB0_1037:
	s_add_u32 s4, s2, 0xfffc0080
	s_addc_u32 s5, s3, -1
	s_add_i32 s33, 0, 0x10000
	v_add_u32_e32 v0, s33, v181
	ds_read_b128 v[136:139], v0
	ds_read_b128 v[140:143], v0 offset:1024
	ds_read_b128 v[144:147], v0 offset:2048
	ds_read_b128 v[148:151], v0 offset:3072
	s_cmp_eq_u32 s15, 12
	s_cselect_b32 s5, s17, s5
	s_cselect_b32 s4, s16, s4
	s_cselect_b32 s21, s19, s7
	s_cselect_b32 s20, s18, s6
	v_lshl_add_u64 v[184:185], s[2:3], 0, v[166:167]
	s_add_i32 m0, s24, 0xc000
	ds_read_b128 v[152:155], v182
	ds_read_b128 v[156:159], v182 offset:1024
	ds_read_b128 v[160:163], v182 offset:2048
	ds_read_b128 v[172:175], v182 offset:3072
	ds_read_b128 v[176:179], v182 offset:4096
	ds_read_b128 v[196:199], v182 offset:5120
	ds_read_b128 v[200:203], v182 offset:6144
	ds_read_b128 v[204:207], v182 offset:7168
	global_load_lds_dwordx4 v[184:185], off
	v_lshl_add_u64 v[184:185], v[184:185], 0, s[0:1]
	s_add_i32 m0, s24, 0xe000
	s_nop 0
	global_load_lds_dwordx4 v[184:185], off
	s_waitcnt lgkmcnt(8)
	s_barrier
	s_waitcnt lgkmcnt(0)
	s_setprio 3
	s_waitcnt lgkmcnt(0)
	v_mfma_f32_16x16x32_bf16 v[132:135], v[136:139], v[152:155], v[132:135]
	v_mfma_f32_16x16x32_bf16 v[128:131], v[144:147], v[152:155], v[128:131]
	v_mfma_f32_16x16x32_bf16 v[116:119], v[136:139], v[160:163], v[116:119]
	v_mfma_f32_16x16x32_bf16 v[112:115], v[144:147], v[160:163], v[112:115]
	v_mfma_f32_16x16x32_bf16 v[100:103], v[136:139], v[176:179], v[100:103]
	v_mfma_f32_16x16x32_bf16 v[96:99], v[144:147], v[176:179], v[96:99]
	v_mfma_f32_16x16x32_bf16 v[84:87], v[136:139], v[200:203], v[84:87]
	v_mfma_f32_16x16x32_bf16 v[80:83], v[144:147], v[200:203], v[80:83]
	v_mfma_f32_16x16x32_bf16 v[132:135], v[140:143], v[156:159], v[132:135]
	v_mfma_f32_16x16x32_bf16 v[128:131], v[148:151], v[156:159], v[128:131]
	v_mfma_f32_16x16x32_bf16 v[116:119], v[140:143], v[172:175], v[116:119]
	v_mfma_f32_16x16x32_bf16 v[112:115], v[148:151], v[172:175], v[112:115]
	v_mfma_f32_16x16x32_bf16 v[100:103], v[140:143], v[196:199], v[100:103]
	v_mfma_f32_16x16x32_bf16 v[96:99], v[148:151], v[196:199], v[96:99]
	v_mfma_f32_16x16x32_bf16 v[84:87], v[140:143], v[204:207], v[84:87]
	v_mfma_f32_16x16x32_bf16 v[80:83], v[148:151], v[204:207], v[80:83]
	s_setprio 0
	s_barrier
	s_add_i32 s41, 0, 0x14000
	v_lshl_add_u64 v[184:185], s[20:21], 0, v[164:165]
	s_add_i32 s20, s33, s23
	v_add_u32_e32 v0, s41, v181
	s_mov_b32 m0, s20
	ds_read_b128 v[208:211], v0
	ds_read_b128 v[212:215], v0 offset:1024
	ds_read_b128 v[216:219], v0 offset:2048
	ds_read_b128 v[220:223], v0 offset:3072
	global_load_lds_dwordx4 v[184:185], off
	v_lshl_add_u64 v[224:225], v[184:185], 0, s[0:1]
	s_add_i32 m0, s20, 0x2000
	s_nop 0
	global_load_lds_dwordx4 v[224:225], off
	s_barrier
	s_waitcnt lgkmcnt(0)
	s_setprio 3
	s_waitcnt lgkmcnt(0)
	v_mfma_f32_16x16x32_bf16 v[124:127], v[208:211], v[152:155], v[124:127]
	v_mfma_f32_16x16x32_bf16 v[120:123], v[216:219], v[152:155], v[120:123]
	v_mfma_f32_16x16x32_bf16 v[108:111], v[208:211], v[160:163], v[108:111]
	v_mfma_f32_16x16x32_bf16 v[104:107], v[216:219], v[160:163], v[104:107]
	v_mfma_f32_16x16x32_bf16 v[92:95], v[208:211], v[176:179], v[92:95]
	v_mfma_f32_16x16x32_bf16 v[88:91], v[216:219], v[176:179], v[88:91]
	v_mfma_f32_16x16x32_bf16 v[76:79], v[208:211], v[200:203], v[76:79]
	v_mfma_f32_16x16x32_bf16 v[72:75], v[216:219], v[200:203], v[72:75]
	v_mfma_f32_16x16x32_bf16 v[124:127], v[212:215], v[156:159], v[124:127]
	v_mfma_f32_16x16x32_bf16 v[120:123], v[220:223], v[156:159], v[120:123]
	v_mfma_f32_16x16x32_bf16 v[108:111], v[212:215], v[172:175], v[108:111]
	v_mfma_f32_16x16x32_bf16 v[104:107], v[220:223], v[172:175], v[104:107]
	v_mfma_f32_16x16x32_bf16 v[92:95], v[212:215], v[196:199], v[92:95]
	v_mfma_f32_16x16x32_bf16 v[88:91], v[220:223], v[196:199], v[88:91]
	v_mfma_f32_16x16x32_bf16 v[76:79], v[212:215], v[204:207], v[76:79]
	v_mfma_f32_16x16x32_bf16 v[72:75], v[220:223], v[204:207], v[72:75]
	s_setprio 0
	s_mov_b32 m0, s24
	v_lshl_add_u64 v[224:225], s[4:5], 0, v[2:3]
	s_barrier
; #define G_STAGE(bufoff, gbase, o0, h64) do { \
;         __builtin_amdgcn_global_load_lds((const unsigned*)((const char*)(gbase) + (o0)), (LAS unsigned*)(lds + (bufoff) + ldsw), 16, 0, 0); \
;         __builtin_amdgcn_global_load_lds((const unsigned*)((const char*)(gbase) + (h64) + (o0)), (LAS unsigned*)(lds + (bufoff) + ldsw + 8192), 16, 0, 0); } while (0)
; #define G_LDA(dst, b, h) do { _Pragma("unroll") for (int m = 0; m < 4; ++m) _Pragma("unroll") for (int k = 0; k < 2; ++k) dst[m][k] = *(const LAS bf16x8*)(lds + G_SA(b, h) + aoff + m * 2048 + k * 1024); } while (0)
; #define G_LDB(dst, b, h) do { _Pragma("unroll") for (int n = 0; n < 2; ++n) _Pragma("unroll") for (int k = 0; k < 2; ++k) dst[n][k] = *(const LAS bf16x8*)(lds + G_SB(b, h) + boff + n * 2048 + k * 1024); } while (0)
; #define G_WAIT_V(n) asm volatile("s_waitcnt vmcnt(" #n ")" ::: "memory")
; #define G_WAIT_L(n) asm volatile("s_waitcnt lgkmcnt(" #n ")" ::: "memory")
; #define G_BAR __builtin_amdgcn_s_barrier()
; #define G_SCHED __builtin_amdgcn_sched_barrier(0)
;     ...
;             G_BAR; G_WAIT_L(0); G_MMA(0, 1, At, B1); G_BAR;
;             G_LDA(At, 0, 1); G_STAGE(G_SA(0, 0), a2, cA0, qA);
;             G_BAR; G_WAIT_L(0); G_MMA(1, 0, At, B0); G_BAR; G_SCHED;
;             G_STAGE(G_SB(0, 1), b2 + chB, cB0, qB);
;             G_WAIT_V(6); G_BAR; G_MMA(1, 1, At, B1); G_BAR;
;             G_LDB(B0, 1, 0); G_SCHED; G_LDA(At, 1, 0); G_STAGE(G_SA(0, 1), a2 + chA, cA0, qA);
;             G_WAIT_L(8); G_BAR; G_WAIT_L(0); G_MMA(0, 0, At, B0); G_BAR; G_SCHED;
;             G_LDB(B1, 1, 1); G_STAGE(G_SB(1, 0), b3, cB0, qB);
;             G_BAR; G_WAIT_L(0); G_MMA(0, 1, At, B1); G_BAR;
;             G_LDA(At, 1, 1); G_STAGE(G_SA(1, 0), a3, cA0, qA);
;             G_BAR; G_WAIT_L(0); G_MMA(1, 0, At, B0); G_BAR; G_SCHED;
	ds_read_b128 v[152:155], v182 offset:16384
	ds_read_b128 v[156:159], v182 offset:17408
	ds_read_b128 v[160:163], v182 offset:18432
	ds_read_b128 v[172:175], v182 offset:19456
	ds_read_b128 v[176:179], v182 offset:20480
	ds_read_b128 v[196:199], v182 offset:21504
	ds_read_b128 v[200:203], v182 offset:22528
	ds_read_b128 v[204:207], v182 offset:23552
	global_load_lds_dwordx4 v[224:225], off
	v_lshl_add_u64 v[226:227], v[224:225], 0, s[0:1]
	s_mov_b32 m0, s25
	s_nop 0
	global_load_lds_dwordx4 v[226:227], off
	s_barrier
	s_waitcnt lgkmcnt(0)
	s_setprio 3
	s_waitcnt lgkmcnt(0)
	v_mfma_f32_16x16x32_bf16 v[68:71], v[136:139], v[152:155], v[68:71]
	v_mfma_f32_16x16x32_bf16 v[64:67], v[144:147], v[152:155], v[64:67]
	v_mfma_f32_16x16x32_bf16 v[52:55], v[136:139], v[160:163], v[52:55]
	v_mfma_f32_16x16x32_bf16 v[48:51], v[144:147], v[160:163], v[48:51]
	v_mfma_f32_16x16x32_bf16 v[36:39], v[136:139], v[176:179], v[36:39]
	v_mfma_f32_16x16x32_bf16 v[32:35], v[144:147], v[176:179], v[32:35]
	v_mfma_f32_16x16x32_bf16 v[20:23], v[136:139], v[200:203], v[20:23]
	v_mfma_f32_16x16x32_bf16 v[16:19], v[144:147], v[200:203], v[16:19]
	v_mfma_f32_16x16x32_bf16 v[68:71], v[140:143], v[156:159], v[68:71]
	v_mfma_f32_16x16x32_bf16 v[64:67], v[148:151], v[156:159], v[64:67]
	v_mfma_f32_16x16x32_bf16 v[52:55], v[140:143], v[172:175], v[52:55]
	v_mfma_f32_16x16x32_bf16 v[48:51], v[148:151], v[172:175], v[48:51]
	v_mfma_f32_16x16x32_bf16 v[36:39], v[140:143], v[196:199], v[36:39]
	v_mfma_f32_16x16x32_bf16 v[32:35], v[148:151], v[196:199], v[32:35]
	v_mfma_f32_16x16x32_bf16 v[20:23], v[140:143], v[204:207], v[20:23]
	v_mfma_f32_16x16x32_bf16 v[16:19], v[148:151], v[204:207], v[16:19]
	s_setprio 0
	s_barrier
	s_add_i32 s4, s41, s23
	v_lshl_add_u64 v[136:137], v[184:185], 0, s[42:43]
	s_mov_b32 m0, s4
	s_nop 0
	global_load_lds_dwordx4 v[136:137], off
	v_lshl_add_u64 v[136:137], v[184:185], 0, s[50:51]
	s_add_i32 m0, s4, 0x2000
	s_nop 0
	global_load_lds_dwordx4 v[136:137], off
	s_waitcnt vmcnt(6)
	s_barrier
	s_setprio 3
	v_mfma_f32_16x16x32_bf16 v[60:63], v[208:211], v[152:155], v[60:63]
	v_mfma_f32_16x16x32_bf16 v[56:59], v[216:219], v[152:155], v[56:59]
	v_mfma_f32_16x16x32_bf16 v[44:47], v[208:211], v[160:163], v[44:47]
	v_mfma_f32_16x16x32_bf16 v[40:43], v[216:219], v[160:163], v[40:43]
	v_mfma_f32_16x16x32_bf16 v[28:31], v[208:211], v[176:179], v[28:31]
	v_mfma_f32_16x16x32_bf16 v[24:27], v[216:219], v[176:179], v[24:27]
	v_mfma_f32_16x16x32_bf16 v[12:15], v[208:211], v[200:203], v[12:15]
	v_mfma_f32_16x16x32_bf16 v[8:11], v[216:219], v[200:203], v[8:11]
	v_mfma_f32_16x16x32_bf16 v[60:63], v[212:215], v[156:159], v[60:63]
	v_mfma_f32_16x16x32_bf16 v[56:59], v[220:223], v[156:159], v[56:59]
	v_mfma_f32_16x16x32_bf16 v[44:47], v[212:215], v[172:175], v[44:47]
	v_mfma_f32_16x16x32_bf16 v[40:43], v[220:223], v[172:175], v[40:43]
	v_mfma_f32_16x16x32_bf16 v[28:31], v[212:215], v[196:199], v[28:31]
	v_mfma_f32_16x16x32_bf16 v[24:27], v[220:223], v[196:199], v[24:27]
	v_mfma_f32_16x16x32_bf16 v[12:15], v[212:215], v[204:207], v[12:15]
	v_mfma_f32_16x16x32_bf16 v[8:11], v[220:223], v[204:207], v[8:11]
	s_setprio 0
	s_add_i32 s4, 0, 0x18000
	v_add_u32_e32 v0, s4, v181
	s_barrier
	ds_read_b128 v[136:139], v0
	ds_read_b128 v[140:143], v0 offset:1024
	ds_read_b128 v[144:147], v0 offset:2048
	ds_read_b128 v[148:151], v0 offset:3072
	s_mov_b32 m0, s26
	v_lshl_add_u64 v[208:209], v[224:225], 0, s[42:43]
	ds_read_b128 v[152:155], v182 offset:32768
	ds_read_b128 v[156:159], v182 offset:33792
	ds_read_b128 v[160:163], v182 offset:34816
	ds_read_b128 v[172:175], v182 offset:35840
	ds_read_b128 v[176:179], v182 offset:36864
	ds_read_b128 v[196:199], v182 offset:37888
	ds_read_b128 v[200:203], v182 offset:38912
	ds_read_b128 v[204:207], v182 offset:39936
	global_load_lds_dwordx4 v[208:209], off
	v_lshl_add_u64 v[208:209], v[224:225], 0, s[50:51]
	s_mov_b32 m0, s27
	s_nop 0
	global_load_lds_dwordx4 v[208:209], off
	s_waitcnt lgkmcnt(8)
	s_barrier
	s_waitcnt lgkmcnt(0)
	s_setprio 3
	s_waitcnt lgkmcnt(0)
	v_mfma_f32_16x16x32_bf16 v[132:135], v[136:139], v[152:155], v[132:135]
	v_mfma_f32_16x16x32_bf16 v[128:131], v[144:147], v[152:155], v[128:131]
	v_mfma_f32_16x16x32_bf16 v[116:119], v[136:139], v[160:163], v[116:119]
	v_mfma_f32_16x16x32_bf16 v[112:115], v[144:147], v[160:163], v[112:115]
	v_mfma_f32_16x16x32_bf16 v[100:103], v[136:139], v[176:179], v[100:103]
	v_mfma_f32_16x16x32_bf16 v[96:99], v[144:147], v[176:179], v[96:99]
	v_mfma_f32_16x16x32_bf16 v[84:87], v[136:139], v[200:203], v[84:87]
	v_mfma_f32_16x16x32_bf16 v[80:83], v[144:147], v[200:203], v[80:83]
	v_mfma_f32_16x16x32_bf16 v[132:135], v[140:143], v[156:159], v[132:135]
	v_mfma_f32_16x16x32_bf16 v[128:131], v[148:151], v[156:159], v[128:131]
	v_mfma_f32_16x16x32_bf16 v[116:119], v[140:143], v[172:175], v[116:119]
	v_mfma_f32_16x16x32_bf16 v[112:115], v[148:151], v[172:175], v[112:115]
	v_mfma_f32_16x16x32_bf16 v[100:103], v[140:143], v[196:199], v[100:103]
	v_mfma_f32_16x16x32_bf16 v[96:99], v[148:151], v[196:199], v[96:99]
	v_mfma_f32_16x16x32_bf16 v[84:87], v[140:143], v[204:207], v[84:87]
	v_mfma_f32_16x16x32_bf16 v[80:83], v[148:151], v[204:207], v[80:83]
	s_setprio 0
	s_barrier
; #define G_STAGE(bufoff, gbase, o0, h64) do { \
;         __builtin_amdgcn_global_load_lds((const unsigned*)((const char*)(gbase) + (o0)), (LAS unsigned*)(lds + (bufoff) + ldsw), 16, 0, 0); \
;         __builtin_amdgcn_global_load_lds((const unsigned*)((const char*)(gbase) + (h64) + (o0)), (LAS unsigned*)(lds + (bufoff) + ldsw + 8192), 16, 0, 0); } while (0)
; #define G_LDA(dst, b, h) do { _Pragma("unroll") for (int m = 0; m < 4; ++m) _Pragma("unroll") for (int k = 0; k < 2; ++k) dst[m][k] = *(const LAS bf16x8*)(lds + G_SA(b, h) + aoff + m * 2048 + k * 1024); } while (0)
; #define G_LDB(dst, b, h) do { _Pragma("unroll") for (int n = 0; n < 2; ++n) _Pragma("unroll") for (int k = 0; k < 2; ++k) dst[n][k] = *(const LAS bf16x8*)(lds + G_SB(b, h) + boff + n * 2048 + k * 1024); } while (0)
; #define G_WAIT_V(n) asm volatile("s_waitcnt vmcnt(" #n ")" ::: "memory")
; #define G_WAIT_L(n) asm volatile("s_waitcnt lgkmcnt(" #n ")" ::: "memory")
; #define G_BAR __builtin_amdgcn_s_barrier()
; #define G_SCHED __builtin_amdgcn_sched_barrier(0)
;     ...
;             G_WAIT_L(8); G_BAR; G_WAIT_L(0); G_MMA(0, 0, At, B0); G_BAR; G_SCHED;
;             G_LDB(B1, 1, 1); G_STAGE(G_SB(1, 0), b3, cB0, qB);
;             G_BAR; G_WAIT_L(0); G_MMA(0, 1, At, B1); G_BAR;
;             G_LDA(At, 1, 1); G_STAGE(G_SA(1, 0), a3, cA0, qA);
;             G_BAR; G_WAIT_L(0); G_MMA(1, 0, At, B0); G_BAR; G_SCHED;
;             G_STAGE(G_SB(1, 1), b3 + chB, cB0, qB);
;             G_WAIT_V(6); G_BAR; G_MMA(1, 1, At, B1); G_BAR;
;         }
	s_add_i32 s5, 0, 0x1c000
	s_add_i32 s4, s4, s23
	v_add_u32_e32 v0, s5, v181
	v_lshl_add_u64 v[226:227], v[184:185], 0, s[46:47]
	s_mov_b32 m0, s4
	ds_read_b128 v[208:211], v0
	ds_read_b128 v[212:215], v0 offset:1024
	ds_read_b128 v[216:219], v0 offset:2048
	ds_read_b128 v[220:223], v0 offset:3072
	global_load_lds_dwordx4 v[226:227], off
	v_lshl_add_u64 v[226:227], v[184:185], 0, s[52:53]
	s_add_i32 m0, s4, 0x2000
	s_nop 0
	global_load_lds_dwordx4 v[226:227], off
	s_barrier
	s_waitcnt lgkmcnt(0)
	s_setprio 3
	s_waitcnt lgkmcnt(0)
	v_mfma_f32_16x16x32_bf16 v[124:127], v[208:211], v[152:155], v[124:127]
	v_mfma_f32_16x16x32_bf16 v[120:123], v[216:219], v[152:155], v[120:123]
	v_mfma_f32_16x16x32_bf16 v[108:111], v[208:211], v[160:163], v[108:111]
	v_mfma_f32_16x16x32_bf16 v[104:107], v[216:219], v[160:163], v[104:107]
	v_mfma_f32_16x16x32_bf16 v[92:95], v[208:211], v[176:179], v[92:95]
	v_mfma_f32_16x16x32_bf16 v[88:91], v[216:219], v[176:179], v[88:91]
	v_mfma_f32_16x16x32_bf16 v[76:79], v[208:211], v[200:203], v[76:79]
	v_mfma_f32_16x16x32_bf16 v[72:75], v[216:219], v[200:203], v[72:75]
	v_mfma_f32_16x16x32_bf16 v[124:127], v[212:215], v[156:159], v[124:127]
	v_mfma_f32_16x16x32_bf16 v[120:123], v[220:223], v[156:159], v[120:123]
	v_mfma_f32_16x16x32_bf16 v[108:111], v[212:215], v[172:175], v[108:111]
	v_mfma_f32_16x16x32_bf16 v[104:107], v[220:223], v[172:175], v[104:107]
	v_mfma_f32_16x16x32_bf16 v[92:95], v[212:215], v[196:199], v[92:95]
	v_mfma_f32_16x16x32_bf16 v[88:91], v[220:223], v[196:199], v[88:91]
	v_mfma_f32_16x16x32_bf16 v[76:79], v[212:215], v[204:207], v[76:79]
	v_mfma_f32_16x16x32_bf16 v[72:75], v[220:223], v[204:207], v[72:75]
	s_setprio 0
	s_mov_b32 m0, s29
	v_lshl_add_u64 v[226:227], v[224:225], 0, s[46:47]
	s_barrier
	ds_read_b128 v[152:155], v182 offset:49152
	ds_read_b128 v[156:159], v182 offset:50176
	ds_read_b128 v[160:163], v182 offset:51200
	ds_read_b128 v[172:175], v182 offset:52224
	ds_read_b128 v[176:179], v182 offset:53248
	ds_read_b128 v[196:199], v182 offset:54272
	ds_read_b128 v[200:203], v182 offset:55296
	ds_read_b128 v[204:207], v182 offset:56320
	global_load_lds_dwordx4 v[226:227], off
	v_lshl_add_u64 v[224:225], v[224:225], 0, s[52:53]
	s_mov_b32 m0, s30
	s_nop 0
	global_load_lds_dwordx4 v[224:225], off
	s_barrier
	s_waitcnt lgkmcnt(0)
	s_setprio 3
	s_waitcnt lgkmcnt(0)
	v_mfma_f32_16x16x32_bf16 v[68:71], v[136:139], v[152:155], v[68:71]
	v_mfma_f32_16x16x32_bf16 v[64:67], v[144:147], v[152:155], v[64:67]
	v_mfma_f32_16x16x32_bf16 v[52:55], v[136:139], v[160:163], v[52:55]
	v_mfma_f32_16x16x32_bf16 v[48:51], v[144:147], v[160:163], v[48:51]
	v_mfma_f32_16x16x32_bf16 v[36:39], v[136:139], v[176:179], v[36:39]
	v_mfma_f32_16x16x32_bf16 v[32:35], v[144:147], v[176:179], v[32:35]
	v_mfma_f32_16x16x32_bf16 v[20:23], v[136:139], v[200:203], v[20:23]
	v_mfma_f32_16x16x32_bf16 v[16:19], v[144:147], v[200:203], v[16:19]
	v_mfma_f32_16x16x32_bf16 v[68:71], v[140:143], v[156:159], v[68:71]
	v_mfma_f32_16x16x32_bf16 v[64:67], v[148:151], v[156:159], v[64:67]
	v_mfma_f32_16x16x32_bf16 v[52:55], v[140:143], v[172:175], v[52:55]
	v_mfma_f32_16x16x32_bf16 v[48:51], v[148:151], v[172:175], v[48:51]
	v_mfma_f32_16x16x32_bf16 v[36:39], v[140:143], v[196:199], v[36:39]
	v_mfma_f32_16x16x32_bf16 v[32:35], v[148:151], v[196:199], v[32:35]
	v_mfma_f32_16x16x32_bf16 v[20:23], v[140:143], v[204:207], v[20:23]
	v_mfma_f32_16x16x32_bf16 v[16:19], v[148:151], v[204:207], v[16:19]
	s_setprio 0
	s_barrier
	s_add_i32 s4, s5, s23
	v_lshl_add_u64 v[136:137], v[184:185], 0, s[54:55]
	s_mov_b32 m0, s4
	s_nop 0
	global_load_lds_dwordx4 v[136:137], off
	v_lshl_add_u64 v[136:137], v[184:185], 0, s[58:59]
	s_add_i32 m0, s4, 0x2000
	s_nop 0
	global_load_lds_dwordx4 v[136:137], off
	s_waitcnt vmcnt(6)
	s_barrier
	s_setprio 3
	v_mfma_f32_16x16x32_bf16 v[60:63], v[208:211], v[152:155], v[60:63]
	v_mfma_f32_16x16x32_bf16 v[56:59], v[216:219], v[152:155], v[56:59]
	v_mfma_f32_16x16x32_bf16 v[44:47], v[208:211], v[160:163], v[44:47]
	v_mfma_f32_16x16x32_bf16 v[40:43], v[216:219], v[160:163], v[40:43]
	v_mfma_f32_16x16x32_bf16 v[28:31], v[208:211], v[176:179], v[28:31]
	v_mfma_f32_16x16x32_bf16 v[24:27], v[216:219], v[176:179], v[24:27]
	v_mfma_f32_16x16x32_bf16 v[12:15], v[208:211], v[200:203], v[12:15]
	v_mfma_f32_16x16x32_bf16 v[8:11], v[216:219], v[200:203], v[8:11]
	v_mfma_f32_16x16x32_bf16 v[60:63], v[212:215], v[156:159], v[60:63]
	v_mfma_f32_16x16x32_bf16 v[56:59], v[220:223], v[156:159], v[56:59]
	v_mfma_f32_16x16x32_bf16 v[44:47], v[212:215], v[172:175], v[44:47]
	v_mfma_f32_16x16x32_bf16 v[40:43], v[220:223], v[172:175], v[40:43]
	v_mfma_f32_16x16x32_bf16 v[28:31], v[212:215], v[196:199], v[28:31]
	v_mfma_f32_16x16x32_bf16 v[24:27], v[220:223], v[196:199], v[24:27]
	v_mfma_f32_16x16x32_bf16 v[12:15], v[212:215], v[204:207], v[12:15]
	v_mfma_f32_16x16x32_bf16 v[8:11], v[220:223], v[204:207], v[8:11]
	s_setprio 0
	s_add_i32 s15, s15, 2
	s_add_u32 s2, s2, 0x100
	s_addc_u32 s3, s3, 0
	s_add_u32 s6, s6, 0x100
	s_addc_u32 s7, s7, 0
	s_cmp_gt_u32 s15, 13
	s_cbranch_scc0 .Ldb_WOUT_cont
	v_readfirstlane_b32 s101, v186
	s_cmpk_gt_u32 s101, 0xff
	s_cbranch_scc1 .Ldb_WOUT_exit
	s_barrier
	s_branch .Ldb_WOUT_exit

; #define G_STAGE(bufoff, gbase, o0, h64) do { \
;         __builtin_amdgcn_global_load_lds((const unsigned*)((const char*)(gbase) + (o0)), (LAS unsigned*)(lds + (bufoff) + ldsw), 16, 0, 0); \
;         __builtin_amdgcn_global_load_lds((const unsigned*)((const char*)(gbase) + (h64) + (o0)), (LAS unsigned*)(lds + (bufoff) + ldsw + 8192), 16, 0, 0); } while (0)
; #define G_LDA(dst, b, h) do { _Pragma("unroll") for (int m = 0; m < 4; ++m) _Pragma("unroll") for (int k = 0; k < 2; ++k) dst[m][k] = *(const LAS bf16x8*)(lds + G_SA(b, h) + aoff + m * 2048 + k * 1024); } while (0)
; #define G_LDB(dst, b, h) do { _Pragma("unroll") for (int n = 0; n < 2; ++n) _Pragma("unroll") for (int k = 0; k < 2; ++k) dst[n][k] = *(const LAS bf16x8*)(lds + G_SB(b, h) + boff + n * 2048 + k * 1024); } while (0)
; #define G_WAIT_L(n) asm volatile("s_waitcnt lgkmcnt(" #n ")" ::: "memory")
; #define G_BAR __builtin_amdgcn_s_barrier()
; #define G_SCHED __builtin_amdgcn_sched_barrier(0)
;     ...
;         for (int t = 0; t < nt; t += 2) {
;             const bool last = (t == nt - 2);
;             const char* a1 = cA + (size_t)(t + 1) * ckA;
;             const char* a2 = last ? nA : cA + (size_t)(t + 2) * ckA; const char* b2 = last ? nB : cB + (size_t)(t + 2) * kB;
;             const char* a3 = a2 + ckA; const char* b3 = b2 + kB;
;             G_LDB(B0, 0, 0); G_SCHED; G_LDA(At, 0, 0); G_STAGE(G_SA(1, 1), a1 + chA, cA0, qA);
;             G_WAIT_L(8); G_BAR; G_WAIT_L(0); G_MMA(0, 0, At, B0); G_BAR; G_SCHED;
;             G_LDB(B1, 0, 1); G_STAGE(G_SB(0, 0), b2, cB0, qB);
;             G_BAR; G_WAIT_L(0); G_MMA(0, 1, At, B1); G_BAR;
;     ...
;         if (!(cs.kind == K_MG_B && cur.aux < 2))
; #pragma unroll
;         for (int a = 0; a < 2; ++a)
; #pragma unroll
;             for (int b = 0; b < 2; ++b)
; #pragma unroll
;                 for (int m = 0; m < 4; ++m)
; #pragma unroll
;                     for (int n = 0; n < 2; ++n) acc[a][b][m][n] = (f32x4){0.f, 0.f, 0.f, 0.f};
;         cur = nxt; cA = nA; cB = nB; ++ui;
.LBB0_1119:
	s_add_u32 s2, s16, 0x40080
	s_addc_u32 s3, s17, 0
	s_add_u32 s16, s18, 0x100
	v_mov_b64_e32 v[8:9], 0
	s_addc_u32 s17, s19, 0
	s_mov_b32 s18, -2
	v_mov_b64_e32 v[10:11], 0
	v_mov_b64_e32 v[16:17], 0
	v_mov_b64_e32 v[18:19], 0
	v_mov_b64_e32 v[24:25], 0
	v_mov_b64_e32 v[26:27], 0
	v_mov_b64_e32 v[32:33], 0
	v_mov_b64_e32 v[34:35], 0
	v_mov_b64_e32 v[40:41], 0
	v_mov_b64_e32 v[42:43], 0
	v_mov_b64_e32 v[48:49], 0
	v_mov_b64_e32 v[50:51], 0
	v_mov_b64_e32 v[56:57], 0
	v_mov_b64_e32 v[58:59], 0
	v_mov_b64_e32 v[64:65], 0
	v_mov_b64_e32 v[66:67], 0
	v_mov_b64_e32 v[12:13], 0
	v_mov_b64_e32 v[14:15], 0
	v_mov_b64_e32 v[20:21], 0
	v_mov_b64_e32 v[22:23], 0
	v_mov_b64_e32 v[28:29], 0
	v_mov_b64_e32 v[30:31], 0
	v_mov_b64_e32 v[36:37], 0
	v_mov_b64_e32 v[38:39], 0
	v_mov_b64_e32 v[44:45], 0
	v_mov_b64_e32 v[46:47], 0
	v_mov_b64_e32 v[52:53], 0
	v_mov_b64_e32 v[54:55], 0
	v_mov_b64_e32 v[60:61], 0
	v_mov_b64_e32 v[62:63], 0
	v_mov_b64_e32 v[68:69], 0
	v_mov_b64_e32 v[70:71], 0
	v_mov_b64_e32 v[72:73], 0
	v_mov_b64_e32 v[74:75], 0
	v_mov_b64_e32 v[80:81], 0
	v_mov_b64_e32 v[82:83], 0
	v_mov_b64_e32 v[88:89], 0
	v_mov_b64_e32 v[90:91], 0
	v_mov_b64_e32 v[96:97], 0
	v_mov_b64_e32 v[98:99], 0
	v_mov_b64_e32 v[104:105], 0
	v_mov_b64_e32 v[106:107], 0
	v_mov_b64_e32 v[112:113], 0
	v_mov_b64_e32 v[114:115], 0
	v_mov_b64_e32 v[120:121], 0
	v_mov_b64_e32 v[122:123], 0
	v_mov_b64_e32 v[128:129], 0
	v_mov_b64_e32 v[130:131], 0
	v_mov_b64_e32 v[76:77], 0
	v_mov_b64_e32 v[78:79], 0
	v_mov_b64_e32 v[84:85], 0
	v_mov_b64_e32 v[86:87], 0
	v_mov_b64_e32 v[92:93], 0
	v_mov_b64_e32 v[94:95], 0
	v_mov_b64_e32 v[100:101], 0
	v_mov_b64_e32 v[102:103], 0
	v_mov_b64_e32 v[108:109], 0
	v_mov_b64_e32 v[110:111], 0
	v_mov_b64_e32 v[116:117], 0
	v_mov_b64_e32 v[118:119], 0
	v_mov_b64_e32 v[124:125], 0
	v_mov_b64_e32 v[126:127], 0
	v_mov_b64_e32 v[132:133], 0
	v_mov_b64_e32 v[134:135], 0
	s_mov_b64 s[42:43], 0x40000
	s_mov_b64 s[50:51], 0x60000
	s_mov_b64 s[52:53], 0x20080
	s_mov_b64 s[54:55], 0x40080
	s_mov_b64 s[58:59], 0x60080
	s_cmpk_gt_u32 s101, 0xff
	s_cbranch_scc0 .Ldbj_FFI_in
	s_barrier
	s_mov_b32 s101, 0
.Ldbj_FFI_in:
.LBB0_1120:
	s_add_u32 s4, s2, 0xfffc0080
	s_addc_u32 s5, s3, -1
	s_add_i32 s19, 0, 0x10000
	v_add_u32_e32 v0, s19, v149
	ds_read_b128 v[140:143], v0
	ds_read_b128 v[144:147], v0 offset:1024
	ds_read_b128 v[152:155], v0 offset:2048
	ds_read_b128 v[156:159], v0 offset:3072
	s_cmp_eq_u32 s18, 12
	s_cselect_b32 s5, s13, s5
	s_cselect_b32 s4, s12, s4
	s_cselect_b32 s41, s15, s17
	s_cselect_b32 s40, s14, s16
	v_lshl_add_u64 v[184:185], s[2:3], 0, v[138:139]
	s_add_i32 m0, s26, 0xc000
	ds_read_b128 v[160:163], v150
	ds_read_b128 v[164:167], v150 offset:1024
	ds_read_b128 v[172:175], v150 offset:2048
	ds_read_b128 v[176:179], v150 offset:3072
	ds_read_b128 v[180:183], v150 offset:4096
	ds_read_b128 v[196:199], v150 offset:5120
	ds_read_b128 v[200:203], v150 offset:6144
	ds_read_b128 v[204:207], v150 offset:7168
	global_load_lds_dwordx4 v[184:185], off
	v_lshl_add_u64 v[184:185], v[184:185], 0, s[0:1]
	s_add_i32 m0, s26, 0xe000
	s_nop 0
	global_load_lds_dwordx4 v[184:185], off
	s_waitcnt lgkmcnt(8)
	s_barrier
	s_waitcnt lgkmcnt(0)
	s_setprio 3
	s_waitcnt lgkmcnt(0)
	v_mfma_f32_16x16x32_bf16 v[132:135], v[140:143], v[160:163], v[132:135]
	v_mfma_f32_16x16x32_bf16 v[124:127], v[152:155], v[160:163], v[124:127]
	v_mfma_f32_16x16x32_bf16 v[116:119], v[140:143], v[172:175], v[116:119]
	v_mfma_f32_16x16x32_bf16 v[108:111], v[152:155], v[172:175], v[108:111]
	v_mfma_f32_16x16x32_bf16 v[100:103], v[140:143], v[180:183], v[100:103]
	v_mfma_f32_16x16x32_bf16 v[92:95], v[152:155], v[180:183], v[92:95]
	v_mfma_f32_16x16x32_bf16 v[84:87], v[140:143], v[200:203], v[84:87]
	v_mfma_f32_16x16x32_bf16 v[76:79], v[152:155], v[200:203], v[76:79]
	v_mfma_f32_16x16x32_bf16 v[132:135], v[144:147], v[164:167], v[132:135]
	v_mfma_f32_16x16x32_bf16 v[124:127], v[156:159], v[164:167], v[124:127]
	v_mfma_f32_16x16x32_bf16 v[116:119], v[144:147], v[176:179], v[116:119]
	v_mfma_f32_16x16x32_bf16 v[108:111], v[156:159], v[176:179], v[108:111]
	v_mfma_f32_16x16x32_bf16 v[100:103], v[144:147], v[196:199], v[100:103]
	v_mfma_f32_16x16x32_bf16 v[92:95], v[156:159], v[196:199], v[92:95]
	v_mfma_f32_16x16x32_bf16 v[84:87], v[144:147], v[204:207], v[84:87]
	v_mfma_f32_16x16x32_bf16 v[76:79], v[156:159], v[204:207], v[76:79]
	s_setprio 0
	s_barrier
	s_add_i32 s39, 0, 0x14000
	s_add_i32 s19, s19, s21
	v_add_u32_e32 v0, s39, v149
	v_lshl_add_u64 v[184:185], s[40:41], 0, v[2:3]
	s_mov_b32 m0, s19
	ds_read_b128 v[208:211], v0
	ds_read_b128 v[212:215], v0 offset:1024
	ds_read_b128 v[216:219], v0 offset:2048
	ds_read_b128 v[220:223], v0 offset:3072
	global_load_lds_dwordx4 v[184:185], off
	v_lshl_add_u64 v[224:225], v[184:185], 0, s[0:1]
	s_add_i32 m0, s19, 0x2000
	s_nop 0
	global_load_lds_dwordx4 v[224:225], off
	s_barrier
	s_waitcnt lgkmcnt(0)
	s_setprio 3
	s_waitcnt lgkmcnt(0)
	v_mfma_f32_16x16x32_bf16 v[128:131], v[208:211], v[160:163], v[128:131]
	v_mfma_f32_16x16x32_bf16 v[120:123], v[216:219], v[160:163], v[120:123]
	v_mfma_f32_16x16x32_bf16 v[112:115], v[208:211], v[172:175], v[112:115]
	v_mfma_f32_16x16x32_bf16 v[104:107], v[216:219], v[172:175], v[104:107]
	v_mfma_f32_16x16x32_bf16 v[96:99], v[208:211], v[180:183], v[96:99]
	v_mfma_f32_16x16x32_bf16 v[88:91], v[216:219], v[180:183], v[88:91]
	v_mfma_f32_16x16x32_bf16 v[80:83], v[208:211], v[200:203], v[80:83]
	v_mfma_f32_16x16x32_bf16 v[72:75], v[216:219], v[200:203], v[72:75]
	v_mfma_f32_16x16x32_bf16 v[128:131], v[212:215], v[164:167], v[128:131]
	v_mfma_f32_16x16x32_bf16 v[120:123], v[220:223], v[164:167], v[120:123]
	v_mfma_f32_16x16x32_bf16 v[112:115], v[212:215], v[176:179], v[112:115]
	v_mfma_f32_16x16x32_bf16 v[104:107], v[220:223], v[176:179], v[104:107]
	v_mfma_f32_16x16x32_bf16 v[96:99], v[212:215], v[196:199], v[96:99]
	v_mfma_f32_16x16x32_bf16 v[88:91], v[220:223], v[196:199], v[88:91]
	v_mfma_f32_16x16x32_bf16 v[80:83], v[212:215], v[204:207], v[80:83]
	v_mfma_f32_16x16x32_bf16 v[72:75], v[220:223], v[204:207], v[72:75]
	s_setprio 0
	s_mov_b32 m0, s26
	v_lshl_add_u64 v[224:225], s[4:5], 0, v[136:137]
	s_barrier
; #define G_STAGE(bufoff, gbase, o0, h64) do { \
;         __builtin_amdgcn_global_load_lds((const unsigned*)((const char*)(gbase) + (o0)), (LAS unsigned*)(lds + (bufoff) + ldsw), 16, 0, 0); \
;         __builtin_amdgcn_global_load_lds((const unsigned*)((const char*)(gbase) + (h64) + (o0)), (LAS unsigned*)(lds + (bufoff) + ldsw + 8192), 16, 0, 0); } while (0)
; #define G_LDA(dst, b, h) do { _Pragma("unroll") for (int m = 0; m < 4; ++m) _Pragma("unroll") for (int k = 0; k < 2; ++k) dst[m][k] = *(const LAS bf16x8*)(lds + G_SA(b, h) + aoff + m * 2048 + k * 1024); } while (0)
; #define G_LDB(dst, b, h) do { _Pragma("unroll") for (int n = 0; n < 2; ++n) _Pragma("unroll") for (int k = 0; k < 2; ++k) dst[n][k] = *(const LAS bf16x8*)(lds + G_SB(b, h) + boff + n * 2048 + k * 1024); } while (0)
; #define G_WAIT_V(n) asm volatile("s_waitcnt vmcnt(" #n ")" ::: "memory")
; #define G_WAIT_L(n) asm volatile("s_waitcnt lgkmcnt(" #n ")" ::: "memory")
; #define G_BAR __builtin_amdgcn_s_barrier()
; #define G_SCHED __builtin_amdgcn_sched_barrier(0)
;     ...
;             G_BAR; G_WAIT_L(0); G_MMA(0, 1, At, B1); G_BAR;
;             G_LDA(At, 0, 1); G_STAGE(G_SA(0, 0), a2, cA0, qA);
;             G_BAR; G_WAIT_L(0); G_MMA(1, 0, At, B0); G_BAR; G_SCHED;
;             G_STAGE(G_SB(0, 1), b2 + chB, cB0, qB);
;             G_WAIT_V(6); G_BAR; G_MMA(1, 1, At, B1); G_BAR;
;             G_LDB(B0, 1, 0); G_SCHED; G_LDA(At, 1, 0); G_STAGE(G_SA(0, 1), a2 + chA, cA0, qA);
;             G_WAIT_L(8); G_BAR; G_WAIT_L(0); G_MMA(0, 0, At, B0); G_BAR; G_SCHED;
;             G_LDB(B1, 1, 1); G_STAGE(G_SB(1, 0), b3, cB0, qB);
;             G_BAR; G_WAIT_L(0); G_MMA(0, 1, At, B1); G_BAR;
;             G_LDA(At, 1, 1); G_STAGE(G_SA(1, 0), a3, cA0, qA);
;             G_BAR; G_WAIT_L(0); G_MMA(1, 0, At, B0); G_BAR; G_SCHED;
	ds_read_b128 v[160:163], v150 offset:16384
	ds_read_b128 v[164:167], v150 offset:17408
	ds_read_b128 v[172:175], v150 offset:18432
	ds_read_b128 v[176:179], v150 offset:19456
	ds_read_b128 v[180:183], v150 offset:20480
	ds_read_b128 v[196:199], v150 offset:21504
	ds_read_b128 v[200:203], v150 offset:22528
	ds_read_b128 v[204:207], v150 offset:23552
	global_load_lds_dwordx4 v[224:225], off
	v_lshl_add_u64 v[226:227], v[224:225], 0, s[0:1]
	s_mov_b32 m0, s27
	s_nop 0
	global_load_lds_dwordx4 v[226:227], off
	s_barrier
	s_waitcnt lgkmcnt(0)
	s_setprio 3
	s_waitcnt lgkmcnt(0)
	v_mfma_f32_16x16x32_bf16 v[68:71], v[140:143], v[160:163], v[68:71]
	v_mfma_f32_16x16x32_bf16 v[60:63], v[152:155], v[160:163], v[60:63]
	v_mfma_f32_16x16x32_bf16 v[52:55], v[140:143], v[172:175], v[52:55]
	v_mfma_f32_16x16x32_bf16 v[44:47], v[152:155], v[172:175], v[44:47]
	v_mfma_f32_16x16x32_bf16 v[36:39], v[140:143], v[180:183], v[36:39]
	v_mfma_f32_16x16x32_bf16 v[28:31], v[152:155], v[180:183], v[28:31]
	v_mfma_f32_16x16x32_bf16 v[20:23], v[140:143], v[200:203], v[20:23]
	v_mfma_f32_16x16x32_bf16 v[12:15], v[152:155], v[200:203], v[12:15]
	v_mfma_f32_16x16x32_bf16 v[68:71], v[144:147], v[164:167], v[68:71]
	v_mfma_f32_16x16x32_bf16 v[60:63], v[156:159], v[164:167], v[60:63]
	v_mfma_f32_16x16x32_bf16 v[52:55], v[144:147], v[176:179], v[52:55]
	v_mfma_f32_16x16x32_bf16 v[44:47], v[156:159], v[176:179], v[44:47]
	v_mfma_f32_16x16x32_bf16 v[36:39], v[144:147], v[196:199], v[36:39]
	v_mfma_f32_16x16x32_bf16 v[28:31], v[156:159], v[196:199], v[28:31]
	v_mfma_f32_16x16x32_bf16 v[20:23], v[144:147], v[204:207], v[20:23]
	v_mfma_f32_16x16x32_bf16 v[12:15], v[156:159], v[204:207], v[12:15]
	s_setprio 0
	s_barrier
	s_add_i32 s4, s39, s21
	v_lshl_add_u64 v[140:141], v[184:185], 0, s[42:43]
	s_mov_b32 m0, s4
	s_nop 0
	global_load_lds_dwordx4 v[140:141], off
	v_lshl_add_u64 v[140:141], v[184:185], 0, s[50:51]
	s_add_i32 m0, s4, 0x2000
	s_nop 0
	global_load_lds_dwordx4 v[140:141], off
	s_waitcnt vmcnt(6)
	s_barrier
	s_setprio 3
	v_mfma_f32_16x16x32_bf16 v[64:67], v[208:211], v[160:163], v[64:67]
	v_mfma_f32_16x16x32_bf16 v[56:59], v[216:219], v[160:163], v[56:59]
	v_mfma_f32_16x16x32_bf16 v[48:51], v[208:211], v[172:175], v[48:51]
	v_mfma_f32_16x16x32_bf16 v[40:43], v[216:219], v[172:175], v[40:43]
	v_mfma_f32_16x16x32_bf16 v[32:35], v[208:211], v[180:183], v[32:35]
	v_mfma_f32_16x16x32_bf16 v[24:27], v[216:219], v[180:183], v[24:27]
	v_mfma_f32_16x16x32_bf16 v[16:19], v[208:211], v[200:203], v[16:19]
	v_mfma_f32_16x16x32_bf16 v[8:11], v[216:219], v[200:203], v[8:11]
	v_mfma_f32_16x16x32_bf16 v[64:67], v[212:215], v[164:167], v[64:67]
	v_mfma_f32_16x16x32_bf16 v[56:59], v[220:223], v[164:167], v[56:59]
	v_mfma_f32_16x16x32_bf16 v[48:51], v[212:215], v[176:179], v[48:51]
	v_mfma_f32_16x16x32_bf16 v[40:43], v[220:223], v[176:179], v[40:43]
	v_mfma_f32_16x16x32_bf16 v[32:35], v[212:215], v[196:199], v[32:35]
	v_mfma_f32_16x16x32_bf16 v[24:27], v[220:223], v[196:199], v[24:27]
	v_mfma_f32_16x16x32_bf16 v[16:19], v[212:215], v[204:207], v[16:19]
	v_mfma_f32_16x16x32_bf16 v[8:11], v[220:223], v[204:207], v[8:11]
	s_setprio 0
	s_add_i32 s4, 0, 0x18000
	v_add_u32_e32 v0, s4, v149
	s_barrier
	ds_read_b128 v[140:143], v0
	ds_read_b128 v[144:147], v0 offset:1024
	ds_read_b128 v[152:155], v0 offset:2048
	ds_read_b128 v[156:159], v0 offset:3072
	s_mov_b32 m0, s29
	v_lshl_add_u64 v[208:209], v[224:225], 0, s[42:43]
	ds_read_b128 v[160:163], v150 offset:32768
	ds_read_b128 v[164:167], v150 offset:33792
	ds_read_b128 v[172:175], v150 offset:34816
	ds_read_b128 v[176:179], v150 offset:35840
	ds_read_b128 v[180:183], v150 offset:36864
	ds_read_b128 v[196:199], v150 offset:37888
	ds_read_b128 v[200:203], v150 offset:38912
	ds_read_b128 v[204:207], v150 offset:39936
	global_load_lds_dwordx4 v[208:209], off
	v_lshl_add_u64 v[208:209], v[224:225], 0, s[50:51]
	s_mov_b32 m0, s30
	s_nop 0
	global_load_lds_dwordx4 v[208:209], off
	s_waitcnt lgkmcnt(8)
	s_barrier
	s_waitcnt lgkmcnt(0)
	s_setprio 3
	s_waitcnt lgkmcnt(0)
	v_mfma_f32_16x16x32_bf16 v[132:135], v[140:143], v[160:163], v[132:135]
	v_mfma_f32_16x16x32_bf16 v[124:127], v[152:155], v[160:163], v[124:127]
	v_mfma_f32_16x16x32_bf16 v[116:119], v[140:143], v[172:175], v[116:119]
	v_mfma_f32_16x16x32_bf16 v[108:111], v[152:155], v[172:175], v[108:111]
	v_mfma_f32_16x16x32_bf16 v[100:103], v[140:143], v[180:183], v[100:103]
	v_mfma_f32_16x16x32_bf16 v[92:95], v[152:155], v[180:183], v[92:95]
	v_mfma_f32_16x16x32_bf16 v[84:87], v[140:143], v[200:203], v[84:87]
	v_mfma_f32_16x16x32_bf16 v[76:79], v[152:155], v[200:203], v[76:79]
	v_mfma_f32_16x16x32_bf16 v[132:135], v[144:147], v[164:167], v[132:135]
	v_mfma_f32_16x16x32_bf16 v[124:127], v[156:159], v[164:167], v[124:127]
	v_mfma_f32_16x16x32_bf16 v[116:119], v[144:147], v[176:179], v[116:119]
	v_mfma_f32_16x16x32_bf16 v[108:111], v[156:159], v[176:179], v[108:111]
	v_mfma_f32_16x16x32_bf16 v[100:103], v[144:147], v[196:199], v[100:103]
	v_mfma_f32_16x16x32_bf16 v[92:95], v[156:159], v[196:199], v[92:95]
	v_mfma_f32_16x16x32_bf16 v[84:87], v[144:147], v[204:207], v[84:87]
	v_mfma_f32_16x16x32_bf16 v[76:79], v[156:159], v[204:207], v[76:79]
	s_setprio 0
	s_barrier
; #define G_STAGE(bufoff, gbase, o0, h64) do { \
;         __builtin_amdgcn_global_load_lds((const unsigned*)((const char*)(gbase) + (o0)), (LAS unsigned*)(lds + (bufoff) + ldsw), 16, 0, 0); \
;         __builtin_amdgcn_global_load_lds((const unsigned*)((const char*)(gbase) + (h64) + (o0)), (LAS unsigned*)(lds + (bufoff) + ldsw + 8192), 16, 0, 0); } while (0)
; #define G_LDA(dst, b, h) do { _Pragma("unroll") for (int m = 0; m < 4; ++m) _Pragma("unroll") for (int k = 0; k < 2; ++k) dst[m][k] = *(const LAS bf16x8*)(lds + G_SA(b, h) + aoff + m * 2048 + k * 1024); } while (0)
; #define G_LDB(dst, b, h) do { _Pragma("unroll") for (int n = 0; n < 2; ++n) _Pragma("unroll") for (int k = 0; k < 2; ++k) dst[n][k] = *(const LAS bf16x8*)(lds + G_SB(b, h) + boff + n * 2048 + k * 1024); } while (0)
; #define G_WAIT_V(n) asm volatile("s_waitcnt vmcnt(" #n ")" ::: "memory")
; #define G_WAIT_L(n) asm volatile("s_waitcnt lgkmcnt(" #n ")" ::: "memory")
; #define G_BAR __builtin_amdgcn_s_barrier()
; #define G_SCHED __builtin_amdgcn_sched_barrier(0)
;     ...
;             G_WAIT_L(8); G_BAR; G_WAIT_L(0); G_MMA(0, 0, At, B0); G_BAR; G_SCHED;
;             G_LDB(B1, 1, 1); G_STAGE(G_SB(1, 0), b3, cB0, qB);
;             G_BAR; G_WAIT_L(0); G_MMA(0, 1, At, B1); G_BAR;
;             G_LDA(At, 1, 1); G_STAGE(G_SA(1, 0), a3, cA0, qA);
;             G_BAR; G_WAIT_L(0); G_MMA(1, 0, At, B0); G_BAR; G_SCHED;
;             G_STAGE(G_SB(1, 1), b3 + chB, cB0, qB);
;             G_WAIT_V(6); G_BAR; G_MMA(1, 1, At, B1); G_BAR;
;         }
	s_add_i32 s5, 0, 0x1c000
	s_add_i32 s4, s4, s21
	v_add_u32_e32 v0, s5, v149
	v_lshl_add_u64 v[226:227], v[184:185], 0, s[46:47]
	s_mov_b32 m0, s4
	ds_read_b128 v[208:211], v0
	ds_read_b128 v[212:215], v0 offset:1024
	ds_read_b128 v[216:219], v0 offset:2048
	ds_read_b128 v[220:223], v0 offset:3072
	global_load_lds_dwordx4 v[226:227], off
	v_lshl_add_u64 v[226:227], v[184:185], 0, s[52:53]
	s_add_i32 m0, s4, 0x2000
	s_nop 0
	global_load_lds_dwordx4 v[226:227], off
	s_barrier
	s_waitcnt lgkmcnt(0)
	s_setprio 3
	s_waitcnt lgkmcnt(0)
	v_mfma_f32_16x16x32_bf16 v[128:131], v[208:211], v[160:163], v[128:131]
	v_mfma_f32_16x16x32_bf16 v[120:123], v[216:219], v[160:163], v[120:123]
	v_mfma_f32_16x16x32_bf16 v[112:115], v[208:211], v[172:175], v[112:115]
	v_mfma_f32_16x16x32_bf16 v[104:107], v[216:219], v[172:175], v[104:107]
	v_mfma_f32_16x16x32_bf16 v[96:99], v[208:211], v[180:183], v[96:99]
	v_mfma_f32_16x16x32_bf16 v[88:91], v[216:219], v[180:183], v[88:91]
	v_mfma_f32_16x16x32_bf16 v[80:83], v[208:211], v[200:203], v[80:83]
	v_mfma_f32_16x16x32_bf16 v[72:75], v[216:219], v[200:203], v[72:75]
	v_mfma_f32_16x16x32_bf16 v[128:131], v[212:215], v[164:167], v[128:131]
	v_mfma_f32_16x16x32_bf16 v[120:123], v[220:223], v[164:167], v[120:123]
	v_mfma_f32_16x16x32_bf16 v[112:115], v[212:215], v[176:179], v[112:115]
	v_mfma_f32_16x16x32_bf16 v[104:107], v[220:223], v[176:179], v[104:107]
	v_mfma_f32_16x16x32_bf16 v[96:99], v[212:215], v[196:199], v[96:99]
	v_mfma_f32_16x16x32_bf16 v[88:91], v[220:223], v[196:199], v[88:91]
	v_mfma_f32_16x16x32_bf16 v[80:83], v[212:215], v[204:207], v[80:83]
	v_mfma_f32_16x16x32_bf16 v[72:75], v[220:223], v[204:207], v[72:75]
	s_setprio 0
	s_mov_b32 m0, s31
	v_lshl_add_u64 v[226:227], v[224:225], 0, s[46:47]
	s_barrier
	ds_read_b128 v[160:163], v150 offset:49152
	ds_read_b128 v[164:167], v150 offset:50176
	ds_read_b128 v[172:175], v150 offset:51200
	ds_read_b128 v[176:179], v150 offset:52224
	ds_read_b128 v[180:183], v150 offset:53248
	ds_read_b128 v[196:199], v150 offset:54272
	ds_read_b128 v[200:203], v150 offset:55296
	ds_read_b128 v[204:207], v150 offset:56320
	global_load_lds_dwordx4 v[226:227], off
	v_lshl_add_u64 v[224:225], v[224:225], 0, s[52:53]
	s_mov_b32 m0, s34
	s_nop 0
	global_load_lds_dwordx4 v[224:225], off
	s_barrier
	s_waitcnt lgkmcnt(0)
	s_setprio 3
	s_waitcnt lgkmcnt(0)
	v_mfma_f32_16x16x32_bf16 v[68:71], v[140:143], v[160:163], v[68:71]
	v_mfma_f32_16x16x32_bf16 v[60:63], v[152:155], v[160:163], v[60:63]
	v_mfma_f32_16x16x32_bf16 v[52:55], v[140:143], v[172:175], v[52:55]
	v_mfma_f32_16x16x32_bf16 v[44:47], v[152:155], v[172:175], v[44:47]
	v_mfma_f32_16x16x32_bf16 v[36:39], v[140:143], v[180:183], v[36:39]
	v_mfma_f32_16x16x32_bf16 v[28:31], v[152:155], v[180:183], v[28:31]
	v_mfma_f32_16x16x32_bf16 v[20:23], v[140:143], v[200:203], v[20:23]
	v_mfma_f32_16x16x32_bf16 v[12:15], v[152:155], v[200:203], v[12:15]
	v_mfma_f32_16x16x32_bf16 v[68:71], v[144:147], v[164:167], v[68:71]
	v_mfma_f32_16x16x32_bf16 v[60:63], v[156:159], v[164:167], v[60:63]
	v_mfma_f32_16x16x32_bf16 v[52:55], v[144:147], v[176:179], v[52:55]
	v_mfma_f32_16x16x32_bf16 v[44:47], v[156:159], v[176:179], v[44:47]
	v_mfma_f32_16x16x32_bf16 v[36:39], v[144:147], v[196:199], v[36:39]
	v_mfma_f32_16x16x32_bf16 v[28:31], v[156:159], v[196:199], v[28:31]
	v_mfma_f32_16x16x32_bf16 v[20:23], v[144:147], v[204:207], v[20:23]
	v_mfma_f32_16x16x32_bf16 v[12:15], v[156:159], v[204:207], v[12:15]
	s_setprio 0
	s_barrier
	s_add_i32 s4, s5, s21
	v_lshl_add_u64 v[140:141], v[184:185], 0, s[54:55]
	s_mov_b32 m0, s4
	s_nop 0
	global_load_lds_dwordx4 v[140:141], off
	v_lshl_add_u64 v[140:141], v[184:185], 0, s[58:59]
	s_add_i32 m0, s4, 0x2000
	s_nop 0
	global_load_lds_dwordx4 v[140:141], off
	s_waitcnt vmcnt(6)
	s_barrier
	s_setprio 3
	v_mfma_f32_16x16x32_bf16 v[64:67], v[208:211], v[160:163], v[64:67]
	v_mfma_f32_16x16x32_bf16 v[56:59], v[216:219], v[160:163], v[56:59]
	v_mfma_f32_16x16x32_bf16 v[48:51], v[208:211], v[172:175], v[48:51]
	v_mfma_f32_16x16x32_bf16 v[40:43], v[216:219], v[172:175], v[40:43]
	v_mfma_f32_16x16x32_bf16 v[32:35], v[208:211], v[180:183], v[32:35]
	v_mfma_f32_16x16x32_bf16 v[24:27], v[216:219], v[180:183], v[24:27]
	v_mfma_f32_16x16x32_bf16 v[16:19], v[208:211], v[200:203], v[16:19]
	v_mfma_f32_16x16x32_bf16 v[8:11], v[216:219], v[200:203], v[8:11]
	v_mfma_f32_16x16x32_bf16 v[64:67], v[212:215], v[164:167], v[64:67]
	v_mfma_f32_16x16x32_bf16 v[56:59], v[220:223], v[164:167], v[56:59]
	v_mfma_f32_16x16x32_bf16 v[48:51], v[212:215], v[176:179], v[48:51]
	v_mfma_f32_16x16x32_bf16 v[40:43], v[220:223], v[176:179], v[40:43]
	v_mfma_f32_16x16x32_bf16 v[32:35], v[212:215], v[196:199], v[32:35]
	v_mfma_f32_16x16x32_bf16 v[24:27], v[220:223], v[196:199], v[24:27]
	v_mfma_f32_16x16x32_bf16 v[16:19], v[212:215], v[204:207], v[16:19]
	v_mfma_f32_16x16x32_bf16 v[8:11], v[220:223], v[204:207], v[8:11]
	s_setprio 0
	s_add_i32 s18, s18, 2
	s_add_u32 s2, s2, 0x100
	s_addc_u32 s3, s3, 0
	s_add_u32 s16, s16, 0x100
	s_addc_u32 s17, s17, 0
	s_cmp_gt_u32 s18, 13
	s_cbranch_scc0 .Ldb_FFI_cont
	v_readfirstlane_b32 s101, v186
	s_cmpk_gt_u32 s101, 0xff
	s_cbranch_scc1 .Ldb_FFI_exit
	s_barrier
	s_branch .Ldb_FFI_exit

; __device__ __forceinline__ float sigmoidf_(float v) { return __builtin_amdgcn_rcpf(1.0f + __expf(-v)); }
; __device__ __forceinline__ u32x4 pack8(const f32x4 a, const f32x4 b) { u32x4 w; w.x = cvt_pk_bf16(a[0], a[1]); w.y = cvt_pk_bf16(a[2], a[3]); w.z = cvt_pk_bf16(b[0], b[1]); w.w = cvt_pk_bf16(b[2], b[3]); return w; }
; #define MEMFENCE asm volatile("" ::: "memory")
;     __device__ __forceinline__ void get_rs(const Unit& u, int wr, int fr, float (&rs)[8]) const {
; #pragma unroll
;         for (int r8 = 0; r8 < 8; ++r8) rs[r8] = rstab[u.ord * 256 + (r8 >> 2) * 128 + wr * 64 + (r8 & 3) * 16 + fr];
;     }
;     template <int KIND> __device__ __forceinline__ void run(f32x4 (&acc)[2][2][4][2], const Unit& u, int tid_in) const {
;     ...
;         if constexpr (KIND == K_FFI) { bf16_t* act = zb; float rs[8]; get_rs(u, wr, fr, rs);
; #pragma unroll
;             for (int ai = 0; ai < 2; ++ai)
; #pragma unroll
;                 for (int m = 0; m < 4; ++m) { int row = rbase + ai * 128 + m * 16; asm volatile("" : "+v"(row)); const float r = rs[ai * 4 + m]; f32x4 o[2];
; #pragma unroll
;                     for (int n = 0; n < 2; ++n) { const f32x4 g = acc[ai][0][m][n] * r, v = acc[ai][1][m][n] * r;
; #pragma unroll
;                         for (int j = 0; j < 4; ++j) o[n][j] = g[j] * sigmoidf_(g[j]) * v[j]; }
;                     *(u32x4*)(act + (size_t)row * ZW + u.pn * 128 + cl) = pack8(o[0], o[1]); MEMFENCE; }
.Ldb_FFI_exit:
	v_readfirstlane_b32 s2, v148
	s_lshr_b32 s4, s2, 1
	s_and_b32 s4, s4, 0x60
	v_lshrrev_b32_e32 v0, 1, v148
	v_and_or_b32 v0, v0, 24, s4
	v_and_b32_e32 v140, 15, v148
	s_lshl_b32 s4, s38, 10
	s_and_b32 s3, s2, 0xffffff00
	s_add_i32 s4, s4, s3
	v_lshl_add_u32 v141, v140, 2, s4
	v_add_u32_e32 v141, 0x20010, v141
	ds_read_b32 v240, v141
	ds_read_b32 v242, v141 offset:64
	ds_read_b32 v244, v141 offset:128
	ds_read_b32 v246, v141 offset:192
	ds_read_b32 v248, v141 offset:512
	ds_read_b32 v250, v141 offset:576
	ds_read_b32 v252, v141 offset:640
	ds_read_b32 v254, v141 offset:704
	s_ashr_i32 s3, s2, 2
	s_andn2_b32 s3, s3, 63
	v_or_b32_e32 v140, s3, v140
	v_lshl_add_u32 v140, s37, 8, v140
	v_mul_lo_u32 v140, v140, s76
	s_lshl_b32 s3, s33, 8
	v_lshlrev_b32_e32 v0, 1, v0
	v_add3_u32 v140, v140, v0, s3
	s_mov_b64 s[4:5], s[6:7]
	s_mov_b32 s2, 0xbfb8aa3b
	s_mov_b32 s100, 1.0
	s_waitcnt lgkmcnt(0)
	v_pk_mul_f32 v[132:133], v[132:133], v[240:241] op_sel_hi:[1,0]
	v_pk_mul_f32 v[128:129], v[128:129], v[240:241] op_sel_hi:[1,0]
	v_pk_mul_f32 v[216:217], v[132:133], s[2:3] op_sel_hi:[1,0]
	v_pk_mul_f32 v[134:135], v[134:135], v[240:241] op_sel_hi:[1,0]
	v_pk_mul_f32 v[130:131], v[130:131], v[240:241] op_sel_hi:[1,0]
	v_pk_mul_f32 v[218:219], v[134:135], s[2:3] op_sel_hi:[1,0]
	v_pk_mul_f32 v[124:125], v[124:125], v[240:241] op_sel_hi:[1,0]
	v_pk_mul_f32 v[120:121], v[120:121], v[240:241] op_sel_hi:[1,0]
	v_pk_mul_f32 v[220:221], v[124:125], s[2:3] op_sel_hi:[1,0]
	v_pk_mul_f32 v[126:127], v[126:127], v[240:241] op_sel_hi:[1,0]
	v_pk_mul_f32 v[122:123], v[122:123], v[240:241] op_sel_hi:[1,0]
	v_pk_mul_f32 v[222:223], v[126:127], s[2:3] op_sel_hi:[1,0]
	v_exp_f32_e32 v216, v216
	v_exp_f32_e32 v217, v217
	v_exp_f32_e32 v218, v218
	v_exp_f32_e32 v219, v219
	v_exp_f32_e32 v220, v220
	v_exp_f32_e32 v221, v221
	v_exp_f32_e32 v222, v222
	v_exp_f32_e32 v223, v223
	v_pk_add_f32 v[216:217], v[216:217], s[100:101] op_sel_hi:[1,0]
	v_pk_add_f32 v[218:219], v[218:219], s[100:101] op_sel_hi:[1,0]
	v_pk_add_f32 v[220:221], v[220:221], s[100:101] op_sel_hi:[1,0]
	v_pk_add_f32 v[222:223], v[222:223], s[100:101] op_sel_hi:[1,0]
	v_rcp_f32_e32 v216, v216
	v_rcp_f32_e32 v217, v217
	v_rcp_f32_e32 v218, v218
	v_rcp_f32_e32 v219, v219
	v_rcp_f32_e32 v220, v220
	v_rcp_f32_e32 v221, v221
	v_rcp_f32_e32 v222, v222
	v_rcp_f32_e32 v223, v223
	v_pk_mul_f32 v[132:133], v[132:133], v[216:217]
	v_pk_mul_f32 v[134:135], v[134:135], v[218:219]
	v_pk_mul_f32 v[124:125], v[124:125], v[220:221]
	v_pk_mul_f32 v[126:127], v[126:127], v[222:223]
	v_pk_mul_f32 v[132:133], v[132:133], v[128:129]
	v_pk_mul_f32 v[134:135], v[134:135], v[130:131]
	v_pk_mul_f32 v[124:125], v[124:125], v[120:121]
	v_pk_mul_f32 v[126:127], v[126:127], v[122:123]
	v_cvt_pk_bf16_f32 v236, v132, v133
	v_cvt_pk_bf16_f32 v237, v134, v135
	v_cvt_pk_bf16_f32 v238, v124, v125
	v_cvt_pk_bf16_f32 v239, v126, v127
	global_store_dwordx4 v140, v[236:239], s[4:5]
	s_add_u32 s4, s4, 0x16000
	s_addc_u32 s5, s5, 0
	v_pk_mul_f32 v[116:117], v[116:117], v[242:243] op_sel_hi:[1,0]
	v_pk_mul_f32 v[112:113], v[112:113], v[242:243] op_sel_hi:[1,0]
	v_pk_mul_f32 v[216:217], v[116:117], s[2:3] op_sel_hi:[1,0]
	v_pk_mul_f32 v[118:119], v[118:119], v[242:243] op_sel_hi:[1,0]
	v_pk_mul_f32 v[114:115], v[114:115], v[242:243] op_sel_hi:[1,0]
	v_pk_mul_f32 v[218:219], v[118:119], s[2:3] op_sel_hi:[1,0]
	v_pk_mul_f32 v[108:109], v[108:109], v[242:243] op_sel_hi:[1,0]
	v_pk_mul_f32 v[104:105], v[104:105], v[242:243] op_sel_hi:[1,0]
	v_pk_mul_f32 v[220:221], v[108:109], s[2:3] op_sel_hi:[1,0]
	v_pk_mul_f32 v[110:111], v[110:111], v[242:243] op_sel_hi:[1,0]
	v_pk_mul_f32 v[106:107], v[106:107], v[242:243] op_sel_hi:[1,0]
	v_pk_mul_f32 v[222:223], v[110:111], s[2:3] op_sel_hi:[1,0]
	v_exp_f32_e32 v216, v216
	v_exp_f32_e32 v217, v217
	v_exp_f32_e32 v218, v218
	v_exp_f32_e32 v219, v219
	v_exp_f32_e32 v220, v220
	v_exp_f32_e32 v221, v221
	v_exp_f32_e32 v222, v222
	v_exp_f32_e32 v223, v223
	v_pk_add_f32 v[216:217], v[216:217], s[100:101] op_sel_hi:[1,0]
	v_pk_add_f32 v[218:219], v[218:219], s[100:101] op_sel_hi:[1,0]
	v_pk_add_f32 v[220:221], v[220:221], s[100:101] op_sel_hi:[1,0]
	v_pk_add_f32 v[222:223], v[222:223], s[100:101] op_sel_hi:[1,0]
	v_rcp_f32_e32 v216, v216
	v_rcp_f32_e32 v217, v217
	v_rcp_f32_e32 v218, v218
	v_rcp_f32_e32 v219, v219
	v_rcp_f32_e32 v220, v220
	v_rcp_f32_e32 v221, v221
	v_rcp_f32_e32 v222, v222
	v_rcp_f32_e32 v223, v223
	v_pk_mul_f32 v[116:117], v[116:117], v[216:217]
	v_pk_mul_f32 v[118:119], v[118:119], v[218:219]
	v_pk_mul_f32 v[108:109], v[108:109], v[220:221]
	v_pk_mul_f32 v[110:111], v[110:111], v[222:223]
	v_pk_mul_f32 v[116:117], v[116:117], v[112:113]
	v_pk_mul_f32 v[118:119], v[118:119], v[114:115]
	v_pk_mul_f32 v[108:109], v[108:109], v[104:105]
	v_pk_mul_f32 v[110:111], v[110:111], v[106:107]
	v_cvt_pk_bf16_f32 v236, v116, v117
	v_cvt_pk_bf16_f32 v237, v118, v119
	v_cvt_pk_bf16_f32 v238, v108, v109
	v_cvt_pk_bf16_f32 v239, v110, v111
	global_store_dwordx4 v140, v[236:239], s[4:5]
	s_add_u32 s4, s4, 0x16000
	s_addc_u32 s5, s5, 0
	v_pk_mul_f32 v[100:101], v[100:101], v[244:245] op_sel_hi:[1,0]
	v_pk_mul_f32 v[96:97], v[96:97], v[244:245] op_sel_hi:[1,0]
	v_pk_mul_f32 v[216:217], v[100:101], s[2:3] op_sel_hi:[1,0]
	v_pk_mul_f32 v[102:103], v[102:103], v[244:245] op_sel_hi:[1,0]
	v_pk_mul_f32 v[98:99], v[98:99], v[244:245] op_sel_hi:[1,0]
	v_pk_mul_f32 v[218:219], v[102:103], s[2:3] op_sel_hi:[1,0]
	v_pk_mul_f32 v[92:93], v[92:93], v[244:245] op_sel_hi:[1,0]
	v_pk_mul_f32 v[88:89], v[88:89], v[244:245] op_sel_hi:[1,0]
	v_pk_mul_f32 v[220:221], v[92:93], s[2:3] op_sel_hi:[1,0]
; __device__ __forceinline__ float sigmoidf_(float v) { return __builtin_amdgcn_rcpf(1.0f + __expf(-v)); }
; __device__ __forceinline__ u32x4 pack8(const f32x4 a, const f32x4 b) { u32x4 w; w.x = cvt_pk_bf16(a[0], a[1]); w.y = cvt_pk_bf16(a[2], a[3]); w.z = cvt_pk_bf16(b[0], b[1]); w.w = cvt_pk_bf16(b[2], b[3]); return w; }
; #define MEMFENCE asm volatile("" ::: "memory")
;     template <int KIND> __device__ __forceinline__ void run(f32x4 (&acc)[2][2][4][2], const Unit& u, int tid_in) const {
;     ...
;         if constexpr (KIND == K_FFI) { bf16_t* act = zb; float rs[8]; get_rs(u, wr, fr, rs);
; #pragma unroll
;             for (int ai = 0; ai < 2; ++ai)
; #pragma unroll
;                 for (int m = 0; m < 4; ++m) { int row = rbase + ai * 128 + m * 16; asm volatile("" : "+v"(row)); const float r = rs[ai * 4 + m]; f32x4 o[2];
; #pragma unroll
;                     for (int n = 0; n < 2; ++n) { const f32x4 g = acc[ai][0][m][n] * r, v = acc[ai][1][m][n] * r;
; #pragma unroll
;                         for (int j = 0; j < 4; ++j) o[n][j] = g[j] * sigmoidf_(g[j]) * v[j]; }
;                     *(u32x4*)(act + (size_t)row * ZW + u.pn * 128 + cl) = pack8(o[0], o[1]); MEMFENCE; }
	v_pk_mul_f32 v[94:95], v[94:95], v[244:245] op_sel_hi:[1,0]
	v_pk_mul_f32 v[90:91], v[90:91], v[244:245] op_sel_hi:[1,0]
	v_pk_mul_f32 v[222:223], v[94:95], s[2:3] op_sel_hi:[1,0]
	v_exp_f32_e32 v216, v216
	v_exp_f32_e32 v217, v217
	v_exp_f32_e32 v218, v218
	v_exp_f32_e32 v219, v219
	v_exp_f32_e32 v220, v220
	v_exp_f32_e32 v221, v221
	v_exp_f32_e32 v222, v222
	v_exp_f32_e32 v223, v223
	v_pk_add_f32 v[216:217], v[216:217], s[100:101] op_sel_hi:[1,0]
	v_pk_add_f32 v[218:219], v[218:219], s[100:101] op_sel_hi:[1,0]
	v_pk_add_f32 v[220:221], v[220:221], s[100:101] op_sel_hi:[1,0]
	v_pk_add_f32 v[222:223], v[222:223], s[100:101] op_sel_hi:[1,0]
	v_rcp_f32_e32 v216, v216
	v_rcp_f32_e32 v217, v217
	v_rcp_f32_e32 v218, v218
	v_rcp_f32_e32 v219, v219
	v_rcp_f32_e32 v220, v220
	v_rcp_f32_e32 v221, v221
	v_rcp_f32_e32 v222, v222
	v_rcp_f32_e32 v223, v223
	v_pk_mul_f32 v[100:101], v[100:101], v[216:217]
	v_pk_mul_f32 v[102:103], v[102:103], v[218:219]
	v_pk_mul_f32 v[92:93], v[92:93], v[220:221]
	v_pk_mul_f32 v[94:95], v[94:95], v[222:223]
	v_pk_mul_f32 v[100:101], v[100:101], v[96:97]
	v_pk_mul_f32 v[102:103], v[102:103], v[98:99]
	v_pk_mul_f32 v[92:93], v[92:93], v[88:89]
	v_pk_mul_f32 v[94:95], v[94:95], v[90:91]
	v_cvt_pk_bf16_f32 v236, v100, v101
	v_cvt_pk_bf16_f32 v237, v102, v103
	v_cvt_pk_bf16_f32 v238, v92, v93
	v_cvt_pk_bf16_f32 v239, v94, v95
	global_store_dwordx4 v140, v[236:239], s[4:5]
	s_add_u32 s4, s4, 0x16000
	s_addc_u32 s5, s5, 0
	v_pk_mul_f32 v[84:85], v[84:85], v[246:247] op_sel_hi:[1,0]
	v_pk_mul_f32 v[80:81], v[80:81], v[246:247] op_sel_hi:[1,0]
	v_pk_mul_f32 v[216:217], v[84:85], s[2:3] op_sel_hi:[1,0]
	v_pk_mul_f32 v[86:87], v[86:87], v[246:247] op_sel_hi:[1,0]
	v_pk_mul_f32 v[82:83], v[82:83], v[246:247] op_sel_hi:[1,0]
	v_pk_mul_f32 v[218:219], v[86:87], s[2:3] op_sel_hi:[1,0]
	v_pk_mul_f32 v[76:77], v[76:77], v[246:247] op_sel_hi:[1,0]
	v_pk_mul_f32 v[72:73], v[72:73], v[246:247] op_sel_hi:[1,0]
	v_pk_mul_f32 v[220:221], v[76:77], s[2:3] op_sel_hi:[1,0]
	v_pk_mul_f32 v[78:79], v[78:79], v[246:247] op_sel_hi:[1,0]
	v_pk_mul_f32 v[74:75], v[74:75], v[246:247] op_sel_hi:[1,0]
	v_pk_mul_f32 v[222:223], v[78:79], s[2:3] op_sel_hi:[1,0]
	v_exp_f32_e32 v216, v216
	v_exp_f32_e32 v217, v217
	v_exp_f32_e32 v218, v218
	v_exp_f32_e32 v219, v219
	v_exp_f32_e32 v220, v220
	v_exp_f32_e32 v221, v221
	v_exp_f32_e32 v222, v222
	v_exp_f32_e32 v223, v223
	v_pk_add_f32 v[216:217], v[216:217], s[100:101] op_sel_hi:[1,0]
	v_pk_add_f32 v[218:219], v[218:219], s[100:101] op_sel_hi:[1,0]
	v_pk_add_f32 v[220:221], v[220:221], s[100:101] op_sel_hi:[1,0]
	v_pk_add_f32 v[222:223], v[222:223], s[100:101] op_sel_hi:[1,0]
	v_rcp_f32_e32 v216, v216
	v_rcp_f32_e32 v217, v217
	v_rcp_f32_e32 v218, v218
	v_rcp_f32_e32 v219, v219
	v_rcp_f32_e32 v220, v220
	v_rcp_f32_e32 v221, v221
	v_rcp_f32_e32 v222, v222
	v_rcp_f32_e32 v223, v223
	v_pk_mul_f32 v[84:85], v[84:85], v[216:217]
	v_pk_mul_f32 v[86:87], v[86:87], v[218:219]
	v_pk_mul_f32 v[76:77], v[76:77], v[220:221]
	v_pk_mul_f32 v[78:79], v[78:79], v[222:223]
	v_pk_mul_f32 v[84:85], v[84:85], v[80:81]
	v_pk_mul_f32 v[86:87], v[86:87], v[82:83]
	v_pk_mul_f32 v[76:77], v[76:77], v[72:73]
	v_pk_mul_f32 v[78:79], v[78:79], v[74:75]
	v_cvt_pk_bf16_f32 v236, v84, v85
	v_cvt_pk_bf16_f32 v237, v86, v87
	v_cvt_pk_bf16_f32 v238, v76, v77
	v_cvt_pk_bf16_f32 v239, v78, v79
	global_store_dwordx4 v140, v[236:239], s[4:5]
	s_add_u32 s4, s4, 0x6e000
	s_addc_u32 s5, s5, 0
	v_pk_mul_f32 v[68:69], v[68:69], v[248:249] op_sel_hi:[1,0]
	v_pk_mul_f32 v[64:65], v[64:65], v[248:249] op_sel_hi:[1,0]
	v_pk_mul_f32 v[216:217], v[68:69], s[2:3] op_sel_hi:[1,0]
	v_pk_mul_f32 v[70:71], v[70:71], v[248:249] op_sel_hi:[1,0]
	v_pk_mul_f32 v[66:67], v[66:67], v[248:249] op_sel_hi:[1,0]
	v_pk_mul_f32 v[218:219], v[70:71], s[2:3] op_sel_hi:[1,0]
	v_pk_mul_f32 v[60:61], v[60:61], v[248:249] op_sel_hi:[1,0]
	v_pk_mul_f32 v[56:57], v[56:57], v[248:249] op_sel_hi:[1,0]
	v_pk_mul_f32 v[220:221], v[60:61], s[2:3] op_sel_hi:[1,0]
	v_pk_mul_f32 v[62:63], v[62:63], v[248:249] op_sel_hi:[1,0]
	v_pk_mul_f32 v[58:59], v[58:59], v[248:249] op_sel_hi:[1,0]
	v_pk_mul_f32 v[222:223], v[62:63], s[2:3] op_sel_hi:[1,0]
	v_exp_f32_e32 v216, v216
	v_exp_f32_e32 v217, v217
	v_exp_f32_e32 v218, v218
	v_exp_f32_e32 v219, v219
	v_exp_f32_e32 v220, v220
	v_exp_f32_e32 v221, v221
	v_exp_f32_e32 v222, v222
	v_exp_f32_e32 v223, v223
	v_pk_add_f32 v[216:217], v[216:217], s[100:101] op_sel_hi:[1,0]
	v_pk_add_f32 v[218:219], v[218:219], s[100:101] op_sel_hi:[1,0]
	v_pk_add_f32 v[220:221], v[220:221], s[100:101] op_sel_hi:[1,0]
	v_pk_add_f32 v[222:223], v[222:223], s[100:101] op_sel_hi:[1,0]
	v_rcp_f32_e32 v216, v216
	v_rcp_f32_e32 v217, v217
	v_rcp_f32_e32 v218, v218
	v_rcp_f32_e32 v219, v219
	v_rcp_f32_e32 v220, v220
	v_rcp_f32_e32 v221, v221
	v_rcp_f32_e32 v222, v222
	v_rcp_f32_e32 v223, v223
	v_pk_mul_f32 v[68:69], v[68:69], v[216:217]
	v_pk_mul_f32 v[70:71], v[70:71], v[218:219]
	v_pk_mul_f32 v[60:61], v[60:61], v[220:221]
	v_pk_mul_f32 v[62:63], v[62:63], v[222:223]
	v_pk_mul_f32 v[68:69], v[68:69], v[64:65]
	v_pk_mul_f32 v[70:71], v[70:71], v[66:67]
	v_pk_mul_f32 v[60:61], v[60:61], v[56:57]
	v_pk_mul_f32 v[62:63], v[62:63], v[58:59]
	v_cvt_pk_bf16_f32 v236, v68, v69
	v_cvt_pk_bf16_f32 v237, v70, v71
	v_cvt_pk_bf16_f32 v238, v60, v61
	v_cvt_pk_bf16_f32 v239, v62, v63
	global_store_dwordx4 v140, v[236:239], s[4:5]
	s_add_u32 s4, s4, 0x16000
	s_addc_u32 s5, s5, 0
	v_pk_mul_f32 v[52:53], v[52:53], v[250:251] op_sel_hi:[1,0]
	v_pk_mul_f32 v[48:49], v[48:49], v[250:251] op_sel_hi:[1,0]
	v_pk_mul_f32 v[216:217], v[52:53], s[2:3] op_sel_hi:[1,0]
; __device__ __forceinline__ float sigmoidf_(float v) { return __builtin_amdgcn_rcpf(1.0f + __expf(-v)); }
; __device__ __forceinline__ u32x4 pack8(const f32x4 a, const f32x4 b) { u32x4 w; w.x = cvt_pk_bf16(a[0], a[1]); w.y = cvt_pk_bf16(a[2], a[3]); w.z = cvt_pk_bf16(b[0], b[1]); w.w = cvt_pk_bf16(b[2], b[3]); return w; }
; #define MEMFENCE asm volatile("" ::: "memory")
;     template <int KIND> __device__ __forceinline__ void run(f32x4 (&acc)[2][2][4][2], const Unit& u, int tid_in) const {
;     ...
;             for (int ai = 0; ai < 2; ++ai)
; #pragma unroll
;                 for (int m = 0; m < 4; ++m) { int row = rbase + ai * 128 + m * 16; asm volatile("" : "+v"(row)); const float r = rs[ai * 4 + m]; f32x4 o[2];
; #pragma unroll
;                     for (int n = 0; n < 2; ++n) { const f32x4 g = acc[ai][0][m][n] * r, v = acc[ai][1][m][n] * r;
; #pragma unroll
;                         for (int j = 0; j < 4; ++j) o[n][j] = g[j] * sigmoidf_(g[j]) * v[j]; }
;                     *(u32x4*)(act + (size_t)row * ZW + u.pn * 128 + cl) = pack8(o[0], o[1]); MEMFENCE; }
;     ...
;         E.template run<cs.kind>(acc, cur, tid);
;         if (!has_next) break;
;         if (!(cs.kind == K_MG_B && cur.aux < 2))
	v_pk_mul_f32 v[54:55], v[54:55], v[250:251] op_sel_hi:[1,0]
	v_pk_mul_f32 v[50:51], v[50:51], v[250:251] op_sel_hi:[1,0]
	v_pk_mul_f32 v[218:219], v[54:55], s[2:3] op_sel_hi:[1,0]
	v_pk_mul_f32 v[44:45], v[44:45], v[250:251] op_sel_hi:[1,0]
	v_pk_mul_f32 v[40:41], v[40:41], v[250:251] op_sel_hi:[1,0]
	v_pk_mul_f32 v[220:221], v[44:45], s[2:3] op_sel_hi:[1,0]
	v_pk_mul_f32 v[46:47], v[46:47], v[250:251] op_sel_hi:[1,0]
	v_pk_mul_f32 v[42:43], v[42:43], v[250:251] op_sel_hi:[1,0]
	v_pk_mul_f32 v[222:223], v[46:47], s[2:3] op_sel_hi:[1,0]
	v_exp_f32_e32 v216, v216
	v_exp_f32_e32 v217, v217
	v_exp_f32_e32 v218, v218
	v_exp_f32_e32 v219, v219
	v_exp_f32_e32 v220, v220
	v_exp_f32_e32 v221, v221
	v_exp_f32_e32 v222, v222
	v_exp_f32_e32 v223, v223
	v_pk_add_f32 v[216:217], v[216:217], s[100:101] op_sel_hi:[1,0]
	v_pk_add_f32 v[218:219], v[218:219], s[100:101] op_sel_hi:[1,0]
	v_pk_add_f32 v[220:221], v[220:221], s[100:101] op_sel_hi:[1,0]
	v_pk_add_f32 v[222:223], v[222:223], s[100:101] op_sel_hi:[1,0]
	v_rcp_f32_e32 v216, v216
	v_rcp_f32_e32 v217, v217
	v_rcp_f32_e32 v218, v218
	v_rcp_f32_e32 v219, v219
	v_rcp_f32_e32 v220, v220
	v_rcp_f32_e32 v221, v221
	v_rcp_f32_e32 v222, v222
	v_rcp_f32_e32 v223, v223
	v_pk_mul_f32 v[52:53], v[52:53], v[216:217]
	v_pk_mul_f32 v[54:55], v[54:55], v[218:219]
	v_pk_mul_f32 v[44:45], v[44:45], v[220:221]
	v_pk_mul_f32 v[46:47], v[46:47], v[222:223]
	v_pk_mul_f32 v[52:53], v[52:53], v[48:49]
	v_pk_mul_f32 v[54:55], v[54:55], v[50:51]
	v_pk_mul_f32 v[44:45], v[44:45], v[40:41]
	v_pk_mul_f32 v[46:47], v[46:47], v[42:43]
	v_cvt_pk_bf16_f32 v236, v52, v53
	v_cvt_pk_bf16_f32 v237, v54, v55
	v_cvt_pk_bf16_f32 v238, v44, v45
	v_cvt_pk_bf16_f32 v239, v46, v47
	global_store_dwordx4 v140, v[236:239], s[4:5]
	s_add_u32 s4, s4, 0x16000
	s_addc_u32 s5, s5, 0
	v_pk_mul_f32 v[36:37], v[36:37], v[252:253] op_sel_hi:[1,0]
	v_pk_mul_f32 v[32:33], v[32:33], v[252:253] op_sel_hi:[1,0]
	v_pk_mul_f32 v[216:217], v[36:37], s[2:3] op_sel_hi:[1,0]
	v_pk_mul_f32 v[38:39], v[38:39], v[252:253] op_sel_hi:[1,0]
	v_pk_mul_f32 v[34:35], v[34:35], v[252:253] op_sel_hi:[1,0]
	v_pk_mul_f32 v[218:219], v[38:39], s[2:3] op_sel_hi:[1,0]
	v_pk_mul_f32 v[28:29], v[28:29], v[252:253] op_sel_hi:[1,0]
	v_pk_mul_f32 v[24:25], v[24:25], v[252:253] op_sel_hi:[1,0]
	v_pk_mul_f32 v[220:221], v[28:29], s[2:3] op_sel_hi:[1,0]
	v_pk_mul_f32 v[30:31], v[30:31], v[252:253] op_sel_hi:[1,0]
	v_pk_mul_f32 v[26:27], v[26:27], v[252:253] op_sel_hi:[1,0]
	v_pk_mul_f32 v[222:223], v[30:31], s[2:3] op_sel_hi:[1,0]
	v_exp_f32_e32 v216, v216
	v_exp_f32_e32 v217, v217
	v_exp_f32_e32 v218, v218
	v_exp_f32_e32 v219, v219
	v_exp_f32_e32 v220, v220
	v_exp_f32_e32 v221, v221
	v_exp_f32_e32 v222, v222
	v_exp_f32_e32 v223, v223
	v_pk_add_f32 v[216:217], v[216:217], s[100:101] op_sel_hi:[1,0]
	v_pk_add_f32 v[218:219], v[218:219], s[100:101] op_sel_hi:[1,0]
	v_pk_add_f32 v[220:221], v[220:221], s[100:101] op_sel_hi:[1,0]
	v_pk_add_f32 v[222:223], v[222:223], s[100:101] op_sel_hi:[1,0]
	v_rcp_f32_e32 v216, v216
	v_rcp_f32_e32 v217, v217
	v_rcp_f32_e32 v218, v218
	v_rcp_f32_e32 v219, v219
	v_rcp_f32_e32 v220, v220
	v_rcp_f32_e32 v221, v221
	v_rcp_f32_e32 v222, v222
	v_rcp_f32_e32 v223, v223
	v_pk_mul_f32 v[36:37], v[36:37], v[216:217]
	v_pk_mul_f32 v[38:39], v[38:39], v[218:219]
	v_pk_mul_f32 v[28:29], v[28:29], v[220:221]
	v_pk_mul_f32 v[30:31], v[30:31], v[222:223]
	v_pk_mul_f32 v[36:37], v[36:37], v[32:33]
	v_pk_mul_f32 v[38:39], v[38:39], v[34:35]
	v_pk_mul_f32 v[28:29], v[28:29], v[24:25]
	v_pk_mul_f32 v[30:31], v[30:31], v[26:27]
	v_cvt_pk_bf16_f32 v236, v36, v37
	v_cvt_pk_bf16_f32 v237, v38, v39
	v_cvt_pk_bf16_f32 v238, v28, v29
	v_cvt_pk_bf16_f32 v239, v30, v31
	global_store_dwordx4 v140, v[236:239], s[4:5]
	s_add_u32 s4, s4, 0x16000
	s_addc_u32 s5, s5, 0
	v_pk_mul_f32 v[20:21], v[20:21], v[254:255] op_sel_hi:[1,0]
	v_pk_mul_f32 v[16:17], v[16:17], v[254:255] op_sel_hi:[1,0]
	v_pk_mul_f32 v[216:217], v[20:21], s[2:3] op_sel_hi:[1,0]
	v_pk_mul_f32 v[22:23], v[22:23], v[254:255] op_sel_hi:[1,0]
	v_pk_mul_f32 v[18:19], v[18:19], v[254:255] op_sel_hi:[1,0]
	v_pk_mul_f32 v[218:219], v[22:23], s[2:3] op_sel_hi:[1,0]
	v_pk_mul_f32 v[12:13], v[12:13], v[254:255] op_sel_hi:[1,0]
	v_pk_mul_f32 v[8:9], v[8:9], v[254:255] op_sel_hi:[1,0]
	v_pk_mul_f32 v[220:221], v[12:13], s[2:3] op_sel_hi:[1,0]
	v_pk_mul_f32 v[14:15], v[14:15], v[254:255] op_sel_hi:[1,0]
	v_pk_mul_f32 v[10:11], v[10:11], v[254:255] op_sel_hi:[1,0]
	v_pk_mul_f32 v[222:223], v[14:15], s[2:3] op_sel_hi:[1,0]
	v_exp_f32_e32 v216, v216
	v_exp_f32_e32 v217, v217
	v_exp_f32_e32 v218, v218
	v_exp_f32_e32 v219, v219
	v_exp_f32_e32 v220, v220
	v_exp_f32_e32 v221, v221
	v_exp_f32_e32 v222, v222
	v_exp_f32_e32 v223, v223
	v_pk_add_f32 v[216:217], v[216:217], s[100:101] op_sel_hi:[1,0]
	v_pk_add_f32 v[218:219], v[218:219], s[100:101] op_sel_hi:[1,0]
	v_pk_add_f32 v[220:221], v[220:221], s[100:101] op_sel_hi:[1,0]
	v_pk_add_f32 v[222:223], v[222:223], s[100:101] op_sel_hi:[1,0]
	v_rcp_f32_e32 v216, v216
	v_rcp_f32_e32 v217, v217
	v_rcp_f32_e32 v218, v218
	v_rcp_f32_e32 v219, v219
	v_rcp_f32_e32 v220, v220
	v_rcp_f32_e32 v221, v221
	v_rcp_f32_e32 v222, v222
	v_rcp_f32_e32 v223, v223
	v_pk_mul_f32 v[20:21], v[20:21], v[216:217]
	v_pk_mul_f32 v[22:23], v[22:23], v[218:219]
	v_pk_mul_f32 v[12:13], v[12:13], v[220:221]
	v_pk_mul_f32 v[14:15], v[14:15], v[222:223]
	v_pk_mul_f32 v[20:21], v[20:21], v[16:17]
	v_pk_mul_f32 v[22:23], v[22:23], v[18:19]
	v_pk_mul_f32 v[12:13], v[12:13], v[8:9]
	v_pk_mul_f32 v[14:15], v[14:15], v[10:11]
	v_cvt_pk_bf16_f32 v236, v20, v21
	v_cvt_pk_bf16_f32 v237, v22, v23
	v_cvt_pk_bf16_f32 v238, v12, v13
	v_cvt_pk_bf16_f32 v239, v14, v15
	global_store_dwordx4 v140, v[236:239], s[4:5]
	s_mov_b32 s38, s11
	s_mov_b32 s37, s10
	s_mov_b64 s[18:19], s[14:15]
	s_mov_b64 s[16:17], s[12:13]
	s_mov_b32 s33, s36
	s_and_b64 vcc, exec, s[8:9]
	s_cbranch_vccz .LBB0_1115
	s_cmpk_gt_u32 s101, 0xff
	s_cbranch_scc0 .Ldbj_FFI_pe
	s_barrier
	s_mov_b32 s101, 0

; #define G_STAGE(bufoff, gbase, o0, h64) do { \
;         __builtin_amdgcn_global_load_lds((const unsigned*)((const char*)(gbase) + (o0)), (LAS unsigned*)(lds + (bufoff) + ldsw), 16, 0, 0); \
;         __builtin_amdgcn_global_load_lds((const unsigned*)((const char*)(gbase) + (h64) + (o0)), (LAS unsigned*)(lds + (bufoff) + ldsw + 8192), 16, 0, 0); } while (0)
; #define G_LDA(dst, b, h) do { _Pragma("unroll") for (int m = 0; m < 4; ++m) _Pragma("unroll") for (int k = 0; k < 2; ++k) dst[m][k] = *(const LAS bf16x8*)(lds + G_SA(b, h) + aoff + m * 2048 + k * 1024); } while (0)
; #define G_LDB(dst, b, h) do { _Pragma("unroll") for (int n = 0; n < 2; ++n) _Pragma("unroll") for (int k = 0; k < 2; ++k) dst[n][k] = *(const LAS bf16x8*)(lds + G_SB(b, h) + boff + n * 2048 + k * 1024); } while (0)
; #define G_WAIT_L(n) asm volatile("s_waitcnt lgkmcnt(" #n ")" ::: "memory")
; #define G_BAR __builtin_amdgcn_s_barrier()
; #define G_SCHED __builtin_amdgcn_sched_barrier(0)
;     ...
;         for (int t = 0; t < nt; t += 2) {
;             const bool last = (t == nt - 2);
;             const char* a1 = cA + (size_t)(t + 1) * ckA;
;             const char* a2 = last ? nA : cA + (size_t)(t + 2) * ckA; const char* b2 = last ? nB : cB + (size_t)(t + 2) * kB;
;             const char* a3 = a2 + ckA; const char* b3 = b2 + kB;
;             G_LDB(B0, 0, 0); G_SCHED; G_LDA(At, 0, 0); G_STAGE(G_SA(1, 1), a1 + chA, cA0, qA);
;             G_WAIT_L(8); G_BAR; G_WAIT_L(0); G_MMA(0, 0, At, B0); G_BAR; G_SCHED;
;             G_LDB(B1, 0, 1); G_STAGE(G_SB(0, 0), b2, cB0, qB);
;             G_BAR; G_WAIT_L(0); G_MMA(0, 1, At, B1); G_BAR;
;     ...
;         if (!(cs.kind == K_MG_B && cur.aux < 2))
; #pragma unroll
;         for (int a = 0; a < 2; ++a)
; #pragma unroll
;             for (int b = 0; b < 2; ++b)
; #pragma unroll
;                 for (int m = 0; m < 4; ++m)
; #pragma unroll
;                     for (int n = 0; n < 2; ++n) acc[a][b][m][n] = (f32x4){0.f, 0.f, 0.f, 0.f};
;         cur = nxt; cA = nA; cB = nB; ++ui;
.LBB0_1184:
	s_add_u32 s2, s2, 0xb0080
	s_addc_u32 s3, s3, 0
	s_add_u32 s6, s6, 0x100
	s_waitcnt lgkmcnt(0)
	v_mov_b64_e32 v[8:9], 0
	s_addc_u32 s7, s7, 0
	s_mov_b32 s21, -2
	v_mov_b64_e32 v[10:11], 0
	v_mov_b64_e32 v[12:13], 0
	v_mov_b64_e32 v[14:15], 0
	v_mov_b64_e32 v[24:25], 0
	v_mov_b64_e32 v[26:27], 0
	v_mov_b64_e32 v[28:29], 0
	v_mov_b64_e32 v[30:31], 0
	v_mov_b64_e32 v[40:41], 0
	v_mov_b64_e32 v[42:43], 0
	v_mov_b64_e32 v[44:45], 0
	v_mov_b64_e32 v[46:47], 0
	v_mov_b64_e32 v[56:57], 0
	v_mov_b64_e32 v[58:59], 0
	v_mov_b64_e32 v[60:61], 0
	v_mov_b64_e32 v[62:63], 0
	v_mov_b64_e32 v[16:17], 0
	v_mov_b64_e32 v[18:19], 0
	v_mov_b64_e32 v[20:21], 0
	v_mov_b64_e32 v[22:23], 0
	v_mov_b64_e32 v[32:33], 0
	v_mov_b64_e32 v[34:35], 0
	v_mov_b64_e32 v[36:37], 0
	v_mov_b64_e32 v[38:39], 0
	v_mov_b64_e32 v[48:49], 0
	v_mov_b64_e32 v[50:51], 0
	v_mov_b64_e32 v[52:53], 0
	v_mov_b64_e32 v[54:55], 0
	v_mov_b64_e32 v[64:65], 0
	v_mov_b64_e32 v[66:67], 0
	v_mov_b64_e32 v[68:69], 0
	v_mov_b64_e32 v[70:71], 0
	v_mov_b64_e32 v[72:73], 0
	v_mov_b64_e32 v[74:75], 0
	v_mov_b64_e32 v[76:77], 0
	v_mov_b64_e32 v[78:79], 0
	v_mov_b64_e32 v[88:89], 0
	v_mov_b64_e32 v[90:91], 0
	v_mov_b64_e32 v[92:93], 0
	v_mov_b64_e32 v[94:95], 0
	v_mov_b64_e32 v[104:105], 0
	v_mov_b64_e32 v[106:107], 0
	v_mov_b64_e32 v[108:109], 0
	v_mov_b64_e32 v[110:111], 0
	v_mov_b64_e32 v[120:121], 0
	v_mov_b64_e32 v[122:123], 0
	v_mov_b64_e32 v[124:125], 0
	v_mov_b64_e32 v[126:127], 0
	v_mov_b64_e32 v[80:81], 0
	v_mov_b64_e32 v[82:83], 0
	v_mov_b64_e32 v[84:85], 0
	v_mov_b64_e32 v[86:87], 0
	v_mov_b64_e32 v[96:97], 0
	v_mov_b64_e32 v[98:99], 0
	v_mov_b64_e32 v[100:101], 0
	v_mov_b64_e32 v[102:103], 0
	v_mov_b64_e32 v[112:113], 0
	v_mov_b64_e32 v[114:115], 0
	v_mov_b64_e32 v[116:117], 0
	v_mov_b64_e32 v[118:119], 0
	v_mov_b64_e32 v[128:129], 0
	v_mov_b64_e32 v[130:131], 0
	v_mov_b64_e32 v[132:133], 0
	v_mov_b64_e32 v[134:135], 0
	s_mov_b64 s[52:53], 0xb0080
	s_mov_b64 s[54:55], 0x108080
	s_cmpk_gt_u32 s101, 0xff
	s_cbranch_scc0 .Ldbj_FFO_in
	s_barrier
	s_mov_b32 s101, 0
.Ldbj_FFO_in:
.LBB0_1185:
	s_add_u32 s4, s2, 0xfff50080
	s_addc_u32 s5, s3, -1
	s_add_i32 s33, 0, 0x10000
	v_add_u32_e32 v0, s33, v185
	ds_read_b128 v[136:139], v0
	ds_read_b128 v[140:143], v0 offset:1024
	ds_read_b128 v[144:147], v0 offset:2048
	ds_read_b128 v[148:151], v0 offset:3072
	s_cmp_eq_u32 s21, 40
	s_cselect_b32 s5, s17, s5
	s_cselect_b32 s4, s16, s4
	s_cselect_b32 s23, s19, s7
	s_cselect_b32 s22, s18, s6
	v_lshl_add_u64 v[204:205], s[2:3], 0, v[174:175]
	s_add_i32 m0, s26, 0xc000
	ds_read_b128 v[152:155], v195
	ds_read_b128 v[156:159], v195 offset:1024
	ds_read_b128 v[160:163], v195 offset:2048
	ds_read_b128 v[164:167], v195 offset:3072
	ds_read_b128 v[176:179], v195 offset:4096
	ds_read_b128 v[180:183], v195 offset:5120
	ds_read_b128 v[196:199], v195 offset:6144
	ds_read_b128 v[200:203], v195 offset:7168
	global_load_lds_dwordx4 v[204:205], off
	v_lshl_add_u64 v[204:205], v[204:205], 0, s[86:87]
	s_add_i32 m0, s26, 0xe000
	s_nop 0
	global_load_lds_dwordx4 v[204:205], off
	s_waitcnt lgkmcnt(8)
	s_barrier
	s_waitcnt lgkmcnt(0)
	s_setprio 3
	s_waitcnt lgkmcnt(0)
	v_mfma_f32_16x16x32_bf16 v[132:135], v[136:139], v[152:155], v[132:135]
	v_mfma_f32_16x16x32_bf16 v[128:131], v[144:147], v[152:155], v[128:131]
	v_mfma_f32_16x16x32_bf16 v[116:119], v[136:139], v[160:163], v[116:119]
	v_mfma_f32_16x16x32_bf16 v[112:115], v[144:147], v[160:163], v[112:115]
	v_mfma_f32_16x16x32_bf16 v[100:103], v[136:139], v[176:179], v[100:103]
	v_mfma_f32_16x16x32_bf16 v[96:99], v[144:147], v[176:179], v[96:99]
	v_mfma_f32_16x16x32_bf16 v[84:87], v[136:139], v[196:199], v[84:87]
	v_mfma_f32_16x16x32_bf16 v[80:83], v[144:147], v[196:199], v[80:83]
	v_mfma_f32_16x16x32_bf16 v[132:135], v[140:143], v[156:159], v[132:135]
	v_mfma_f32_16x16x32_bf16 v[128:131], v[148:151], v[156:159], v[128:131]
	v_mfma_f32_16x16x32_bf16 v[116:119], v[140:143], v[164:167], v[116:119]
	v_mfma_f32_16x16x32_bf16 v[112:115], v[148:151], v[164:167], v[112:115]
	v_mfma_f32_16x16x32_bf16 v[100:103], v[140:143], v[180:183], v[100:103]
	v_mfma_f32_16x16x32_bf16 v[96:99], v[148:151], v[180:183], v[96:99]
	v_mfma_f32_16x16x32_bf16 v[84:87], v[140:143], v[200:203], v[84:87]
	v_mfma_f32_16x16x32_bf16 v[80:83], v[148:151], v[200:203], v[80:83]
	s_setprio 0
	s_barrier
	s_add_i32 s44, 0, 0x14000
	v_lshl_add_u64 v[220:221], s[22:23], 0, v[172:173]
	s_add_i32 s22, s33, s25
	v_add_u32_e32 v0, s44, v185
	s_mov_b32 m0, s22
	ds_read_b128 v[204:207], v0
	ds_read_b128 v[208:211], v0 offset:1024
	ds_read_b128 v[212:215], v0 offset:2048
	ds_read_b128 v[216:219], v0 offset:3072
	global_load_lds_dwordx4 v[220:221], off
	v_lshl_add_u64 v[222:223], v[220:221], 0, s[86:87]
	s_add_i32 m0, s22, 0x2000
	s_nop 0
	global_load_lds_dwordx4 v[222:223], off
	s_barrier
	s_waitcnt lgkmcnt(0)
	s_setprio 3
	s_waitcnt lgkmcnt(0)
	v_mfma_f32_16x16x32_bf16 v[124:127], v[204:207], v[152:155], v[124:127]
	v_mfma_f32_16x16x32_bf16 v[120:123], v[212:215], v[152:155], v[120:123]
	v_mfma_f32_16x16x32_bf16 v[108:111], v[204:207], v[160:163], v[108:111]
	v_mfma_f32_16x16x32_bf16 v[104:107], v[212:215], v[160:163], v[104:107]
	v_mfma_f32_16x16x32_bf16 v[92:95], v[204:207], v[176:179], v[92:95]
	v_mfma_f32_16x16x32_bf16 v[88:91], v[212:215], v[176:179], v[88:91]
	v_mfma_f32_16x16x32_bf16 v[76:79], v[204:207], v[196:199], v[76:79]
	v_mfma_f32_16x16x32_bf16 v[72:75], v[212:215], v[196:199], v[72:75]
	v_mfma_f32_16x16x32_bf16 v[124:127], v[208:211], v[156:159], v[124:127]
	v_mfma_f32_16x16x32_bf16 v[120:123], v[216:219], v[156:159], v[120:123]
	v_mfma_f32_16x16x32_bf16 v[108:111], v[208:211], v[164:167], v[108:111]
	v_mfma_f32_16x16x32_bf16 v[104:107], v[216:219], v[164:167], v[104:107]
	v_mfma_f32_16x16x32_bf16 v[92:95], v[208:211], v[180:183], v[92:95]
	v_mfma_f32_16x16x32_bf16 v[88:91], v[216:219], v[180:183], v[88:91]
	v_mfma_f32_16x16x32_bf16 v[76:79], v[208:211], v[200:203], v[76:79]
	v_mfma_f32_16x16x32_bf16 v[72:75], v[216:219], v[200:203], v[72:75]
	s_setprio 0
	s_mov_b32 m0, s26
	v_lshl_add_u64 v[222:223], s[4:5], 0, v[2:3]
	s_barrier
; #define G_STAGE(bufoff, gbase, o0, h64) do { \
;         __builtin_amdgcn_global_load_lds((const unsigned*)((const char*)(gbase) + (o0)), (LAS unsigned*)(lds + (bufoff) + ldsw), 16, 0, 0); \
;         __builtin_amdgcn_global_load_lds((const unsigned*)((const char*)(gbase) + (h64) + (o0)), (LAS unsigned*)(lds + (bufoff) + ldsw + 8192), 16, 0, 0); } while (0)
; #define G_LDA(dst, b, h) do { _Pragma("unroll") for (int m = 0; m < 4; ++m) _Pragma("unroll") for (int k = 0; k < 2; ++k) dst[m][k] = *(const LAS bf16x8*)(lds + G_SA(b, h) + aoff + m * 2048 + k * 1024); } while (0)
; #define G_LDB(dst, b, h) do { _Pragma("unroll") for (int n = 0; n < 2; ++n) _Pragma("unroll") for (int k = 0; k < 2; ++k) dst[n][k] = *(const LAS bf16x8*)(lds + G_SB(b, h) + boff + n * 2048 + k * 1024); } while (0)
; #define G_WAIT_V(n) asm volatile("s_waitcnt vmcnt(" #n ")" ::: "memory")
; #define G_WAIT_L(n) asm volatile("s_waitcnt lgkmcnt(" #n ")" ::: "memory")
; #define G_BAR __builtin_amdgcn_s_barrier()
; #define G_SCHED __builtin_amdgcn_sched_barrier(0)
;     ...
;             G_BAR; G_WAIT_L(0); G_MMA(0, 1, At, B1); G_BAR;
;             G_LDA(At, 0, 1); G_STAGE(G_SA(0, 0), a2, cA0, qA);
;             G_BAR; G_WAIT_L(0); G_MMA(1, 0, At, B0); G_BAR; G_SCHED;
;             G_STAGE(G_SB(0, 1), b2 + chB, cB0, qB);
;             G_WAIT_V(6); G_BAR; G_MMA(1, 1, At, B1); G_BAR;
;             G_LDB(B0, 1, 0); G_SCHED; G_LDA(At, 1, 0); G_STAGE(G_SA(0, 1), a2 + chA, cA0, qA);
;             G_WAIT_L(8); G_BAR; G_WAIT_L(0); G_MMA(0, 0, At, B0); G_BAR; G_SCHED;
;             G_LDB(B1, 1, 1); G_STAGE(G_SB(1, 0), b3, cB0, qB);
;             G_BAR; G_WAIT_L(0); G_MMA(0, 1, At, B1); G_BAR;
;             G_LDA(At, 1, 1); G_STAGE(G_SA(1, 0), a3, cA0, qA);
;             G_BAR; G_WAIT_L(0); G_MMA(1, 0, At, B0); G_BAR; G_SCHED;
	ds_read_b128 v[152:155], v195 offset:16384
	ds_read_b128 v[156:159], v195 offset:17408
	ds_read_b128 v[160:163], v195 offset:18432
	ds_read_b128 v[164:167], v195 offset:19456
	ds_read_b128 v[176:179], v195 offset:20480
	ds_read_b128 v[180:183], v195 offset:21504
	ds_read_b128 v[196:199], v195 offset:22528
	ds_read_b128 v[200:203], v195 offset:23552
	global_load_lds_dwordx4 v[222:223], off
	v_lshl_add_u64 v[224:225], v[222:223], 0, s[86:87]
	s_mov_b32 m0, s27
	s_nop 0
	global_load_lds_dwordx4 v[224:225], off
	s_barrier
	s_waitcnt lgkmcnt(0)
	s_setprio 3
	s_waitcnt lgkmcnt(0)
	v_mfma_f32_16x16x32_bf16 v[68:71], v[136:139], v[152:155], v[68:71]
	v_mfma_f32_16x16x32_bf16 v[64:67], v[144:147], v[152:155], v[64:67]
	v_mfma_f32_16x16x32_bf16 v[52:55], v[136:139], v[160:163], v[52:55]
	v_mfma_f32_16x16x32_bf16 v[48:51], v[144:147], v[160:163], v[48:51]
	v_mfma_f32_16x16x32_bf16 v[36:39], v[136:139], v[176:179], v[36:39]
	v_mfma_f32_16x16x32_bf16 v[32:35], v[144:147], v[176:179], v[32:35]
	v_mfma_f32_16x16x32_bf16 v[20:23], v[136:139], v[196:199], v[20:23]
	v_mfma_f32_16x16x32_bf16 v[16:19], v[144:147], v[196:199], v[16:19]
	v_mfma_f32_16x16x32_bf16 v[68:71], v[140:143], v[156:159], v[68:71]
	v_mfma_f32_16x16x32_bf16 v[64:67], v[148:151], v[156:159], v[64:67]
	v_mfma_f32_16x16x32_bf16 v[52:55], v[140:143], v[164:167], v[52:55]
	v_mfma_f32_16x16x32_bf16 v[48:51], v[148:151], v[164:167], v[48:51]
	v_mfma_f32_16x16x32_bf16 v[36:39], v[140:143], v[180:183], v[36:39]
	v_mfma_f32_16x16x32_bf16 v[32:35], v[148:151], v[180:183], v[32:35]
	v_mfma_f32_16x16x32_bf16 v[20:23], v[140:143], v[200:203], v[20:23]
	v_mfma_f32_16x16x32_bf16 v[16:19], v[148:151], v[200:203], v[16:19]
	s_setprio 0
	s_barrier
	s_add_i32 s4, s44, s25
	v_lshl_add_u64 v[136:137], v[220:221], 0, s[88:89]
	s_mov_b32 m0, s4
	s_nop 0
	global_load_lds_dwordx4 v[136:137], off
	v_lshl_add_u64 v[136:137], v[220:221], 0, s[64:65]
	s_add_i32 m0, s4, 0x2000
	s_nop 0
	global_load_lds_dwordx4 v[136:137], off
	s_waitcnt vmcnt(6)
	s_barrier
	s_setprio 3
	v_mfma_f32_16x16x32_bf16 v[60:63], v[204:207], v[152:155], v[60:63]
	v_mfma_f32_16x16x32_bf16 v[56:59], v[212:215], v[152:155], v[56:59]
	v_mfma_f32_16x16x32_bf16 v[44:47], v[204:207], v[160:163], v[44:47]
	v_mfma_f32_16x16x32_bf16 v[40:43], v[212:215], v[160:163], v[40:43]
	v_mfma_f32_16x16x32_bf16 v[28:31], v[204:207], v[176:179], v[28:31]
	v_mfma_f32_16x16x32_bf16 v[24:27], v[212:215], v[176:179], v[24:27]
	v_mfma_f32_16x16x32_bf16 v[12:15], v[204:207], v[196:199], v[12:15]
	v_mfma_f32_16x16x32_bf16 v[8:11], v[212:215], v[196:199], v[8:11]
	v_mfma_f32_16x16x32_bf16 v[60:63], v[208:211], v[156:159], v[60:63]
	v_mfma_f32_16x16x32_bf16 v[56:59], v[216:219], v[156:159], v[56:59]
	v_mfma_f32_16x16x32_bf16 v[44:47], v[208:211], v[164:167], v[44:47]
	v_mfma_f32_16x16x32_bf16 v[40:43], v[216:219], v[164:167], v[40:43]
	v_mfma_f32_16x16x32_bf16 v[28:31], v[208:211], v[180:183], v[28:31]
	v_mfma_f32_16x16x32_bf16 v[24:27], v[216:219], v[180:183], v[24:27]
	v_mfma_f32_16x16x32_bf16 v[12:15], v[208:211], v[200:203], v[12:15]
	v_mfma_f32_16x16x32_bf16 v[8:11], v[216:219], v[200:203], v[8:11]
	s_setprio 0
	s_add_i32 s4, 0, 0x18000
	v_add_u32_e32 v0, s4, v185
	s_barrier
	ds_read_b128 v[136:139], v0
	ds_read_b128 v[140:143], v0 offset:1024
	ds_read_b128 v[144:147], v0 offset:2048
	ds_read_b128 v[148:151], v0 offset:3072
	s_mov_b32 m0, s29
	v_lshl_add_u64 v[204:205], v[222:223], 0, s[88:89]
	ds_read_b128 v[152:155], v195 offset:32768
	ds_read_b128 v[156:159], v195 offset:33792
	ds_read_b128 v[160:163], v195 offset:34816
	ds_read_b128 v[164:167], v195 offset:35840
	ds_read_b128 v[176:179], v195 offset:36864
	ds_read_b128 v[180:183], v195 offset:37888
	ds_read_b128 v[196:199], v195 offset:38912
	ds_read_b128 v[200:203], v195 offset:39936
	global_load_lds_dwordx4 v[204:205], off
	v_lshl_add_u64 v[204:205], v[222:223], 0, s[64:65]
	s_mov_b32 m0, s30
	s_nop 0
	global_load_lds_dwordx4 v[204:205], off
	s_waitcnt lgkmcnt(8)
	s_barrier
	s_waitcnt lgkmcnt(0)
	s_setprio 3
	s_waitcnt lgkmcnt(0)
	v_mfma_f32_16x16x32_bf16 v[132:135], v[136:139], v[152:155], v[132:135]
	v_mfma_f32_16x16x32_bf16 v[128:131], v[144:147], v[152:155], v[128:131]
	v_mfma_f32_16x16x32_bf16 v[116:119], v[136:139], v[160:163], v[116:119]
	v_mfma_f32_16x16x32_bf16 v[112:115], v[144:147], v[160:163], v[112:115]
	v_mfma_f32_16x16x32_bf16 v[100:103], v[136:139], v[176:179], v[100:103]
	v_mfma_f32_16x16x32_bf16 v[96:99], v[144:147], v[176:179], v[96:99]
	v_mfma_f32_16x16x32_bf16 v[84:87], v[136:139], v[196:199], v[84:87]
	v_mfma_f32_16x16x32_bf16 v[80:83], v[144:147], v[196:199], v[80:83]
	v_mfma_f32_16x16x32_bf16 v[132:135], v[140:143], v[156:159], v[132:135]
	v_mfma_f32_16x16x32_bf16 v[128:131], v[148:151], v[156:159], v[128:131]
	v_mfma_f32_16x16x32_bf16 v[116:119], v[140:143], v[164:167], v[116:119]
	v_mfma_f32_16x16x32_bf16 v[112:115], v[148:151], v[164:167], v[112:115]
	v_mfma_f32_16x16x32_bf16 v[100:103], v[140:143], v[180:183], v[100:103]
	v_mfma_f32_16x16x32_bf16 v[96:99], v[148:151], v[180:183], v[96:99]
	v_mfma_f32_16x16x32_bf16 v[84:87], v[140:143], v[200:203], v[84:87]
	v_mfma_f32_16x16x32_bf16 v[80:83], v[148:151], v[200:203], v[80:83]
	s_setprio 0
	s_barrier
; #define G_STAGE(bufoff, gbase, o0, h64) do { \
;         __builtin_amdgcn_global_load_lds((const unsigned*)((const char*)(gbase) + (o0)), (LAS unsigned*)(lds + (bufoff) + ldsw), 16, 0, 0); \
;         __builtin_amdgcn_global_load_lds((const unsigned*)((const char*)(gbase) + (h64) + (o0)), (LAS unsigned*)(lds + (bufoff) + ldsw + 8192), 16, 0, 0); } while (0)
; #define G_LDA(dst, b, h) do { _Pragma("unroll") for (int m = 0; m < 4; ++m) _Pragma("unroll") for (int k = 0; k < 2; ++k) dst[m][k] = *(const LAS bf16x8*)(lds + G_SA(b, h) + aoff + m * 2048 + k * 1024); } while (0)
; #define G_LDB(dst, b, h) do { _Pragma("unroll") for (int n = 0; n < 2; ++n) _Pragma("unroll") for (int k = 0; k < 2; ++k) dst[n][k] = *(const LAS bf16x8*)(lds + G_SB(b, h) + boff + n * 2048 + k * 1024); } while (0)
; #define G_WAIT_V(n) asm volatile("s_waitcnt vmcnt(" #n ")" ::: "memory")
; #define G_WAIT_L(n) asm volatile("s_waitcnt lgkmcnt(" #n ")" ::: "memory")
; #define G_BAR __builtin_amdgcn_s_barrier()
; #define G_SCHED __builtin_amdgcn_sched_barrier(0)
;     ...
;             G_WAIT_L(8); G_BAR; G_WAIT_L(0); G_MMA(0, 0, At, B0); G_BAR; G_SCHED;
;             G_LDB(B1, 1, 1); G_STAGE(G_SB(1, 0), b3, cB0, qB);
;             G_BAR; G_WAIT_L(0); G_MMA(0, 1, At, B1); G_BAR;
;             G_LDA(At, 1, 1); G_STAGE(G_SA(1, 0), a3, cA0, qA);
;             G_BAR; G_WAIT_L(0); G_MMA(1, 0, At, B0); G_BAR; G_SCHED;
;             G_STAGE(G_SB(1, 1), b3 + chB, cB0, qB);
;             G_WAIT_V(6); G_BAR; G_MMA(1, 1, At, B1); G_BAR;
;         }
	s_add_i32 s5, 0, 0x1c000
	s_add_i32 s4, s4, s25
	v_add_u32_e32 v0, s5, v185
	v_lshl_add_u64 v[224:225], v[220:221], 0, s[46:47]
	s_mov_b32 m0, s4
	ds_read_b128 v[204:207], v0
	ds_read_b128 v[208:211], v0 offset:1024
	ds_read_b128 v[212:215], v0 offset:2048
	ds_read_b128 v[216:219], v0 offset:3072
	global_load_lds_dwordx4 v[224:225], off
	v_lshl_add_u64 v[224:225], v[220:221], 0, s[66:67]
	s_add_i32 m0, s4, 0x2000
	s_nop 0
	global_load_lds_dwordx4 v[224:225], off
	s_barrier
	s_waitcnt lgkmcnt(0)
	s_setprio 3
	s_waitcnt lgkmcnt(0)
	v_mfma_f32_16x16x32_bf16 v[124:127], v[204:207], v[152:155], v[124:127]
	v_mfma_f32_16x16x32_bf16 v[120:123], v[212:215], v[152:155], v[120:123]
	v_mfma_f32_16x16x32_bf16 v[108:111], v[204:207], v[160:163], v[108:111]
	v_mfma_f32_16x16x32_bf16 v[104:107], v[212:215], v[160:163], v[104:107]
	v_mfma_f32_16x16x32_bf16 v[92:95], v[204:207], v[176:179], v[92:95]
	v_mfma_f32_16x16x32_bf16 v[88:91], v[212:215], v[176:179], v[88:91]
	v_mfma_f32_16x16x32_bf16 v[76:79], v[204:207], v[196:199], v[76:79]
	v_mfma_f32_16x16x32_bf16 v[72:75], v[212:215], v[196:199], v[72:75]
	v_mfma_f32_16x16x32_bf16 v[124:127], v[208:211], v[156:159], v[124:127]
	v_mfma_f32_16x16x32_bf16 v[120:123], v[216:219], v[156:159], v[120:123]
	v_mfma_f32_16x16x32_bf16 v[108:111], v[208:211], v[164:167], v[108:111]
	v_mfma_f32_16x16x32_bf16 v[104:107], v[216:219], v[164:167], v[104:107]
	v_mfma_f32_16x16x32_bf16 v[92:95], v[208:211], v[180:183], v[92:95]
	v_mfma_f32_16x16x32_bf16 v[88:91], v[216:219], v[180:183], v[88:91]
	v_mfma_f32_16x16x32_bf16 v[76:79], v[208:211], v[200:203], v[76:79]
	v_mfma_f32_16x16x32_bf16 v[72:75], v[216:219], v[200:203], v[72:75]
	s_setprio 0
	s_mov_b32 m0, s31
	v_lshl_add_u64 v[224:225], v[222:223], 0, s[46:47]
	s_barrier
	ds_read_b128 v[152:155], v195 offset:49152
	ds_read_b128 v[156:159], v195 offset:50176
	ds_read_b128 v[160:163], v195 offset:51200
	ds_read_b128 v[164:167], v195 offset:52224
	ds_read_b128 v[176:179], v195 offset:53248
	ds_read_b128 v[180:183], v195 offset:54272
	ds_read_b128 v[196:199], v195 offset:55296
	ds_read_b128 v[200:203], v195 offset:56320
	global_load_lds_dwordx4 v[224:225], off
	v_lshl_add_u64 v[222:223], v[222:223], 0, s[66:67]
	s_mov_b32 m0, s34
	s_nop 0
	global_load_lds_dwordx4 v[222:223], off
	s_barrier
	s_waitcnt lgkmcnt(0)
	s_setprio 3
	s_waitcnt lgkmcnt(0)
	v_mfma_f32_16x16x32_bf16 v[68:71], v[136:139], v[152:155], v[68:71]
	v_mfma_f32_16x16x32_bf16 v[64:67], v[144:147], v[152:155], v[64:67]
	v_mfma_f32_16x16x32_bf16 v[52:55], v[136:139], v[160:163], v[52:55]
	v_mfma_f32_16x16x32_bf16 v[48:51], v[144:147], v[160:163], v[48:51]
	v_mfma_f32_16x16x32_bf16 v[36:39], v[136:139], v[176:179], v[36:39]
	v_mfma_f32_16x16x32_bf16 v[32:35], v[144:147], v[176:179], v[32:35]
	v_mfma_f32_16x16x32_bf16 v[20:23], v[136:139], v[196:199], v[20:23]
	v_mfma_f32_16x16x32_bf16 v[16:19], v[144:147], v[196:199], v[16:19]
	v_mfma_f32_16x16x32_bf16 v[68:71], v[140:143], v[156:159], v[68:71]
	v_mfma_f32_16x16x32_bf16 v[64:67], v[148:151], v[156:159], v[64:67]
	v_mfma_f32_16x16x32_bf16 v[52:55], v[140:143], v[164:167], v[52:55]
	v_mfma_f32_16x16x32_bf16 v[48:51], v[148:151], v[164:167], v[48:51]
	v_mfma_f32_16x16x32_bf16 v[36:39], v[140:143], v[180:183], v[36:39]
	v_mfma_f32_16x16x32_bf16 v[32:35], v[148:151], v[180:183], v[32:35]
	v_mfma_f32_16x16x32_bf16 v[20:23], v[140:143], v[200:203], v[20:23]
	v_mfma_f32_16x16x32_bf16 v[16:19], v[148:151], v[200:203], v[16:19]
	s_setprio 0
	s_barrier
	s_add_i32 s4, s5, s25
	v_lshl_add_u64 v[136:137], v[220:221], 0, s[52:53]
	s_mov_b32 m0, s4
	s_nop 0
	global_load_lds_dwordx4 v[136:137], off
	v_lshl_add_u64 v[136:137], v[220:221], 0, s[54:55]
	s_add_i32 m0, s4, 0x2000
	s_nop 0
	global_load_lds_dwordx4 v[136:137], off
	s_waitcnt vmcnt(6)
	s_barrier
	s_setprio 3
	v_mfma_f32_16x16x32_bf16 v[60:63], v[204:207], v[152:155], v[60:63]
	v_mfma_f32_16x16x32_bf16 v[56:59], v[212:215], v[152:155], v[56:59]
	v_mfma_f32_16x16x32_bf16 v[44:47], v[204:207], v[160:163], v[44:47]
	v_mfma_f32_16x16x32_bf16 v[40:43], v[212:215], v[160:163], v[40:43]
	v_mfma_f32_16x16x32_bf16 v[28:31], v[204:207], v[176:179], v[28:31]
	v_mfma_f32_16x16x32_bf16 v[24:27], v[212:215], v[176:179], v[24:27]
	v_mfma_f32_16x16x32_bf16 v[12:15], v[204:207], v[196:199], v[12:15]
	v_mfma_f32_16x16x32_bf16 v[8:11], v[212:215], v[196:199], v[8:11]
	v_mfma_f32_16x16x32_bf16 v[60:63], v[208:211], v[156:159], v[60:63]
	v_mfma_f32_16x16x32_bf16 v[56:59], v[216:219], v[156:159], v[56:59]
	v_mfma_f32_16x16x32_bf16 v[44:47], v[208:211], v[164:167], v[44:47]
	v_mfma_f32_16x16x32_bf16 v[40:43], v[216:219], v[164:167], v[40:43]
	v_mfma_f32_16x16x32_bf16 v[28:31], v[208:211], v[180:183], v[28:31]
	v_mfma_f32_16x16x32_bf16 v[24:27], v[216:219], v[180:183], v[24:27]
	v_mfma_f32_16x16x32_bf16 v[12:15], v[208:211], v[200:203], v[12:15]
	v_mfma_f32_16x16x32_bf16 v[8:11], v[216:219], v[200:203], v[8:11]
	s_setprio 0
	s_add_i32 s21, s21, 2
	s_add_u32 s2, s2, 0x100
	s_addc_u32 s3, s3, 0
	s_add_u32 s6, s6, 0x100
	s_addc_u32 s7, s7, 0
	s_cmp_gt_u32 s21, 41
	s_cbranch_scc0 .Ldb_FFO_cont
	v_readfirstlane_b32 s101, v186
	s_cmpk_gt_u32 s101, 0xff
	s_cbranch_scc1 .Ldb_FFO_exit
	s_barrier
	s_branch .Ldb_FFO_exit

; #define G_STAGE(bufoff, gbase, o0, h64) do { \
;         __builtin_amdgcn_global_load_lds((const unsigned*)((const char*)(gbase) + (o0)), (LAS unsigned*)(lds + (bufoff) + ldsw), 16, 0, 0); \
;         __builtin_amdgcn_global_load_lds((const unsigned*)((const char*)(gbase) + (h64) + (o0)), (LAS unsigned*)(lds + (bufoff) + ldsw + 8192), 16, 0, 0); } while (0)
; #define G_LDA(dst, b, h) do { _Pragma("unroll") for (int m = 0; m < 4; ++m) _Pragma("unroll") for (int k = 0; k < 2; ++k) dst[m][k] = *(const LAS bf16x8*)(lds + G_SA(b, h) + aoff + m * 2048 + k * 1024); } while (0)
; #define G_LDB(dst, b, h) do { _Pragma("unroll") for (int n = 0; n < 2; ++n) _Pragma("unroll") for (int k = 0; k < 2; ++k) dst[n][k] = *(const LAS bf16x8*)(lds + G_SB(b, h) + boff + n * 2048 + k * 1024); } while (0)
; #define G_WAIT_L(n) asm volatile("s_waitcnt lgkmcnt(" #n ")" ::: "memory")
; #define G_BAR __builtin_amdgcn_s_barrier()
; #define G_SCHED __builtin_amdgcn_sched_barrier(0)
;     ...
;         for (int t = 0; t < nt; t += 2) {
;             const bool last = (t == nt - 2);
;             const char* a1 = cA + (size_t)(t + 1) * ckA;
;             const char* a2 = last ? nA : cA + (size_t)(t + 2) * ckA; const char* b2 = last ? nB : cB + (size_t)(t + 2) * kB;
;             const char* a3 = a2 + ckA; const char* b3 = b2 + kB;
;             G_LDB(B0, 0, 0); G_SCHED; G_LDA(At, 0, 0); G_STAGE(G_SA(1, 1), a1 + chA, cA0, qA);
;             G_WAIT_L(8); G_BAR; G_WAIT_L(0); G_MMA(0, 0, At, B0); G_BAR; G_SCHED;
;             G_LDB(B1, 0, 1); G_STAGE(G_SB(0, 0), b2, cB0, qB);
;             G_BAR; G_WAIT_L(0); G_MMA(0, 1, At, B1); G_BAR;
;     ...
;         if (!(cs.kind == K_MG_B && cur.aux < 2))
; #pragma unroll
;         for (int a = 0; a < 2; ++a)
; #pragma unroll
;             for (int b = 0; b < 2; ++b)
; #pragma unroll
;                 for (int m = 0; m < 4; ++m)
; #pragma unroll
;                     for (int n = 0; n < 2; ++n) acc[a][b][m][n] = (f32x4){0.f, 0.f, 0.f, 0.f};
;         cur = nxt; cA = nA; cB = nB; ++ui;
.LBB0_1259:
	v_mov_b64_e32 v[8:9], 0
	s_mov_b64 s[18:19], 0
	s_mov_b64 s[14:15], -1
	s_mov_b64 s[16:17], 0
	v_mov_b64_e32 v[10:11], 0
	v_mov_b64_e32 v[12:13], 0
	v_mov_b64_e32 v[14:15], 0
	v_mov_b64_e32 v[16:17], 0
	v_mov_b64_e32 v[18:19], 0
	v_mov_b64_e32 v[24:25], 0
	v_mov_b64_e32 v[26:27], 0
	v_mov_b64_e32 v[32:33], 0
	v_mov_b64_e32 v[34:35], 0
	v_mov_b64_e32 v[40:41], 0
	v_mov_b64_e32 v[42:43], 0
	v_mov_b64_e32 v[48:49], 0
	v_mov_b64_e32 v[50:51], 0
	v_mov_b64_e32 v[56:57], 0
	v_mov_b64_e32 v[58:59], 0
	v_mov_b64_e32 v[20:21], 0
	v_mov_b64_e32 v[22:23], 0
	v_mov_b64_e32 v[28:29], 0
	v_mov_b64_e32 v[30:31], 0
	v_mov_b64_e32 v[36:37], 0
	v_mov_b64_e32 v[38:39], 0
	v_mov_b64_e32 v[44:45], 0
	v_mov_b64_e32 v[46:47], 0
	v_mov_b64_e32 v[52:53], 0
	v_mov_b64_e32 v[54:55], 0
	v_mov_b64_e32 v[60:61], 0
	v_mov_b64_e32 v[62:63], 0
	v_mov_b64_e32 v[64:65], 0
	v_mov_b64_e32 v[66:67], 0
	v_mov_b64_e32 v[68:69], 0
	v_mov_b64_e32 v[70:71], 0
	v_mov_b64_e32 v[72:73], 0
	v_mov_b64_e32 v[74:75], 0
	v_mov_b64_e32 v[76:77], 0
	v_mov_b64_e32 v[78:79], 0
	v_mov_b64_e32 v[80:81], 0
	v_mov_b64_e32 v[82:83], 0
	v_mov_b64_e32 v[88:89], 0
	v_mov_b64_e32 v[90:91], 0
	v_mov_b64_e32 v[96:97], 0
	v_mov_b64_e32 v[98:99], 0
	v_mov_b64_e32 v[104:105], 0
	v_mov_b64_e32 v[106:107], 0
	v_mov_b64_e32 v[112:113], 0
	v_mov_b64_e32 v[114:115], 0
	v_mov_b64_e32 v[120:121], 0
	v_mov_b64_e32 v[122:123], 0
	v_mov_b64_e32 v[84:85], 0
	v_mov_b64_e32 v[86:87], 0
	v_mov_b64_e32 v[92:93], 0
	v_mov_b64_e32 v[94:95], 0
	v_mov_b64_e32 v[100:101], 0
	v_mov_b64_e32 v[102:103], 0
	v_mov_b64_e32 v[108:109], 0
	v_mov_b64_e32 v[110:111], 0
	v_mov_b64_e32 v[116:117], 0
	v_mov_b64_e32 v[118:119], 0
	v_mov_b64_e32 v[124:125], 0
	v_mov_b64_e32 v[126:127], 0
	v_mov_b64_e32 v[128:129], 0
	v_mov_b64_e32 v[130:131], 0
	v_mov_b64_e32 v[132:133], 0
	v_mov_b64_e32 v[134:135], 0
	s_mov_b64 s[58:59], 0x10000
	s_cmpk_gt_u32 s101, 0xff
	s_cbranch_scc0 .Ldbj_PLE0_in
	s_barrier
	s_mov_b32 s101, 0
.Ldbj_PLE0_in:
.LBB0_1260:
	s_add_u32 s22, s10, s18
	s_addc_u32 s23, s11, s19
	s_add_u32 s20, s22, 0x100
	s_addc_u32 s21, s23, 0
	s_and_b64 s[4:5], s[16:17], exec
	s_cselect_b32 s20, s6, s20
	s_cselect_b32 s21, s7, s21
	s_add_u32 s4, s12, s18
	s_addc_u32 s5, s13, s19
	s_add_u32 s18, s4, 0x100
	s_addc_u32 s19, s5, 0
	s_add_i32 s44, 0, 0x10000
	v_add_u32_e32 v139, s44, v137
	ds_read_b128 v[140:143], v139
	ds_read_b128 v[144:147], v139 offset:1024
	ds_read_b128 v[148:151], v139 offset:2048
	ds_read_b128 v[152:155], v139 offset:3072
	s_and_b64 s[4:5], s[16:17], exec
	s_cselect_b32 s16, s8, s18
	s_cselect_b32 s17, s9, s19
	s_add_i32 s5, 0, 0x14000
	s_add_i32 s43, 0, 0x18000
	s_add_i32 s18, 0, 0x1c000
	s_add_i32 s45, s44, s25
	s_add_i32 s51, s5, s25
	s_add_i32 s19, s43, s25
	s_add_i32 s53, s18, s25
	s_mov_b64 s[64:65], 0x8000
	s_mov_b64 s[62:63], 0x10080
	s_add_i32 m0, s31, 0xc000
	s_add_i32 s4, s31, 0xe000
	s_add_i32 s54, s45, 0x2000
	s_add_i32 s50, s51, 0x2000
	s_add_i32 s44, s19, 0x2000
	s_add_i32 s52, s53, 0x2000
	v_lshl_add_u64 v[184:185], s[22:23], 0, v[2:3]
	v_lshl_add_u64 v[204:205], v[184:185], 0, s[62:63]
	ds_read_b128 v[156:159], v138
	ds_read_b128 v[160:163], v138 offset:1024
	ds_read_b128 v[164:167], v138 offset:2048
	ds_read_b128 v[172:175], v138 offset:3072
	ds_read_b128 v[176:179], v138 offset:4096
	ds_read_b128 v[180:183], v138 offset:5120
	ds_read_b128 v[196:199], v138 offset:6144
	ds_read_b128 v[200:203], v138 offset:7168
	global_load_lds_dwordx4 v[204:205], off
	v_lshl_add_u64 v[184:185], v[184:185], 0, s[68:69]
	s_mov_b32 m0, s4
	s_nop 0
	global_load_lds_dwordx4 v[184:185], off
	s_waitcnt lgkmcnt(8)
	s_barrier
	s_waitcnt lgkmcnt(0)
	s_setprio 3
	s_waitcnt lgkmcnt(0)
	v_mfma_f32_16x16x32_bf16 v[132:135], v[140:143], v[156:159], v[132:135]
	v_mfma_f32_16x16x32_bf16 v[128:131], v[148:151], v[156:159], v[128:131]
	v_mfma_f32_16x16x32_bf16 v[124:127], v[140:143], v[164:167], v[124:127]
	v_mfma_f32_16x16x32_bf16 v[116:119], v[148:151], v[164:167], v[116:119]
	v_mfma_f32_16x16x32_bf16 v[108:111], v[140:143], v[176:179], v[108:111]
	v_mfma_f32_16x16x32_bf16 v[100:103], v[148:151], v[176:179], v[100:103]
	v_mfma_f32_16x16x32_bf16 v[92:95], v[140:143], v[196:199], v[92:95]
	v_mfma_f32_16x16x32_bf16 v[84:87], v[148:151], v[196:199], v[84:87]
	v_mfma_f32_16x16x32_bf16 v[132:135], v[144:147], v[160:163], v[132:135]
	v_mfma_f32_16x16x32_bf16 v[128:131], v[152:155], v[160:163], v[128:131]
	v_mfma_f32_16x16x32_bf16 v[124:127], v[144:147], v[172:175], v[124:127]
	v_mfma_f32_16x16x32_bf16 v[116:119], v[152:155], v[172:175], v[116:119]
	v_mfma_f32_16x16x32_bf16 v[108:111], v[144:147], v[180:183], v[108:111]
	v_mfma_f32_16x16x32_bf16 v[100:103], v[152:155], v[180:183], v[100:103]
	v_mfma_f32_16x16x32_bf16 v[92:95], v[144:147], v[200:203], v[92:95]
	v_mfma_f32_16x16x32_bf16 v[84:87], v[152:155], v[200:203], v[84:87]
	s_setprio 0
	s_barrier
	s_mov_b32 m0, s45
	v_add_u32_e32 v139, s5, v137
	v_lshl_add_u64 v[184:185], s[16:17], 0, v[0:1]
	ds_read_b128 v[204:207], v139
	ds_read_b128 v[208:211], v139 offset:1024
	ds_read_b128 v[212:215], v139 offset:2048
	ds_read_b128 v[216:219], v139 offset:3072
	global_load_lds_dwordx4 v[184:185], off
	v_lshl_add_u64 v[220:221], v[184:185], 0, s[64:65]
	s_mov_b32 m0, s54
	s_nop 0
	global_load_lds_dwordx4 v[220:221], off
	s_barrier
; #define G_STAGE(bufoff, gbase, o0, h64) do { \
;         __builtin_amdgcn_global_load_lds((const unsigned*)((const char*)(gbase) + (o0)), (LAS unsigned*)(lds + (bufoff) + ldsw), 16, 0, 0); \
;         __builtin_amdgcn_global_load_lds((const unsigned*)((const char*)(gbase) + (h64) + (o0)), (LAS unsigned*)(lds + (bufoff) + ldsw + 8192), 16, 0, 0); } while (0)
; #define G_LDA(dst, b, h) do { _Pragma("unroll") for (int m = 0; m < 4; ++m) _Pragma("unroll") for (int k = 0; k < 2; ++k) dst[m][k] = *(const LAS bf16x8*)(lds + G_SA(b, h) + aoff + m * 2048 + k * 1024); } while (0)
; #define G_LDB(dst, b, h) do { _Pragma("unroll") for (int n = 0; n < 2; ++n) _Pragma("unroll") for (int k = 0; k < 2; ++k) dst[n][k] = *(const LAS bf16x8*)(lds + G_SB(b, h) + boff + n * 2048 + k * 1024); } while (0)
; #define G_WAIT_V(n) asm volatile("s_waitcnt vmcnt(" #n ")" ::: "memory")
; #define G_WAIT_L(n) asm volatile("s_waitcnt lgkmcnt(" #n ")" ::: "memory")
; #define G_BAR __builtin_amdgcn_s_barrier()
; #define G_SCHED __builtin_amdgcn_sched_barrier(0)
;     ...
;             G_BAR; G_WAIT_L(0); G_MMA(0, 1, At, B1); G_BAR;
;             G_LDA(At, 0, 1); G_STAGE(G_SA(0, 0), a2, cA0, qA);
;             G_BAR; G_WAIT_L(0); G_MMA(1, 0, At, B0); G_BAR; G_SCHED;
;             G_STAGE(G_SB(0, 1), b2 + chB, cB0, qB);
;             G_WAIT_V(6); G_BAR; G_MMA(1, 1, At, B1); G_BAR;
;             G_LDB(B0, 1, 0); G_SCHED; G_LDA(At, 1, 0); G_STAGE(G_SA(0, 1), a2 + chA, cA0, qA);
;             G_WAIT_L(8); G_BAR; G_WAIT_L(0); G_MMA(0, 0, At, B0); G_BAR; G_SCHED;
;             G_LDB(B1, 1, 1); G_STAGE(G_SB(1, 0), b3, cB0, qB);
;             G_BAR; G_WAIT_L(0); G_MMA(0, 1, At, B1); G_BAR;
;             G_LDA(At, 1, 1); G_STAGE(G_SA(1, 0), a3, cA0, qA);
;             G_BAR; G_WAIT_L(0); G_MMA(1, 0, At, B0); G_BAR; G_SCHED;
	s_waitcnt lgkmcnt(0)
	s_setprio 3
	s_waitcnt lgkmcnt(0)
	v_mfma_f32_16x16x32_bf16 v[120:123], v[204:207], v[156:159], v[120:123]
	v_mfma_f32_16x16x32_bf16 v[112:115], v[212:215], v[156:159], v[112:115]
	v_mfma_f32_16x16x32_bf16 v[104:107], v[204:207], v[164:167], v[104:107]
	v_mfma_f32_16x16x32_bf16 v[96:99], v[212:215], v[164:167], v[96:99]
	v_mfma_f32_16x16x32_bf16 v[88:91], v[204:207], v[176:179], v[88:91]
	v_mfma_f32_16x16x32_bf16 v[80:83], v[212:215], v[176:179], v[80:83]
	v_mfma_f32_16x16x32_bf16 v[76:79], v[204:207], v[196:199], v[76:79]
	v_mfma_f32_16x16x32_bf16 v[72:75], v[212:215], v[196:199], v[72:75]
	v_mfma_f32_16x16x32_bf16 v[120:123], v[208:211], v[160:163], v[120:123]
	v_mfma_f32_16x16x32_bf16 v[112:115], v[216:219], v[160:163], v[112:115]
	v_mfma_f32_16x16x32_bf16 v[104:107], v[208:211], v[172:175], v[104:107]
	v_mfma_f32_16x16x32_bf16 v[96:99], v[216:219], v[172:175], v[96:99]
	v_mfma_f32_16x16x32_bf16 v[88:91], v[208:211], v[180:183], v[88:91]
	v_mfma_f32_16x16x32_bf16 v[80:83], v[216:219], v[180:183], v[80:83]
	v_mfma_f32_16x16x32_bf16 v[76:79], v[208:211], v[200:203], v[76:79]
	v_mfma_f32_16x16x32_bf16 v[72:75], v[216:219], v[200:203], v[72:75]
	s_setprio 0
	s_mov_b32 m0, s31
	v_lshl_add_u64 v[220:221], s[20:21], 0, v[2:3]
	s_mov_b64 s[4:5], 0x8000
	s_barrier
	ds_read_b128 v[156:159], v138 offset:16384
	ds_read_b128 v[160:163], v138 offset:17408
	ds_read_b128 v[164:167], v138 offset:18432
	ds_read_b128 v[172:175], v138 offset:19456
	ds_read_b128 v[176:179], v138 offset:20480
	ds_read_b128 v[180:183], v138 offset:21504
	ds_read_b128 v[196:199], v138 offset:22528
	ds_read_b128 v[200:203], v138 offset:23552
	global_load_lds_dwordx4 v[220:221], off
	v_lshl_add_u64 v[222:223], v[220:221], 0, s[4:5]
	s_mov_b32 m0, s33
	s_mov_b64 s[16:17], 0x18000
	global_load_lds_dwordx4 v[222:223], off
	s_barrier
	s_waitcnt lgkmcnt(0)
	s_mov_b64 s[20:21], 0x8080
	s_setprio 3
	s_waitcnt lgkmcnt(0)
	v_mfma_f32_16x16x32_bf16 v[68:71], v[140:143], v[156:159], v[68:71]
	v_mfma_f32_16x16x32_bf16 v[64:67], v[148:151], v[156:159], v[64:67]
	v_mfma_f32_16x16x32_bf16 v[60:63], v[140:143], v[164:167], v[60:63]
	v_mfma_f32_16x16x32_bf16 v[52:55], v[148:151], v[164:167], v[52:55]
	v_mfma_f32_16x16x32_bf16 v[44:47], v[140:143], v[176:179], v[44:47]
	v_mfma_f32_16x16x32_bf16 v[36:39], v[148:151], v[176:179], v[36:39]
	v_mfma_f32_16x16x32_bf16 v[28:31], v[140:143], v[196:199], v[28:31]
	v_mfma_f32_16x16x32_bf16 v[20:23], v[148:151], v[196:199], v[20:23]
	v_mfma_f32_16x16x32_bf16 v[68:71], v[144:147], v[160:163], v[68:71]
	v_mfma_f32_16x16x32_bf16 v[64:67], v[152:155], v[160:163], v[64:67]
	v_mfma_f32_16x16x32_bf16 v[60:63], v[144:147], v[172:175], v[60:63]
	v_mfma_f32_16x16x32_bf16 v[52:55], v[152:155], v[172:175], v[52:55]
	v_mfma_f32_16x16x32_bf16 v[44:47], v[144:147], v[180:183], v[44:47]
	v_mfma_f32_16x16x32_bf16 v[36:39], v[152:155], v[180:183], v[36:39]
	v_mfma_f32_16x16x32_bf16 v[28:31], v[144:147], v[200:203], v[28:31]
	v_mfma_f32_16x16x32_bf16 v[20:23], v[152:155], v[200:203], v[20:23]
	s_setprio 0
	s_barrier
	s_mov_b32 m0, s51
	v_lshl_add_u64 v[140:141], v[184:185], 0, s[58:59]
	global_load_lds_dwordx4 v[140:141], off
	v_lshl_add_u64 v[140:141], v[184:185], 0, s[16:17]
	s_mov_b32 m0, s50
	s_nop 0
	global_load_lds_dwordx4 v[140:141], off
	s_waitcnt vmcnt(6)
	s_barrier
	s_setprio 3
	v_mfma_f32_16x16x32_bf16 v[56:59], v[204:207], v[156:159], v[56:59]
	v_mfma_f32_16x16x32_bf16 v[48:51], v[212:215], v[156:159], v[48:51]
	v_mfma_f32_16x16x32_bf16 v[40:43], v[204:207], v[164:167], v[40:43]
	v_mfma_f32_16x16x32_bf16 v[32:35], v[212:215], v[164:167], v[32:35]
	v_mfma_f32_16x16x32_bf16 v[24:27], v[204:207], v[176:179], v[24:27]
	v_mfma_f32_16x16x32_bf16 v[16:19], v[212:215], v[176:179], v[16:19]
	v_mfma_f32_16x16x32_bf16 v[12:15], v[204:207], v[196:199], v[12:15]
	v_mfma_f32_16x16x32_bf16 v[8:11], v[212:215], v[196:199], v[8:11]
	v_mfma_f32_16x16x32_bf16 v[56:59], v[208:211], v[160:163], v[56:59]
	v_mfma_f32_16x16x32_bf16 v[48:51], v[216:219], v[160:163], v[48:51]
	v_mfma_f32_16x16x32_bf16 v[40:43], v[208:211], v[172:175], v[40:43]
	v_mfma_f32_16x16x32_bf16 v[32:35], v[216:219], v[172:175], v[32:35]
	v_mfma_f32_16x16x32_bf16 v[24:27], v[208:211], v[180:183], v[24:27]
	v_mfma_f32_16x16x32_bf16 v[16:19], v[216:219], v[180:183], v[16:19]
	v_mfma_f32_16x16x32_bf16 v[12:15], v[208:211], v[200:203], v[12:15]
	v_mfma_f32_16x16x32_bf16 v[8:11], v[216:219], v[200:203], v[8:11]
	s_setprio 0
	v_add_u32_e32 v139, s43, v137
	s_barrier
	ds_read_b128 v[140:143], v139
	ds_read_b128 v[144:147], v139 offset:1024
	ds_read_b128 v[148:151], v139 offset:2048
	ds_read_b128 v[152:155], v139 offset:3072
	s_mov_b32 m0, s34
	v_lshl_add_u64 v[204:205], v[220:221], 0, s[58:59]
	ds_read_b128 v[156:159], v138 offset:32768
	ds_read_b128 v[160:163], v138 offset:33792
	ds_read_b128 v[164:167], v138 offset:34816
	ds_read_b128 v[172:175], v138 offset:35840
	ds_read_b128 v[176:179], v138 offset:36864
	ds_read_b128 v[180:183], v138 offset:37888
	ds_read_b128 v[196:199], v138 offset:38912
	ds_read_b128 v[200:203], v138 offset:39936
	global_load_lds_dwordx4 v[204:205], off
	v_lshl_add_u64 v[204:205], v[220:221], 0, s[16:17]
	s_mov_b32 m0, s35
	s_nop 0
	global_load_lds_dwordx4 v[204:205], off
	s_waitcnt lgkmcnt(8)
	s_barrier
; #define G_STAGE(bufoff, gbase, o0, h64) do { \
;         __builtin_amdgcn_global_load_lds((const unsigned*)((const char*)(gbase) + (o0)), (LAS unsigned*)(lds + (bufoff) + ldsw), 16, 0, 0); \
;         __builtin_amdgcn_global_load_lds((const unsigned*)((const char*)(gbase) + (h64) + (o0)), (LAS unsigned*)(lds + (bufoff) + ldsw + 8192), 16, 0, 0); } while (0)
; #define G_LDA(dst, b, h) do { _Pragma("unroll") for (int m = 0; m < 4; ++m) _Pragma("unroll") for (int k = 0; k < 2; ++k) dst[m][k] = *(const LAS bf16x8*)(lds + G_SA(b, h) + aoff + m * 2048 + k * 1024); } while (0)
; #define G_LDB(dst, b, h) do { _Pragma("unroll") for (int n = 0; n < 2; ++n) _Pragma("unroll") for (int k = 0; k < 2; ++k) dst[n][k] = *(const LAS bf16x8*)(lds + G_SB(b, h) + boff + n * 2048 + k * 1024); } while (0)
; #define G_WAIT_V(n) asm volatile("s_waitcnt vmcnt(" #n ")" ::: "memory")
; #define G_WAIT_L(n) asm volatile("s_waitcnt lgkmcnt(" #n ")" ::: "memory")
; #define G_BAR __builtin_amdgcn_s_barrier()
; #define G_SCHED __builtin_amdgcn_sched_barrier(0)
;     ...
;             G_BAR; G_WAIT_L(0); G_MMA(1, 0, At, B0); G_BAR; G_SCHED;
;             G_STAGE(G_SB(0, 1), b2 + chB, cB0, qB);
;             G_WAIT_V(6); G_BAR; G_MMA(1, 1, At, B1); G_BAR;
;             G_LDB(B0, 1, 0); G_SCHED; G_LDA(At, 1, 0); G_STAGE(G_SA(0, 1), a2 + chA, cA0, qA);
;             G_WAIT_L(8); G_BAR; G_WAIT_L(0); G_MMA(0, 0, At, B0); G_BAR; G_SCHED;
;             G_LDB(B1, 1, 1); G_STAGE(G_SB(1, 0), b3, cB0, qB);
;             G_BAR; G_WAIT_L(0); G_MMA(0, 1, At, B1); G_BAR;
;             G_LDA(At, 1, 1); G_STAGE(G_SA(1, 0), a3, cA0, qA);
;             G_BAR; G_WAIT_L(0); G_MMA(1, 0, At, B0); G_BAR; G_SCHED;
;             G_STAGE(G_SB(1, 1), b3 + chB, cB0, qB);
;             G_WAIT_V(6); G_BAR; G_MMA(1, 1, At, B1); G_BAR;
;         }
	s_waitcnt lgkmcnt(0)
	s_setprio 3
	s_waitcnt lgkmcnt(0)
	v_mfma_f32_16x16x32_bf16 v[132:135], v[140:143], v[156:159], v[132:135]
	v_mfma_f32_16x16x32_bf16 v[128:131], v[148:151], v[156:159], v[128:131]
	v_mfma_f32_16x16x32_bf16 v[124:127], v[140:143], v[164:167], v[124:127]
	v_mfma_f32_16x16x32_bf16 v[116:119], v[148:151], v[164:167], v[116:119]
	v_mfma_f32_16x16x32_bf16 v[108:111], v[140:143], v[176:179], v[108:111]
	v_mfma_f32_16x16x32_bf16 v[100:103], v[148:151], v[176:179], v[100:103]
	v_mfma_f32_16x16x32_bf16 v[92:95], v[140:143], v[196:199], v[92:95]
	v_mfma_f32_16x16x32_bf16 v[84:87], v[148:151], v[196:199], v[84:87]
	v_mfma_f32_16x16x32_bf16 v[132:135], v[144:147], v[160:163], v[132:135]
	v_mfma_f32_16x16x32_bf16 v[128:131], v[152:155], v[160:163], v[128:131]
	v_mfma_f32_16x16x32_bf16 v[124:127], v[144:147], v[172:175], v[124:127]
	v_mfma_f32_16x16x32_bf16 v[116:119], v[152:155], v[172:175], v[116:119]
	v_mfma_f32_16x16x32_bf16 v[108:111], v[144:147], v[180:183], v[108:111]
	v_mfma_f32_16x16x32_bf16 v[100:103], v[152:155], v[180:183], v[100:103]
	v_mfma_f32_16x16x32_bf16 v[92:95], v[144:147], v[200:203], v[92:95]
	v_mfma_f32_16x16x32_bf16 v[84:87], v[152:155], v[200:203], v[84:87]
	s_setprio 0
	s_barrier
	s_mov_b32 m0, s19
	v_add_u32_e32 v139, s18, v137
	v_lshl_add_u64 v[222:223], v[184:185], 0, s[46:47]
	ds_read_b128 v[204:207], v139
	ds_read_b128 v[208:211], v139 offset:1024
	ds_read_b128 v[212:215], v139 offset:2048
	ds_read_b128 v[216:219], v139 offset:3072
	global_load_lds_dwordx4 v[222:223], off
	v_lshl_add_u64 v[222:223], v[184:185], 0, s[20:21]
	s_mov_b32 m0, s44
	s_mov_b64 s[4:5], 0x10080
	global_load_lds_dwordx4 v[222:223], off
	s_barrier
	s_waitcnt lgkmcnt(0)
	s_setprio 3
	s_waitcnt lgkmcnt(0)
	v_mfma_f32_16x16x32_bf16 v[120:123], v[204:207], v[156:159], v[120:123]
	v_mfma_f32_16x16x32_bf16 v[112:115], v[212:215], v[156:159], v[112:115]
	v_mfma_f32_16x16x32_bf16 v[104:107], v[204:207], v[164:167], v[104:107]
	v_mfma_f32_16x16x32_bf16 v[96:99], v[212:215], v[164:167], v[96:99]
	v_mfma_f32_16x16x32_bf16 v[88:91], v[204:207], v[176:179], v[88:91]
	v_mfma_f32_16x16x32_bf16 v[80:83], v[212:215], v[176:179], v[80:83]
	v_mfma_f32_16x16x32_bf16 v[76:79], v[204:207], v[196:199], v[76:79]
	v_mfma_f32_16x16x32_bf16 v[72:75], v[212:215], v[196:199], v[72:75]
	v_mfma_f32_16x16x32_bf16 v[120:123], v[208:211], v[160:163], v[120:123]
	v_mfma_f32_16x16x32_bf16 v[112:115], v[216:219], v[160:163], v[112:115]
	v_mfma_f32_16x16x32_bf16 v[104:107], v[208:211], v[172:175], v[104:107]
	v_mfma_f32_16x16x32_bf16 v[96:99], v[216:219], v[172:175], v[96:99]
	v_mfma_f32_16x16x32_bf16 v[88:91], v[208:211], v[180:183], v[88:91]
	v_mfma_f32_16x16x32_bf16 v[80:83], v[216:219], v[180:183], v[80:83]
	v_mfma_f32_16x16x32_bf16 v[76:79], v[208:211], v[200:203], v[76:79]
	v_mfma_f32_16x16x32_bf16 v[72:75], v[216:219], v[200:203], v[72:75]
	s_setprio 0
	s_mov_b32 m0, s36
	v_lshl_add_u64 v[222:223], v[220:221], 0, s[46:47]
	s_barrier
	ds_read_b128 v[156:159], v138 offset:49152
	ds_read_b128 v[160:163], v138 offset:50176
	ds_read_b128 v[164:167], v138 offset:51200
	ds_read_b128 v[172:175], v138 offset:52224
	ds_read_b128 v[176:179], v138 offset:53248
	ds_read_b128 v[180:183], v138 offset:54272
	ds_read_b128 v[196:199], v138 offset:55296
	ds_read_b128 v[200:203], v138 offset:56320
	global_load_lds_dwordx4 v[222:223], off
	v_lshl_add_u64 v[220:221], v[220:221], 0, s[20:21]
	s_mov_b32 m0, s37
	s_nop 0
	global_load_lds_dwordx4 v[220:221], off
	s_barrier
	s_waitcnt lgkmcnt(0)
	s_setprio 3
	s_waitcnt lgkmcnt(0)
	v_mfma_f32_16x16x32_bf16 v[68:71], v[140:143], v[156:159], v[68:71]
	v_mfma_f32_16x16x32_bf16 v[64:67], v[148:151], v[156:159], v[64:67]
	v_mfma_f32_16x16x32_bf16 v[60:63], v[140:143], v[164:167], v[60:63]
	v_mfma_f32_16x16x32_bf16 v[52:55], v[148:151], v[164:167], v[52:55]
	v_mfma_f32_16x16x32_bf16 v[44:47], v[140:143], v[176:179], v[44:47]
	v_mfma_f32_16x16x32_bf16 v[36:39], v[148:151], v[176:179], v[36:39]
	v_mfma_f32_16x16x32_bf16 v[28:31], v[140:143], v[196:199], v[28:31]
	v_mfma_f32_16x16x32_bf16 v[20:23], v[148:151], v[196:199], v[20:23]
	v_mfma_f32_16x16x32_bf16 v[68:71], v[144:147], v[160:163], v[68:71]
	v_mfma_f32_16x16x32_bf16 v[64:67], v[152:155], v[160:163], v[64:67]
	v_mfma_f32_16x16x32_bf16 v[60:63], v[144:147], v[172:175], v[60:63]
	v_mfma_f32_16x16x32_bf16 v[52:55], v[152:155], v[172:175], v[52:55]
	v_mfma_f32_16x16x32_bf16 v[44:47], v[144:147], v[180:183], v[44:47]
	v_mfma_f32_16x16x32_bf16 v[36:39], v[152:155], v[180:183], v[36:39]
	v_mfma_f32_16x16x32_bf16 v[28:31], v[144:147], v[200:203], v[28:31]
	v_mfma_f32_16x16x32_bf16 v[20:23], v[152:155], v[200:203], v[20:23]
	s_setprio 0
	s_barrier
	s_mov_b32 m0, s53
	v_lshl_add_u64 v[140:141], v[184:185], 0, s[4:5]
	global_load_lds_dwordx4 v[140:141], off
	v_lshl_add_u64 v[140:141], v[184:185], 0, s[68:69]
	s_mov_b32 m0, s52
	s_nop 0
	global_load_lds_dwordx4 v[140:141], off
	s_waitcnt vmcnt(6)
	s_barrier
	s_setprio 3
	v_mfma_f32_16x16x32_bf16 v[56:59], v[204:207], v[156:159], v[56:59]
	v_mfma_f32_16x16x32_bf16 v[48:51], v[212:215], v[156:159], v[48:51]
	v_mfma_f32_16x16x32_bf16 v[40:43], v[204:207], v[164:167], v[40:43]
	v_mfma_f32_16x16x32_bf16 v[32:35], v[212:215], v[164:167], v[32:35]
	v_mfma_f32_16x16x32_bf16 v[24:27], v[204:207], v[176:179], v[24:27]
	v_mfma_f32_16x16x32_bf16 v[16:19], v[212:215], v[176:179], v[16:19]
	v_mfma_f32_16x16x32_bf16 v[12:15], v[204:207], v[196:199], v[12:15]
	v_mfma_f32_16x16x32_bf16 v[8:11], v[212:215], v[196:199], v[8:11]
	v_mfma_f32_16x16x32_bf16 v[56:59], v[208:211], v[160:163], v[56:59]
	v_mfma_f32_16x16x32_bf16 v[48:51], v[216:219], v[160:163], v[48:51]
	v_mfma_f32_16x16x32_bf16 v[40:43], v[208:211], v[172:175], v[40:43]
	v_mfma_f32_16x16x32_bf16 v[32:35], v[216:219], v[172:175], v[32:35]
	v_mfma_f32_16x16x32_bf16 v[24:27], v[208:211], v[180:183], v[24:27]
	v_mfma_f32_16x16x32_bf16 v[16:19], v[216:219], v[180:183], v[16:19]
	v_mfma_f32_16x16x32_bf16 v[12:15], v[208:211], v[200:203], v[12:15]
	v_mfma_f32_16x16x32_bf16 v[8:11], v[216:219], v[200:203], v[8:11]
	s_setprio 0
	s_andn2_b64 vcc, exec, s[14:15]
	s_mov_b64 s[16:17], -1
	s_mov_b64 s[14:15], 0
	s_mov_b64 s[18:19], 0x100
	s_cbranch_vccz .Ldb_PLE0_cont
	v_readfirstlane_b32 s101, v186
	s_cmpk_gt_u32 s101, 0xff
	s_cbranch_scc1 .Ldb_PLE0_exit
	s_barrier
	s_branch .Ldb_PLE0_exit

; __device__ __forceinline__ u32x4 pack8(const f32x4 a, const f32x4 b) { u32x4 w; w.x = cvt_pk_bf16(a[0], a[1]); w.y = cvt_pk_bf16(a[2], a[3]); w.z = cvt_pk_bf16(b[0], b[1]); w.w = cvt_pk_bf16(b[2], b[3]); return w; }
; #define MEMFENCE asm volatile("" ::: "memory")
; #define G_WAIT_V(n) asm volatile("s_waitcnt vmcnt(" #n ")" ::: "memory")
; #define G_BAR __builtin_amdgcn_s_barrier()
;     template <int KIND> __device__ __forceinline__ void run(f32x4 (&acc)[2][2][4][2], const Unit& u, int tid_in) const {
;     ...
;         if constexpr (KIND == K_PP) {
; #pragma unroll
;             for (int ai = 0; ai < 2; ++ai)
; #pragma unroll
;                 for (int m = 0; m < 4; ++m)
; #pragma unroll
;                     for (int bj = 0; bj < 2; ++bj) { scr[((ai * 4 + m) * 2 + bj) * 512 + tid] = pack8(acc[ai][bj][m][0], acc[ai][bj][m][1]); if (bj == 1) MEMFENCE; }
;         }
;     ...
;         E.template run<cs.kind>(acc, cur, tid);
;         if (!has_next) break;
;         if (!(cs.kind == K_MG_B && cur.aux < 2))
; #pragma unroll
;         for (int a = 0; a < 2; ++a)
; #pragma unroll
;             for (int b = 0; b < 2; ++b)
; #pragma unroll
;                 for (int m = 0; m < 4; ++m)
; #pragma unroll
;                     for (int n = 0; n < 2; ++n) acc[a][b][m][n] = (f32x4){0.f, 0.f, 0.f, 0.f};
;         cur = nxt; cA = nA; cB = nB; ++ui;
;     }
;     G_WAIT_V(0);
;     if (wr == 0) G_BAR;
;     G_BAR;
.Ldb_PLE0_exit:
	s_lshl_b32 s4, s42, 17
	s_and_b32 s4, s4, 0x20000
	v_mov_b32_e32 v140, v136
	s_add_u32 s4, s38, s4
	s_addc_u32 s5, s39, 0
	v_ashrrev_i32_e32 v141, 31, v140
	v_cvt_pk_bf16_f32 v132, v132, v133
	v_cvt_pk_bf16_f32 v133, v134, v135
	v_cvt_pk_bf16_f32 v134, v128, v129
	v_lshl_add_u64 v[128:129], v[140:141], 4, s[4:5]
	s_movk_i32 s4, 0x2000
	v_cvt_pk_bf16_f32 v135, v130, v131
	global_store_dwordx4 v[128:129], v[132:135], off
	v_cvt_pk_bf16_f32 v120, v120, v121
	v_cvt_pk_bf16_f32 v121, v122, v123
	v_cvt_pk_bf16_f32 v122, v112, v113
	v_add_co_u32_e32 v112, vcc, s4, v128
	v_cvt_pk_bf16_f32 v123, v114, v115
	s_movk_i32 s4, 0x6000
	s_nop 0
	v_addc_co_u32_e32 v113, vcc, 0, v129, vcc
	global_store_dwordx4 v[112:113], v[120:123], off
	v_cvt_pk_bf16_f32 v112, v124, v125
	v_cvt_pk_bf16_f32 v113, v126, v127
	v_cvt_pk_bf16_f32 v114, v116, v117
	v_add_co_u32_e32 v116, vcc, s49, v128
	v_cvt_pk_bf16_f32 v115, v118, v119
	s_mov_b32 s42, s41
	s_nop 0
	v_addc_co_u32_e32 v117, vcc, 0, v129, vcc
	global_store_dwordx4 v[116:117], v[112:115], off
	v_cvt_pk_bf16_f32 v104, v104, v105
	v_cvt_pk_bf16_f32 v105, v106, v107
	v_cvt_pk_bf16_f32 v106, v96, v97
	v_add_co_u32_e32 v96, vcc, s4, v128
	v_cvt_pk_bf16_f32 v107, v98, v99
	s_mov_b32 s4, 0xa000
	s_nop 0
	v_addc_co_u32_e32 v97, vcc, 0, v129, vcc
	global_store_dwordx4 v[96:97], v[104:107], off
	v_cvt_pk_bf16_f32 v96, v108, v109
	v_cvt_pk_bf16_f32 v97, v110, v111
	v_cvt_pk_bf16_f32 v98, v100, v101
	v_add_co_u32_e32 v100, vcc, s77, v128
	v_cvt_pk_bf16_f32 v99, v102, v103
	s_mov_b64 s[12:13], s[8:9]
	s_nop 0
	v_addc_co_u32_e32 v101, vcc, 0, v129, vcc
	global_store_dwordx4 v[100:101], v[96:99], off
	v_cvt_pk_bf16_f32 v88, v88, v89
	v_cvt_pk_bf16_f32 v89, v90, v91
	v_cvt_pk_bf16_f32 v90, v80, v81
	v_add_co_u32_e32 v80, vcc, s4, v128
	v_cvt_pk_bf16_f32 v91, v82, v83
	s_mov_b32 s4, 0xc000
	s_nop 0
	v_addc_co_u32_e32 v81, vcc, 0, v129, vcc
	global_store_dwordx4 v[80:81], v[88:91], off
	v_cvt_pk_bf16_f32 v80, v92, v93
	v_cvt_pk_bf16_f32 v81, v94, v95
	v_cvt_pk_bf16_f32 v82, v84, v85
	v_add_co_u32_e32 v84, vcc, s4, v128
	s_mov_b32 s4, 0xe000
	s_nop 0
	v_addc_co_u32_e32 v85, vcc, 0, v129, vcc
	v_cvt_pk_bf16_f32 v83, v86, v87
	global_store_dwordx4 v[84:85], v[80:83], off
	v_cvt_pk_bf16_f32 v76, v76, v77
	v_cvt_pk_bf16_f32 v77, v78, v79
	v_cvt_pk_bf16_f32 v78, v72, v73
	v_add_co_u32_e32 v72, vcc, s4, v128
	v_cvt_pk_bf16_f32 v79, v74, v75
	s_mov_b32 s4, 0x12000
	s_nop 0
	v_addc_co_u32_e32 v73, vcc, 0, v129, vcc
	global_store_dwordx4 v[72:73], v[76:79], off
	v_cvt_pk_bf16_f32 v68, v68, v69
	v_cvt_pk_bf16_f32 v69, v70, v71
	v_cvt_pk_bf16_f32 v70, v64, v65
	v_add_co_u32_e32 v64, vcc, s91, v128
	v_cvt_pk_bf16_f32 v71, v66, v67
	s_mov_b64 s[10:11], s[6:7]
	s_nop 0
	v_addc_co_u32_e32 v65, vcc, 0, v129, vcc
	global_store_dwordx4 v[64:65], v[68:71], off
	v_cvt_pk_bf16_f32 v56, v56, v57
	v_cvt_pk_bf16_f32 v57, v58, v59
	v_cvt_pk_bf16_f32 v58, v48, v49
	v_add_co_u32_e32 v48, vcc, s4, v128
	v_cvt_pk_bf16_f32 v59, v50, v51
	s_mov_b32 s4, 0x14000
	s_nop 0
	v_addc_co_u32_e32 v49, vcc, 0, v129, vcc
	global_store_dwordx4 v[48:49], v[56:59], off
	v_cvt_pk_bf16_f32 v48, v60, v61
	v_cvt_pk_bf16_f32 v49, v62, v63
	v_cvt_pk_bf16_f32 v50, v52, v53
	v_add_co_u32_e32 v52, vcc, s4, v128
	s_mov_b32 s4, 0x16000
	s_nop 0
	v_addc_co_u32_e32 v53, vcc, 0, v129, vcc
	v_cvt_pk_bf16_f32 v51, v54, v55
	global_store_dwordx4 v[52:53], v[48:51], off
	v_cvt_pk_bf16_f32 v40, v40, v41
	v_cvt_pk_bf16_f32 v41, v42, v43
	v_cvt_pk_bf16_f32 v42, v32, v33
	v_add_co_u32_e32 v32, vcc, s4, v128
	v_cvt_pk_bf16_f32 v43, v34, v35
	s_mov_b32 s4, 0x18000
	s_nop 0
	v_addc_co_u32_e32 v33, vcc, 0, v129, vcc
	global_store_dwordx4 v[32:33], v[40:43], off
	v_cvt_pk_bf16_f32 v32, v44, v45
	v_cvt_pk_bf16_f32 v33, v46, v47
	v_cvt_pk_bf16_f32 v34, v36, v37
	v_add_co_u32_e32 v36, vcc, s4, v128
	s_mov_b32 s4, 0x1a000
	s_nop 0
	v_addc_co_u32_e32 v37, vcc, 0, v129, vcc
	v_cvt_pk_bf16_f32 v35, v38, v39
	global_store_dwordx4 v[36:37], v[32:35], off
	v_cvt_pk_bf16_f32 v24, v24, v25
	v_cvt_pk_bf16_f32 v25, v26, v27
	v_cvt_pk_bf16_f32 v26, v16, v17
	v_add_co_u32_e32 v16, vcc, s4, v128
	v_cvt_pk_bf16_f32 v27, v18, v19
	s_mov_b32 s4, 0x1c000
	s_nop 0
	v_addc_co_u32_e32 v17, vcc, 0, v129, vcc
	global_store_dwordx4 v[16:17], v[24:27], off
	v_cvt_pk_bf16_f32 v16, v28, v29
	v_cvt_pk_bf16_f32 v17, v30, v31
	v_cvt_pk_bf16_f32 v18, v20, v21
	v_add_co_u32_e32 v20, vcc, s4, v128
	v_cvt_pk_bf16_f32 v19, v22, v23
	s_nop 1
	v_addc_co_u32_e32 v21, vcc, 0, v129, vcc
	global_store_dwordx4 v[20:21], v[16:19], off
	v_cvt_pk_bf16_f32 v12, v12, v13
	v_cvt_pk_bf16_f32 v13, v14, v15
	v_cvt_pk_bf16_f32 v14, v8, v9
	v_add_co_u32_e32 v8, vcc, 0x1e000, v128
	v_cvt_pk_bf16_f32 v15, v10, v11
	s_nop 1
	v_addc_co_u32_e32 v9, vcc, 0, v129, vcc
	global_store_dwordx4 v[8:9], v[12:15], off
	s_and_b64 vcc, exec, s[2:3]
	s_cbranch_vccz .LBB0_1257
	s_cmpk_gt_u32 s101, 0xff
	s_cbranch_scc0 .Ldbj_PLE0_pe
	s_barrier
	s_mov_b32 s101, 0
.Ldbj_PLE0_pe:
	s_waitcnt vmcnt(0)
	s_cmpk_gt_u32 s24, 0xff
	s_cbranch_scc1 .LBB0_1264
	s_barrier
.LBB0_1264:
	v_readlane_b32 s44, v230, 7
	v_readlane_b32 s45, v230, 8
	s_barrier

; #define G_STAGE(bufoff, gbase, o0, h64) do { \
;         __builtin_amdgcn_global_load_lds((const unsigned*)((const char*)(gbase) + (o0)), (LAS unsigned*)(lds + (bufoff) + ldsw), 16, 0, 0); \
;         __builtin_amdgcn_global_load_lds((const unsigned*)((const char*)(gbase) + (h64) + (o0)), (LAS unsigned*)(lds + (bufoff) + ldsw + 8192), 16, 0, 0); } while (0)
; #define G_LDA(dst, b, h) do { _Pragma("unroll") for (int m = 0; m < 4; ++m) _Pragma("unroll") for (int k = 0; k < 2; ++k) dst[m][k] = *(const LAS bf16x8*)(lds + G_SA(b, h) + aoff + m * 2048 + k * 1024); } while (0)
; #define G_LDB(dst, b, h) do { _Pragma("unroll") for (int n = 0; n < 2; ++n) _Pragma("unroll") for (int k = 0; k < 2; ++k) dst[n][k] = *(const LAS bf16x8*)(lds + G_SB(b, h) + boff + n * 2048 + k * 1024); } while (0)
; #define G_WAIT_L(n) asm volatile("s_waitcnt lgkmcnt(" #n ")" ::: "memory")
; #define G_BAR __builtin_amdgcn_s_barrier()
; #define G_SCHED __builtin_amdgcn_sched_barrier(0)
;     ...
;         for (int t = 0; t < nt; t += 2) {
;             const bool last = (t == nt - 2);
;             const char* a1 = cA + (size_t)(t + 1) * ckA;
;             const char* a2 = last ? nA : cA + (size_t)(t + 2) * ckA; const char* b2 = last ? nB : cB + (size_t)(t + 2) * kB;
;             const char* a3 = a2 + ckA; const char* b3 = b2 + kB;
;             G_LDB(B0, 0, 0); G_SCHED; G_LDA(At, 0, 0); G_STAGE(G_SA(1, 1), a1 + chA, cA0, qA);
;             G_WAIT_L(8); G_BAR; G_WAIT_L(0); G_MMA(0, 0, At, B0); G_BAR; G_SCHED;
;             G_LDB(B1, 0, 1); G_STAGE(G_SB(0, 0), b2, cB0, qB);
;             G_BAR; G_WAIT_L(0); G_MMA(0, 1, At, B1); G_BAR;
;             G_LDA(At, 0, 1); G_STAGE(G_SA(0, 0), a2, cA0, qA);
;             G_BAR; G_WAIT_L(0); G_MMA(1, 0, At, B0); G_BAR; G_SCHED;
;     ...
;         if (!(cs.kind == K_MG_B && cur.aux < 2))
; #pragma unroll
;         for (int a = 0; a < 2; ++a)
; #pragma unroll
;             for (int b = 0; b < 2; ++b)
; #pragma unroll
;                 for (int m = 0; m < 4; ++m)
; #pragma unroll
;                     for (int n = 0; n < 2; ++n) acc[a][b][m][n] = (f32x4){0.f, 0.f, 0.f, 0.f};
.LBB0_1282:
	s_add_u32 s2, s24, 0x40080
	s_addc_u32 s3, s25, 0
	s_add_u32 s22, s22, 0x100
	s_waitcnt lgkmcnt(0)
	v_mov_b64_e32 v[8:9], 0
	s_addc_u32 s23, s23, 0
	s_mov_b32 s24, -2
	v_mov_b64_e32 v[10:11], 0
	v_mov_b64_e32 v[12:13], 0
	v_mov_b64_e32 v[14:15], 0
	v_mov_b64_e32 v[24:25], 0
	v_mov_b64_e32 v[26:27], 0
	v_mov_b64_e32 v[28:29], 0
	v_mov_b64_e32 v[30:31], 0
	v_mov_b64_e32 v[40:41], 0
	v_mov_b64_e32 v[42:43], 0
	v_mov_b64_e32 v[44:45], 0
	v_mov_b64_e32 v[46:47], 0
	v_mov_b64_e32 v[56:57], 0
	v_mov_b64_e32 v[58:59], 0
	v_mov_b64_e32 v[60:61], 0
	v_mov_b64_e32 v[62:63], 0
	v_mov_b64_e32 v[16:17], 0
	v_mov_b64_e32 v[18:19], 0
	v_mov_b64_e32 v[20:21], 0
	v_mov_b64_e32 v[22:23], 0
	v_mov_b64_e32 v[32:33], 0
	v_mov_b64_e32 v[34:35], 0
	v_mov_b64_e32 v[36:37], 0
	v_mov_b64_e32 v[38:39], 0
	v_mov_b64_e32 v[48:49], 0
	v_mov_b64_e32 v[50:51], 0
	v_mov_b64_e32 v[52:53], 0
	v_mov_b64_e32 v[54:55], 0
	v_mov_b64_e32 v[64:65], 0
	v_mov_b64_e32 v[66:67], 0
	v_mov_b64_e32 v[68:69], 0
	v_mov_b64_e32 v[70:71], 0
	v_mov_b64_e32 v[72:73], 0
	v_mov_b64_e32 v[74:75], 0
	v_mov_b64_e32 v[76:77], 0
	v_mov_b64_e32 v[78:79], 0
	v_mov_b64_e32 v[88:89], 0
	v_mov_b64_e32 v[90:91], 0
	v_mov_b64_e32 v[92:93], 0
	v_mov_b64_e32 v[94:95], 0
	v_mov_b64_e32 v[104:105], 0
	v_mov_b64_e32 v[106:107], 0
	v_mov_b64_e32 v[108:109], 0
	v_mov_b64_e32 v[110:111], 0
	v_mov_b64_e32 v[120:121], 0
	v_mov_b64_e32 v[122:123], 0
	v_mov_b64_e32 v[124:125], 0
	v_mov_b64_e32 v[126:127], 0
	v_mov_b64_e32 v[80:81], 0
	v_mov_b64_e32 v[82:83], 0
	v_mov_b64_e32 v[84:85], 0
	v_mov_b64_e32 v[86:87], 0
	v_mov_b64_e32 v[96:97], 0
	v_mov_b64_e32 v[98:99], 0
	v_mov_b64_e32 v[100:101], 0
	v_mov_b64_e32 v[102:103], 0
	v_mov_b64_e32 v[112:113], 0
	v_mov_b64_e32 v[114:115], 0
	v_mov_b64_e32 v[116:117], 0
	v_mov_b64_e32 v[118:119], 0
	v_mov_b64_e32 v[128:129], 0
	v_mov_b64_e32 v[130:131], 0
	v_mov_b64_e32 v[132:133], 0
	v_mov_b64_e32 v[134:135], 0
	s_mov_b64 s[54:55], 0x40000
	s_mov_b64 s[58:59], 0x60000
	s_mov_b64 s[62:63], 0x20080
	s_mov_b64 s[64:65], 0x40080
	s_mov_b64 s[66:67], 0x60080
	s_cmpk_gt_u32 s101, 0xff
	s_cbranch_scc0 .Ldbj_PLE1_in
	s_barrier
	s_mov_b32 s101, 0
.Ldbj_PLE1_in:
.LBB0_1283:
	s_add_u32 s4, s2, 0xfffc0080
	s_addc_u32 s5, s3, -1
	s_add_i32 s25, 0, 0x10000
	v_add_u32_e32 v0, s25, v181
	ds_read_b128 v[136:139], v0
	ds_read_b128 v[140:143], v0 offset:1024
	ds_read_b128 v[144:147], v0 offset:2048
	ds_read_b128 v[148:151], v0 offset:3072
	s_cmp_eq_u32 s24, 12
	s_cselect_b32 s5, s19, s5
	s_cselect_b32 s4, s18, s4
	s_cselect_b32 s41, s21, s23
	s_cselect_b32 s40, s20, s22
	v_lshl_add_u64 v[184:185], s[2:3], 0, v[158:159]
	s_add_i32 m0, s29, 0xc000
	ds_read_b128 v[152:155], v182
	ds_read_b128 v[160:163], v182 offset:1024
	ds_read_b128 v[164:167], v182 offset:2048
	ds_read_b128 v[172:175], v182 offset:3072
	ds_read_b128 v[176:179], v182 offset:4096
	ds_read_b128 v[196:199], v182 offset:5120
	ds_read_b128 v[200:203], v182 offset:6144
	ds_read_b128 v[204:207], v182 offset:7168
	global_load_lds_dwordx4 v[184:185], off
	v_lshl_add_u64 v[184:185], v[184:185], 0, s[0:1]
	s_add_i32 m0, s29, 0xe000
	s_nop 0
	global_load_lds_dwordx4 v[184:185], off
	s_waitcnt lgkmcnt(8)
	s_barrier
	s_waitcnt lgkmcnt(0)
	s_setprio 3
	s_waitcnt lgkmcnt(0)
	v_mfma_f32_16x16x32_bf16 v[132:135], v[136:139], v[152:155], v[132:135]
	v_mfma_f32_16x16x32_bf16 v[128:131], v[144:147], v[152:155], v[128:131]
	v_mfma_f32_16x16x32_bf16 v[116:119], v[136:139], v[164:167], v[116:119]
	v_mfma_f32_16x16x32_bf16 v[112:115], v[144:147], v[164:167], v[112:115]
	v_mfma_f32_16x16x32_bf16 v[100:103], v[136:139], v[176:179], v[100:103]
	v_mfma_f32_16x16x32_bf16 v[96:99], v[144:147], v[176:179], v[96:99]
	v_mfma_f32_16x16x32_bf16 v[84:87], v[136:139], v[200:203], v[84:87]
	v_mfma_f32_16x16x32_bf16 v[80:83], v[144:147], v[200:203], v[80:83]
	v_mfma_f32_16x16x32_bf16 v[132:135], v[140:143], v[160:163], v[132:135]
	v_mfma_f32_16x16x32_bf16 v[128:131], v[148:151], v[160:163], v[128:131]
	v_mfma_f32_16x16x32_bf16 v[116:119], v[140:143], v[172:175], v[116:119]
	v_mfma_f32_16x16x32_bf16 v[112:115], v[148:151], v[172:175], v[112:115]
	v_mfma_f32_16x16x32_bf16 v[100:103], v[140:143], v[196:199], v[100:103]
	v_mfma_f32_16x16x32_bf16 v[96:99], v[148:151], v[196:199], v[96:99]
	v_mfma_f32_16x16x32_bf16 v[84:87], v[140:143], v[204:207], v[84:87]
	v_mfma_f32_16x16x32_bf16 v[80:83], v[148:151], v[204:207], v[80:83]
	s_setprio 0
	s_barrier
	s_add_i32 s44, 0, 0x14000
	s_add_i32 s25, s25, s27
	v_add_u32_e32 v0, s44, v181
	v_lshl_add_u64 v[184:185], s[40:41], 0, v[156:157]
	s_mov_b32 m0, s25
	ds_read_b128 v[208:211], v0
	ds_read_b128 v[212:215], v0 offset:1024
	ds_read_b128 v[216:219], v0 offset:2048
	ds_read_b128 v[220:223], v0 offset:3072
	global_load_lds_dwordx4 v[184:185], off
	v_lshl_add_u64 v[224:225], v[184:185], 0, s[0:1]
	s_add_i32 m0, s25, 0x2000
	s_nop 0
	global_load_lds_dwordx4 v[224:225], off
	s_barrier
	s_waitcnt lgkmcnt(0)
	s_setprio 3
	s_waitcnt lgkmcnt(0)
	v_mfma_f32_16x16x32_bf16 v[124:127], v[208:211], v[152:155], v[124:127]
	v_mfma_f32_16x16x32_bf16 v[120:123], v[216:219], v[152:155], v[120:123]
	v_mfma_f32_16x16x32_bf16 v[108:111], v[208:211], v[164:167], v[108:111]
	v_mfma_f32_16x16x32_bf16 v[104:107], v[216:219], v[164:167], v[104:107]
	v_mfma_f32_16x16x32_bf16 v[92:95], v[208:211], v[176:179], v[92:95]
	v_mfma_f32_16x16x32_bf16 v[88:91], v[216:219], v[176:179], v[88:91]
	v_mfma_f32_16x16x32_bf16 v[76:79], v[208:211], v[200:203], v[76:79]
	v_mfma_f32_16x16x32_bf16 v[72:75], v[216:219], v[200:203], v[72:75]
	v_mfma_f32_16x16x32_bf16 v[124:127], v[212:215], v[160:163], v[124:127]
	v_mfma_f32_16x16x32_bf16 v[120:123], v[220:223], v[160:163], v[120:123]
	v_mfma_f32_16x16x32_bf16 v[108:111], v[212:215], v[172:175], v[108:111]
	v_mfma_f32_16x16x32_bf16 v[104:107], v[220:223], v[172:175], v[104:107]
	v_mfma_f32_16x16x32_bf16 v[92:95], v[212:215], v[196:199], v[92:95]
	v_mfma_f32_16x16x32_bf16 v[88:91], v[220:223], v[196:199], v[88:91]
	v_mfma_f32_16x16x32_bf16 v[76:79], v[212:215], v[204:207], v[76:79]
	v_mfma_f32_16x16x32_bf16 v[72:75], v[220:223], v[204:207], v[72:75]
	s_setprio 0
	s_mov_b32 m0, s29
	v_lshl_add_u64 v[224:225], s[4:5], 0, v[2:3]
	s_barrier
; #define G_STAGE(bufoff, gbase, o0, h64) do { \
;         __builtin_amdgcn_global_load_lds((const unsigned*)((const char*)(gbase) + (o0)), (LAS unsigned*)(lds + (bufoff) + ldsw), 16, 0, 0); \
;         __builtin_amdgcn_global_load_lds((const unsigned*)((const char*)(gbase) + (h64) + (o0)), (LAS unsigned*)(lds + (bufoff) + ldsw + 8192), 16, 0, 0); } while (0)
; #define G_LDA(dst, b, h) do { _Pragma("unroll") for (int m = 0; m < 4; ++m) _Pragma("unroll") for (int k = 0; k < 2; ++k) dst[m][k] = *(const LAS bf16x8*)(lds + G_SA(b, h) + aoff + m * 2048 + k * 1024); } while (0)
; #define G_LDB(dst, b, h) do { _Pragma("unroll") for (int n = 0; n < 2; ++n) _Pragma("unroll") for (int k = 0; k < 2; ++k) dst[n][k] = *(const LAS bf16x8*)(lds + G_SB(b, h) + boff + n * 2048 + k * 1024); } while (0)
; #define G_WAIT_V(n) asm volatile("s_waitcnt vmcnt(" #n ")" ::: "memory")
; #define G_WAIT_L(n) asm volatile("s_waitcnt lgkmcnt(" #n ")" ::: "memory")
; #define G_BAR __builtin_amdgcn_s_barrier()
; #define G_SCHED __builtin_amdgcn_sched_barrier(0)
;     ...
;             G_LDB(B1, 0, 1); G_STAGE(G_SB(0, 0), b2, cB0, qB);
;             G_BAR; G_WAIT_L(0); G_MMA(0, 1, At, B1); G_BAR;
;             G_LDA(At, 0, 1); G_STAGE(G_SA(0, 0), a2, cA0, qA);
;             G_BAR; G_WAIT_L(0); G_MMA(1, 0, At, B0); G_BAR; G_SCHED;
;             G_STAGE(G_SB(0, 1), b2 + chB, cB0, qB);
;             G_WAIT_V(6); G_BAR; G_MMA(1, 1, At, B1); G_BAR;
;             G_LDB(B0, 1, 0); G_SCHED; G_LDA(At, 1, 0); G_STAGE(G_SA(0, 1), a2 + chA, cA0, qA);
;             G_WAIT_L(8); G_BAR; G_WAIT_L(0); G_MMA(0, 0, At, B0); G_BAR; G_SCHED;
	ds_read_b128 v[152:155], v182 offset:16384
	ds_read_b128 v[160:163], v182 offset:17408
	ds_read_b128 v[164:167], v182 offset:18432
	ds_read_b128 v[172:175], v182 offset:19456
	ds_read_b128 v[176:179], v182 offset:20480
	ds_read_b128 v[196:199], v182 offset:21504
	ds_read_b128 v[200:203], v182 offset:22528
	ds_read_b128 v[204:207], v182 offset:23552
	global_load_lds_dwordx4 v[224:225], off
	v_lshl_add_u64 v[226:227], v[224:225], 0, s[0:1]
	s_mov_b32 m0, s30
	s_nop 0
	global_load_lds_dwordx4 v[226:227], off
	s_barrier
	s_waitcnt lgkmcnt(0)
	s_setprio 3
	s_waitcnt lgkmcnt(0)
	v_mfma_f32_16x16x32_bf16 v[68:71], v[136:139], v[152:155], v[68:71]
	v_mfma_f32_16x16x32_bf16 v[64:67], v[144:147], v[152:155], v[64:67]
	v_mfma_f32_16x16x32_bf16 v[52:55], v[136:139], v[164:167], v[52:55]
	v_mfma_f32_16x16x32_bf16 v[48:51], v[144:147], v[164:167], v[48:51]
	v_mfma_f32_16x16x32_bf16 v[36:39], v[136:139], v[176:179], v[36:39]
	v_mfma_f32_16x16x32_bf16 v[32:35], v[144:147], v[176:179], v[32:35]
	v_mfma_f32_16x16x32_bf16 v[20:23], v[136:139], v[200:203], v[20:23]
	v_mfma_f32_16x16x32_bf16 v[16:19], v[144:147], v[200:203], v[16:19]
	v_mfma_f32_16x16x32_bf16 v[68:71], v[140:143], v[160:163], v[68:71]
	v_mfma_f32_16x16x32_bf16 v[64:67], v[148:151], v[160:163], v[64:67]
	v_mfma_f32_16x16x32_bf16 v[52:55], v[140:143], v[172:175], v[52:55]
	v_mfma_f32_16x16x32_bf16 v[48:51], v[148:151], v[172:175], v[48:51]
	v_mfma_f32_16x16x32_bf16 v[36:39], v[140:143], v[196:199], v[36:39]
	v_mfma_f32_16x16x32_bf16 v[32:35], v[148:151], v[196:199], v[32:35]
	v_mfma_f32_16x16x32_bf16 v[20:23], v[140:143], v[204:207], v[20:23]
	v_mfma_f32_16x16x32_bf16 v[16:19], v[148:151], v[204:207], v[16:19]
	s_setprio 0
	s_barrier
	s_add_i32 s4, s44, s27
	v_lshl_add_u64 v[136:137], v[184:185], 0, s[54:55]
	s_mov_b32 m0, s4
	s_nop 0
	global_load_lds_dwordx4 v[136:137], off
	v_lshl_add_u64 v[136:137], v[184:185], 0, s[58:59]
	s_add_i32 m0, s4, 0x2000
	s_nop 0
	global_load_lds_dwordx4 v[136:137], off
	s_waitcnt vmcnt(6)
	s_barrier
	s_setprio 3
	v_mfma_f32_16x16x32_bf16 v[60:63], v[208:211], v[152:155], v[60:63]
	v_mfma_f32_16x16x32_bf16 v[56:59], v[216:219], v[152:155], v[56:59]
	v_mfma_f32_16x16x32_bf16 v[44:47], v[208:211], v[164:167], v[44:47]
	v_mfma_f32_16x16x32_bf16 v[40:43], v[216:219], v[164:167], v[40:43]
	v_mfma_f32_16x16x32_bf16 v[28:31], v[208:211], v[176:179], v[28:31]
	v_mfma_f32_16x16x32_bf16 v[24:27], v[216:219], v[176:179], v[24:27]
	v_mfma_f32_16x16x32_bf16 v[12:15], v[208:211], v[200:203], v[12:15]
	v_mfma_f32_16x16x32_bf16 v[8:11], v[216:219], v[200:203], v[8:11]
	v_mfma_f32_16x16x32_bf16 v[60:63], v[212:215], v[160:163], v[60:63]
	v_mfma_f32_16x16x32_bf16 v[56:59], v[220:223], v[160:163], v[56:59]
	v_mfma_f32_16x16x32_bf16 v[44:47], v[212:215], v[172:175], v[44:47]
	v_mfma_f32_16x16x32_bf16 v[40:43], v[220:223], v[172:175], v[40:43]
	v_mfma_f32_16x16x32_bf16 v[28:31], v[212:215], v[196:199], v[28:31]
	v_mfma_f32_16x16x32_bf16 v[24:27], v[220:223], v[196:199], v[24:27]
	v_mfma_f32_16x16x32_bf16 v[12:15], v[212:215], v[204:207], v[12:15]
	v_mfma_f32_16x16x32_bf16 v[8:11], v[220:223], v[204:207], v[8:11]
	s_setprio 0
	s_add_i32 s4, 0, 0x18000
	v_add_u32_e32 v0, s4, v181
	s_barrier
	ds_read_b128 v[136:139], v0
	ds_read_b128 v[140:143], v0 offset:1024
	ds_read_b128 v[144:147], v0 offset:2048
	ds_read_b128 v[148:151], v0 offset:3072
	s_mov_b32 m0, s31
	v_lshl_add_u64 v[208:209], v[224:225], 0, s[54:55]
	ds_read_b128 v[152:155], v182 offset:32768
	ds_read_b128 v[160:163], v182 offset:33792
	ds_read_b128 v[164:167], v182 offset:34816
	ds_read_b128 v[172:175], v182 offset:35840
	ds_read_b128 v[176:179], v182 offset:36864
	ds_read_b128 v[196:199], v182 offset:37888
	ds_read_b128 v[200:203], v182 offset:38912
	ds_read_b128 v[204:207], v182 offset:39936
	global_load_lds_dwordx4 v[208:209], off
	v_lshl_add_u64 v[208:209], v[224:225], 0, s[58:59]
	s_mov_b32 m0, s34
	s_nop 0
	global_load_lds_dwordx4 v[208:209], off
	s_waitcnt lgkmcnt(8)
	s_barrier
	s_waitcnt lgkmcnt(0)
	s_setprio 3
	s_waitcnt lgkmcnt(0)
	v_mfma_f32_16x16x32_bf16 v[132:135], v[136:139], v[152:155], v[132:135]
	v_mfma_f32_16x16x32_bf16 v[128:131], v[144:147], v[152:155], v[128:131]
	v_mfma_f32_16x16x32_bf16 v[116:119], v[136:139], v[164:167], v[116:119]
	v_mfma_f32_16x16x32_bf16 v[112:115], v[144:147], v[164:167], v[112:115]
	v_mfma_f32_16x16x32_bf16 v[100:103], v[136:139], v[176:179], v[100:103]
	v_mfma_f32_16x16x32_bf16 v[96:99], v[144:147], v[176:179], v[96:99]
	v_mfma_f32_16x16x32_bf16 v[84:87], v[136:139], v[200:203], v[84:87]
	v_mfma_f32_16x16x32_bf16 v[80:83], v[144:147], v[200:203], v[80:83]
	v_mfma_f32_16x16x32_bf16 v[132:135], v[140:143], v[160:163], v[132:135]
	v_mfma_f32_16x16x32_bf16 v[128:131], v[148:151], v[160:163], v[128:131]
	v_mfma_f32_16x16x32_bf16 v[116:119], v[140:143], v[172:175], v[116:119]
	v_mfma_f32_16x16x32_bf16 v[112:115], v[148:151], v[172:175], v[112:115]
	v_mfma_f32_16x16x32_bf16 v[100:103], v[140:143], v[196:199], v[100:103]
	v_mfma_f32_16x16x32_bf16 v[96:99], v[148:151], v[196:199], v[96:99]
	v_mfma_f32_16x16x32_bf16 v[84:87], v[140:143], v[204:207], v[84:87]
	v_mfma_f32_16x16x32_bf16 v[80:83], v[148:151], v[204:207], v[80:83]
	s_setprio 0
	s_barrier
; #define G_STAGE(bufoff, gbase, o0, h64) do { \
;         __builtin_amdgcn_global_load_lds((const unsigned*)((const char*)(gbase) + (o0)), (LAS unsigned*)(lds + (bufoff) + ldsw), 16, 0, 0); \
;         __builtin_amdgcn_global_load_lds((const unsigned*)((const char*)(gbase) + (h64) + (o0)), (LAS unsigned*)(lds + (bufoff) + ldsw + 8192), 16, 0, 0); } while (0)
; #define G_LDA(dst, b, h) do { _Pragma("unroll") for (int m = 0; m < 4; ++m) _Pragma("unroll") for (int k = 0; k < 2; ++k) dst[m][k] = *(const LAS bf16x8*)(lds + G_SA(b, h) + aoff + m * 2048 + k * 1024); } while (0)
; #define G_LDB(dst, b, h) do { _Pragma("unroll") for (int n = 0; n < 2; ++n) _Pragma("unroll") for (int k = 0; k < 2; ++k) dst[n][k] = *(const LAS bf16x8*)(lds + G_SB(b, h) + boff + n * 2048 + k * 1024); } while (0)
; #define G_WAIT_V(n) asm volatile("s_waitcnt vmcnt(" #n ")" ::: "memory")
; #define G_WAIT_L(n) asm volatile("s_waitcnt lgkmcnt(" #n ")" ::: "memory")
; #define G_BAR __builtin_amdgcn_s_barrier()
; #define G_SCHED __builtin_amdgcn_sched_barrier(0)
;     ...
;             G_LDB(B1, 1, 1); G_STAGE(G_SB(1, 0), b3, cB0, qB);
;             G_BAR; G_WAIT_L(0); G_MMA(0, 1, At, B1); G_BAR;
;             G_LDA(At, 1, 1); G_STAGE(G_SA(1, 0), a3, cA0, qA);
;             G_BAR; G_WAIT_L(0); G_MMA(1, 0, At, B0); G_BAR; G_SCHED;
;             G_STAGE(G_SB(1, 1), b3 + chB, cB0, qB);
;             G_WAIT_V(6); G_BAR; G_MMA(1, 1, At, B1); G_BAR;
;         }
;     ...
;     G_WAIT_V(0);
;     if (wr == 0) G_BAR;
;     G_BAR;
	s_add_i32 s5, 0, 0x1c000
	s_add_i32 s4, s4, s27
	v_add_u32_e32 v0, s5, v181
	v_lshl_add_u64 v[226:227], v[184:185], 0, s[46:47]
	s_mov_b32 m0, s4
	ds_read_b128 v[208:211], v0
	ds_read_b128 v[212:215], v0 offset:1024
	ds_read_b128 v[216:219], v0 offset:2048
	ds_read_b128 v[220:223], v0 offset:3072
	global_load_lds_dwordx4 v[226:227], off
	v_lshl_add_u64 v[226:227], v[184:185], 0, s[62:63]
	s_add_i32 m0, s4, 0x2000
	s_nop 0
	global_load_lds_dwordx4 v[226:227], off
	s_barrier
	s_waitcnt lgkmcnt(0)
	s_setprio 3
	s_waitcnt lgkmcnt(0)
	v_mfma_f32_16x16x32_bf16 v[124:127], v[208:211], v[152:155], v[124:127]
	v_mfma_f32_16x16x32_bf16 v[120:123], v[216:219], v[152:155], v[120:123]
	v_mfma_f32_16x16x32_bf16 v[108:111], v[208:211], v[164:167], v[108:111]
	v_mfma_f32_16x16x32_bf16 v[104:107], v[216:219], v[164:167], v[104:107]
	v_mfma_f32_16x16x32_bf16 v[92:95], v[208:211], v[176:179], v[92:95]
	v_mfma_f32_16x16x32_bf16 v[88:91], v[216:219], v[176:179], v[88:91]
	v_mfma_f32_16x16x32_bf16 v[76:79], v[208:211], v[200:203], v[76:79]
	v_mfma_f32_16x16x32_bf16 v[72:75], v[216:219], v[200:203], v[72:75]
	v_mfma_f32_16x16x32_bf16 v[124:127], v[212:215], v[160:163], v[124:127]
	v_mfma_f32_16x16x32_bf16 v[120:123], v[220:223], v[160:163], v[120:123]
	v_mfma_f32_16x16x32_bf16 v[108:111], v[212:215], v[172:175], v[108:111]
	v_mfma_f32_16x16x32_bf16 v[104:107], v[220:223], v[172:175], v[104:107]
	v_mfma_f32_16x16x32_bf16 v[92:95], v[212:215], v[196:199], v[92:95]
	v_mfma_f32_16x16x32_bf16 v[88:91], v[220:223], v[196:199], v[88:91]
	v_mfma_f32_16x16x32_bf16 v[76:79], v[212:215], v[204:207], v[76:79]
	v_mfma_f32_16x16x32_bf16 v[72:75], v[220:223], v[204:207], v[72:75]
	s_setprio 0
	s_mov_b32 m0, s35
	v_lshl_add_u64 v[226:227], v[224:225], 0, s[46:47]
	s_barrier
	ds_read_b128 v[152:155], v182 offset:49152
	ds_read_b128 v[160:163], v182 offset:50176
	ds_read_b128 v[164:167], v182 offset:51200
	ds_read_b128 v[172:175], v182 offset:52224
	ds_read_b128 v[176:179], v182 offset:53248
	ds_read_b128 v[196:199], v182 offset:54272
	ds_read_b128 v[200:203], v182 offset:55296
	ds_read_b128 v[204:207], v182 offset:56320
	global_load_lds_dwordx4 v[226:227], off
	v_lshl_add_u64 v[224:225], v[224:225], 0, s[62:63]
	s_mov_b32 m0, s36
	s_nop 0
	global_load_lds_dwordx4 v[224:225], off
	s_barrier
	s_waitcnt lgkmcnt(0)
	s_setprio 3
	s_waitcnt lgkmcnt(0)
	v_mfma_f32_16x16x32_bf16 v[68:71], v[136:139], v[152:155], v[68:71]
	v_mfma_f32_16x16x32_bf16 v[64:67], v[144:147], v[152:155], v[64:67]
	v_mfma_f32_16x16x32_bf16 v[52:55], v[136:139], v[164:167], v[52:55]
	v_mfma_f32_16x16x32_bf16 v[48:51], v[144:147], v[164:167], v[48:51]
	v_mfma_f32_16x16x32_bf16 v[36:39], v[136:139], v[176:179], v[36:39]
	v_mfma_f32_16x16x32_bf16 v[32:35], v[144:147], v[176:179], v[32:35]
	v_mfma_f32_16x16x32_bf16 v[20:23], v[136:139], v[200:203], v[20:23]
	v_mfma_f32_16x16x32_bf16 v[16:19], v[144:147], v[200:203], v[16:19]
	v_mfma_f32_16x16x32_bf16 v[68:71], v[140:143], v[160:163], v[68:71]
	v_mfma_f32_16x16x32_bf16 v[64:67], v[148:151], v[160:163], v[64:67]
	v_mfma_f32_16x16x32_bf16 v[52:55], v[140:143], v[172:175], v[52:55]
	v_mfma_f32_16x16x32_bf16 v[48:51], v[148:151], v[172:175], v[48:51]
	v_mfma_f32_16x16x32_bf16 v[36:39], v[140:143], v[196:199], v[36:39]
	v_mfma_f32_16x16x32_bf16 v[32:35], v[148:151], v[196:199], v[32:35]
	v_mfma_f32_16x16x32_bf16 v[20:23], v[140:143], v[204:207], v[20:23]
	v_mfma_f32_16x16x32_bf16 v[16:19], v[148:151], v[204:207], v[16:19]
	s_setprio 0
	s_barrier
	s_add_i32 s4, s5, s27
	v_lshl_add_u64 v[136:137], v[184:185], 0, s[64:65]
	s_mov_b32 m0, s4
	s_nop 0
	global_load_lds_dwordx4 v[136:137], off
	v_lshl_add_u64 v[136:137], v[184:185], 0, s[66:67]
	s_add_i32 m0, s4, 0x2000
	s_nop 0
	global_load_lds_dwordx4 v[136:137], off
	s_waitcnt vmcnt(6)
	s_barrier
	s_setprio 3
	v_mfma_f32_16x16x32_bf16 v[60:63], v[208:211], v[152:155], v[60:63]
	v_mfma_f32_16x16x32_bf16 v[56:59], v[216:219], v[152:155], v[56:59]
	v_mfma_f32_16x16x32_bf16 v[44:47], v[208:211], v[164:167], v[44:47]
	v_mfma_f32_16x16x32_bf16 v[40:43], v[216:219], v[164:167], v[40:43]
	v_mfma_f32_16x16x32_bf16 v[28:31], v[208:211], v[176:179], v[28:31]
	v_mfma_f32_16x16x32_bf16 v[24:27], v[216:219], v[176:179], v[24:27]
	v_mfma_f32_16x16x32_bf16 v[12:15], v[208:211], v[200:203], v[12:15]
	v_mfma_f32_16x16x32_bf16 v[8:11], v[216:219], v[200:203], v[8:11]
	v_mfma_f32_16x16x32_bf16 v[60:63], v[212:215], v[160:163], v[60:63]
	v_mfma_f32_16x16x32_bf16 v[56:59], v[220:223], v[160:163], v[56:59]
	v_mfma_f32_16x16x32_bf16 v[44:47], v[212:215], v[172:175], v[44:47]
	v_mfma_f32_16x16x32_bf16 v[40:43], v[220:223], v[172:175], v[40:43]
	v_mfma_f32_16x16x32_bf16 v[28:31], v[212:215], v[196:199], v[28:31]
	v_mfma_f32_16x16x32_bf16 v[24:27], v[220:223], v[196:199], v[24:27]
	v_mfma_f32_16x16x32_bf16 v[12:15], v[212:215], v[204:207], v[12:15]
	v_mfma_f32_16x16x32_bf16 v[8:11], v[220:223], v[204:207], v[8:11]
	s_setprio 0
	s_add_i32 s24, s24, 2
	s_add_u32 s2, s2, 0x100
	s_addc_u32 s3, s3, 0
	s_add_u32 s22, s22, 0x100
	s_addc_u32 s23, s23, 0
	s_cmp_gt_u32 s24, 13
	s_cbranch_scc0 .Ldb_PLE1_cont
	v_readfirstlane_b32 s101, v186
	s_cmpk_gt_u32 s101, 0xff
	s_cbranch_scc1 .Ldb_PLE1_exit
	s_barrier
	s_branch .Ldb_PLE1_exit
